# v27 + K-loop MMA wave signals the phase barrier one MFMA before the end of its MFMA block (hides barrier handoff)
# baseline (speedup 1.0000x reference)
.Lpeel_13:
	ds_read_b128 v[152:155], v149
	ds_read_b128 v[156:159], v149 offset:1024
	s_add_i32 s37, s25, 2
	s_add_u32 s40, s38, 0xfff80080
	s_addc_u32 s41, s39, -1
	s_cmp_eq_u32 s36, s25
	s_cselect_b32 s43, s27, s41
	s_cselect_b32 s42, s26, s40
	s_cselect_b32 s41, s29, s23
	s_cselect_b32 s40, s28, s21
	v_lshl_add_u64 v[144:145], s[38:39], 0, v[140:141]
	s_add_i32 m0, s35, 0xc000
	global_load_lds_dwordx4 v[144:145], off
	v_lshl_add_u64 v[144:145], s[38:39], 0, v[142:143]
	s_add_i32 m0, s35, 0xe000
	s_nop 0
	global_load_lds_dwordx4 v[144:145], off
	s_waitcnt vmcnt(8)
	s_waitcnt lgkmcnt(0)
	s_barrier
	s_setprio 1
	s_waitcnt lgkmcnt(0)
	v_mfma_f32_16x16x32_bf16 v[126:129], v[152:155], v[184:187], 0
	v_mfma_f32_16x16x32_bf16 v[122:125], v[160:163], v[184:187], 0
	v_mfma_f32_16x16x32_bf16 v[110:113], v[152:155], v[196:199], 0
	v_mfma_f32_16x16x32_bf16 v[106:109], v[160:163], v[196:199], 0
	v_mfma_f32_16x16x32_bf16 v[94:97], v[152:155], v[204:207], 0
	v_mfma_f32_16x16x32_bf16 v[90:93], v[160:163], v[204:207], 0
	v_mfma_f32_16x16x32_bf16 v[78:81], v[152:155], v[212:215], 0
	v_mfma_f32_16x16x32_bf16 v[74:77], v[160:163], v[212:215], 0
	v_mfma_f32_16x16x32_bf16 v[126:129], v[156:159], v[188:191], v[126:129]
	v_mfma_f32_16x16x32_bf16 v[122:125], v[164:167], v[188:191], v[122:125]
	v_mfma_f32_16x16x32_bf16 v[110:113], v[156:159], v[200:203], v[110:113]
	v_mfma_f32_16x16x32_bf16 v[106:109], v[164:167], v[200:203], v[106:109]
	v_mfma_f32_16x16x32_bf16 v[94:97], v[156:159], v[208:211], v[94:97]
	v_mfma_f32_16x16x32_bf16 v[90:93], v[164:167], v[208:211], v[90:93]
	v_mfma_f32_16x16x32_bf16 v[78:81], v[156:159], v[216:219], v[78:81]
	v_mfma_f32_16x16x32_bf16 v[74:77], v[164:167], v[216:219], v[74:77]
	s_setprio 0
	s_setprio 1
	v_mfma_f32_16x16x32_bf16 v[118:121], v[168:171], v[184:187], 0
	v_mfma_f32_16x16x32_bf16 v[114:117], v[176:179], v[184:187], 0
	v_mfma_f32_16x16x32_bf16 v[102:105], v[168:171], v[196:199], 0
	v_mfma_f32_16x16x32_bf16 v[98:101], v[176:179], v[196:199], 0
	v_mfma_f32_16x16x32_bf16 v[86:89], v[168:171], v[204:207], 0
	v_mfma_f32_16x16x32_bf16 v[82:85], v[176:179], v[204:207], 0
	v_mfma_f32_16x16x32_bf16 v[70:73], v[168:171], v[212:215], 0
	v_mfma_f32_16x16x32_bf16 v[66:69], v[176:179], v[212:215], 0
	v_mfma_f32_16x16x32_bf16 v[118:121], v[172:175], v[188:191], v[118:121]
	v_mfma_f32_16x16x32_bf16 v[114:117], v[180:183], v[188:191], v[114:117]
	v_mfma_f32_16x16x32_bf16 v[102:105], v[172:175], v[200:203], v[102:105]
	v_mfma_f32_16x16x32_bf16 v[98:101], v[180:183], v[200:203], v[98:101]
	v_mfma_f32_16x16x32_bf16 v[86:89], v[172:175], v[208:211], v[86:89]
	v_mfma_f32_16x16x32_bf16 v[82:85], v[180:183], v[208:211], v[82:85]
	v_mfma_f32_16x16x32_bf16 v[70:73], v[172:175], v[216:219], v[70:73]
	s_barrier
	v_mfma_f32_16x16x32_bf16 v[66:69], v[180:183], v[216:219], v[66:69]
	s_setprio 0
	s_add_i32 s25, s54, s33
	v_lshl_add_u64 v[144:145], s[40:41], 0, v[132:133]
	s_mov_b32 m0, s25
	ds_read_b128 v[184:187], v151 offset:16384
	ds_read_b128 v[188:191], v151 offset:17408
	ds_read_b128 v[196:199], v151 offset:18432
	ds_read_b128 v[200:203], v151 offset:19456
	ds_read_b128 v[204:207], v151 offset:20480
	ds_read_b128 v[208:211], v151 offset:21504
	ds_read_b128 v[212:215], v151 offset:22528
	ds_read_b128 v[216:219], v151 offset:23552
	global_load_lds_dwordx4 v[144:145], off
	s_add_i32 m0, s25, 0x2000
	s_add_u32 s44, s40, 0x80000
	v_lshl_add_u64 v[192:193], s[40:41], 0, v[136:137]
	s_addc_u32 s45, s41, 0
	s_add_i32 s25, s55, s33
	global_load_lds_dwordx4 v[192:193], off
	v_lshl_add_u64 v[220:221], s[44:45], 0, v[132:133]
	s_mov_b32 m0, s25
	v_lshl_add_u64 v[222:223], s[42:43], 0, v[134:135]
	global_load_lds_dwordx4 v[220:221], off
	v_lshl_add_u64 v[220:221], s[44:45], 0, v[136:137]
	s_add_i32 m0, s25, 0x2000
	s_nop 0
	global_load_lds_dwordx4 v[220:221], off
	v_lshl_add_u64 v[220:221], s[42:43], 0, v[130:131]
	s_mov_b32 m0, s35
	s_nop 0
	global_load_lds_dwordx4 v[220:221], off
	s_mov_b32 m0, s47
	s_nop 0
	global_load_lds_dwordx4 v[222:223], off
	s_waitcnt vmcnt(8)
	s_waitcnt lgkmcnt(0)
	s_barrier
	s_setprio 1
	s_waitcnt lgkmcnt(0)
	v_mfma_f32_16x16x32_bf16 v[62:65], v[152:155], v[184:187], 0
	v_mfma_f32_16x16x32_bf16 v[58:61], v[160:163], v[184:187], 0
	v_mfma_f32_16x16x32_bf16 v[46:49], v[152:155], v[196:199], 0
	v_mfma_f32_16x16x32_bf16 v[42:45], v[160:163], v[196:199], 0
	v_mfma_f32_16x16x32_bf16 v[30:33], v[152:155], v[204:207], 0
	v_mfma_f32_16x16x32_bf16 v[26:29], v[160:163], v[204:207], 0
	v_mfma_f32_16x16x32_bf16 v[14:17], v[152:155], v[212:215], 0
	v_mfma_f32_16x16x32_bf16 v[10:13], v[160:163], v[212:215], 0
	v_mfma_f32_16x16x32_bf16 v[62:65], v[156:159], v[188:191], v[62:65]
	v_mfma_f32_16x16x32_bf16 v[58:61], v[164:167], v[188:191], v[58:61]
	v_mfma_f32_16x16x32_bf16 v[46:49], v[156:159], v[200:203], v[46:49]
	v_mfma_f32_16x16x32_bf16 v[42:45], v[164:167], v[200:203], v[42:45]
	v_mfma_f32_16x16x32_bf16 v[30:33], v[156:159], v[208:211], v[30:33]
	v_mfma_f32_16x16x32_bf16 v[26:29], v[164:167], v[208:211], v[26:29]
	v_mfma_f32_16x16x32_bf16 v[14:17], v[156:159], v[216:219], v[14:17]
	v_mfma_f32_16x16x32_bf16 v[10:13], v[164:167], v[216:219], v[10:13]
	s_setprio 0
	s_setprio 1
	v_mfma_f32_16x16x32_bf16 v[54:57], v[168:171], v[184:187], 0
	v_mfma_f32_16x16x32_bf16 v[50:53], v[176:179], v[184:187], 0
	v_mfma_f32_16x16x32_bf16 v[38:41], v[168:171], v[196:199], 0
	v_mfma_f32_16x16x32_bf16 v[34:37], v[176:179], v[196:199], 0
	v_mfma_f32_16x16x32_bf16 v[22:25], v[168:171], v[204:207], 0
	v_mfma_f32_16x16x32_bf16 v[18:21], v[176:179], v[204:207], 0
	v_mfma_f32_16x16x32_bf16 v[6:9], v[168:171], v[212:215], 0
	v_mfma_f32_16x16x32_bf16 v[2:5], v[176:179], v[212:215], 0
	v_mfma_f32_16x16x32_bf16 v[54:57], v[172:175], v[188:191], v[54:57]
	v_mfma_f32_16x16x32_bf16 v[50:53], v[180:183], v[188:191], v[50:53]
	v_mfma_f32_16x16x32_bf16 v[38:41], v[172:175], v[200:203], v[38:41]
	v_mfma_f32_16x16x32_bf16 v[34:37], v[180:183], v[200:203], v[34:37]
	v_mfma_f32_16x16x32_bf16 v[22:25], v[172:175], v[208:211], v[22:25]
	v_mfma_f32_16x16x32_bf16 v[18:21], v[180:183], v[208:211], v[18:21]
	v_mfma_f32_16x16x32_bf16 v[6:9], v[172:175], v[216:219], v[6:9]
	s_barrier
	v_mfma_f32_16x16x32_bf16 v[2:5], v[180:183], v[216:219], v[2:5]
	s_setprio 0
	s_add_i32 s25, 0, 0x18000
	s_add_i32 s44, 0, 0x1c000
	v_add_u32_e32 v164, s25, v147
	v_add_u32_e32 v180, s44, v147
	ds_read_b128 v[152:155], v164
	ds_read_b128 v[156:159], v164 offset:1024
	ds_read_b128 v[160:163], v164 offset:2048
	ds_read_b128 v[164:167], v164 offset:3072
	ds_read_b128 v[168:171], v180
	ds_read_b128 v[172:175], v180 offset:1024
	ds_read_b128 v[176:179], v180 offset:2048
	ds_read_b128 v[180:183], v180 offset:3072
	s_add_u32 s42, s42, 0x80000
	s_addc_u32 s43, s43, 0
	s_mov_b32 m0, s48
	v_lshl_add_u64 v[224:225], s[42:43], 0, v[130:131]
	ds_read_b128 v[184:187], v151 offset:32768
	ds_read_b128 v[188:191], v151 offset:33792
	ds_read_b128 v[196:199], v151 offset:34816
	ds_read_b128 v[200:203], v151 offset:35840
	ds_read_b128 v[204:207], v151 offset:36864
	ds_read_b128 v[208:211], v151 offset:37888
	ds_read_b128 v[212:215], v151 offset:38912
	ds_read_b128 v[216:219], v151 offset:39936
	global_load_lds_dwordx4 v[224:225], off
	v_lshl_add_u64 v[224:225], s[42:43], 0, v[134:135]
	s_mov_b32 m0, s49
	s_nop 0
	global_load_lds_dwordx4 v[224:225], off
	s_waitcnt vmcnt(8)
	s_waitcnt lgkmcnt(0)
	s_barrier
	s_setprio 1
	s_waitcnt lgkmcnt(0)
	v_mfma_f32_16x16x32_bf16 v[126:129], v[152:155], v[184:187], v[126:129]
	v_mfma_f32_16x16x32_bf16 v[122:125], v[160:163], v[184:187], v[122:125]
	v_mfma_f32_16x16x32_bf16 v[110:113], v[152:155], v[196:199], v[110:113]
	v_mfma_f32_16x16x32_bf16 v[106:109], v[160:163], v[196:199], v[106:109]
	v_mfma_f32_16x16x32_bf16 v[94:97], v[152:155], v[204:207], v[94:97]
	v_mfma_f32_16x16x32_bf16 v[90:93], v[160:163], v[204:207], v[90:93]
	v_mfma_f32_16x16x32_bf16 v[78:81], v[152:155], v[212:215], v[78:81]
	v_mfma_f32_16x16x32_bf16 v[74:77], v[160:163], v[212:215], v[74:77]
	v_mfma_f32_16x16x32_bf16 v[126:129], v[156:159], v[188:191], v[126:129]
	v_mfma_f32_16x16x32_bf16 v[122:125], v[164:167], v[188:191], v[122:125]
	v_mfma_f32_16x16x32_bf16 v[110:113], v[156:159], v[200:203], v[110:113]
	v_mfma_f32_16x16x32_bf16 v[106:109], v[164:167], v[200:203], v[106:109]
	v_mfma_f32_16x16x32_bf16 v[94:97], v[156:159], v[208:211], v[94:97]
	v_mfma_f32_16x16x32_bf16 v[90:93], v[164:167], v[208:211], v[90:93]
	v_mfma_f32_16x16x32_bf16 v[78:81], v[156:159], v[216:219], v[78:81]
	v_mfma_f32_16x16x32_bf16 v[74:77], v[164:167], v[216:219], v[74:77]
	s_setprio 0
	s_setprio 1
	v_mfma_f32_16x16x32_bf16 v[118:121], v[168:171], v[184:187], v[118:121]
	v_mfma_f32_16x16x32_bf16 v[114:117], v[176:179], v[184:187], v[114:117]
	v_mfma_f32_16x16x32_bf16 v[102:105], v[168:171], v[196:199], v[102:105]
	v_mfma_f32_16x16x32_bf16 v[98:101], v[176:179], v[196:199], v[98:101]
	v_mfma_f32_16x16x32_bf16 v[86:89], v[168:171], v[204:207], v[86:89]
	v_mfma_f32_16x16x32_bf16 v[82:85], v[176:179], v[204:207], v[82:85]
	v_mfma_f32_16x16x32_bf16 v[70:73], v[168:171], v[212:215], v[70:73]
	v_mfma_f32_16x16x32_bf16 v[66:69], v[176:179], v[212:215], v[66:69]
	v_mfma_f32_16x16x32_bf16 v[118:121], v[172:175], v[188:191], v[118:121]
	v_mfma_f32_16x16x32_bf16 v[114:117], v[180:183], v[188:191], v[114:117]
	v_mfma_f32_16x16x32_bf16 v[102:105], v[172:175], v[200:203], v[102:105]
	v_mfma_f32_16x16x32_bf16 v[98:101], v[180:183], v[200:203], v[98:101]
	v_mfma_f32_16x16x32_bf16 v[86:89], v[172:175], v[208:211], v[86:89]
	v_mfma_f32_16x16x32_bf16 v[82:85], v[180:183], v[208:211], v[82:85]
	v_mfma_f32_16x16x32_bf16 v[70:73], v[172:175], v[216:219], v[70:73]
	s_barrier
	v_mfma_f32_16x16x32_bf16 v[66:69], v[180:183], v[216:219], v[66:69]
	s_setprio 0
	s_add_i32 s25, s25, s33
	v_lshl_add_u64 v[144:145], v[144:145], 0, s[16:17]
	s_mov_b32 m0, s25
	ds_read_b128 v[184:187], v151 offset:49152
	ds_read_b128 v[188:191], v151 offset:50176
	ds_read_b128 v[196:199], v151 offset:51200
	ds_read_b128 v[200:203], v151 offset:52224
	ds_read_b128 v[204:207], v151 offset:53248
	ds_read_b128 v[208:211], v151 offset:54272
	ds_read_b128 v[212:215], v151 offset:55296
	ds_read_b128 v[216:219], v151 offset:56320
	global_load_lds_dwordx4 v[144:145], off
	s_add_i32 m0, s25, 0x2000
	s_add_u32 s40, s40, 0x80080
	v_lshl_add_u64 v[144:145], v[192:193], 0, s[16:17]
	s_addc_u32 s41, s41, 0
	s_add_i32 s25, s44, s33
	global_load_lds_dwordx4 v[144:145], off
	v_lshl_add_u64 v[144:145], s[40:41], 0, v[132:133]
	s_mov_b32 m0, s25
	s_nop 0
	global_load_lds_dwordx4 v[144:145], off
	v_lshl_add_u64 v[144:145], s[40:41], 0, v[136:137]
	s_add_i32 m0, s25, 0x2000
	s_nop 0
	global_load_lds_dwordx4 v[144:145], off
	v_lshl_add_u64 v[144:145], v[220:221], 0, s[16:17]
	s_mov_b32 m0, s50
	s_nop 0
	global_load_lds_dwordx4 v[144:145], off
	v_lshl_add_u64 v[144:145], v[222:223], 0, s[16:17]
	s_mov_b32 m0, s51
	s_nop 0
	global_load_lds_dwordx4 v[144:145], off
	s_waitcnt vmcnt(8)
	s_waitcnt lgkmcnt(0)
	s_barrier
	s_setprio 1
	s_waitcnt lgkmcnt(0)
	v_mfma_f32_16x16x32_bf16 v[62:65], v[152:155], v[184:187], v[62:65]
	v_mfma_f32_16x16x32_bf16 v[58:61], v[160:163], v[184:187], v[58:61]
	v_mfma_f32_16x16x32_bf16 v[46:49], v[152:155], v[196:199], v[46:49]
	v_mfma_f32_16x16x32_bf16 v[42:45], v[160:163], v[196:199], v[42:45]
	v_mfma_f32_16x16x32_bf16 v[30:33], v[152:155], v[204:207], v[30:33]
	v_mfma_f32_16x16x32_bf16 v[26:29], v[160:163], v[204:207], v[26:29]
	v_mfma_f32_16x16x32_bf16 v[14:17], v[152:155], v[212:215], v[14:17]
	v_mfma_f32_16x16x32_bf16 v[10:13], v[160:163], v[212:215], v[10:13]
	v_mfma_f32_16x16x32_bf16 v[62:65], v[156:159], v[188:191], v[62:65]
	v_mfma_f32_16x16x32_bf16 v[58:61], v[164:167], v[188:191], v[58:61]
	v_mfma_f32_16x16x32_bf16 v[46:49], v[156:159], v[200:203], v[46:49]
	v_mfma_f32_16x16x32_bf16 v[42:45], v[164:167], v[200:203], v[42:45]
	v_mfma_f32_16x16x32_bf16 v[30:33], v[156:159], v[208:211], v[30:33]
	v_mfma_f32_16x16x32_bf16 v[26:29], v[164:167], v[208:211], v[26:29]
	v_mfma_f32_16x16x32_bf16 v[14:17], v[156:159], v[216:219], v[14:17]
	v_mfma_f32_16x16x32_bf16 v[10:13], v[164:167], v[216:219], v[10:13]
	s_setprio 0
	s_setprio 1
	v_mfma_f32_16x16x32_bf16 v[54:57], v[168:171], v[184:187], v[54:57]
	v_mfma_f32_16x16x32_bf16 v[50:53], v[176:179], v[184:187], v[50:53]
	v_mfma_f32_16x16x32_bf16 v[38:41], v[168:171], v[196:199], v[38:41]
	v_mfma_f32_16x16x32_bf16 v[34:37], v[176:179], v[196:199], v[34:37]
	v_mfma_f32_16x16x32_bf16 v[22:25], v[168:171], v[204:207], v[22:25]
	v_mfma_f32_16x16x32_bf16 v[18:21], v[176:179], v[204:207], v[18:21]
	v_mfma_f32_16x16x32_bf16 v[6:9], v[168:171], v[212:215], v[6:9]
	v_mfma_f32_16x16x32_bf16 v[2:5], v[176:179], v[212:215], v[2:5]
	v_mfma_f32_16x16x32_bf16 v[54:57], v[172:175], v[188:191], v[54:57]
	v_mfma_f32_16x16x32_bf16 v[50:53], v[180:183], v[188:191], v[50:53]
	v_mfma_f32_16x16x32_bf16 v[38:41], v[172:175], v[200:203], v[38:41]
	v_mfma_f32_16x16x32_bf16 v[34:37], v[180:183], v[200:203], v[34:37]
	v_mfma_f32_16x16x32_bf16 v[22:25], v[172:175], v[208:211], v[22:25]
	v_mfma_f32_16x16x32_bf16 v[18:21], v[180:183], v[208:211], v[18:21]
	v_mfma_f32_16x16x32_bf16 v[6:9], v[172:175], v[216:219], v[6:9]
	s_barrier
	v_mfma_f32_16x16x32_bf16 v[2:5], v[180:183], v[216:219], v[2:5]
	s_setprio 0
	s_add_u32 s38, s38, 0x100
	s_addc_u32 s39, s39, 0
	s_add_u32 s21, s21, 0x100
	s_addc_u32 s23, s23, 0
	s_cmp_ge_i32 s37, s62
	s_mov_b32 s25, s37
	s_cbranch_scc0 .LBB0_221
	s_branch .Lpeeldone_13
.LBB0_221:
	ds_read_b128 v[152:155], v149
	ds_read_b128 v[156:159], v149 offset:1024
	ds_read_b128 v[160:163], v149 offset:2048
	ds_read_b128 v[164:167], v149 offset:3072
	ds_read_b128 v[168:171], v150
	ds_read_b128 v[172:175], v150 offset:1024
	ds_read_b128 v[176:179], v150 offset:2048
	ds_read_b128 v[180:183], v150 offset:3072
	s_add_i32 s37, s25, 2
	s_add_u32 s40, s38, 0xfff80080
	s_addc_u32 s41, s39, -1
	s_cmp_eq_u32 s36, s25
	s_cselect_b32 s43, s27, s41
	s_cselect_b32 s42, s26, s40
	s_cselect_b32 s41, s29, s23
	s_cselect_b32 s40, s28, s21
	v_lshl_add_u64 v[144:145], s[38:39], 0, v[140:141]
	s_add_i32 m0, s35, 0xc000
	ds_read_b128 v[184:187], v151
	ds_read_b128 v[188:191], v151 offset:1024
	ds_read_b128 v[196:199], v151 offset:2048
	ds_read_b128 v[200:203], v151 offset:3072
	ds_read_b128 v[204:207], v151 offset:4096
	ds_read_b128 v[208:211], v151 offset:5120
	ds_read_b128 v[212:215], v151 offset:6144
	ds_read_b128 v[216:219], v151 offset:7168
	global_load_lds_dwordx4 v[144:145], off
	v_lshl_add_u64 v[144:145], s[38:39], 0, v[142:143]
	s_add_i32 m0, s35, 0xe000
	s_nop 0
	global_load_lds_dwordx4 v[144:145], off
	s_waitcnt vmcnt(8)
	s_waitcnt lgkmcnt(0)
	s_barrier
	s_setprio 1
	s_waitcnt lgkmcnt(0)
	v_mfma_f32_16x16x32_bf16 v[126:129], v[152:155], v[184:187], v[126:129]
	v_mfma_f32_16x16x32_bf16 v[122:125], v[160:163], v[184:187], v[122:125]
	v_mfma_f32_16x16x32_bf16 v[110:113], v[152:155], v[196:199], v[110:113]
	v_mfma_f32_16x16x32_bf16 v[106:109], v[160:163], v[196:199], v[106:109]
	v_mfma_f32_16x16x32_bf16 v[94:97], v[152:155], v[204:207], v[94:97]
	v_mfma_f32_16x16x32_bf16 v[90:93], v[160:163], v[204:207], v[90:93]
	v_mfma_f32_16x16x32_bf16 v[78:81], v[152:155], v[212:215], v[78:81]
	v_mfma_f32_16x16x32_bf16 v[74:77], v[160:163], v[212:215], v[74:77]
	v_mfma_f32_16x16x32_bf16 v[126:129], v[156:159], v[188:191], v[126:129]
	v_mfma_f32_16x16x32_bf16 v[122:125], v[164:167], v[188:191], v[122:125]
	v_mfma_f32_16x16x32_bf16 v[110:113], v[156:159], v[200:203], v[110:113]
	v_mfma_f32_16x16x32_bf16 v[106:109], v[164:167], v[200:203], v[106:109]
	v_mfma_f32_16x16x32_bf16 v[94:97], v[156:159], v[208:211], v[94:97]
	v_mfma_f32_16x16x32_bf16 v[90:93], v[164:167], v[208:211], v[90:93]
	v_mfma_f32_16x16x32_bf16 v[78:81], v[156:159], v[216:219], v[78:81]
	v_mfma_f32_16x16x32_bf16 v[74:77], v[164:167], v[216:219], v[74:77]
	s_setprio 0
	s_setprio 1
	v_mfma_f32_16x16x32_bf16 v[118:121], v[168:171], v[184:187], v[118:121]
	v_mfma_f32_16x16x32_bf16 v[114:117], v[176:179], v[184:187], v[114:117]
	v_mfma_f32_16x16x32_bf16 v[102:105], v[168:171], v[196:199], v[102:105]
	v_mfma_f32_16x16x32_bf16 v[98:101], v[176:179], v[196:199], v[98:101]
	v_mfma_f32_16x16x32_bf16 v[86:89], v[168:171], v[204:207], v[86:89]
	v_mfma_f32_16x16x32_bf16 v[82:85], v[176:179], v[204:207], v[82:85]
	v_mfma_f32_16x16x32_bf16 v[70:73], v[168:171], v[212:215], v[70:73]
	v_mfma_f32_16x16x32_bf16 v[66:69], v[176:179], v[212:215], v[66:69]
	v_mfma_f32_16x16x32_bf16 v[118:121], v[172:175], v[188:191], v[118:121]
	v_mfma_f32_16x16x32_bf16 v[114:117], v[180:183], v[188:191], v[114:117]
	v_mfma_f32_16x16x32_bf16 v[102:105], v[172:175], v[200:203], v[102:105]
	v_mfma_f32_16x16x32_bf16 v[98:101], v[180:183], v[200:203], v[98:101]
	v_mfma_f32_16x16x32_bf16 v[86:89], v[172:175], v[208:211], v[86:89]
	v_mfma_f32_16x16x32_bf16 v[82:85], v[180:183], v[208:211], v[82:85]
	v_mfma_f32_16x16x32_bf16 v[70:73], v[172:175], v[216:219], v[70:73]
	s_barrier
	v_mfma_f32_16x16x32_bf16 v[66:69], v[180:183], v[216:219], v[66:69]
	s_setprio 0
	s_add_i32 s25, s54, s33
	v_lshl_add_u64 v[144:145], s[40:41], 0, v[132:133]
	s_mov_b32 m0, s25
	ds_read_b128 v[184:187], v151 offset:16384
	ds_read_b128 v[188:191], v151 offset:17408
	ds_read_b128 v[196:199], v151 offset:18432
	ds_read_b128 v[200:203], v151 offset:19456
	ds_read_b128 v[204:207], v151 offset:20480
	ds_read_b128 v[208:211], v151 offset:21504
	ds_read_b128 v[212:215], v151 offset:22528
	ds_read_b128 v[216:219], v151 offset:23552
	global_load_lds_dwordx4 v[144:145], off
	s_add_i32 m0, s25, 0x2000
	s_add_u32 s44, s40, 0x80000
	v_lshl_add_u64 v[192:193], s[40:41], 0, v[136:137]
	s_addc_u32 s45, s41, 0
	s_add_i32 s25, s55, s33
	global_load_lds_dwordx4 v[192:193], off
	v_lshl_add_u64 v[220:221], s[44:45], 0, v[132:133]
	s_mov_b32 m0, s25
	v_lshl_add_u64 v[222:223], s[42:43], 0, v[134:135]
	global_load_lds_dwordx4 v[220:221], off
	v_lshl_add_u64 v[220:221], s[44:45], 0, v[136:137]
	s_add_i32 m0, s25, 0x2000
	s_nop 0
	global_load_lds_dwordx4 v[220:221], off
	v_lshl_add_u64 v[220:221], s[42:43], 0, v[130:131]
	s_mov_b32 m0, s35
	s_nop 0
	global_load_lds_dwordx4 v[220:221], off
	s_mov_b32 m0, s47
	s_nop 0
	global_load_lds_dwordx4 v[222:223], off
	s_waitcnt vmcnt(8)
	s_waitcnt lgkmcnt(0)
	s_barrier
	s_setprio 1
	s_waitcnt lgkmcnt(0)
	v_mfma_f32_16x16x32_bf16 v[62:65], v[152:155], v[184:187], v[62:65]
	v_mfma_f32_16x16x32_bf16 v[58:61], v[160:163], v[184:187], v[58:61]
	v_mfma_f32_16x16x32_bf16 v[46:49], v[152:155], v[196:199], v[46:49]
	v_mfma_f32_16x16x32_bf16 v[42:45], v[160:163], v[196:199], v[42:45]
	v_mfma_f32_16x16x32_bf16 v[30:33], v[152:155], v[204:207], v[30:33]
	v_mfma_f32_16x16x32_bf16 v[26:29], v[160:163], v[204:207], v[26:29]
	v_mfma_f32_16x16x32_bf16 v[14:17], v[152:155], v[212:215], v[14:17]
	v_mfma_f32_16x16x32_bf16 v[10:13], v[160:163], v[212:215], v[10:13]
	v_mfma_f32_16x16x32_bf16 v[62:65], v[156:159], v[188:191], v[62:65]
	v_mfma_f32_16x16x32_bf16 v[58:61], v[164:167], v[188:191], v[58:61]
	v_mfma_f32_16x16x32_bf16 v[46:49], v[156:159], v[200:203], v[46:49]
	v_mfma_f32_16x16x32_bf16 v[42:45], v[164:167], v[200:203], v[42:45]
	v_mfma_f32_16x16x32_bf16 v[30:33], v[156:159], v[208:211], v[30:33]
	v_mfma_f32_16x16x32_bf16 v[26:29], v[164:167], v[208:211], v[26:29]
	v_mfma_f32_16x16x32_bf16 v[14:17], v[156:159], v[216:219], v[14:17]
	v_mfma_f32_16x16x32_bf16 v[10:13], v[164:167], v[216:219], v[10:13]
	s_setprio 0
	s_setprio 1
	v_mfma_f32_16x16x32_bf16 v[54:57], v[168:171], v[184:187], v[54:57]
	v_mfma_f32_16x16x32_bf16 v[50:53], v[176:179], v[184:187], v[50:53]
	v_mfma_f32_16x16x32_bf16 v[38:41], v[168:171], v[196:199], v[38:41]
	v_mfma_f32_16x16x32_bf16 v[34:37], v[176:179], v[196:199], v[34:37]
	v_mfma_f32_16x16x32_bf16 v[22:25], v[168:171], v[204:207], v[22:25]
	v_mfma_f32_16x16x32_bf16 v[18:21], v[176:179], v[204:207], v[18:21]
	v_mfma_f32_16x16x32_bf16 v[6:9], v[168:171], v[212:215], v[6:9]
	v_mfma_f32_16x16x32_bf16 v[2:5], v[176:179], v[212:215], v[2:5]
	v_mfma_f32_16x16x32_bf16 v[54:57], v[172:175], v[188:191], v[54:57]
	v_mfma_f32_16x16x32_bf16 v[50:53], v[180:183], v[188:191], v[50:53]
	v_mfma_f32_16x16x32_bf16 v[38:41], v[172:175], v[200:203], v[38:41]
	v_mfma_f32_16x16x32_bf16 v[34:37], v[180:183], v[200:203], v[34:37]
	v_mfma_f32_16x16x32_bf16 v[22:25], v[172:175], v[208:211], v[22:25]
	v_mfma_f32_16x16x32_bf16 v[18:21], v[180:183], v[208:211], v[18:21]
	v_mfma_f32_16x16x32_bf16 v[6:9], v[172:175], v[216:219], v[6:9]
	s_barrier
	v_mfma_f32_16x16x32_bf16 v[2:5], v[180:183], v[216:219], v[2:5]
	s_setprio 0
	s_add_i32 s25, 0, 0x18000
	s_add_i32 s44, 0, 0x1c000
	v_add_u32_e32 v164, s25, v147
	v_add_u32_e32 v180, s44, v147
	ds_read_b128 v[152:155], v164
	ds_read_b128 v[156:159], v164 offset:1024
	ds_read_b128 v[160:163], v164 offset:2048
	ds_read_b128 v[164:167], v164 offset:3072
	ds_read_b128 v[168:171], v180
	ds_read_b128 v[172:175], v180 offset:1024
	ds_read_b128 v[176:179], v180 offset:2048
	ds_read_b128 v[180:183], v180 offset:3072
	s_add_u32 s42, s42, 0x80000
	s_addc_u32 s43, s43, 0
	s_mov_b32 m0, s48
	v_lshl_add_u64 v[224:225], s[42:43], 0, v[130:131]
	ds_read_b128 v[184:187], v151 offset:32768
	ds_read_b128 v[188:191], v151 offset:33792
	ds_read_b128 v[196:199], v151 offset:34816
	ds_read_b128 v[200:203], v151 offset:35840
	ds_read_b128 v[204:207], v151 offset:36864
	ds_read_b128 v[208:211], v151 offset:37888
	ds_read_b128 v[212:215], v151 offset:38912
	ds_read_b128 v[216:219], v151 offset:39936
	global_load_lds_dwordx4 v[224:225], off
	v_lshl_add_u64 v[224:225], s[42:43], 0, v[134:135]
	s_mov_b32 m0, s49
	s_nop 0
	global_load_lds_dwordx4 v[224:225], off
	s_waitcnt vmcnt(8)
	s_waitcnt lgkmcnt(0)
	s_barrier
	s_setprio 1
	s_waitcnt lgkmcnt(0)
	v_mfma_f32_16x16x32_bf16 v[126:129], v[152:155], v[184:187], v[126:129]
	v_mfma_f32_16x16x32_bf16 v[122:125], v[160:163], v[184:187], v[122:125]
	v_mfma_f32_16x16x32_bf16 v[110:113], v[152:155], v[196:199], v[110:113]
	v_mfma_f32_16x16x32_bf16 v[106:109], v[160:163], v[196:199], v[106:109]
	v_mfma_f32_16x16x32_bf16 v[94:97], v[152:155], v[204:207], v[94:97]
	v_mfma_f32_16x16x32_bf16 v[90:93], v[160:163], v[204:207], v[90:93]
	v_mfma_f32_16x16x32_bf16 v[78:81], v[152:155], v[212:215], v[78:81]
	v_mfma_f32_16x16x32_bf16 v[74:77], v[160:163], v[212:215], v[74:77]
	v_mfma_f32_16x16x32_bf16 v[126:129], v[156:159], v[188:191], v[126:129]
	v_mfma_f32_16x16x32_bf16 v[122:125], v[164:167], v[188:191], v[122:125]
	v_mfma_f32_16x16x32_bf16 v[110:113], v[156:159], v[200:203], v[110:113]
	v_mfma_f32_16x16x32_bf16 v[106:109], v[164:167], v[200:203], v[106:109]
	v_mfma_f32_16x16x32_bf16 v[94:97], v[156:159], v[208:211], v[94:97]
	v_mfma_f32_16x16x32_bf16 v[90:93], v[164:167], v[208:211], v[90:93]
	v_mfma_f32_16x16x32_bf16 v[78:81], v[156:159], v[216:219], v[78:81]
	v_mfma_f32_16x16x32_bf16 v[74:77], v[164:167], v[216:219], v[74:77]
	s_setprio 0
	s_setprio 1
	v_mfma_f32_16x16x32_bf16 v[118:121], v[168:171], v[184:187], v[118:121]
	v_mfma_f32_16x16x32_bf16 v[114:117], v[176:179], v[184:187], v[114:117]
	v_mfma_f32_16x16x32_bf16 v[102:105], v[168:171], v[196:199], v[102:105]
	v_mfma_f32_16x16x32_bf16 v[98:101], v[176:179], v[196:199], v[98:101]
	v_mfma_f32_16x16x32_bf16 v[86:89], v[168:171], v[204:207], v[86:89]
	v_mfma_f32_16x16x32_bf16 v[82:85], v[176:179], v[204:207], v[82:85]
	v_mfma_f32_16x16x32_bf16 v[70:73], v[168:171], v[212:215], v[70:73]
	v_mfma_f32_16x16x32_bf16 v[66:69], v[176:179], v[212:215], v[66:69]
	v_mfma_f32_16x16x32_bf16 v[118:121], v[172:175], v[188:191], v[118:121]
	v_mfma_f32_16x16x32_bf16 v[114:117], v[180:183], v[188:191], v[114:117]
	v_mfma_f32_16x16x32_bf16 v[102:105], v[172:175], v[200:203], v[102:105]
	v_mfma_f32_16x16x32_bf16 v[98:101], v[180:183], v[200:203], v[98:101]
	v_mfma_f32_16x16x32_bf16 v[86:89], v[172:175], v[208:211], v[86:89]
	v_mfma_f32_16x16x32_bf16 v[82:85], v[180:183], v[208:211], v[82:85]
	v_mfma_f32_16x16x32_bf16 v[70:73], v[172:175], v[216:219], v[70:73]
	s_barrier
	v_mfma_f32_16x16x32_bf16 v[66:69], v[180:183], v[216:219], v[66:69]
	s_setprio 0
	s_add_i32 s25, s25, s33
	v_lshl_add_u64 v[144:145], v[144:145], 0, s[16:17]
	s_mov_b32 m0, s25
	ds_read_b128 v[184:187], v151 offset:49152
	ds_read_b128 v[188:191], v151 offset:50176
	ds_read_b128 v[196:199], v151 offset:51200
	ds_read_b128 v[200:203], v151 offset:52224
	ds_read_b128 v[204:207], v151 offset:53248
	ds_read_b128 v[208:211], v151 offset:54272
	ds_read_b128 v[212:215], v151 offset:55296
	ds_read_b128 v[216:219], v151 offset:56320
	global_load_lds_dwordx4 v[144:145], off
	s_add_i32 m0, s25, 0x2000
	s_add_u32 s40, s40, 0x80080
	v_lshl_add_u64 v[144:145], v[192:193], 0, s[16:17]
	s_addc_u32 s41, s41, 0
	s_add_i32 s25, s44, s33
	global_load_lds_dwordx4 v[144:145], off
	v_lshl_add_u64 v[144:145], s[40:41], 0, v[132:133]
	s_mov_b32 m0, s25
	s_nop 0
	global_load_lds_dwordx4 v[144:145], off
	v_lshl_add_u64 v[144:145], s[40:41], 0, v[136:137]
	s_add_i32 m0, s25, 0x2000
	s_nop 0
	global_load_lds_dwordx4 v[144:145], off
	v_lshl_add_u64 v[144:145], v[220:221], 0, s[16:17]
	s_mov_b32 m0, s50
	s_nop 0
	global_load_lds_dwordx4 v[144:145], off
	v_lshl_add_u64 v[144:145], v[222:223], 0, s[16:17]
	s_mov_b32 m0, s51
	s_nop 0
	global_load_lds_dwordx4 v[144:145], off
	s_waitcnt vmcnt(8)
	s_waitcnt lgkmcnt(0)
	s_barrier
	s_setprio 1
	s_waitcnt lgkmcnt(0)
	v_mfma_f32_16x16x32_bf16 v[62:65], v[152:155], v[184:187], v[62:65]
	v_mfma_f32_16x16x32_bf16 v[58:61], v[160:163], v[184:187], v[58:61]
	v_mfma_f32_16x16x32_bf16 v[46:49], v[152:155], v[196:199], v[46:49]
	v_mfma_f32_16x16x32_bf16 v[42:45], v[160:163], v[196:199], v[42:45]
	v_mfma_f32_16x16x32_bf16 v[30:33], v[152:155], v[204:207], v[30:33]
	v_mfma_f32_16x16x32_bf16 v[26:29], v[160:163], v[204:207], v[26:29]
	v_mfma_f32_16x16x32_bf16 v[14:17], v[152:155], v[212:215], v[14:17]
	v_mfma_f32_16x16x32_bf16 v[10:13], v[160:163], v[212:215], v[10:13]
	v_mfma_f32_16x16x32_bf16 v[62:65], v[156:159], v[188:191], v[62:65]
	v_mfma_f32_16x16x32_bf16 v[58:61], v[164:167], v[188:191], v[58:61]
	v_mfma_f32_16x16x32_bf16 v[46:49], v[156:159], v[200:203], v[46:49]
	v_mfma_f32_16x16x32_bf16 v[42:45], v[164:167], v[200:203], v[42:45]
	v_mfma_f32_16x16x32_bf16 v[30:33], v[156:159], v[208:211], v[30:33]
	v_mfma_f32_16x16x32_bf16 v[26:29], v[164:167], v[208:211], v[26:29]
	v_mfma_f32_16x16x32_bf16 v[14:17], v[156:159], v[216:219], v[14:17]
	v_mfma_f32_16x16x32_bf16 v[10:13], v[164:167], v[216:219], v[10:13]
	s_setprio 0
	s_setprio 1
	v_mfma_f32_16x16x32_bf16 v[54:57], v[168:171], v[184:187], v[54:57]
	v_mfma_f32_16x16x32_bf16 v[50:53], v[176:179], v[184:187], v[50:53]
	v_mfma_f32_16x16x32_bf16 v[38:41], v[168:171], v[196:199], v[38:41]
	v_mfma_f32_16x16x32_bf16 v[34:37], v[176:179], v[196:199], v[34:37]
	v_mfma_f32_16x16x32_bf16 v[22:25], v[168:171], v[204:207], v[22:25]
	v_mfma_f32_16x16x32_bf16 v[18:21], v[176:179], v[204:207], v[18:21]
	v_mfma_f32_16x16x32_bf16 v[6:9], v[168:171], v[212:215], v[6:9]
	v_mfma_f32_16x16x32_bf16 v[2:5], v[176:179], v[212:215], v[2:5]
	v_mfma_f32_16x16x32_bf16 v[54:57], v[172:175], v[188:191], v[54:57]
	v_mfma_f32_16x16x32_bf16 v[50:53], v[180:183], v[188:191], v[50:53]
	v_mfma_f32_16x16x32_bf16 v[38:41], v[172:175], v[200:203], v[38:41]
	v_mfma_f32_16x16x32_bf16 v[34:37], v[180:183], v[200:203], v[34:37]
	v_mfma_f32_16x16x32_bf16 v[22:25], v[172:175], v[208:211], v[22:25]
	v_mfma_f32_16x16x32_bf16 v[18:21], v[180:183], v[208:211], v[18:21]
	v_mfma_f32_16x16x32_bf16 v[6:9], v[172:175], v[216:219], v[6:9]
	s_barrier
	v_mfma_f32_16x16x32_bf16 v[2:5], v[180:183], v[216:219], v[2:5]
	s_setprio 0
	s_add_u32 s38, s38, 0x100
	s_addc_u32 s39, s39, 0
	s_add_u32 s21, s21, 0x100
	s_addc_u32 s23, s23, 0
	s_cmp_ge_i32 s37, s62
	s_mov_b32 s25, s37
	s_cbranch_scc0 .LBB0_221

.Lpeel_12:
	ds_read_b128 v[130:133], v215
	ds_read_b128 v[134:137], v215 offset:1024
	ds_read_b128 v[138:141], v215 offset:2048
	ds_read_b128 v[142:145], v215 offset:3072
	ds_read_b128 v[146:149], v216
	ds_read_b128 v[150:153], v216 offset:1024
	ds_read_b128 v[154:157], v216 offset:2048
	ds_read_b128 v[158:161], v216 offset:3072
	s_add_i32 s38, s34, 2
	s_add_u32 s35, s30, 0xffea0080
	s_addc_u32 s36, s31, -1
	s_cmp_eq_u32 s28, s34
	s_cselect_b32 s34, s26, s23
	s_cselect_b32 s37, s25, s36
	s_cselect_b32 s36, s24, s35
	s_cselect_b32 s35, s27, s29
	v_lshl_add_u64 v[192:193], s[30:31], 0, v[188:189]
	s_add_i32 m0, s40, 0xc000
	ds_read_b128 v[162:165], v217
	ds_read_b128 v[166:169], v217 offset:1024
	ds_read_b128 v[170:173], v217 offset:2048
	ds_read_b128 v[174:177], v217 offset:3072
	ds_read_b128 v[196:199], v217 offset:4096
	ds_read_b128 v[200:203], v217 offset:5120
	ds_read_b128 v[204:207], v217 offset:6144
	ds_read_b128 v[208:211], v217 offset:7168
	global_load_lds_dwordx4 v[192:193], off
	v_lshl_add_u64 v[192:193], s[30:31], 0, v[190:191]
	s_add_i32 m0, s40, 0xe000
	s_nop 0
	global_load_lds_dwordx4 v[192:193], off
	s_waitcnt vmcnt(8)
	s_waitcnt lgkmcnt(0)
	s_barrier
	s_setprio 1
	s_waitcnt lgkmcnt(0)
	v_mfma_f32_16x16x32_bf16 v[126:129], v[130:133], v[162:165], 0
	v_mfma_f32_16x16x32_bf16 v[122:125], v[138:141], v[162:165], 0
	v_mfma_f32_16x16x32_bf16 v[118:121], v[130:133], v[170:173], 0
	v_mfma_f32_16x16x32_bf16 v[114:117], v[138:141], v[170:173], 0
	v_mfma_f32_16x16x32_bf16 v[94:97], v[130:133], v[196:199], 0
	v_mfma_f32_16x16x32_bf16 v[90:93], v[138:141], v[196:199], 0
	v_mfma_f32_16x16x32_bf16 v[86:89], v[130:133], v[204:207], 0
	v_mfma_f32_16x16x32_bf16 v[82:85], v[138:141], v[204:207], 0
	v_mfma_f32_16x16x32_bf16 v[126:129], v[134:137], v[166:169], v[126:129]
	v_mfma_f32_16x16x32_bf16 v[122:125], v[142:145], v[166:169], v[122:125]
	v_mfma_f32_16x16x32_bf16 v[118:121], v[134:137], v[174:177], v[118:121]
	v_mfma_f32_16x16x32_bf16 v[114:117], v[142:145], v[174:177], v[114:117]
	v_mfma_f32_16x16x32_bf16 v[94:97], v[134:137], v[200:203], v[94:97]
	v_mfma_f32_16x16x32_bf16 v[90:93], v[142:145], v[200:203], v[90:93]
	v_mfma_f32_16x16x32_bf16 v[86:89], v[134:137], v[208:211], v[86:89]
	v_mfma_f32_16x16x32_bf16 v[82:85], v[142:145], v[208:211], v[82:85]
	s_setprio 0
	s_setprio 1
	v_mfma_f32_16x16x32_bf16 v[110:113], v[146:149], v[162:165], 0
	v_mfma_f32_16x16x32_bf16 v[106:109], v[154:157], v[162:165], 0
	v_mfma_f32_16x16x32_bf16 v[102:105], v[146:149], v[170:173], 0
	v_mfma_f32_16x16x32_bf16 v[98:101], v[154:157], v[170:173], 0
	v_mfma_f32_16x16x32_bf16 v[78:81], v[146:149], v[196:199], 0
	v_mfma_f32_16x16x32_bf16 v[74:77], v[154:157], v[196:199], 0
	v_mfma_f32_16x16x32_bf16 v[70:73], v[146:149], v[204:207], 0
	v_mfma_f32_16x16x32_bf16 v[66:69], v[154:157], v[204:207], 0
	v_mfma_f32_16x16x32_bf16 v[110:113], v[150:153], v[166:169], v[110:113]
	v_mfma_f32_16x16x32_bf16 v[106:109], v[158:161], v[166:169], v[106:109]
	v_mfma_f32_16x16x32_bf16 v[102:105], v[150:153], v[174:177], v[102:105]
	v_mfma_f32_16x16x32_bf16 v[98:101], v[158:161], v[174:177], v[98:101]
	v_mfma_f32_16x16x32_bf16 v[78:81], v[150:153], v[200:203], v[78:81]
	v_mfma_f32_16x16x32_bf16 v[74:77], v[158:161], v[200:203], v[74:77]
	v_mfma_f32_16x16x32_bf16 v[70:73], v[150:153], v[208:211], v[70:73]
	s_barrier
	v_mfma_f32_16x16x32_bf16 v[66:69], v[158:161], v[208:211], v[66:69]
	s_setprio 0
	s_add_i32 s39, s53, s33
	v_lshl_add_u64 v[192:193], s[34:35], 0, v[180:181]
	s_mov_b32 m0, s39
	ds_read_b128 v[162:165], v217 offset:16384
	ds_read_b128 v[166:169], v217 offset:17408
	ds_read_b128 v[170:173], v217 offset:18432
	ds_read_b128 v[174:177], v217 offset:19456
	ds_read_b128 v[196:199], v217 offset:20480
	ds_read_b128 v[200:203], v217 offset:21504
	ds_read_b128 v[204:207], v217 offset:22528
	ds_read_b128 v[208:211], v217 offset:23552
	global_load_lds_dwordx4 v[192:193], off
	s_add_i32 m0, s39, 0x2000
	s_add_u32 s62, s34, 0x160000
	v_lshl_add_u64 v[218:219], s[34:35], 0, v[184:185]
	s_addc_u32 s63, s35, 0
	s_add_i32 s39, s54, s33
	global_load_lds_dwordx4 v[218:219], off
	v_lshl_add_u64 v[220:221], s[62:63], 0, v[180:181]
	s_mov_b32 m0, s39
	v_lshl_add_u64 v[222:223], s[36:37], 0, v[182:183]
	global_load_lds_dwordx4 v[220:221], off
	v_lshl_add_u64 v[220:221], s[62:63], 0, v[184:185]
	s_add_i32 m0, s39, 0x2000
	s_nop 0
	global_load_lds_dwordx4 v[220:221], off
	v_lshl_add_u64 v[220:221], s[36:37], 0, v[178:179]
	s_mov_b32 m0, s40
	s_nop 0
	global_load_lds_dwordx4 v[220:221], off
	s_mov_b32 m0, s41
	s_nop 0
	global_load_lds_dwordx4 v[222:223], off
	s_waitcnt vmcnt(8)
	s_waitcnt lgkmcnt(0)
	s_barrier
	s_setprio 1
	s_waitcnt lgkmcnt(0)
	v_mfma_f32_16x16x32_bf16 v[62:65], v[130:133], v[162:165], 0
	v_mfma_f32_16x16x32_bf16 v[58:61], v[138:141], v[162:165], 0
	v_mfma_f32_16x16x32_bf16 v[54:57], v[130:133], v[170:173], 0
	v_mfma_f32_16x16x32_bf16 v[50:53], v[138:141], v[170:173], 0
	v_mfma_f32_16x16x32_bf16 v[30:33], v[130:133], v[196:199], 0
	v_mfma_f32_16x16x32_bf16 v[26:29], v[138:141], v[196:199], 0
	v_mfma_f32_16x16x32_bf16 v[22:25], v[130:133], v[204:207], 0
	v_mfma_f32_16x16x32_bf16 v[18:21], v[138:141], v[204:207], 0
	v_mfma_f32_16x16x32_bf16 v[62:65], v[134:137], v[166:169], v[62:65]
	v_mfma_f32_16x16x32_bf16 v[58:61], v[142:145], v[166:169], v[58:61]
	v_mfma_f32_16x16x32_bf16 v[54:57], v[134:137], v[174:177], v[54:57]
	v_mfma_f32_16x16x32_bf16 v[50:53], v[142:145], v[174:177], v[50:53]
	v_mfma_f32_16x16x32_bf16 v[30:33], v[134:137], v[200:203], v[30:33]
	v_mfma_f32_16x16x32_bf16 v[26:29], v[142:145], v[200:203], v[26:29]
	v_mfma_f32_16x16x32_bf16 v[22:25], v[134:137], v[208:211], v[22:25]
	v_mfma_f32_16x16x32_bf16 v[18:21], v[142:145], v[208:211], v[18:21]
	s_setprio 0
	s_setprio 1
	v_mfma_f32_16x16x32_bf16 v[46:49], v[146:149], v[162:165], 0
	v_mfma_f32_16x16x32_bf16 v[42:45], v[154:157], v[162:165], 0
	v_mfma_f32_16x16x32_bf16 v[38:41], v[146:149], v[170:173], 0
	v_mfma_f32_16x16x32_bf16 v[34:37], v[154:157], v[170:173], 0
	v_mfma_f32_16x16x32_bf16 v[14:17], v[146:149], v[196:199], 0
	v_mfma_f32_16x16x32_bf16 v[10:13], v[154:157], v[196:199], 0
	v_mfma_f32_16x16x32_bf16 v[6:9], v[146:149], v[204:207], 0
	v_mfma_f32_16x16x32_bf16 v[2:5], v[154:157], v[204:207], 0
	v_mfma_f32_16x16x32_bf16 v[46:49], v[150:153], v[166:169], v[46:49]
	v_mfma_f32_16x16x32_bf16 v[42:45], v[158:161], v[166:169], v[42:45]
	v_mfma_f32_16x16x32_bf16 v[38:41], v[150:153], v[174:177], v[38:41]
	v_mfma_f32_16x16x32_bf16 v[34:37], v[158:161], v[174:177], v[34:37]
	v_mfma_f32_16x16x32_bf16 v[14:17], v[150:153], v[200:203], v[14:17]
	v_mfma_f32_16x16x32_bf16 v[10:13], v[158:161], v[200:203], v[10:13]
	v_mfma_f32_16x16x32_bf16 v[6:9], v[150:153], v[208:211], v[6:9]
	s_barrier
	v_mfma_f32_16x16x32_bf16 v[2:5], v[158:161], v[208:211], v[2:5]
	s_setprio 0
	s_add_i32 s39, 0, 0x18000
	s_add_i32 s62, 0, 0x1c000
	v_add_u32_e32 v142, s39, v213
	v_add_u32_e32 v158, s62, v213
	ds_read_b128 v[130:133], v142
	ds_read_b128 v[134:137], v142 offset:1024
	ds_read_b128 v[138:141], v142 offset:2048
	ds_read_b128 v[142:145], v142 offset:3072
	ds_read_b128 v[146:149], v158
	ds_read_b128 v[150:153], v158 offset:1024
	ds_read_b128 v[154:157], v158 offset:2048
	ds_read_b128 v[158:161], v158 offset:3072
	s_add_u32 s36, s36, 0x160000
	s_addc_u32 s37, s37, 0
	s_mov_b32 m0, s42
	v_lshl_add_u64 v[224:225], s[36:37], 0, v[178:179]
	ds_read_b128 v[162:165], v217 offset:32768
	ds_read_b128 v[166:169], v217 offset:33792
	ds_read_b128 v[170:173], v217 offset:34816
	ds_read_b128 v[174:177], v217 offset:35840
	ds_read_b128 v[196:199], v217 offset:36864
	ds_read_b128 v[200:203], v217 offset:37888
	ds_read_b128 v[204:207], v217 offset:38912
	ds_read_b128 v[208:211], v217 offset:39936
	global_load_lds_dwordx4 v[224:225], off
	v_lshl_add_u64 v[224:225], s[36:37], 0, v[182:183]
	s_mov_b32 m0, s43
	s_nop 0
	global_load_lds_dwordx4 v[224:225], off
	s_waitcnt vmcnt(8)
	s_waitcnt lgkmcnt(0)
	s_barrier
	s_setprio 1
	s_waitcnt lgkmcnt(0)
	v_mfma_f32_16x16x32_bf16 v[126:129], v[130:133], v[162:165], v[126:129]
	v_mfma_f32_16x16x32_bf16 v[122:125], v[138:141], v[162:165], v[122:125]
	v_mfma_f32_16x16x32_bf16 v[118:121], v[130:133], v[170:173], v[118:121]
	v_mfma_f32_16x16x32_bf16 v[114:117], v[138:141], v[170:173], v[114:117]
	v_mfma_f32_16x16x32_bf16 v[94:97], v[130:133], v[196:199], v[94:97]
	v_mfma_f32_16x16x32_bf16 v[90:93], v[138:141], v[196:199], v[90:93]
	v_mfma_f32_16x16x32_bf16 v[86:89], v[130:133], v[204:207], v[86:89]
	v_mfma_f32_16x16x32_bf16 v[82:85], v[138:141], v[204:207], v[82:85]
	v_mfma_f32_16x16x32_bf16 v[126:129], v[134:137], v[166:169], v[126:129]
	v_mfma_f32_16x16x32_bf16 v[122:125], v[142:145], v[166:169], v[122:125]
	v_mfma_f32_16x16x32_bf16 v[118:121], v[134:137], v[174:177], v[118:121]
	v_mfma_f32_16x16x32_bf16 v[114:117], v[142:145], v[174:177], v[114:117]
	v_mfma_f32_16x16x32_bf16 v[94:97], v[134:137], v[200:203], v[94:97]
	v_mfma_f32_16x16x32_bf16 v[90:93], v[142:145], v[200:203], v[90:93]
	v_mfma_f32_16x16x32_bf16 v[86:89], v[134:137], v[208:211], v[86:89]
	v_mfma_f32_16x16x32_bf16 v[82:85], v[142:145], v[208:211], v[82:85]
	s_setprio 0
	s_setprio 1
	v_mfma_f32_16x16x32_bf16 v[110:113], v[146:149], v[162:165], v[110:113]
	v_mfma_f32_16x16x32_bf16 v[106:109], v[154:157], v[162:165], v[106:109]
	v_mfma_f32_16x16x32_bf16 v[102:105], v[146:149], v[170:173], v[102:105]
	v_mfma_f32_16x16x32_bf16 v[98:101], v[154:157], v[170:173], v[98:101]
	v_mfma_f32_16x16x32_bf16 v[78:81], v[146:149], v[196:199], v[78:81]
	v_mfma_f32_16x16x32_bf16 v[74:77], v[154:157], v[196:199], v[74:77]
	v_mfma_f32_16x16x32_bf16 v[70:73], v[146:149], v[204:207], v[70:73]
	v_mfma_f32_16x16x32_bf16 v[66:69], v[154:157], v[204:207], v[66:69]
	v_mfma_f32_16x16x32_bf16 v[110:113], v[150:153], v[166:169], v[110:113]
	v_mfma_f32_16x16x32_bf16 v[106:109], v[158:161], v[166:169], v[106:109]
	v_mfma_f32_16x16x32_bf16 v[102:105], v[150:153], v[174:177], v[102:105]
	v_mfma_f32_16x16x32_bf16 v[98:101], v[158:161], v[174:177], v[98:101]
	v_mfma_f32_16x16x32_bf16 v[78:81], v[150:153], v[200:203], v[78:81]
	v_mfma_f32_16x16x32_bf16 v[74:77], v[158:161], v[200:203], v[74:77]
	v_mfma_f32_16x16x32_bf16 v[70:73], v[150:153], v[208:211], v[70:73]
	s_barrier
	v_mfma_f32_16x16x32_bf16 v[66:69], v[158:161], v[208:211], v[66:69]
	s_setprio 0
	s_add_i32 s36, s39, s33
	v_lshl_add_u64 v[192:193], v[192:193], 0, s[18:19]
	s_mov_b32 m0, s36
	ds_read_b128 v[162:165], v217 offset:49152
	ds_read_b128 v[166:169], v217 offset:50176
	ds_read_b128 v[170:173], v217 offset:51200
	ds_read_b128 v[174:177], v217 offset:52224
	ds_read_b128 v[196:199], v217 offset:53248
	ds_read_b128 v[200:203], v217 offset:54272
	ds_read_b128 v[204:207], v217 offset:55296
	ds_read_b128 v[208:211], v217 offset:56320
	global_load_lds_dwordx4 v[192:193], off
	s_add_i32 m0, s36, 0x2000
	s_add_u32 s34, s34, 0x160080
	v_lshl_add_u64 v[192:193], v[218:219], 0, s[18:19]
	s_addc_u32 s35, s35, 0
	s_add_i32 s36, s62, s33
	global_load_lds_dwordx4 v[192:193], off
	v_lshl_add_u64 v[192:193], s[34:35], 0, v[180:181]
	s_mov_b32 m0, s36
	s_nop 0
	global_load_lds_dwordx4 v[192:193], off
	v_lshl_add_u64 v[192:193], s[34:35], 0, v[184:185]
	s_add_i32 m0, s36, 0x2000
	s_nop 0
	global_load_lds_dwordx4 v[192:193], off
	v_lshl_add_u64 v[192:193], v[220:221], 0, s[18:19]
	s_mov_b32 m0, s46
	s_nop 0
	global_load_lds_dwordx4 v[192:193], off
	v_lshl_add_u64 v[192:193], v[222:223], 0, s[18:19]
	s_mov_b32 m0, s47
	s_nop 0
	global_load_lds_dwordx4 v[192:193], off
	s_waitcnt vmcnt(8)
	s_waitcnt lgkmcnt(0)
	s_barrier
	s_setprio 1
	s_waitcnt lgkmcnt(0)
	v_mfma_f32_16x16x32_bf16 v[62:65], v[130:133], v[162:165], v[62:65]
	v_mfma_f32_16x16x32_bf16 v[58:61], v[138:141], v[162:165], v[58:61]
	v_mfma_f32_16x16x32_bf16 v[54:57], v[130:133], v[170:173], v[54:57]
	v_mfma_f32_16x16x32_bf16 v[50:53], v[138:141], v[170:173], v[50:53]
	v_mfma_f32_16x16x32_bf16 v[30:33], v[130:133], v[196:199], v[30:33]
	v_mfma_f32_16x16x32_bf16 v[26:29], v[138:141], v[196:199], v[26:29]
	v_mfma_f32_16x16x32_bf16 v[22:25], v[130:133], v[204:207], v[22:25]
	v_mfma_f32_16x16x32_bf16 v[18:21], v[138:141], v[204:207], v[18:21]
	v_mfma_f32_16x16x32_bf16 v[62:65], v[134:137], v[166:169], v[62:65]
	v_mfma_f32_16x16x32_bf16 v[58:61], v[142:145], v[166:169], v[58:61]
	v_mfma_f32_16x16x32_bf16 v[54:57], v[134:137], v[174:177], v[54:57]
	v_mfma_f32_16x16x32_bf16 v[50:53], v[142:145], v[174:177], v[50:53]
	v_mfma_f32_16x16x32_bf16 v[30:33], v[134:137], v[200:203], v[30:33]
	v_mfma_f32_16x16x32_bf16 v[26:29], v[142:145], v[200:203], v[26:29]
	v_mfma_f32_16x16x32_bf16 v[22:25], v[134:137], v[208:211], v[22:25]
	v_mfma_f32_16x16x32_bf16 v[18:21], v[142:145], v[208:211], v[18:21]
	s_setprio 0
	s_setprio 1
	v_mfma_f32_16x16x32_bf16 v[46:49], v[146:149], v[162:165], v[46:49]
	v_mfma_f32_16x16x32_bf16 v[42:45], v[154:157], v[162:165], v[42:45]
	v_mfma_f32_16x16x32_bf16 v[38:41], v[146:149], v[170:173], v[38:41]
	v_mfma_f32_16x16x32_bf16 v[34:37], v[154:157], v[170:173], v[34:37]
	v_mfma_f32_16x16x32_bf16 v[14:17], v[146:149], v[196:199], v[14:17]
	v_mfma_f32_16x16x32_bf16 v[10:13], v[154:157], v[196:199], v[10:13]
	v_mfma_f32_16x16x32_bf16 v[6:9], v[146:149], v[204:207], v[6:9]
	v_mfma_f32_16x16x32_bf16 v[2:5], v[154:157], v[204:207], v[2:5]
	v_mfma_f32_16x16x32_bf16 v[46:49], v[150:153], v[166:169], v[46:49]
	v_mfma_f32_16x16x32_bf16 v[42:45], v[158:161], v[166:169], v[42:45]
	v_mfma_f32_16x16x32_bf16 v[38:41], v[150:153], v[174:177], v[38:41]
	v_mfma_f32_16x16x32_bf16 v[34:37], v[158:161], v[174:177], v[34:37]
	v_mfma_f32_16x16x32_bf16 v[14:17], v[150:153], v[200:203], v[14:17]
	v_mfma_f32_16x16x32_bf16 v[10:13], v[158:161], v[200:203], v[10:13]
	v_mfma_f32_16x16x32_bf16 v[6:9], v[150:153], v[208:211], v[6:9]
	s_barrier
	v_mfma_f32_16x16x32_bf16 v[2:5], v[158:161], v[208:211], v[2:5]
	s_setprio 0
	s_add_u32 s30, s30, 0x100
	s_addc_u32 s31, s31, 0
	s_add_u32 s23, s23, 0x100
	s_addc_u32 s29, s29, 0
	s_cmp_ge_i32 s38, s61
	s_mov_b32 s34, s38
	s_cbranch_scc0 .LBB0_357
	s_branch .Lpeeldone_12
.LBB0_357:
	ds_read_b128 v[130:133], v215
	ds_read_b128 v[134:137], v215 offset:1024
	ds_read_b128 v[138:141], v215 offset:2048
	ds_read_b128 v[142:145], v215 offset:3072
	ds_read_b128 v[146:149], v216
	ds_read_b128 v[150:153], v216 offset:1024
	ds_read_b128 v[154:157], v216 offset:2048
	ds_read_b128 v[158:161], v216 offset:3072
	s_add_i32 s38, s34, 2
	s_add_u32 s35, s30, 0xffea0080
	s_addc_u32 s36, s31, -1
	s_cmp_eq_u32 s28, s34
	s_cselect_b32 s34, s26, s23
	s_cselect_b32 s37, s25, s36
	s_cselect_b32 s36, s24, s35
	s_cselect_b32 s35, s27, s29
	v_lshl_add_u64 v[192:193], s[30:31], 0, v[188:189]
	s_add_i32 m0, s40, 0xc000
	ds_read_b128 v[162:165], v217
	ds_read_b128 v[166:169], v217 offset:1024
	ds_read_b128 v[170:173], v217 offset:2048
	ds_read_b128 v[174:177], v217 offset:3072
	ds_read_b128 v[196:199], v217 offset:4096
	ds_read_b128 v[200:203], v217 offset:5120
	ds_read_b128 v[204:207], v217 offset:6144
	ds_read_b128 v[208:211], v217 offset:7168
	global_load_lds_dwordx4 v[192:193], off
	v_lshl_add_u64 v[192:193], s[30:31], 0, v[190:191]
	s_add_i32 m0, s40, 0xe000
	s_nop 0
	global_load_lds_dwordx4 v[192:193], off
	s_waitcnt vmcnt(8)
	s_waitcnt lgkmcnt(0)
	s_barrier
	s_setprio 1
	s_waitcnt lgkmcnt(0)
	v_mfma_f32_16x16x32_bf16 v[126:129], v[130:133], v[162:165], v[126:129]
	v_mfma_f32_16x16x32_bf16 v[122:125], v[138:141], v[162:165], v[122:125]
	v_mfma_f32_16x16x32_bf16 v[118:121], v[130:133], v[170:173], v[118:121]
	v_mfma_f32_16x16x32_bf16 v[114:117], v[138:141], v[170:173], v[114:117]
	v_mfma_f32_16x16x32_bf16 v[94:97], v[130:133], v[196:199], v[94:97]
	v_mfma_f32_16x16x32_bf16 v[90:93], v[138:141], v[196:199], v[90:93]
	v_mfma_f32_16x16x32_bf16 v[86:89], v[130:133], v[204:207], v[86:89]
	v_mfma_f32_16x16x32_bf16 v[82:85], v[138:141], v[204:207], v[82:85]
	v_mfma_f32_16x16x32_bf16 v[126:129], v[134:137], v[166:169], v[126:129]
	v_mfma_f32_16x16x32_bf16 v[122:125], v[142:145], v[166:169], v[122:125]
	v_mfma_f32_16x16x32_bf16 v[118:121], v[134:137], v[174:177], v[118:121]
	v_mfma_f32_16x16x32_bf16 v[114:117], v[142:145], v[174:177], v[114:117]
	v_mfma_f32_16x16x32_bf16 v[94:97], v[134:137], v[200:203], v[94:97]
	v_mfma_f32_16x16x32_bf16 v[90:93], v[142:145], v[200:203], v[90:93]
	v_mfma_f32_16x16x32_bf16 v[86:89], v[134:137], v[208:211], v[86:89]
	v_mfma_f32_16x16x32_bf16 v[82:85], v[142:145], v[208:211], v[82:85]
	s_setprio 0
	s_setprio 1
	v_mfma_f32_16x16x32_bf16 v[110:113], v[146:149], v[162:165], v[110:113]
	v_mfma_f32_16x16x32_bf16 v[106:109], v[154:157], v[162:165], v[106:109]
	v_mfma_f32_16x16x32_bf16 v[102:105], v[146:149], v[170:173], v[102:105]
	v_mfma_f32_16x16x32_bf16 v[98:101], v[154:157], v[170:173], v[98:101]
	v_mfma_f32_16x16x32_bf16 v[78:81], v[146:149], v[196:199], v[78:81]
	v_mfma_f32_16x16x32_bf16 v[74:77], v[154:157], v[196:199], v[74:77]
	v_mfma_f32_16x16x32_bf16 v[70:73], v[146:149], v[204:207], v[70:73]
	v_mfma_f32_16x16x32_bf16 v[66:69], v[154:157], v[204:207], v[66:69]
	v_mfma_f32_16x16x32_bf16 v[110:113], v[150:153], v[166:169], v[110:113]
	v_mfma_f32_16x16x32_bf16 v[106:109], v[158:161], v[166:169], v[106:109]
	v_mfma_f32_16x16x32_bf16 v[102:105], v[150:153], v[174:177], v[102:105]
	v_mfma_f32_16x16x32_bf16 v[98:101], v[158:161], v[174:177], v[98:101]
	v_mfma_f32_16x16x32_bf16 v[78:81], v[150:153], v[200:203], v[78:81]
	v_mfma_f32_16x16x32_bf16 v[74:77], v[158:161], v[200:203], v[74:77]
	v_mfma_f32_16x16x32_bf16 v[70:73], v[150:153], v[208:211], v[70:73]
	s_barrier
	v_mfma_f32_16x16x32_bf16 v[66:69], v[158:161], v[208:211], v[66:69]
	s_setprio 0
	s_add_i32 s39, s53, s33
	v_lshl_add_u64 v[192:193], s[34:35], 0, v[180:181]
	s_mov_b32 m0, s39
	ds_read_b128 v[162:165], v217 offset:16384
	ds_read_b128 v[166:169], v217 offset:17408
	ds_read_b128 v[170:173], v217 offset:18432
	ds_read_b128 v[174:177], v217 offset:19456
	ds_read_b128 v[196:199], v217 offset:20480
	ds_read_b128 v[200:203], v217 offset:21504
	ds_read_b128 v[204:207], v217 offset:22528
	ds_read_b128 v[208:211], v217 offset:23552
	global_load_lds_dwordx4 v[192:193], off
	s_add_i32 m0, s39, 0x2000
	s_add_u32 s62, s34, 0x160000
	v_lshl_add_u64 v[218:219], s[34:35], 0, v[184:185]
	s_addc_u32 s63, s35, 0
	s_add_i32 s39, s54, s33
	global_load_lds_dwordx4 v[218:219], off
	v_lshl_add_u64 v[220:221], s[62:63], 0, v[180:181]
	s_mov_b32 m0, s39
	v_lshl_add_u64 v[222:223], s[36:37], 0, v[182:183]
	global_load_lds_dwordx4 v[220:221], off
	v_lshl_add_u64 v[220:221], s[62:63], 0, v[184:185]
	s_add_i32 m0, s39, 0x2000
	s_nop 0
	global_load_lds_dwordx4 v[220:221], off
	v_lshl_add_u64 v[220:221], s[36:37], 0, v[178:179]
	s_mov_b32 m0, s40
	s_nop 0
	global_load_lds_dwordx4 v[220:221], off
	s_mov_b32 m0, s41
	s_nop 0
	global_load_lds_dwordx4 v[222:223], off
	s_waitcnt vmcnt(8)
	s_waitcnt lgkmcnt(0)
	s_barrier
	s_setprio 1
	s_waitcnt lgkmcnt(0)
	v_mfma_f32_16x16x32_bf16 v[62:65], v[130:133], v[162:165], v[62:65]
	v_mfma_f32_16x16x32_bf16 v[58:61], v[138:141], v[162:165], v[58:61]
	v_mfma_f32_16x16x32_bf16 v[54:57], v[130:133], v[170:173], v[54:57]
	v_mfma_f32_16x16x32_bf16 v[50:53], v[138:141], v[170:173], v[50:53]
	v_mfma_f32_16x16x32_bf16 v[30:33], v[130:133], v[196:199], v[30:33]
	v_mfma_f32_16x16x32_bf16 v[26:29], v[138:141], v[196:199], v[26:29]
	v_mfma_f32_16x16x32_bf16 v[22:25], v[130:133], v[204:207], v[22:25]
	v_mfma_f32_16x16x32_bf16 v[18:21], v[138:141], v[204:207], v[18:21]
	v_mfma_f32_16x16x32_bf16 v[62:65], v[134:137], v[166:169], v[62:65]
	v_mfma_f32_16x16x32_bf16 v[58:61], v[142:145], v[166:169], v[58:61]
	v_mfma_f32_16x16x32_bf16 v[54:57], v[134:137], v[174:177], v[54:57]
	v_mfma_f32_16x16x32_bf16 v[50:53], v[142:145], v[174:177], v[50:53]
	v_mfma_f32_16x16x32_bf16 v[30:33], v[134:137], v[200:203], v[30:33]
	v_mfma_f32_16x16x32_bf16 v[26:29], v[142:145], v[200:203], v[26:29]
	v_mfma_f32_16x16x32_bf16 v[22:25], v[134:137], v[208:211], v[22:25]
	v_mfma_f32_16x16x32_bf16 v[18:21], v[142:145], v[208:211], v[18:21]
	s_setprio 0
	s_setprio 1
	v_mfma_f32_16x16x32_bf16 v[46:49], v[146:149], v[162:165], v[46:49]
	v_mfma_f32_16x16x32_bf16 v[42:45], v[154:157], v[162:165], v[42:45]
	v_mfma_f32_16x16x32_bf16 v[38:41], v[146:149], v[170:173], v[38:41]
	v_mfma_f32_16x16x32_bf16 v[34:37], v[154:157], v[170:173], v[34:37]
	v_mfma_f32_16x16x32_bf16 v[14:17], v[146:149], v[196:199], v[14:17]
	v_mfma_f32_16x16x32_bf16 v[10:13], v[154:157], v[196:199], v[10:13]
	v_mfma_f32_16x16x32_bf16 v[6:9], v[146:149], v[204:207], v[6:9]
	v_mfma_f32_16x16x32_bf16 v[2:5], v[154:157], v[204:207], v[2:5]
	v_mfma_f32_16x16x32_bf16 v[46:49], v[150:153], v[166:169], v[46:49]
	v_mfma_f32_16x16x32_bf16 v[42:45], v[158:161], v[166:169], v[42:45]
	v_mfma_f32_16x16x32_bf16 v[38:41], v[150:153], v[174:177], v[38:41]
	v_mfma_f32_16x16x32_bf16 v[34:37], v[158:161], v[174:177], v[34:37]
	v_mfma_f32_16x16x32_bf16 v[14:17], v[150:153], v[200:203], v[14:17]
	v_mfma_f32_16x16x32_bf16 v[10:13], v[158:161], v[200:203], v[10:13]
	v_mfma_f32_16x16x32_bf16 v[6:9], v[150:153], v[208:211], v[6:9]
	s_barrier
	v_mfma_f32_16x16x32_bf16 v[2:5], v[158:161], v[208:211], v[2:5]
	s_setprio 0
	s_add_i32 s39, 0, 0x18000
	s_add_i32 s62, 0, 0x1c000
	v_add_u32_e32 v142, s39, v213
	v_add_u32_e32 v158, s62, v213
	ds_read_b128 v[130:133], v142
	ds_read_b128 v[134:137], v142 offset:1024
	ds_read_b128 v[138:141], v142 offset:2048
	ds_read_b128 v[142:145], v142 offset:3072
	ds_read_b128 v[146:149], v158
	ds_read_b128 v[150:153], v158 offset:1024
	ds_read_b128 v[154:157], v158 offset:2048
	ds_read_b128 v[158:161], v158 offset:3072
	s_add_u32 s36, s36, 0x160000
	s_addc_u32 s37, s37, 0
	s_mov_b32 m0, s42
	v_lshl_add_u64 v[224:225], s[36:37], 0, v[178:179]
	ds_read_b128 v[162:165], v217 offset:32768
	ds_read_b128 v[166:169], v217 offset:33792
	ds_read_b128 v[170:173], v217 offset:34816
	ds_read_b128 v[174:177], v217 offset:35840
	ds_read_b128 v[196:199], v217 offset:36864
	ds_read_b128 v[200:203], v217 offset:37888
	ds_read_b128 v[204:207], v217 offset:38912
	ds_read_b128 v[208:211], v217 offset:39936
	global_load_lds_dwordx4 v[224:225], off
	v_lshl_add_u64 v[224:225], s[36:37], 0, v[182:183]
	s_mov_b32 m0, s43
	s_nop 0
	global_load_lds_dwordx4 v[224:225], off
	s_waitcnt vmcnt(8)
	s_waitcnt lgkmcnt(0)
	s_barrier
	s_setprio 1
	s_waitcnt lgkmcnt(0)
	v_mfma_f32_16x16x32_bf16 v[126:129], v[130:133], v[162:165], v[126:129]
	v_mfma_f32_16x16x32_bf16 v[122:125], v[138:141], v[162:165], v[122:125]
	v_mfma_f32_16x16x32_bf16 v[118:121], v[130:133], v[170:173], v[118:121]
	v_mfma_f32_16x16x32_bf16 v[114:117], v[138:141], v[170:173], v[114:117]
	v_mfma_f32_16x16x32_bf16 v[94:97], v[130:133], v[196:199], v[94:97]
	v_mfma_f32_16x16x32_bf16 v[90:93], v[138:141], v[196:199], v[90:93]
	v_mfma_f32_16x16x32_bf16 v[86:89], v[130:133], v[204:207], v[86:89]
	v_mfma_f32_16x16x32_bf16 v[82:85], v[138:141], v[204:207], v[82:85]
	v_mfma_f32_16x16x32_bf16 v[126:129], v[134:137], v[166:169], v[126:129]
	v_mfma_f32_16x16x32_bf16 v[122:125], v[142:145], v[166:169], v[122:125]
	v_mfma_f32_16x16x32_bf16 v[118:121], v[134:137], v[174:177], v[118:121]
	v_mfma_f32_16x16x32_bf16 v[114:117], v[142:145], v[174:177], v[114:117]
	v_mfma_f32_16x16x32_bf16 v[94:97], v[134:137], v[200:203], v[94:97]
	v_mfma_f32_16x16x32_bf16 v[90:93], v[142:145], v[200:203], v[90:93]
	v_mfma_f32_16x16x32_bf16 v[86:89], v[134:137], v[208:211], v[86:89]
	v_mfma_f32_16x16x32_bf16 v[82:85], v[142:145], v[208:211], v[82:85]
	s_setprio 0
	s_setprio 1
	v_mfma_f32_16x16x32_bf16 v[110:113], v[146:149], v[162:165], v[110:113]
	v_mfma_f32_16x16x32_bf16 v[106:109], v[154:157], v[162:165], v[106:109]
	v_mfma_f32_16x16x32_bf16 v[102:105], v[146:149], v[170:173], v[102:105]
	v_mfma_f32_16x16x32_bf16 v[98:101], v[154:157], v[170:173], v[98:101]
	v_mfma_f32_16x16x32_bf16 v[78:81], v[146:149], v[196:199], v[78:81]
	v_mfma_f32_16x16x32_bf16 v[74:77], v[154:157], v[196:199], v[74:77]
	v_mfma_f32_16x16x32_bf16 v[70:73], v[146:149], v[204:207], v[70:73]
	v_mfma_f32_16x16x32_bf16 v[66:69], v[154:157], v[204:207], v[66:69]
	v_mfma_f32_16x16x32_bf16 v[110:113], v[150:153], v[166:169], v[110:113]
	v_mfma_f32_16x16x32_bf16 v[106:109], v[158:161], v[166:169], v[106:109]
	v_mfma_f32_16x16x32_bf16 v[102:105], v[150:153], v[174:177], v[102:105]
	v_mfma_f32_16x16x32_bf16 v[98:101], v[158:161], v[174:177], v[98:101]
	v_mfma_f32_16x16x32_bf16 v[78:81], v[150:153], v[200:203], v[78:81]
	v_mfma_f32_16x16x32_bf16 v[74:77], v[158:161], v[200:203], v[74:77]
	v_mfma_f32_16x16x32_bf16 v[70:73], v[150:153], v[208:211], v[70:73]
	s_barrier
	v_mfma_f32_16x16x32_bf16 v[66:69], v[158:161], v[208:211], v[66:69]
	s_setprio 0
	s_add_i32 s36, s39, s33
	v_lshl_add_u64 v[192:193], v[192:193], 0, s[18:19]
	s_mov_b32 m0, s36
	ds_read_b128 v[162:165], v217 offset:49152
	ds_read_b128 v[166:169], v217 offset:50176
	ds_read_b128 v[170:173], v217 offset:51200
	ds_read_b128 v[174:177], v217 offset:52224
	ds_read_b128 v[196:199], v217 offset:53248
	ds_read_b128 v[200:203], v217 offset:54272
	ds_read_b128 v[204:207], v217 offset:55296
	ds_read_b128 v[208:211], v217 offset:56320
	global_load_lds_dwordx4 v[192:193], off
	s_add_i32 m0, s36, 0x2000
	s_add_u32 s34, s34, 0x160080
	v_lshl_add_u64 v[192:193], v[218:219], 0, s[18:19]
	s_addc_u32 s35, s35, 0
	s_add_i32 s36, s62, s33
	global_load_lds_dwordx4 v[192:193], off
	v_lshl_add_u64 v[192:193], s[34:35], 0, v[180:181]
	s_mov_b32 m0, s36
	s_nop 0
	global_load_lds_dwordx4 v[192:193], off
	v_lshl_add_u64 v[192:193], s[34:35], 0, v[184:185]
	s_add_i32 m0, s36, 0x2000
	s_nop 0
	global_load_lds_dwordx4 v[192:193], off
	v_lshl_add_u64 v[192:193], v[220:221], 0, s[18:19]
	s_mov_b32 m0, s46
	s_nop 0
	global_load_lds_dwordx4 v[192:193], off
	v_lshl_add_u64 v[192:193], v[222:223], 0, s[18:19]
	s_mov_b32 m0, s47
	s_nop 0
	global_load_lds_dwordx4 v[192:193], off
	s_waitcnt vmcnt(8)
	s_waitcnt lgkmcnt(0)
	s_barrier
	s_setprio 1
	s_waitcnt lgkmcnt(0)
	v_mfma_f32_16x16x32_bf16 v[62:65], v[130:133], v[162:165], v[62:65]
	v_mfma_f32_16x16x32_bf16 v[58:61], v[138:141], v[162:165], v[58:61]
	v_mfma_f32_16x16x32_bf16 v[54:57], v[130:133], v[170:173], v[54:57]
	v_mfma_f32_16x16x32_bf16 v[50:53], v[138:141], v[170:173], v[50:53]
	v_mfma_f32_16x16x32_bf16 v[30:33], v[130:133], v[196:199], v[30:33]
	v_mfma_f32_16x16x32_bf16 v[26:29], v[138:141], v[196:199], v[26:29]
	v_mfma_f32_16x16x32_bf16 v[22:25], v[130:133], v[204:207], v[22:25]
	v_mfma_f32_16x16x32_bf16 v[18:21], v[138:141], v[204:207], v[18:21]
	v_mfma_f32_16x16x32_bf16 v[62:65], v[134:137], v[166:169], v[62:65]
	v_mfma_f32_16x16x32_bf16 v[58:61], v[142:145], v[166:169], v[58:61]
	v_mfma_f32_16x16x32_bf16 v[54:57], v[134:137], v[174:177], v[54:57]
	v_mfma_f32_16x16x32_bf16 v[50:53], v[142:145], v[174:177], v[50:53]
	v_mfma_f32_16x16x32_bf16 v[30:33], v[134:137], v[200:203], v[30:33]
	v_mfma_f32_16x16x32_bf16 v[26:29], v[142:145], v[200:203], v[26:29]
	v_mfma_f32_16x16x32_bf16 v[22:25], v[134:137], v[208:211], v[22:25]
	v_mfma_f32_16x16x32_bf16 v[18:21], v[142:145], v[208:211], v[18:21]
	s_setprio 0
	s_setprio 1
	v_mfma_f32_16x16x32_bf16 v[46:49], v[146:149], v[162:165], v[46:49]
	v_mfma_f32_16x16x32_bf16 v[42:45], v[154:157], v[162:165], v[42:45]
	v_mfma_f32_16x16x32_bf16 v[38:41], v[146:149], v[170:173], v[38:41]
	v_mfma_f32_16x16x32_bf16 v[34:37], v[154:157], v[170:173], v[34:37]
	v_mfma_f32_16x16x32_bf16 v[14:17], v[146:149], v[196:199], v[14:17]
	v_mfma_f32_16x16x32_bf16 v[10:13], v[154:157], v[196:199], v[10:13]
	v_mfma_f32_16x16x32_bf16 v[6:9], v[146:149], v[204:207], v[6:9]
	v_mfma_f32_16x16x32_bf16 v[2:5], v[154:157], v[204:207], v[2:5]
	v_mfma_f32_16x16x32_bf16 v[46:49], v[150:153], v[166:169], v[46:49]
	v_mfma_f32_16x16x32_bf16 v[42:45], v[158:161], v[166:169], v[42:45]
	v_mfma_f32_16x16x32_bf16 v[38:41], v[150:153], v[174:177], v[38:41]
	v_mfma_f32_16x16x32_bf16 v[34:37], v[158:161], v[174:177], v[34:37]
	v_mfma_f32_16x16x32_bf16 v[14:17], v[150:153], v[200:203], v[14:17]
	v_mfma_f32_16x16x32_bf16 v[10:13], v[158:161], v[200:203], v[10:13]
	v_mfma_f32_16x16x32_bf16 v[6:9], v[150:153], v[208:211], v[6:9]
	s_barrier
	v_mfma_f32_16x16x32_bf16 v[2:5], v[158:161], v[208:211], v[2:5]
	s_setprio 0
	s_add_u32 s30, s30, 0x100
	s_addc_u32 s31, s31, 0
	s_add_u32 s23, s23, 0x100
	s_addc_u32 s29, s29, 0
	s_cmp_ge_i32 s38, s61
	s_mov_b32 s34, s38
	s_cbranch_scc0 .LBB0_357

.Lpeel_11:
	ds_read_b128 v[148:151], v145
	ds_read_b128 v[152:155], v145 offset:1024
	s_add_u32 s36, s34, 0xfff80080
	s_addc_u32 s37, s35, -1
	s_cmp_eq_u32 s58, 28
	s_cselect_b32 s39, s21, s37
	s_cselect_b32 s38, s54, s36
	s_cselect_b32 s37, s23, s57
	s_cselect_b32 s36, s55, s56
	v_lshl_add_u64 v[192:193], s[34:35], 0, v[138:139]
	s_add_i32 m0, s27, 0xc000
	global_load_lds_dwordx4 v[192:193], off
	v_lshl_add_u64 v[192:193], s[34:35], 0, v[140:141]
	s_add_i32 m0, s27, 0xe000
	s_nop 0
	global_load_lds_dwordx4 v[192:193], off
	s_waitcnt vmcnt(8)
	s_waitcnt lgkmcnt(0)
	s_barrier
	s_setprio 1
	s_waitcnt lgkmcnt(0)
	v_mfma_f32_16x16x32_bf16 v[126:129], v[148:151], v[180:183], 0
	v_mfma_f32_16x16x32_bf16 v[122:125], v[156:159], v[180:183], 0
	v_mfma_f32_16x16x32_bf16 v[118:121], v[148:151], v[188:191], 0
	v_mfma_f32_16x16x32_bf16 v[114:117], v[156:159], v[188:191], 0
	v_mfma_f32_16x16x32_bf16 v[102:105], v[148:151], v[200:203], 0
	v_mfma_f32_16x16x32_bf16 v[98:101], v[156:159], v[200:203], 0
	v_mfma_f32_16x16x32_bf16 v[86:89], v[148:151], v[208:211], 0
	v_mfma_f32_16x16x32_bf16 v[82:85], v[156:159], v[208:211], 0
	v_mfma_f32_16x16x32_bf16 v[126:129], v[152:155], v[184:187], v[126:129]
	v_mfma_f32_16x16x32_bf16 v[122:125], v[160:163], v[184:187], v[122:125]
	v_mfma_f32_16x16x32_bf16 v[118:121], v[152:155], v[196:199], v[118:121]
	v_mfma_f32_16x16x32_bf16 v[114:117], v[160:163], v[196:199], v[114:117]
	v_mfma_f32_16x16x32_bf16 v[102:105], v[152:155], v[204:207], v[102:105]
	v_mfma_f32_16x16x32_bf16 v[98:101], v[160:163], v[204:207], v[98:101]
	v_mfma_f32_16x16x32_bf16 v[86:89], v[152:155], v[212:215], v[86:89]
	v_mfma_f32_16x16x32_bf16 v[82:85], v[160:163], v[212:215], v[82:85]
	s_setprio 0
	s_setprio 1
	v_mfma_f32_16x16x32_bf16 v[110:113], v[164:167], v[180:183], 0
	v_mfma_f32_16x16x32_bf16 v[106:109], v[172:175], v[180:183], 0
	v_mfma_f32_16x16x32_bf16 v[94:97], v[164:167], v[188:191], 0
	v_mfma_f32_16x16x32_bf16 v[90:93], v[172:175], v[188:191], 0
	v_mfma_f32_16x16x32_bf16 v[78:81], v[164:167], v[200:203], 0
	v_mfma_f32_16x16x32_bf16 v[74:77], v[172:175], v[200:203], 0
	v_mfma_f32_16x16x32_bf16 v[70:73], v[164:167], v[208:211], 0
	v_mfma_f32_16x16x32_bf16 v[66:69], v[172:175], v[208:211], 0
	v_mfma_f32_16x16x32_bf16 v[110:113], v[168:171], v[184:187], v[110:113]
	v_mfma_f32_16x16x32_bf16 v[106:109], v[176:179], v[184:187], v[106:109]
	v_mfma_f32_16x16x32_bf16 v[94:97], v[168:171], v[196:199], v[94:97]
	v_mfma_f32_16x16x32_bf16 v[90:93], v[176:179], v[196:199], v[90:93]
	v_mfma_f32_16x16x32_bf16 v[78:81], v[168:171], v[204:207], v[78:81]
	v_mfma_f32_16x16x32_bf16 v[74:77], v[176:179], v[204:207], v[74:77]
	v_mfma_f32_16x16x32_bf16 v[70:73], v[168:171], v[212:215], v[70:73]
	s_barrier
	v_mfma_f32_16x16x32_bf16 v[66:69], v[176:179], v[212:215], v[66:69]
	s_setprio 0
	s_add_i32 s59, s47, s33
	v_lshl_add_u64 v[192:193], s[36:37], 0, v[134:135]
	s_mov_b32 m0, s59
	ds_read_b128 v[180:183], v147 offset:16384
	ds_read_b128 v[184:187], v147 offset:17408
	ds_read_b128 v[188:191], v147 offset:18432
	ds_read_b128 v[196:199], v147 offset:19456
	ds_read_b128 v[200:203], v147 offset:20480
	ds_read_b128 v[204:207], v147 offset:21504
	ds_read_b128 v[208:211], v147 offset:22528
	ds_read_b128 v[212:215], v147 offset:23552
	global_load_lds_dwordx4 v[192:193], off
	s_add_i32 m0, s59, 0x2000
	s_add_u32 s60, s36, 0x80000
	v_lshl_add_u64 v[216:217], s[36:37], 0, v[130:131]
	s_addc_u32 s61, s37, 0
	s_add_i32 s59, s48, s33
	global_load_lds_dwordx4 v[216:217], off
	v_lshl_add_u64 v[218:219], s[60:61], 0, v[134:135]
	s_mov_b32 m0, s59
	v_lshl_add_u64 v[220:221], s[38:39], 0, v[132:133]
	global_load_lds_dwordx4 v[218:219], off
	v_lshl_add_u64 v[218:219], s[60:61], 0, v[130:131]
	s_add_i32 m0, s59, 0x2000
	s_nop 0
	global_load_lds_dwordx4 v[218:219], off
	v_lshl_add_u64 v[218:219], s[38:39], 0, v[136:137]
	s_mov_b32 m0, s27
	s_nop 0
	global_load_lds_dwordx4 v[218:219], off
	s_mov_b32 m0, s41
	s_nop 0
	global_load_lds_dwordx4 v[220:221], off
	s_waitcnt vmcnt(8)
	s_waitcnt lgkmcnt(0)
	s_barrier
	s_setprio 1
	s_waitcnt lgkmcnt(0)
	v_mfma_f32_16x16x32_bf16 v[62:65], v[148:151], v[180:183], 0
	v_mfma_f32_16x16x32_bf16 v[58:61], v[156:159], v[180:183], 0
	v_mfma_f32_16x16x32_bf16 v[54:57], v[148:151], v[188:191], 0
	v_mfma_f32_16x16x32_bf16 v[50:53], v[156:159], v[188:191], 0
	v_mfma_f32_16x16x32_bf16 v[38:41], v[148:151], v[200:203], 0
	v_mfma_f32_16x16x32_bf16 v[34:37], v[156:159], v[200:203], 0
	v_mfma_f32_16x16x32_bf16 v[22:25], v[148:151], v[208:211], 0
	v_mfma_f32_16x16x32_bf16 v[18:21], v[156:159], v[208:211], 0
	v_mfma_f32_16x16x32_bf16 v[62:65], v[152:155], v[184:187], v[62:65]
	v_mfma_f32_16x16x32_bf16 v[58:61], v[160:163], v[184:187], v[58:61]
	v_mfma_f32_16x16x32_bf16 v[54:57], v[152:155], v[196:199], v[54:57]
	v_mfma_f32_16x16x32_bf16 v[50:53], v[160:163], v[196:199], v[50:53]
	v_mfma_f32_16x16x32_bf16 v[38:41], v[152:155], v[204:207], v[38:41]
	v_mfma_f32_16x16x32_bf16 v[34:37], v[160:163], v[204:207], v[34:37]
	v_mfma_f32_16x16x32_bf16 v[22:25], v[152:155], v[212:215], v[22:25]
	v_mfma_f32_16x16x32_bf16 v[18:21], v[160:163], v[212:215], v[18:21]
	s_setprio 0
	s_setprio 1
	v_mfma_f32_16x16x32_bf16 v[46:49], v[164:167], v[180:183], 0
	v_mfma_f32_16x16x32_bf16 v[42:45], v[172:175], v[180:183], 0
	v_mfma_f32_16x16x32_bf16 v[30:33], v[164:167], v[188:191], 0
	v_mfma_f32_16x16x32_bf16 v[26:29], v[172:175], v[188:191], 0
	v_mfma_f32_16x16x32_bf16 v[14:17], v[164:167], v[200:203], 0
	v_mfma_f32_16x16x32_bf16 v[10:13], v[172:175], v[200:203], 0
	v_mfma_f32_16x16x32_bf16 v[6:9], v[164:167], v[208:211], 0
	v_mfma_f32_16x16x32_bf16 v[2:5], v[172:175], v[208:211], 0
	v_mfma_f32_16x16x32_bf16 v[46:49], v[168:171], v[184:187], v[46:49]
	v_mfma_f32_16x16x32_bf16 v[42:45], v[176:179], v[184:187], v[42:45]
	v_mfma_f32_16x16x32_bf16 v[30:33], v[168:171], v[196:199], v[30:33]
	v_mfma_f32_16x16x32_bf16 v[26:29], v[176:179], v[196:199], v[26:29]
	v_mfma_f32_16x16x32_bf16 v[14:17], v[168:171], v[204:207], v[14:17]
	v_mfma_f32_16x16x32_bf16 v[10:13], v[176:179], v[204:207], v[10:13]
	v_mfma_f32_16x16x32_bf16 v[6:9], v[168:171], v[212:215], v[6:9]
	s_barrier
	v_mfma_f32_16x16x32_bf16 v[2:5], v[176:179], v[212:215], v[2:5]
	s_setprio 0
	s_add_i32 s59, 0, 0x18000
	s_add_i32 s60, 0, 0x1c000
	v_add_u32_e32 v160, s59, v143
	v_add_u32_e32 v176, s60, v143
	ds_read_b128 v[148:151], v160
	ds_read_b128 v[152:155], v160 offset:1024
	ds_read_b128 v[156:159], v160 offset:2048
	ds_read_b128 v[160:163], v160 offset:3072
	ds_read_b128 v[164:167], v176
	ds_read_b128 v[168:171], v176 offset:1024
	ds_read_b128 v[172:175], v176 offset:2048
	ds_read_b128 v[176:179], v176 offset:3072
	s_add_u32 s38, s38, 0x80000
	s_addc_u32 s39, s39, 0
	s_mov_b32 m0, s42
	v_lshl_add_u64 v[222:223], s[38:39], 0, v[136:137]
	ds_read_b128 v[180:183], v147 offset:32768
	ds_read_b128 v[184:187], v147 offset:33792
	ds_read_b128 v[188:191], v147 offset:34816
	ds_read_b128 v[196:199], v147 offset:35840
	ds_read_b128 v[200:203], v147 offset:36864
	ds_read_b128 v[204:207], v147 offset:37888
	ds_read_b128 v[208:211], v147 offset:38912
	ds_read_b128 v[212:215], v147 offset:39936
	global_load_lds_dwordx4 v[222:223], off
	v_lshl_add_u64 v[222:223], s[38:39], 0, v[132:133]
	s_mov_b32 m0, s43
	s_nop 0
	global_load_lds_dwordx4 v[222:223], off
	s_waitcnt vmcnt(8)
	s_waitcnt lgkmcnt(0)
	s_barrier
	s_setprio 1
	s_waitcnt lgkmcnt(0)
	v_mfma_f32_16x16x32_bf16 v[126:129], v[148:151], v[180:183], v[126:129]
	v_mfma_f32_16x16x32_bf16 v[122:125], v[156:159], v[180:183], v[122:125]
	v_mfma_f32_16x16x32_bf16 v[118:121], v[148:151], v[188:191], v[118:121]
	v_mfma_f32_16x16x32_bf16 v[114:117], v[156:159], v[188:191], v[114:117]
	v_mfma_f32_16x16x32_bf16 v[102:105], v[148:151], v[200:203], v[102:105]
	v_mfma_f32_16x16x32_bf16 v[98:101], v[156:159], v[200:203], v[98:101]
	v_mfma_f32_16x16x32_bf16 v[86:89], v[148:151], v[208:211], v[86:89]
	v_mfma_f32_16x16x32_bf16 v[82:85], v[156:159], v[208:211], v[82:85]
	v_mfma_f32_16x16x32_bf16 v[126:129], v[152:155], v[184:187], v[126:129]
	v_mfma_f32_16x16x32_bf16 v[122:125], v[160:163], v[184:187], v[122:125]
	v_mfma_f32_16x16x32_bf16 v[118:121], v[152:155], v[196:199], v[118:121]
	v_mfma_f32_16x16x32_bf16 v[114:117], v[160:163], v[196:199], v[114:117]
	v_mfma_f32_16x16x32_bf16 v[102:105], v[152:155], v[204:207], v[102:105]
	v_mfma_f32_16x16x32_bf16 v[98:101], v[160:163], v[204:207], v[98:101]
	v_mfma_f32_16x16x32_bf16 v[86:89], v[152:155], v[212:215], v[86:89]
	v_mfma_f32_16x16x32_bf16 v[82:85], v[160:163], v[212:215], v[82:85]
	s_setprio 0
	s_setprio 1
	v_mfma_f32_16x16x32_bf16 v[110:113], v[164:167], v[180:183], v[110:113]
	v_mfma_f32_16x16x32_bf16 v[106:109], v[172:175], v[180:183], v[106:109]
	v_mfma_f32_16x16x32_bf16 v[94:97], v[164:167], v[188:191], v[94:97]
	v_mfma_f32_16x16x32_bf16 v[90:93], v[172:175], v[188:191], v[90:93]
	v_mfma_f32_16x16x32_bf16 v[78:81], v[164:167], v[200:203], v[78:81]
	v_mfma_f32_16x16x32_bf16 v[74:77], v[172:175], v[200:203], v[74:77]
	v_mfma_f32_16x16x32_bf16 v[70:73], v[164:167], v[208:211], v[70:73]
	v_mfma_f32_16x16x32_bf16 v[66:69], v[172:175], v[208:211], v[66:69]
	v_mfma_f32_16x16x32_bf16 v[110:113], v[168:171], v[184:187], v[110:113]
	v_mfma_f32_16x16x32_bf16 v[106:109], v[176:179], v[184:187], v[106:109]
	v_mfma_f32_16x16x32_bf16 v[94:97], v[168:171], v[196:199], v[94:97]
	v_mfma_f32_16x16x32_bf16 v[90:93], v[176:179], v[196:199], v[90:93]
	v_mfma_f32_16x16x32_bf16 v[78:81], v[168:171], v[204:207], v[78:81]
	v_mfma_f32_16x16x32_bf16 v[74:77], v[176:179], v[204:207], v[74:77]
	v_mfma_f32_16x16x32_bf16 v[70:73], v[168:171], v[212:215], v[70:73]
	s_barrier
	v_mfma_f32_16x16x32_bf16 v[66:69], v[176:179], v[212:215], v[66:69]
	s_setprio 0
	s_add_i32 s38, s59, s33
	v_lshl_add_u64 v[192:193], v[192:193], 0, s[6:7]
	s_mov_b32 m0, s38
	ds_read_b128 v[180:183], v147 offset:49152
	ds_read_b128 v[184:187], v147 offset:50176
	ds_read_b128 v[188:191], v147 offset:51200
	ds_read_b128 v[196:199], v147 offset:52224
	ds_read_b128 v[200:203], v147 offset:53248
	ds_read_b128 v[204:207], v147 offset:54272
	ds_read_b128 v[208:211], v147 offset:55296
	ds_read_b128 v[212:215], v147 offset:56320
	global_load_lds_dwordx4 v[192:193], off
	s_add_i32 m0, s38, 0x2000
	s_add_u32 s36, s36, 0x80080
	v_lshl_add_u64 v[192:193], v[216:217], 0, s[6:7]
	s_addc_u32 s37, s37, 0
	s_add_i32 s38, s60, s33
	global_load_lds_dwordx4 v[192:193], off
	v_lshl_add_u64 v[192:193], s[36:37], 0, v[134:135]
	s_mov_b32 m0, s38
	s_nop 0
	global_load_lds_dwordx4 v[192:193], off
	v_lshl_add_u64 v[192:193], s[36:37], 0, v[130:131]
	s_add_i32 m0, s38, 0x2000
	s_nop 0
	global_load_lds_dwordx4 v[192:193], off
	v_lshl_add_u64 v[192:193], v[218:219], 0, s[6:7]
	s_mov_b32 m0, s45
	s_nop 0
	global_load_lds_dwordx4 v[192:193], off
	v_lshl_add_u64 v[192:193], v[220:221], 0, s[6:7]
	s_mov_b32 m0, s46
	s_nop 0
	global_load_lds_dwordx4 v[192:193], off
	s_waitcnt vmcnt(8)
	s_waitcnt lgkmcnt(0)
	s_barrier
	s_setprio 1
	s_waitcnt lgkmcnt(0)
	v_mfma_f32_16x16x32_bf16 v[62:65], v[148:151], v[180:183], v[62:65]
	v_mfma_f32_16x16x32_bf16 v[58:61], v[156:159], v[180:183], v[58:61]
	v_mfma_f32_16x16x32_bf16 v[54:57], v[148:151], v[188:191], v[54:57]
	v_mfma_f32_16x16x32_bf16 v[50:53], v[156:159], v[188:191], v[50:53]
	v_mfma_f32_16x16x32_bf16 v[38:41], v[148:151], v[200:203], v[38:41]
	v_mfma_f32_16x16x32_bf16 v[34:37], v[156:159], v[200:203], v[34:37]
	v_mfma_f32_16x16x32_bf16 v[22:25], v[148:151], v[208:211], v[22:25]
	v_mfma_f32_16x16x32_bf16 v[18:21], v[156:159], v[208:211], v[18:21]
	v_mfma_f32_16x16x32_bf16 v[62:65], v[152:155], v[184:187], v[62:65]
	v_mfma_f32_16x16x32_bf16 v[58:61], v[160:163], v[184:187], v[58:61]
	v_mfma_f32_16x16x32_bf16 v[54:57], v[152:155], v[196:199], v[54:57]
	v_mfma_f32_16x16x32_bf16 v[50:53], v[160:163], v[196:199], v[50:53]
	v_mfma_f32_16x16x32_bf16 v[38:41], v[152:155], v[204:207], v[38:41]
	v_mfma_f32_16x16x32_bf16 v[34:37], v[160:163], v[204:207], v[34:37]
	v_mfma_f32_16x16x32_bf16 v[22:25], v[152:155], v[212:215], v[22:25]
	v_mfma_f32_16x16x32_bf16 v[18:21], v[160:163], v[212:215], v[18:21]
	s_setprio 0
	s_setprio 1
	v_mfma_f32_16x16x32_bf16 v[46:49], v[164:167], v[180:183], v[46:49]
	v_mfma_f32_16x16x32_bf16 v[42:45], v[172:175], v[180:183], v[42:45]
	v_mfma_f32_16x16x32_bf16 v[30:33], v[164:167], v[188:191], v[30:33]
	v_mfma_f32_16x16x32_bf16 v[26:29], v[172:175], v[188:191], v[26:29]
	v_mfma_f32_16x16x32_bf16 v[14:17], v[164:167], v[200:203], v[14:17]
	v_mfma_f32_16x16x32_bf16 v[10:13], v[172:175], v[200:203], v[10:13]
	v_mfma_f32_16x16x32_bf16 v[6:9], v[164:167], v[208:211], v[6:9]
	v_mfma_f32_16x16x32_bf16 v[2:5], v[172:175], v[208:211], v[2:5]
	v_mfma_f32_16x16x32_bf16 v[46:49], v[168:171], v[184:187], v[46:49]
	v_mfma_f32_16x16x32_bf16 v[42:45], v[176:179], v[184:187], v[42:45]
	v_mfma_f32_16x16x32_bf16 v[30:33], v[168:171], v[196:199], v[30:33]
	v_mfma_f32_16x16x32_bf16 v[26:29], v[176:179], v[196:199], v[26:29]
	v_mfma_f32_16x16x32_bf16 v[14:17], v[168:171], v[204:207], v[14:17]
	v_mfma_f32_16x16x32_bf16 v[10:13], v[176:179], v[204:207], v[10:13]
	v_mfma_f32_16x16x32_bf16 v[6:9], v[168:171], v[212:215], v[6:9]
	s_barrier
	v_mfma_f32_16x16x32_bf16 v[2:5], v[176:179], v[212:215], v[2:5]
	s_setprio 0
	s_add_i32 s58, s58, 2
	s_add_u32 s34, s34, 0x100
	s_addc_u32 s35, s35, 0
	s_add_u32 s56, s56, 0x100
	s_addc_u32 s57, s57, 0
	s_cmp_gt_u32 s58, 29
	s_cbranch_scc0 .LBB0_541
	s_branch .Lpeeldone_11
.LBB0_541:
	ds_read_b128 v[148:151], v145
	ds_read_b128 v[152:155], v145 offset:1024
	ds_read_b128 v[156:159], v145 offset:2048
	ds_read_b128 v[160:163], v145 offset:3072
	ds_read_b128 v[164:167], v146
	ds_read_b128 v[168:171], v146 offset:1024
	ds_read_b128 v[172:175], v146 offset:2048
	ds_read_b128 v[176:179], v146 offset:3072
	s_add_u32 s36, s34, 0xfff80080
	s_addc_u32 s37, s35, -1
	s_cmp_eq_u32 s58, 28
	s_cselect_b32 s39, s21, s37
	s_cselect_b32 s38, s54, s36
	s_cselect_b32 s37, s23, s57
	s_cselect_b32 s36, s55, s56
	v_lshl_add_u64 v[192:193], s[34:35], 0, v[138:139]
	s_add_i32 m0, s27, 0xc000
	ds_read_b128 v[180:183], v147
	ds_read_b128 v[184:187], v147 offset:1024
	ds_read_b128 v[188:191], v147 offset:2048
	ds_read_b128 v[196:199], v147 offset:3072
	ds_read_b128 v[200:203], v147 offset:4096
	ds_read_b128 v[204:207], v147 offset:5120
	ds_read_b128 v[208:211], v147 offset:6144
	ds_read_b128 v[212:215], v147 offset:7168
	global_load_lds_dwordx4 v[192:193], off
	v_lshl_add_u64 v[192:193], s[34:35], 0, v[140:141]
	s_add_i32 m0, s27, 0xe000
	s_nop 0
	global_load_lds_dwordx4 v[192:193], off
	s_waitcnt vmcnt(8)
	s_waitcnt lgkmcnt(0)
	s_barrier
	s_setprio 1
	s_waitcnt lgkmcnt(0)
	v_mfma_f32_16x16x32_bf16 v[126:129], v[148:151], v[180:183], v[126:129]
	v_mfma_f32_16x16x32_bf16 v[122:125], v[156:159], v[180:183], v[122:125]
	v_mfma_f32_16x16x32_bf16 v[118:121], v[148:151], v[188:191], v[118:121]
	v_mfma_f32_16x16x32_bf16 v[114:117], v[156:159], v[188:191], v[114:117]
	v_mfma_f32_16x16x32_bf16 v[102:105], v[148:151], v[200:203], v[102:105]
	v_mfma_f32_16x16x32_bf16 v[98:101], v[156:159], v[200:203], v[98:101]
	v_mfma_f32_16x16x32_bf16 v[86:89], v[148:151], v[208:211], v[86:89]
	v_mfma_f32_16x16x32_bf16 v[82:85], v[156:159], v[208:211], v[82:85]
	v_mfma_f32_16x16x32_bf16 v[126:129], v[152:155], v[184:187], v[126:129]
	v_mfma_f32_16x16x32_bf16 v[122:125], v[160:163], v[184:187], v[122:125]
	v_mfma_f32_16x16x32_bf16 v[118:121], v[152:155], v[196:199], v[118:121]
	v_mfma_f32_16x16x32_bf16 v[114:117], v[160:163], v[196:199], v[114:117]
	v_mfma_f32_16x16x32_bf16 v[102:105], v[152:155], v[204:207], v[102:105]
	v_mfma_f32_16x16x32_bf16 v[98:101], v[160:163], v[204:207], v[98:101]
	v_mfma_f32_16x16x32_bf16 v[86:89], v[152:155], v[212:215], v[86:89]
	v_mfma_f32_16x16x32_bf16 v[82:85], v[160:163], v[212:215], v[82:85]
	s_setprio 0
	s_setprio 1
	v_mfma_f32_16x16x32_bf16 v[110:113], v[164:167], v[180:183], v[110:113]
	v_mfma_f32_16x16x32_bf16 v[106:109], v[172:175], v[180:183], v[106:109]
	v_mfma_f32_16x16x32_bf16 v[94:97], v[164:167], v[188:191], v[94:97]
	v_mfma_f32_16x16x32_bf16 v[90:93], v[172:175], v[188:191], v[90:93]
	v_mfma_f32_16x16x32_bf16 v[78:81], v[164:167], v[200:203], v[78:81]
	v_mfma_f32_16x16x32_bf16 v[74:77], v[172:175], v[200:203], v[74:77]
	v_mfma_f32_16x16x32_bf16 v[70:73], v[164:167], v[208:211], v[70:73]
	v_mfma_f32_16x16x32_bf16 v[66:69], v[172:175], v[208:211], v[66:69]
	v_mfma_f32_16x16x32_bf16 v[110:113], v[168:171], v[184:187], v[110:113]
	v_mfma_f32_16x16x32_bf16 v[106:109], v[176:179], v[184:187], v[106:109]
	v_mfma_f32_16x16x32_bf16 v[94:97], v[168:171], v[196:199], v[94:97]
	v_mfma_f32_16x16x32_bf16 v[90:93], v[176:179], v[196:199], v[90:93]
	v_mfma_f32_16x16x32_bf16 v[78:81], v[168:171], v[204:207], v[78:81]
	v_mfma_f32_16x16x32_bf16 v[74:77], v[176:179], v[204:207], v[74:77]
	v_mfma_f32_16x16x32_bf16 v[70:73], v[168:171], v[212:215], v[70:73]
	s_barrier
	v_mfma_f32_16x16x32_bf16 v[66:69], v[176:179], v[212:215], v[66:69]
	s_setprio 0
	s_add_i32 s59, s47, s33
	v_lshl_add_u64 v[192:193], s[36:37], 0, v[134:135]
	s_mov_b32 m0, s59
	ds_read_b128 v[180:183], v147 offset:16384
	ds_read_b128 v[184:187], v147 offset:17408
	ds_read_b128 v[188:191], v147 offset:18432
	ds_read_b128 v[196:199], v147 offset:19456
	ds_read_b128 v[200:203], v147 offset:20480
	ds_read_b128 v[204:207], v147 offset:21504
	ds_read_b128 v[208:211], v147 offset:22528
	ds_read_b128 v[212:215], v147 offset:23552
	global_load_lds_dwordx4 v[192:193], off
	s_add_i32 m0, s59, 0x2000
	s_add_u32 s60, s36, 0x80000
	v_lshl_add_u64 v[216:217], s[36:37], 0, v[130:131]
	s_addc_u32 s61, s37, 0
	s_add_i32 s59, s48, s33
	global_load_lds_dwordx4 v[216:217], off
	v_lshl_add_u64 v[218:219], s[60:61], 0, v[134:135]
	s_mov_b32 m0, s59
	v_lshl_add_u64 v[220:221], s[38:39], 0, v[132:133]
	global_load_lds_dwordx4 v[218:219], off
	v_lshl_add_u64 v[218:219], s[60:61], 0, v[130:131]
	s_add_i32 m0, s59, 0x2000
	s_nop 0
	global_load_lds_dwordx4 v[218:219], off
	v_lshl_add_u64 v[218:219], s[38:39], 0, v[136:137]
	s_mov_b32 m0, s27
	s_nop 0
	global_load_lds_dwordx4 v[218:219], off
	s_mov_b32 m0, s41
	s_nop 0
	global_load_lds_dwordx4 v[220:221], off
	s_waitcnt vmcnt(8)
	s_waitcnt lgkmcnt(0)
	s_barrier
	s_setprio 1
	s_waitcnt lgkmcnt(0)
	v_mfma_f32_16x16x32_bf16 v[62:65], v[148:151], v[180:183], v[62:65]
	v_mfma_f32_16x16x32_bf16 v[58:61], v[156:159], v[180:183], v[58:61]
	v_mfma_f32_16x16x32_bf16 v[54:57], v[148:151], v[188:191], v[54:57]
	v_mfma_f32_16x16x32_bf16 v[50:53], v[156:159], v[188:191], v[50:53]
	v_mfma_f32_16x16x32_bf16 v[38:41], v[148:151], v[200:203], v[38:41]
	v_mfma_f32_16x16x32_bf16 v[34:37], v[156:159], v[200:203], v[34:37]
	v_mfma_f32_16x16x32_bf16 v[22:25], v[148:151], v[208:211], v[22:25]
	v_mfma_f32_16x16x32_bf16 v[18:21], v[156:159], v[208:211], v[18:21]
	v_mfma_f32_16x16x32_bf16 v[62:65], v[152:155], v[184:187], v[62:65]
	v_mfma_f32_16x16x32_bf16 v[58:61], v[160:163], v[184:187], v[58:61]
	v_mfma_f32_16x16x32_bf16 v[54:57], v[152:155], v[196:199], v[54:57]
	v_mfma_f32_16x16x32_bf16 v[50:53], v[160:163], v[196:199], v[50:53]
	v_mfma_f32_16x16x32_bf16 v[38:41], v[152:155], v[204:207], v[38:41]
	v_mfma_f32_16x16x32_bf16 v[34:37], v[160:163], v[204:207], v[34:37]
	v_mfma_f32_16x16x32_bf16 v[22:25], v[152:155], v[212:215], v[22:25]
	v_mfma_f32_16x16x32_bf16 v[18:21], v[160:163], v[212:215], v[18:21]
	s_setprio 0
	s_setprio 1
	v_mfma_f32_16x16x32_bf16 v[46:49], v[164:167], v[180:183], v[46:49]
	v_mfma_f32_16x16x32_bf16 v[42:45], v[172:175], v[180:183], v[42:45]
	v_mfma_f32_16x16x32_bf16 v[30:33], v[164:167], v[188:191], v[30:33]
	v_mfma_f32_16x16x32_bf16 v[26:29], v[172:175], v[188:191], v[26:29]
	v_mfma_f32_16x16x32_bf16 v[14:17], v[164:167], v[200:203], v[14:17]
	v_mfma_f32_16x16x32_bf16 v[10:13], v[172:175], v[200:203], v[10:13]
	v_mfma_f32_16x16x32_bf16 v[6:9], v[164:167], v[208:211], v[6:9]
	v_mfma_f32_16x16x32_bf16 v[2:5], v[172:175], v[208:211], v[2:5]
	v_mfma_f32_16x16x32_bf16 v[46:49], v[168:171], v[184:187], v[46:49]
	v_mfma_f32_16x16x32_bf16 v[42:45], v[176:179], v[184:187], v[42:45]
	v_mfma_f32_16x16x32_bf16 v[30:33], v[168:171], v[196:199], v[30:33]
	v_mfma_f32_16x16x32_bf16 v[26:29], v[176:179], v[196:199], v[26:29]
	v_mfma_f32_16x16x32_bf16 v[14:17], v[168:171], v[204:207], v[14:17]
	v_mfma_f32_16x16x32_bf16 v[10:13], v[176:179], v[204:207], v[10:13]
	v_mfma_f32_16x16x32_bf16 v[6:9], v[168:171], v[212:215], v[6:9]
	s_barrier
	v_mfma_f32_16x16x32_bf16 v[2:5], v[176:179], v[212:215], v[2:5]
	s_setprio 0
	s_add_i32 s59, 0, 0x18000
	s_add_i32 s60, 0, 0x1c000
	v_add_u32_e32 v160, s59, v143
	v_add_u32_e32 v176, s60, v143
	ds_read_b128 v[148:151], v160
	ds_read_b128 v[152:155], v160 offset:1024
	ds_read_b128 v[156:159], v160 offset:2048
	ds_read_b128 v[160:163], v160 offset:3072
	ds_read_b128 v[164:167], v176
	ds_read_b128 v[168:171], v176 offset:1024
	ds_read_b128 v[172:175], v176 offset:2048
	ds_read_b128 v[176:179], v176 offset:3072
	s_add_u32 s38, s38, 0x80000
	s_addc_u32 s39, s39, 0
	s_mov_b32 m0, s42
	v_lshl_add_u64 v[222:223], s[38:39], 0, v[136:137]
	ds_read_b128 v[180:183], v147 offset:32768
	ds_read_b128 v[184:187], v147 offset:33792
	ds_read_b128 v[188:191], v147 offset:34816
	ds_read_b128 v[196:199], v147 offset:35840
	ds_read_b128 v[200:203], v147 offset:36864
	ds_read_b128 v[204:207], v147 offset:37888
	ds_read_b128 v[208:211], v147 offset:38912
	ds_read_b128 v[212:215], v147 offset:39936
	global_load_lds_dwordx4 v[222:223], off
	v_lshl_add_u64 v[222:223], s[38:39], 0, v[132:133]
	s_mov_b32 m0, s43
	s_nop 0
	global_load_lds_dwordx4 v[222:223], off
	s_waitcnt vmcnt(8)
	s_waitcnt lgkmcnt(0)
	s_barrier
	s_setprio 1
	s_waitcnt lgkmcnt(0)
	v_mfma_f32_16x16x32_bf16 v[126:129], v[148:151], v[180:183], v[126:129]
	v_mfma_f32_16x16x32_bf16 v[122:125], v[156:159], v[180:183], v[122:125]
	v_mfma_f32_16x16x32_bf16 v[118:121], v[148:151], v[188:191], v[118:121]
	v_mfma_f32_16x16x32_bf16 v[114:117], v[156:159], v[188:191], v[114:117]
	v_mfma_f32_16x16x32_bf16 v[102:105], v[148:151], v[200:203], v[102:105]
	v_mfma_f32_16x16x32_bf16 v[98:101], v[156:159], v[200:203], v[98:101]
	v_mfma_f32_16x16x32_bf16 v[86:89], v[148:151], v[208:211], v[86:89]
	v_mfma_f32_16x16x32_bf16 v[82:85], v[156:159], v[208:211], v[82:85]
	v_mfma_f32_16x16x32_bf16 v[126:129], v[152:155], v[184:187], v[126:129]
	v_mfma_f32_16x16x32_bf16 v[122:125], v[160:163], v[184:187], v[122:125]
	v_mfma_f32_16x16x32_bf16 v[118:121], v[152:155], v[196:199], v[118:121]
	v_mfma_f32_16x16x32_bf16 v[114:117], v[160:163], v[196:199], v[114:117]
	v_mfma_f32_16x16x32_bf16 v[102:105], v[152:155], v[204:207], v[102:105]
	v_mfma_f32_16x16x32_bf16 v[98:101], v[160:163], v[204:207], v[98:101]
	v_mfma_f32_16x16x32_bf16 v[86:89], v[152:155], v[212:215], v[86:89]
	v_mfma_f32_16x16x32_bf16 v[82:85], v[160:163], v[212:215], v[82:85]
	s_setprio 0
	s_setprio 1
	v_mfma_f32_16x16x32_bf16 v[110:113], v[164:167], v[180:183], v[110:113]
	v_mfma_f32_16x16x32_bf16 v[106:109], v[172:175], v[180:183], v[106:109]
	v_mfma_f32_16x16x32_bf16 v[94:97], v[164:167], v[188:191], v[94:97]
	v_mfma_f32_16x16x32_bf16 v[90:93], v[172:175], v[188:191], v[90:93]
	v_mfma_f32_16x16x32_bf16 v[78:81], v[164:167], v[200:203], v[78:81]
	v_mfma_f32_16x16x32_bf16 v[74:77], v[172:175], v[200:203], v[74:77]
	v_mfma_f32_16x16x32_bf16 v[70:73], v[164:167], v[208:211], v[70:73]
	v_mfma_f32_16x16x32_bf16 v[66:69], v[172:175], v[208:211], v[66:69]
	v_mfma_f32_16x16x32_bf16 v[110:113], v[168:171], v[184:187], v[110:113]
	v_mfma_f32_16x16x32_bf16 v[106:109], v[176:179], v[184:187], v[106:109]
	v_mfma_f32_16x16x32_bf16 v[94:97], v[168:171], v[196:199], v[94:97]
	v_mfma_f32_16x16x32_bf16 v[90:93], v[176:179], v[196:199], v[90:93]
	v_mfma_f32_16x16x32_bf16 v[78:81], v[168:171], v[204:207], v[78:81]
	v_mfma_f32_16x16x32_bf16 v[74:77], v[176:179], v[204:207], v[74:77]
	v_mfma_f32_16x16x32_bf16 v[70:73], v[168:171], v[212:215], v[70:73]
	s_barrier
	v_mfma_f32_16x16x32_bf16 v[66:69], v[176:179], v[212:215], v[66:69]
	s_setprio 0
	s_add_i32 s38, s59, s33
	v_lshl_add_u64 v[192:193], v[192:193], 0, s[6:7]
	s_mov_b32 m0, s38
	ds_read_b128 v[180:183], v147 offset:49152
	ds_read_b128 v[184:187], v147 offset:50176
	ds_read_b128 v[188:191], v147 offset:51200
	ds_read_b128 v[196:199], v147 offset:52224
	ds_read_b128 v[200:203], v147 offset:53248
	ds_read_b128 v[204:207], v147 offset:54272
	ds_read_b128 v[208:211], v147 offset:55296
	ds_read_b128 v[212:215], v147 offset:56320
	global_load_lds_dwordx4 v[192:193], off
	s_add_i32 m0, s38, 0x2000
	s_add_u32 s36, s36, 0x80080
	v_lshl_add_u64 v[192:193], v[216:217], 0, s[6:7]
	s_addc_u32 s37, s37, 0
	s_add_i32 s38, s60, s33
	global_load_lds_dwordx4 v[192:193], off
	v_lshl_add_u64 v[192:193], s[36:37], 0, v[134:135]
	s_mov_b32 m0, s38
	s_nop 0
	global_load_lds_dwordx4 v[192:193], off
	v_lshl_add_u64 v[192:193], s[36:37], 0, v[130:131]
	s_add_i32 m0, s38, 0x2000
	s_nop 0
	global_load_lds_dwordx4 v[192:193], off
	v_lshl_add_u64 v[192:193], v[218:219], 0, s[6:7]
	s_mov_b32 m0, s45
	s_nop 0
	global_load_lds_dwordx4 v[192:193], off
	v_lshl_add_u64 v[192:193], v[220:221], 0, s[6:7]
	s_mov_b32 m0, s46
	s_nop 0
	global_load_lds_dwordx4 v[192:193], off
	s_waitcnt vmcnt(8)
	s_waitcnt lgkmcnt(0)
	s_barrier
	s_setprio 1
	s_waitcnt lgkmcnt(0)
	v_mfma_f32_16x16x32_bf16 v[62:65], v[148:151], v[180:183], v[62:65]
	v_mfma_f32_16x16x32_bf16 v[58:61], v[156:159], v[180:183], v[58:61]
	v_mfma_f32_16x16x32_bf16 v[54:57], v[148:151], v[188:191], v[54:57]
	v_mfma_f32_16x16x32_bf16 v[50:53], v[156:159], v[188:191], v[50:53]
	v_mfma_f32_16x16x32_bf16 v[38:41], v[148:151], v[200:203], v[38:41]
	v_mfma_f32_16x16x32_bf16 v[34:37], v[156:159], v[200:203], v[34:37]
	v_mfma_f32_16x16x32_bf16 v[22:25], v[148:151], v[208:211], v[22:25]
	v_mfma_f32_16x16x32_bf16 v[18:21], v[156:159], v[208:211], v[18:21]
	v_mfma_f32_16x16x32_bf16 v[62:65], v[152:155], v[184:187], v[62:65]
	v_mfma_f32_16x16x32_bf16 v[58:61], v[160:163], v[184:187], v[58:61]
	v_mfma_f32_16x16x32_bf16 v[54:57], v[152:155], v[196:199], v[54:57]
	v_mfma_f32_16x16x32_bf16 v[50:53], v[160:163], v[196:199], v[50:53]
	v_mfma_f32_16x16x32_bf16 v[38:41], v[152:155], v[204:207], v[38:41]
	v_mfma_f32_16x16x32_bf16 v[34:37], v[160:163], v[204:207], v[34:37]
	v_mfma_f32_16x16x32_bf16 v[22:25], v[152:155], v[212:215], v[22:25]
	v_mfma_f32_16x16x32_bf16 v[18:21], v[160:163], v[212:215], v[18:21]
	s_setprio 0
	s_setprio 1
	v_mfma_f32_16x16x32_bf16 v[46:49], v[164:167], v[180:183], v[46:49]
	v_mfma_f32_16x16x32_bf16 v[42:45], v[172:175], v[180:183], v[42:45]
	v_mfma_f32_16x16x32_bf16 v[30:33], v[164:167], v[188:191], v[30:33]
	v_mfma_f32_16x16x32_bf16 v[26:29], v[172:175], v[188:191], v[26:29]
	v_mfma_f32_16x16x32_bf16 v[14:17], v[164:167], v[200:203], v[14:17]
	v_mfma_f32_16x16x32_bf16 v[10:13], v[172:175], v[200:203], v[10:13]
	v_mfma_f32_16x16x32_bf16 v[6:9], v[164:167], v[208:211], v[6:9]
	v_mfma_f32_16x16x32_bf16 v[2:5], v[172:175], v[208:211], v[2:5]
	v_mfma_f32_16x16x32_bf16 v[46:49], v[168:171], v[184:187], v[46:49]
	v_mfma_f32_16x16x32_bf16 v[42:45], v[176:179], v[184:187], v[42:45]
	v_mfma_f32_16x16x32_bf16 v[30:33], v[168:171], v[196:199], v[30:33]
	v_mfma_f32_16x16x32_bf16 v[26:29], v[176:179], v[196:199], v[26:29]
	v_mfma_f32_16x16x32_bf16 v[14:17], v[168:171], v[204:207], v[14:17]
	v_mfma_f32_16x16x32_bf16 v[10:13], v[176:179], v[204:207], v[10:13]
	v_mfma_f32_16x16x32_bf16 v[6:9], v[168:171], v[212:215], v[6:9]
	s_barrier
	v_mfma_f32_16x16x32_bf16 v[2:5], v[176:179], v[212:215], v[2:5]
	s_setprio 0
	s_add_i32 s58, s58, 2
	s_add_u32 s34, s34, 0x100
	s_addc_u32 s35, s35, 0
	s_add_u32 s56, s56, 0x100
	s_addc_u32 s57, s57, 0
	s_cmp_gt_u32 s58, 29
	s_cbranch_scc0 .LBB0_541

.Lpeel_10:
	ds_read_b128 v[150:153], v147
	ds_read_b128 v[154:157], v147 offset:1024
	s_add_u32 s28, s26, 0xfffe0080
	s_addc_u32 s29, s27, -1
	s_cmp_eq_u32 s50, 4
	s_cselect_b32 s31, s13, s29
	s_cselect_b32 s30, s46, s28
	s_cselect_b32 s29, s17, s49
	s_cselect_b32 s28, s47, s48
	v_lshl_add_u64 v[202:203], s[26:27], 0, v[138:139]
	s_add_i32 m0, s36, 0xc000
	global_load_lds_dwordx4 v[202:203], off
	v_lshl_add_u64 v[202:203], s[26:27], 0, v[140:141]
	s_add_i32 m0, s36, 0xe000
	s_nop 0
	global_load_lds_dwordx4 v[202:203], off
	s_waitcnt vmcnt(8)
	s_waitcnt lgkmcnt(0)
	s_barrier
	s_setprio 1
	s_waitcnt lgkmcnt(0)
	v_mfma_f32_16x16x32_bf16 v[126:129], v[150:153], v[182:185], 0
	v_mfma_f32_16x16x32_bf16 v[122:125], v[158:161], v[182:185], 0
	v_mfma_f32_16x16x32_bf16 v[118:121], v[150:153], v[190:193], 0
	v_mfma_f32_16x16x32_bf16 v[114:117], v[158:161], v[190:193], 0
	v_mfma_f32_16x16x32_bf16 v[102:105], v[150:153], v[210:213], 0
	v_mfma_f32_16x16x32_bf16 v[98:101], v[158:161], v[210:213], 0
	v_mfma_f32_16x16x32_bf16 v[86:89], v[150:153], v[218:221], 0
	v_mfma_f32_16x16x32_bf16 v[82:85], v[158:161], v[218:221], 0
	v_mfma_f32_16x16x32_bf16 v[126:129], v[154:157], v[186:189], v[126:129]
	v_mfma_f32_16x16x32_bf16 v[122:125], v[162:165], v[186:189], v[122:125]
	v_mfma_f32_16x16x32_bf16 v[118:121], v[154:157], v[198:201], v[118:121]
	v_mfma_f32_16x16x32_bf16 v[114:117], v[162:165], v[198:201], v[114:117]
	v_mfma_f32_16x16x32_bf16 v[102:105], v[154:157], v[214:217], v[102:105]
	v_mfma_f32_16x16x32_bf16 v[98:101], v[162:165], v[214:217], v[98:101]
	v_mfma_f32_16x16x32_bf16 v[86:89], v[154:157], v[222:225], v[86:89]
	v_mfma_f32_16x16x32_bf16 v[82:85], v[162:165], v[222:225], v[82:85]
	s_setprio 0
	s_setprio 1
	v_mfma_f32_16x16x32_bf16 v[110:113], v[166:169], v[182:185], 0
	v_mfma_f32_16x16x32_bf16 v[106:109], v[174:177], v[182:185], 0
	v_mfma_f32_16x16x32_bf16 v[94:97], v[166:169], v[190:193], 0
	v_mfma_f32_16x16x32_bf16 v[90:93], v[174:177], v[190:193], 0
	v_mfma_f32_16x16x32_bf16 v[78:81], v[166:169], v[210:213], 0
	v_mfma_f32_16x16x32_bf16 v[74:77], v[174:177], v[210:213], 0
	v_mfma_f32_16x16x32_bf16 v[70:73], v[166:169], v[218:221], 0
	v_mfma_f32_16x16x32_bf16 v[66:69], v[174:177], v[218:221], 0
	v_mfma_f32_16x16x32_bf16 v[110:113], v[170:173], v[186:189], v[110:113]
	v_mfma_f32_16x16x32_bf16 v[106:109], v[178:181], v[186:189], v[106:109]
	v_mfma_f32_16x16x32_bf16 v[94:97], v[170:173], v[198:201], v[94:97]
	v_mfma_f32_16x16x32_bf16 v[90:93], v[178:181], v[198:201], v[90:93]
	v_mfma_f32_16x16x32_bf16 v[78:81], v[170:173], v[214:217], v[78:81]
	v_mfma_f32_16x16x32_bf16 v[74:77], v[178:181], v[214:217], v[74:77]
	v_mfma_f32_16x16x32_bf16 v[70:73], v[170:173], v[222:225], v[70:73]
	s_barrier
	v_mfma_f32_16x16x32_bf16 v[66:69], v[178:181], v[222:225], v[66:69]
	s_setprio 0
	s_add_i32 s51, s43, s35
	v_lshl_add_u64 v[202:203], s[28:29], 0, v[132:133]
	s_mov_b32 m0, s51
	ds_read_b128 v[182:185], v149 offset:16384
	ds_read_b128 v[186:189], v149 offset:17408
	ds_read_b128 v[190:193], v149 offset:18432
	ds_read_b128 v[198:201], v149 offset:19456
	ds_read_b128 v[210:213], v149 offset:20480
	ds_read_b128 v[214:217], v149 offset:21504
	ds_read_b128 v[218:221], v149 offset:22528
	ds_read_b128 v[222:225], v149 offset:23552
	global_load_lds_dwordx4 v[202:203], off
	s_add_i32 m0, s51, 0x2000
	s_add_u32 s52, s28, 0x20000
	v_lshl_add_u64 v[206:207], s[28:29], 0, v[134:135]
	s_addc_u32 s53, s29, 0
	s_add_i32 s51, s44, s35
	global_load_lds_dwordx4 v[206:207], off
	v_lshl_add_u64 v[226:227], s[52:53], 0, v[132:133]
	s_mov_b32 m0, s51
	v_lshl_add_u64 v[228:229], s[30:31], 0, v[136:137]
	global_load_lds_dwordx4 v[226:227], off
	v_lshl_add_u64 v[226:227], s[52:53], 0, v[134:135]
	s_add_i32 m0, s51, 0x2000
	s_nop 0
	global_load_lds_dwordx4 v[226:227], off
	v_lshl_add_u64 v[226:227], s[30:31], 0, v[130:131]
	s_mov_b32 m0, s36
	s_nop 0
	global_load_lds_dwordx4 v[226:227], off
	s_mov_b32 m0, s37
	s_nop 0
	global_load_lds_dwordx4 v[228:229], off
	s_waitcnt vmcnt(8)
	s_waitcnt lgkmcnt(0)
	s_barrier
	s_setprio 1
	s_waitcnt lgkmcnt(0)
	v_mfma_f32_16x16x32_bf16 v[62:65], v[150:153], v[182:185], 0
	v_mfma_f32_16x16x32_bf16 v[58:61], v[158:161], v[182:185], 0
	v_mfma_f32_16x16x32_bf16 v[54:57], v[150:153], v[190:193], 0
	v_mfma_f32_16x16x32_bf16 v[50:53], v[158:161], v[190:193], 0
	v_mfma_f32_16x16x32_bf16 v[38:41], v[150:153], v[210:213], 0
	v_mfma_f32_16x16x32_bf16 v[34:37], v[158:161], v[210:213], 0
	v_mfma_f32_16x16x32_bf16 v[22:25], v[150:153], v[218:221], 0
	v_mfma_f32_16x16x32_bf16 v[18:21], v[158:161], v[218:221], 0
	v_mfma_f32_16x16x32_bf16 v[62:65], v[154:157], v[186:189], v[62:65]
	v_mfma_f32_16x16x32_bf16 v[58:61], v[162:165], v[186:189], v[58:61]
	v_mfma_f32_16x16x32_bf16 v[54:57], v[154:157], v[198:201], v[54:57]
	v_mfma_f32_16x16x32_bf16 v[50:53], v[162:165], v[198:201], v[50:53]
	v_mfma_f32_16x16x32_bf16 v[38:41], v[154:157], v[214:217], v[38:41]
	v_mfma_f32_16x16x32_bf16 v[34:37], v[162:165], v[214:217], v[34:37]
	v_mfma_f32_16x16x32_bf16 v[22:25], v[154:157], v[222:225], v[22:25]
	v_mfma_f32_16x16x32_bf16 v[18:21], v[162:165], v[222:225], v[18:21]
	s_setprio 0
	s_setprio 1
	v_mfma_f32_16x16x32_bf16 v[46:49], v[166:169], v[182:185], 0
	v_mfma_f32_16x16x32_bf16 v[42:45], v[174:177], v[182:185], 0
	v_mfma_f32_16x16x32_bf16 v[30:33], v[166:169], v[190:193], 0
	v_mfma_f32_16x16x32_bf16 v[26:29], v[174:177], v[190:193], 0
	v_mfma_f32_16x16x32_bf16 v[14:17], v[166:169], v[210:213], 0
	v_mfma_f32_16x16x32_bf16 v[10:13], v[174:177], v[210:213], 0
	v_mfma_f32_16x16x32_bf16 v[6:9], v[166:169], v[218:221], 0
	v_mfma_f32_16x16x32_bf16 v[2:5], v[174:177], v[218:221], 0
	v_mfma_f32_16x16x32_bf16 v[46:49], v[170:173], v[186:189], v[46:49]
	v_mfma_f32_16x16x32_bf16 v[42:45], v[178:181], v[186:189], v[42:45]
	v_mfma_f32_16x16x32_bf16 v[30:33], v[170:173], v[198:201], v[30:33]
	v_mfma_f32_16x16x32_bf16 v[26:29], v[178:181], v[198:201], v[26:29]
	v_mfma_f32_16x16x32_bf16 v[14:17], v[170:173], v[214:217], v[14:17]
	v_mfma_f32_16x16x32_bf16 v[10:13], v[178:181], v[214:217], v[10:13]
	v_mfma_f32_16x16x32_bf16 v[6:9], v[170:173], v[222:225], v[6:9]
	s_barrier
	v_mfma_f32_16x16x32_bf16 v[2:5], v[178:181], v[222:225], v[2:5]
	s_setprio 0
	s_add_i32 s51, 0, 0x18000
	s_add_i32 s52, 0, 0x1c000
	v_add_u32_e32 v162, s51, v145
	v_add_u32_e32 v178, s52, v145
	ds_read_b128 v[150:153], v162
	ds_read_b128 v[154:157], v162 offset:1024
	ds_read_b128 v[158:161], v162 offset:2048
	ds_read_b128 v[162:165], v162 offset:3072
	ds_read_b128 v[166:169], v178
	ds_read_b128 v[170:173], v178 offset:1024
	ds_read_b128 v[174:177], v178 offset:2048
	ds_read_b128 v[178:181], v178 offset:3072
	s_add_u32 s30, s30, 0x20000
	s_addc_u32 s31, s31, 0
	s_mov_b32 m0, s38
	v_lshl_add_u64 v[230:231], s[30:31], 0, v[130:131]
	ds_read_b128 v[182:185], v149 offset:32768
	ds_read_b128 v[186:189], v149 offset:33792
	ds_read_b128 v[190:193], v149 offset:34816
	ds_read_b128 v[198:201], v149 offset:35840
	ds_read_b128 v[210:213], v149 offset:36864
	ds_read_b128 v[214:217], v149 offset:37888
	ds_read_b128 v[218:221], v149 offset:38912
	ds_read_b128 v[222:225], v149 offset:39936
	global_load_lds_dwordx4 v[230:231], off
	v_lshl_add_u64 v[230:231], s[30:31], 0, v[136:137]
	s_mov_b32 m0, s39
	s_nop 0
	global_load_lds_dwordx4 v[230:231], off
	s_waitcnt vmcnt(8)
	s_waitcnt lgkmcnt(0)
	s_barrier
	s_setprio 1
	s_waitcnt lgkmcnt(0)
	v_mfma_f32_16x16x32_bf16 v[126:129], v[150:153], v[182:185], v[126:129]
	v_mfma_f32_16x16x32_bf16 v[122:125], v[158:161], v[182:185], v[122:125]
	v_mfma_f32_16x16x32_bf16 v[118:121], v[150:153], v[190:193], v[118:121]
	v_mfma_f32_16x16x32_bf16 v[114:117], v[158:161], v[190:193], v[114:117]
	v_mfma_f32_16x16x32_bf16 v[102:105], v[150:153], v[210:213], v[102:105]
	v_mfma_f32_16x16x32_bf16 v[98:101], v[158:161], v[210:213], v[98:101]
	v_mfma_f32_16x16x32_bf16 v[86:89], v[150:153], v[218:221], v[86:89]
	v_mfma_f32_16x16x32_bf16 v[82:85], v[158:161], v[218:221], v[82:85]
	v_mfma_f32_16x16x32_bf16 v[126:129], v[154:157], v[186:189], v[126:129]
	v_mfma_f32_16x16x32_bf16 v[122:125], v[162:165], v[186:189], v[122:125]
	v_mfma_f32_16x16x32_bf16 v[118:121], v[154:157], v[198:201], v[118:121]
	v_mfma_f32_16x16x32_bf16 v[114:117], v[162:165], v[198:201], v[114:117]
	v_mfma_f32_16x16x32_bf16 v[102:105], v[154:157], v[214:217], v[102:105]
	v_mfma_f32_16x16x32_bf16 v[98:101], v[162:165], v[214:217], v[98:101]
	v_mfma_f32_16x16x32_bf16 v[86:89], v[154:157], v[222:225], v[86:89]
	v_mfma_f32_16x16x32_bf16 v[82:85], v[162:165], v[222:225], v[82:85]
	s_setprio 0
	s_setprio 1
	v_mfma_f32_16x16x32_bf16 v[110:113], v[166:169], v[182:185], v[110:113]
	v_mfma_f32_16x16x32_bf16 v[106:109], v[174:177], v[182:185], v[106:109]
	v_mfma_f32_16x16x32_bf16 v[94:97], v[166:169], v[190:193], v[94:97]
	v_mfma_f32_16x16x32_bf16 v[90:93], v[174:177], v[190:193], v[90:93]
	v_mfma_f32_16x16x32_bf16 v[78:81], v[166:169], v[210:213], v[78:81]
	v_mfma_f32_16x16x32_bf16 v[74:77], v[174:177], v[210:213], v[74:77]
	v_mfma_f32_16x16x32_bf16 v[70:73], v[166:169], v[218:221], v[70:73]
	v_mfma_f32_16x16x32_bf16 v[66:69], v[174:177], v[218:221], v[66:69]
	v_mfma_f32_16x16x32_bf16 v[110:113], v[170:173], v[186:189], v[110:113]
	v_mfma_f32_16x16x32_bf16 v[106:109], v[178:181], v[186:189], v[106:109]
	v_mfma_f32_16x16x32_bf16 v[94:97], v[170:173], v[198:201], v[94:97]
	v_mfma_f32_16x16x32_bf16 v[90:93], v[178:181], v[198:201], v[90:93]
	v_mfma_f32_16x16x32_bf16 v[78:81], v[170:173], v[214:217], v[78:81]
	v_mfma_f32_16x16x32_bf16 v[74:77], v[178:181], v[214:217], v[74:77]
	v_mfma_f32_16x16x32_bf16 v[70:73], v[170:173], v[222:225], v[70:73]
	s_barrier
	v_mfma_f32_16x16x32_bf16 v[66:69], v[178:181], v[222:225], v[66:69]
	s_setprio 0
	s_add_i32 s30, s51, s35
	v_lshl_add_u64 v[202:203], v[202:203], 0, s[8:9]
	s_mov_b32 m0, s30
	ds_read_b128 v[182:185], v149 offset:49152
	ds_read_b128 v[186:189], v149 offset:50176
	ds_read_b128 v[190:193], v149 offset:51200
	ds_read_b128 v[198:201], v149 offset:52224
	ds_read_b128 v[210:213], v149 offset:53248
	ds_read_b128 v[214:217], v149 offset:54272
	ds_read_b128 v[218:221], v149 offset:55296
	ds_read_b128 v[222:225], v149 offset:56320
	global_load_lds_dwordx4 v[202:203], off
	s_add_i32 m0, s30, 0x2000
	s_add_u32 s28, s28, 0x20080
	v_lshl_add_u64 v[202:203], v[206:207], 0, s[8:9]
	s_addc_u32 s29, s29, 0
	s_add_i32 s30, s52, s35
	global_load_lds_dwordx4 v[202:203], off
	v_lshl_add_u64 v[202:203], s[28:29], 0, v[132:133]
	s_mov_b32 m0, s30
	s_nop 0
	global_load_lds_dwordx4 v[202:203], off
	v_lshl_add_u64 v[202:203], s[28:29], 0, v[134:135]
	s_add_i32 m0, s30, 0x2000
	s_nop 0
	global_load_lds_dwordx4 v[202:203], off
	v_lshl_add_u64 v[202:203], v[226:227], 0, s[8:9]
	s_mov_b32 m0, s41
	s_nop 0
	global_load_lds_dwordx4 v[202:203], off
	v_lshl_add_u64 v[202:203], v[228:229], 0, s[8:9]
	s_mov_b32 m0, s42
	s_nop 0
	global_load_lds_dwordx4 v[202:203], off
	s_waitcnt vmcnt(8)
	s_waitcnt lgkmcnt(0)
	s_barrier
	s_setprio 1
	s_waitcnt lgkmcnt(0)
	v_mfma_f32_16x16x32_bf16 v[62:65], v[150:153], v[182:185], v[62:65]
	v_mfma_f32_16x16x32_bf16 v[58:61], v[158:161], v[182:185], v[58:61]
	v_mfma_f32_16x16x32_bf16 v[54:57], v[150:153], v[190:193], v[54:57]
	v_mfma_f32_16x16x32_bf16 v[50:53], v[158:161], v[190:193], v[50:53]
	v_mfma_f32_16x16x32_bf16 v[38:41], v[150:153], v[210:213], v[38:41]
	v_mfma_f32_16x16x32_bf16 v[34:37], v[158:161], v[210:213], v[34:37]
	v_mfma_f32_16x16x32_bf16 v[22:25], v[150:153], v[218:221], v[22:25]
	v_mfma_f32_16x16x32_bf16 v[18:21], v[158:161], v[218:221], v[18:21]
	v_mfma_f32_16x16x32_bf16 v[62:65], v[154:157], v[186:189], v[62:65]
	v_mfma_f32_16x16x32_bf16 v[58:61], v[162:165], v[186:189], v[58:61]
	v_mfma_f32_16x16x32_bf16 v[54:57], v[154:157], v[198:201], v[54:57]
	v_mfma_f32_16x16x32_bf16 v[50:53], v[162:165], v[198:201], v[50:53]
	v_mfma_f32_16x16x32_bf16 v[38:41], v[154:157], v[214:217], v[38:41]
	v_mfma_f32_16x16x32_bf16 v[34:37], v[162:165], v[214:217], v[34:37]
	v_mfma_f32_16x16x32_bf16 v[22:25], v[154:157], v[222:225], v[22:25]
	v_mfma_f32_16x16x32_bf16 v[18:21], v[162:165], v[222:225], v[18:21]
	s_setprio 0
	s_setprio 1
	v_mfma_f32_16x16x32_bf16 v[46:49], v[166:169], v[182:185], v[46:49]
	v_mfma_f32_16x16x32_bf16 v[42:45], v[174:177], v[182:185], v[42:45]
	v_mfma_f32_16x16x32_bf16 v[30:33], v[166:169], v[190:193], v[30:33]
	v_mfma_f32_16x16x32_bf16 v[26:29], v[174:177], v[190:193], v[26:29]
	v_mfma_f32_16x16x32_bf16 v[14:17], v[166:169], v[210:213], v[14:17]
	v_mfma_f32_16x16x32_bf16 v[10:13], v[174:177], v[210:213], v[10:13]
	v_mfma_f32_16x16x32_bf16 v[6:9], v[166:169], v[218:221], v[6:9]
	v_mfma_f32_16x16x32_bf16 v[2:5], v[174:177], v[218:221], v[2:5]
	v_mfma_f32_16x16x32_bf16 v[46:49], v[170:173], v[186:189], v[46:49]
	v_mfma_f32_16x16x32_bf16 v[42:45], v[178:181], v[186:189], v[42:45]
	v_mfma_f32_16x16x32_bf16 v[30:33], v[170:173], v[198:201], v[30:33]
	v_mfma_f32_16x16x32_bf16 v[26:29], v[178:181], v[198:201], v[26:29]
	v_mfma_f32_16x16x32_bf16 v[14:17], v[170:173], v[214:217], v[14:17]
	v_mfma_f32_16x16x32_bf16 v[10:13], v[178:181], v[214:217], v[10:13]
	v_mfma_f32_16x16x32_bf16 v[6:9], v[170:173], v[222:225], v[6:9]
	s_barrier
	v_mfma_f32_16x16x32_bf16 v[2:5], v[178:181], v[222:225], v[2:5]
	s_setprio 0
	s_add_i32 s50, s50, 2
	s_add_u32 s26, s26, 0x100
	s_addc_u32 s27, s27, 0
	s_add_u32 s48, s48, 0x100
	s_addc_u32 s49, s49, 0
	s_cmp_gt_u32 s50, 5
	s_cbranch_scc0 .LBB0_690
	s_branch .Lpeeldone_10
.LBB0_690:
	ds_read_b128 v[150:153], v147
	ds_read_b128 v[154:157], v147 offset:1024
	ds_read_b128 v[158:161], v147 offset:2048
	ds_read_b128 v[162:165], v147 offset:3072
	ds_read_b128 v[166:169], v148
	ds_read_b128 v[170:173], v148 offset:1024
	ds_read_b128 v[174:177], v148 offset:2048
	ds_read_b128 v[178:181], v148 offset:3072
	s_add_u32 s28, s26, 0xfffe0080
	s_addc_u32 s29, s27, -1
	s_cmp_eq_u32 s50, 4
	s_cselect_b32 s31, s13, s29
	s_cselect_b32 s30, s46, s28
	s_cselect_b32 s29, s17, s49
	s_cselect_b32 s28, s47, s48
	v_lshl_add_u64 v[202:203], s[26:27], 0, v[138:139]
	s_add_i32 m0, s36, 0xc000
	ds_read_b128 v[182:185], v149
	ds_read_b128 v[186:189], v149 offset:1024
	ds_read_b128 v[190:193], v149 offset:2048
	ds_read_b128 v[198:201], v149 offset:3072
	ds_read_b128 v[210:213], v149 offset:4096
	ds_read_b128 v[214:217], v149 offset:5120
	ds_read_b128 v[218:221], v149 offset:6144
	ds_read_b128 v[222:225], v149 offset:7168
	global_load_lds_dwordx4 v[202:203], off
	v_lshl_add_u64 v[202:203], s[26:27], 0, v[140:141]
	s_add_i32 m0, s36, 0xe000
	s_nop 0
	global_load_lds_dwordx4 v[202:203], off
	s_waitcnt vmcnt(8)
	s_waitcnt lgkmcnt(0)
	s_barrier
	s_setprio 1
	s_waitcnt lgkmcnt(0)
	v_mfma_f32_16x16x32_bf16 v[126:129], v[150:153], v[182:185], v[126:129]
	v_mfma_f32_16x16x32_bf16 v[122:125], v[158:161], v[182:185], v[122:125]
	v_mfma_f32_16x16x32_bf16 v[118:121], v[150:153], v[190:193], v[118:121]
	v_mfma_f32_16x16x32_bf16 v[114:117], v[158:161], v[190:193], v[114:117]
	v_mfma_f32_16x16x32_bf16 v[102:105], v[150:153], v[210:213], v[102:105]
	v_mfma_f32_16x16x32_bf16 v[98:101], v[158:161], v[210:213], v[98:101]
	v_mfma_f32_16x16x32_bf16 v[86:89], v[150:153], v[218:221], v[86:89]
	v_mfma_f32_16x16x32_bf16 v[82:85], v[158:161], v[218:221], v[82:85]
	v_mfma_f32_16x16x32_bf16 v[126:129], v[154:157], v[186:189], v[126:129]
	v_mfma_f32_16x16x32_bf16 v[122:125], v[162:165], v[186:189], v[122:125]
	v_mfma_f32_16x16x32_bf16 v[118:121], v[154:157], v[198:201], v[118:121]
	v_mfma_f32_16x16x32_bf16 v[114:117], v[162:165], v[198:201], v[114:117]
	v_mfma_f32_16x16x32_bf16 v[102:105], v[154:157], v[214:217], v[102:105]
	v_mfma_f32_16x16x32_bf16 v[98:101], v[162:165], v[214:217], v[98:101]
	v_mfma_f32_16x16x32_bf16 v[86:89], v[154:157], v[222:225], v[86:89]
	v_mfma_f32_16x16x32_bf16 v[82:85], v[162:165], v[222:225], v[82:85]
	s_setprio 0
	s_setprio 1
	v_mfma_f32_16x16x32_bf16 v[110:113], v[166:169], v[182:185], v[110:113]
	v_mfma_f32_16x16x32_bf16 v[106:109], v[174:177], v[182:185], v[106:109]
	v_mfma_f32_16x16x32_bf16 v[94:97], v[166:169], v[190:193], v[94:97]
	v_mfma_f32_16x16x32_bf16 v[90:93], v[174:177], v[190:193], v[90:93]
	v_mfma_f32_16x16x32_bf16 v[78:81], v[166:169], v[210:213], v[78:81]
	v_mfma_f32_16x16x32_bf16 v[74:77], v[174:177], v[210:213], v[74:77]
	v_mfma_f32_16x16x32_bf16 v[70:73], v[166:169], v[218:221], v[70:73]
	v_mfma_f32_16x16x32_bf16 v[66:69], v[174:177], v[218:221], v[66:69]
	v_mfma_f32_16x16x32_bf16 v[110:113], v[170:173], v[186:189], v[110:113]
	v_mfma_f32_16x16x32_bf16 v[106:109], v[178:181], v[186:189], v[106:109]
	v_mfma_f32_16x16x32_bf16 v[94:97], v[170:173], v[198:201], v[94:97]
	v_mfma_f32_16x16x32_bf16 v[90:93], v[178:181], v[198:201], v[90:93]
	v_mfma_f32_16x16x32_bf16 v[78:81], v[170:173], v[214:217], v[78:81]
	v_mfma_f32_16x16x32_bf16 v[74:77], v[178:181], v[214:217], v[74:77]
	v_mfma_f32_16x16x32_bf16 v[70:73], v[170:173], v[222:225], v[70:73]
	s_barrier
	v_mfma_f32_16x16x32_bf16 v[66:69], v[178:181], v[222:225], v[66:69]
	s_setprio 0
	s_add_i32 s51, s43, s35
	v_lshl_add_u64 v[202:203], s[28:29], 0, v[132:133]
	s_mov_b32 m0, s51
	ds_read_b128 v[182:185], v149 offset:16384
	ds_read_b128 v[186:189], v149 offset:17408
	ds_read_b128 v[190:193], v149 offset:18432
	ds_read_b128 v[198:201], v149 offset:19456
	ds_read_b128 v[210:213], v149 offset:20480
	ds_read_b128 v[214:217], v149 offset:21504
	ds_read_b128 v[218:221], v149 offset:22528
	ds_read_b128 v[222:225], v149 offset:23552
	global_load_lds_dwordx4 v[202:203], off
	s_add_i32 m0, s51, 0x2000
	s_add_u32 s52, s28, 0x20000
	v_lshl_add_u64 v[206:207], s[28:29], 0, v[134:135]
	s_addc_u32 s53, s29, 0
	s_add_i32 s51, s44, s35
	global_load_lds_dwordx4 v[206:207], off
	v_lshl_add_u64 v[226:227], s[52:53], 0, v[132:133]
	s_mov_b32 m0, s51
	v_lshl_add_u64 v[228:229], s[30:31], 0, v[136:137]
	global_load_lds_dwordx4 v[226:227], off
	v_lshl_add_u64 v[226:227], s[52:53], 0, v[134:135]
	s_add_i32 m0, s51, 0x2000
	s_nop 0
	global_load_lds_dwordx4 v[226:227], off
	v_lshl_add_u64 v[226:227], s[30:31], 0, v[130:131]
	s_mov_b32 m0, s36
	s_nop 0
	global_load_lds_dwordx4 v[226:227], off
	s_mov_b32 m0, s37
	s_nop 0
	global_load_lds_dwordx4 v[228:229], off
	s_waitcnt vmcnt(8)
	s_waitcnt lgkmcnt(0)
	s_barrier
	s_setprio 1
	s_waitcnt lgkmcnt(0)
	v_mfma_f32_16x16x32_bf16 v[62:65], v[150:153], v[182:185], v[62:65]
	v_mfma_f32_16x16x32_bf16 v[58:61], v[158:161], v[182:185], v[58:61]
	v_mfma_f32_16x16x32_bf16 v[54:57], v[150:153], v[190:193], v[54:57]
	v_mfma_f32_16x16x32_bf16 v[50:53], v[158:161], v[190:193], v[50:53]
	v_mfma_f32_16x16x32_bf16 v[38:41], v[150:153], v[210:213], v[38:41]
	v_mfma_f32_16x16x32_bf16 v[34:37], v[158:161], v[210:213], v[34:37]
	v_mfma_f32_16x16x32_bf16 v[22:25], v[150:153], v[218:221], v[22:25]
	v_mfma_f32_16x16x32_bf16 v[18:21], v[158:161], v[218:221], v[18:21]
	v_mfma_f32_16x16x32_bf16 v[62:65], v[154:157], v[186:189], v[62:65]
	v_mfma_f32_16x16x32_bf16 v[58:61], v[162:165], v[186:189], v[58:61]
	v_mfma_f32_16x16x32_bf16 v[54:57], v[154:157], v[198:201], v[54:57]
	v_mfma_f32_16x16x32_bf16 v[50:53], v[162:165], v[198:201], v[50:53]
	v_mfma_f32_16x16x32_bf16 v[38:41], v[154:157], v[214:217], v[38:41]
	v_mfma_f32_16x16x32_bf16 v[34:37], v[162:165], v[214:217], v[34:37]
	v_mfma_f32_16x16x32_bf16 v[22:25], v[154:157], v[222:225], v[22:25]
	v_mfma_f32_16x16x32_bf16 v[18:21], v[162:165], v[222:225], v[18:21]
	s_setprio 0
	s_setprio 1
	v_mfma_f32_16x16x32_bf16 v[46:49], v[166:169], v[182:185], v[46:49]
	v_mfma_f32_16x16x32_bf16 v[42:45], v[174:177], v[182:185], v[42:45]
	v_mfma_f32_16x16x32_bf16 v[30:33], v[166:169], v[190:193], v[30:33]
	v_mfma_f32_16x16x32_bf16 v[26:29], v[174:177], v[190:193], v[26:29]
	v_mfma_f32_16x16x32_bf16 v[14:17], v[166:169], v[210:213], v[14:17]
	v_mfma_f32_16x16x32_bf16 v[10:13], v[174:177], v[210:213], v[10:13]
	v_mfma_f32_16x16x32_bf16 v[6:9], v[166:169], v[218:221], v[6:9]
	v_mfma_f32_16x16x32_bf16 v[2:5], v[174:177], v[218:221], v[2:5]
	v_mfma_f32_16x16x32_bf16 v[46:49], v[170:173], v[186:189], v[46:49]
	v_mfma_f32_16x16x32_bf16 v[42:45], v[178:181], v[186:189], v[42:45]
	v_mfma_f32_16x16x32_bf16 v[30:33], v[170:173], v[198:201], v[30:33]
	v_mfma_f32_16x16x32_bf16 v[26:29], v[178:181], v[198:201], v[26:29]
	v_mfma_f32_16x16x32_bf16 v[14:17], v[170:173], v[214:217], v[14:17]
	v_mfma_f32_16x16x32_bf16 v[10:13], v[178:181], v[214:217], v[10:13]
	v_mfma_f32_16x16x32_bf16 v[6:9], v[170:173], v[222:225], v[6:9]
	s_barrier
	v_mfma_f32_16x16x32_bf16 v[2:5], v[178:181], v[222:225], v[2:5]
	s_setprio 0
	s_add_i32 s51, 0, 0x18000
	s_add_i32 s52, 0, 0x1c000
	v_add_u32_e32 v162, s51, v145
	v_add_u32_e32 v178, s52, v145
	ds_read_b128 v[150:153], v162
	ds_read_b128 v[154:157], v162 offset:1024
	ds_read_b128 v[158:161], v162 offset:2048
	ds_read_b128 v[162:165], v162 offset:3072
	ds_read_b128 v[166:169], v178
	ds_read_b128 v[170:173], v178 offset:1024
	ds_read_b128 v[174:177], v178 offset:2048
	ds_read_b128 v[178:181], v178 offset:3072
	s_add_u32 s30, s30, 0x20000
	s_addc_u32 s31, s31, 0
	s_mov_b32 m0, s38
	v_lshl_add_u64 v[230:231], s[30:31], 0, v[130:131]
	ds_read_b128 v[182:185], v149 offset:32768
	ds_read_b128 v[186:189], v149 offset:33792
	ds_read_b128 v[190:193], v149 offset:34816
	ds_read_b128 v[198:201], v149 offset:35840
	ds_read_b128 v[210:213], v149 offset:36864
	ds_read_b128 v[214:217], v149 offset:37888
	ds_read_b128 v[218:221], v149 offset:38912
	ds_read_b128 v[222:225], v149 offset:39936
	global_load_lds_dwordx4 v[230:231], off
	v_lshl_add_u64 v[230:231], s[30:31], 0, v[136:137]
	s_mov_b32 m0, s39
	s_nop 0
	global_load_lds_dwordx4 v[230:231], off
	s_waitcnt vmcnt(8)
	s_waitcnt lgkmcnt(0)
	s_barrier
	s_setprio 1
	s_waitcnt lgkmcnt(0)
	v_mfma_f32_16x16x32_bf16 v[126:129], v[150:153], v[182:185], v[126:129]
	v_mfma_f32_16x16x32_bf16 v[122:125], v[158:161], v[182:185], v[122:125]
	v_mfma_f32_16x16x32_bf16 v[118:121], v[150:153], v[190:193], v[118:121]
	v_mfma_f32_16x16x32_bf16 v[114:117], v[158:161], v[190:193], v[114:117]
	v_mfma_f32_16x16x32_bf16 v[102:105], v[150:153], v[210:213], v[102:105]
	v_mfma_f32_16x16x32_bf16 v[98:101], v[158:161], v[210:213], v[98:101]
	v_mfma_f32_16x16x32_bf16 v[86:89], v[150:153], v[218:221], v[86:89]
	v_mfma_f32_16x16x32_bf16 v[82:85], v[158:161], v[218:221], v[82:85]
	v_mfma_f32_16x16x32_bf16 v[126:129], v[154:157], v[186:189], v[126:129]
	v_mfma_f32_16x16x32_bf16 v[122:125], v[162:165], v[186:189], v[122:125]
	v_mfma_f32_16x16x32_bf16 v[118:121], v[154:157], v[198:201], v[118:121]
	v_mfma_f32_16x16x32_bf16 v[114:117], v[162:165], v[198:201], v[114:117]
	v_mfma_f32_16x16x32_bf16 v[102:105], v[154:157], v[214:217], v[102:105]
	v_mfma_f32_16x16x32_bf16 v[98:101], v[162:165], v[214:217], v[98:101]
	v_mfma_f32_16x16x32_bf16 v[86:89], v[154:157], v[222:225], v[86:89]
	v_mfma_f32_16x16x32_bf16 v[82:85], v[162:165], v[222:225], v[82:85]
	s_setprio 0
	s_setprio 1
	v_mfma_f32_16x16x32_bf16 v[110:113], v[166:169], v[182:185], v[110:113]
	v_mfma_f32_16x16x32_bf16 v[106:109], v[174:177], v[182:185], v[106:109]
	v_mfma_f32_16x16x32_bf16 v[94:97], v[166:169], v[190:193], v[94:97]
	v_mfma_f32_16x16x32_bf16 v[90:93], v[174:177], v[190:193], v[90:93]
	v_mfma_f32_16x16x32_bf16 v[78:81], v[166:169], v[210:213], v[78:81]
	v_mfma_f32_16x16x32_bf16 v[74:77], v[174:177], v[210:213], v[74:77]
	v_mfma_f32_16x16x32_bf16 v[70:73], v[166:169], v[218:221], v[70:73]
	v_mfma_f32_16x16x32_bf16 v[66:69], v[174:177], v[218:221], v[66:69]
	v_mfma_f32_16x16x32_bf16 v[110:113], v[170:173], v[186:189], v[110:113]
	v_mfma_f32_16x16x32_bf16 v[106:109], v[178:181], v[186:189], v[106:109]
	v_mfma_f32_16x16x32_bf16 v[94:97], v[170:173], v[198:201], v[94:97]
	v_mfma_f32_16x16x32_bf16 v[90:93], v[178:181], v[198:201], v[90:93]
	v_mfma_f32_16x16x32_bf16 v[78:81], v[170:173], v[214:217], v[78:81]
	v_mfma_f32_16x16x32_bf16 v[74:77], v[178:181], v[214:217], v[74:77]
	v_mfma_f32_16x16x32_bf16 v[70:73], v[170:173], v[222:225], v[70:73]
	s_barrier
	v_mfma_f32_16x16x32_bf16 v[66:69], v[178:181], v[222:225], v[66:69]
	s_setprio 0
	s_add_i32 s30, s51, s35
	v_lshl_add_u64 v[202:203], v[202:203], 0, s[8:9]
	s_mov_b32 m0, s30
	ds_read_b128 v[182:185], v149 offset:49152
	ds_read_b128 v[186:189], v149 offset:50176
	ds_read_b128 v[190:193], v149 offset:51200
	ds_read_b128 v[198:201], v149 offset:52224
	ds_read_b128 v[210:213], v149 offset:53248
	ds_read_b128 v[214:217], v149 offset:54272
	ds_read_b128 v[218:221], v149 offset:55296
	ds_read_b128 v[222:225], v149 offset:56320
	global_load_lds_dwordx4 v[202:203], off
	s_add_i32 m0, s30, 0x2000
	s_add_u32 s28, s28, 0x20080
	v_lshl_add_u64 v[202:203], v[206:207], 0, s[8:9]
	s_addc_u32 s29, s29, 0
	s_add_i32 s30, s52, s35
	global_load_lds_dwordx4 v[202:203], off
	v_lshl_add_u64 v[202:203], s[28:29], 0, v[132:133]
	s_mov_b32 m0, s30
	s_nop 0
	global_load_lds_dwordx4 v[202:203], off
	v_lshl_add_u64 v[202:203], s[28:29], 0, v[134:135]
	s_add_i32 m0, s30, 0x2000
	s_nop 0
	global_load_lds_dwordx4 v[202:203], off
	v_lshl_add_u64 v[202:203], v[226:227], 0, s[8:9]
	s_mov_b32 m0, s41
	s_nop 0
	global_load_lds_dwordx4 v[202:203], off
	v_lshl_add_u64 v[202:203], v[228:229], 0, s[8:9]
	s_mov_b32 m0, s42
	s_nop 0
	global_load_lds_dwordx4 v[202:203], off
	s_waitcnt vmcnt(8)
	s_waitcnt lgkmcnt(0)
	s_barrier
	s_setprio 1
	s_waitcnt lgkmcnt(0)
	v_mfma_f32_16x16x32_bf16 v[62:65], v[150:153], v[182:185], v[62:65]
	v_mfma_f32_16x16x32_bf16 v[58:61], v[158:161], v[182:185], v[58:61]
	v_mfma_f32_16x16x32_bf16 v[54:57], v[150:153], v[190:193], v[54:57]
	v_mfma_f32_16x16x32_bf16 v[50:53], v[158:161], v[190:193], v[50:53]
	v_mfma_f32_16x16x32_bf16 v[38:41], v[150:153], v[210:213], v[38:41]
	v_mfma_f32_16x16x32_bf16 v[34:37], v[158:161], v[210:213], v[34:37]
	v_mfma_f32_16x16x32_bf16 v[22:25], v[150:153], v[218:221], v[22:25]
	v_mfma_f32_16x16x32_bf16 v[18:21], v[158:161], v[218:221], v[18:21]
	v_mfma_f32_16x16x32_bf16 v[62:65], v[154:157], v[186:189], v[62:65]
	v_mfma_f32_16x16x32_bf16 v[58:61], v[162:165], v[186:189], v[58:61]
	v_mfma_f32_16x16x32_bf16 v[54:57], v[154:157], v[198:201], v[54:57]
	v_mfma_f32_16x16x32_bf16 v[50:53], v[162:165], v[198:201], v[50:53]
	v_mfma_f32_16x16x32_bf16 v[38:41], v[154:157], v[214:217], v[38:41]
	v_mfma_f32_16x16x32_bf16 v[34:37], v[162:165], v[214:217], v[34:37]
	v_mfma_f32_16x16x32_bf16 v[22:25], v[154:157], v[222:225], v[22:25]
	v_mfma_f32_16x16x32_bf16 v[18:21], v[162:165], v[222:225], v[18:21]
	s_setprio 0
	s_setprio 1
	v_mfma_f32_16x16x32_bf16 v[46:49], v[166:169], v[182:185], v[46:49]
	v_mfma_f32_16x16x32_bf16 v[42:45], v[174:177], v[182:185], v[42:45]
	v_mfma_f32_16x16x32_bf16 v[30:33], v[166:169], v[190:193], v[30:33]
	v_mfma_f32_16x16x32_bf16 v[26:29], v[174:177], v[190:193], v[26:29]
	v_mfma_f32_16x16x32_bf16 v[14:17], v[166:169], v[210:213], v[14:17]
	v_mfma_f32_16x16x32_bf16 v[10:13], v[174:177], v[210:213], v[10:13]
	v_mfma_f32_16x16x32_bf16 v[6:9], v[166:169], v[218:221], v[6:9]
	v_mfma_f32_16x16x32_bf16 v[2:5], v[174:177], v[218:221], v[2:5]
	v_mfma_f32_16x16x32_bf16 v[46:49], v[170:173], v[186:189], v[46:49]
	v_mfma_f32_16x16x32_bf16 v[42:45], v[178:181], v[186:189], v[42:45]
	v_mfma_f32_16x16x32_bf16 v[30:33], v[170:173], v[198:201], v[30:33]
	v_mfma_f32_16x16x32_bf16 v[26:29], v[178:181], v[198:201], v[26:29]
	v_mfma_f32_16x16x32_bf16 v[14:17], v[170:173], v[214:217], v[14:17]
	v_mfma_f32_16x16x32_bf16 v[10:13], v[178:181], v[214:217], v[10:13]
	v_mfma_f32_16x16x32_bf16 v[6:9], v[170:173], v[222:225], v[6:9]
	s_barrier
	v_mfma_f32_16x16x32_bf16 v[2:5], v[178:181], v[222:225], v[2:5]
	s_setprio 0
	s_add_i32 s50, s50, 2
	s_add_u32 s26, s26, 0x100
	s_addc_u32 s27, s27, 0
	s_add_u32 s48, s48, 0x100
	s_addc_u32 s49, s49, 0
	s_cmp_gt_u32 s50, 5
	s_cbranch_scc0 .LBB0_690

.Lpeel_9:
	ds_read_b128 v[144:147], v140
	ds_read_b128 v[148:151], v140 offset:1024
	s_add_u32 s36, s34, 0xfffe0080
	s_addc_u32 s37, s35, -1
	s_cmp_eq_u32 s59, 4
	s_cselect_b32 s39, s21, s37
	s_cselect_b32 s38, s55, s36
	s_cselect_b32 s37, s25, s58
	s_cselect_b32 s36, s56, s57
	v_lshl_add_u64 v[192:193], s[34:35], 0, v[130:131]
	s_add_i32 m0, s27, 0xc000
	global_load_lds_dwordx4 v[192:193], off
	v_lshl_add_u64 v[192:193], s[34:35], 0, v[136:137]
	s_add_i32 m0, s27, 0xe000
	s_nop 0
	global_load_lds_dwordx4 v[192:193], off
	s_waitcnt vmcnt(8)
	s_waitcnt lgkmcnt(0)
	s_barrier
	s_setprio 1
	s_waitcnt lgkmcnt(0)
	v_mfma_f32_16x16x32_bf16 v[126:129], v[144:147], v[176:179], 0
	v_mfma_f32_16x16x32_bf16 v[122:125], v[152:155], v[176:179], 0
	v_mfma_f32_16x16x32_bf16 v[118:121], v[144:147], v[184:187], 0
	v_mfma_f32_16x16x32_bf16 v[114:117], v[152:155], v[184:187], 0
	v_mfma_f32_16x16x32_bf16 v[102:105], v[144:147], v[198:201], 0
	v_mfma_f32_16x16x32_bf16 v[98:101], v[152:155], v[198:201], 0
	v_mfma_f32_16x16x32_bf16 v[86:89], v[144:147], v[214:217], 0
	v_mfma_f32_16x16x32_bf16 v[82:85], v[152:155], v[214:217], 0
	v_mfma_f32_16x16x32_bf16 v[126:129], v[148:151], v[180:183], v[126:129]
	v_mfma_f32_16x16x32_bf16 v[122:125], v[156:159], v[180:183], v[122:125]
	v_mfma_f32_16x16x32_bf16 v[118:121], v[148:151], v[188:191], v[118:121]
	v_mfma_f32_16x16x32_bf16 v[114:117], v[156:159], v[188:191], v[114:117]
	v_mfma_f32_16x16x32_bf16 v[102:105], v[148:151], v[210:213], v[102:105]
	v_mfma_f32_16x16x32_bf16 v[98:101], v[156:159], v[210:213], v[98:101]
	v_mfma_f32_16x16x32_bf16 v[86:89], v[148:151], v[218:221], v[86:89]
	v_mfma_f32_16x16x32_bf16 v[82:85], v[156:159], v[218:221], v[82:85]
	s_setprio 0
	s_setprio 1
	v_mfma_f32_16x16x32_bf16 v[110:113], v[160:163], v[176:179], 0
	v_mfma_f32_16x16x32_bf16 v[106:109], v[168:171], v[176:179], 0
	v_mfma_f32_16x16x32_bf16 v[94:97], v[160:163], v[184:187], 0
	v_mfma_f32_16x16x32_bf16 v[90:93], v[168:171], v[184:187], 0
	v_mfma_f32_16x16x32_bf16 v[78:81], v[160:163], v[198:201], 0
	v_mfma_f32_16x16x32_bf16 v[74:77], v[168:171], v[198:201], 0
	v_mfma_f32_16x16x32_bf16 v[70:73], v[160:163], v[214:217], 0
	v_mfma_f32_16x16x32_bf16 v[66:69], v[168:171], v[214:217], 0
	v_mfma_f32_16x16x32_bf16 v[110:113], v[164:167], v[180:183], v[110:113]
	v_mfma_f32_16x16x32_bf16 v[106:109], v[172:175], v[180:183], v[106:109]
	v_mfma_f32_16x16x32_bf16 v[94:97], v[164:167], v[188:191], v[94:97]
	v_mfma_f32_16x16x32_bf16 v[90:93], v[172:175], v[188:191], v[90:93]
	v_mfma_f32_16x16x32_bf16 v[78:81], v[164:167], v[210:213], v[78:81]
	v_mfma_f32_16x16x32_bf16 v[74:77], v[172:175], v[210:213], v[74:77]
	v_mfma_f32_16x16x32_bf16 v[70:73], v[164:167], v[218:221], v[70:73]
	s_barrier
	v_mfma_f32_16x16x32_bf16 v[66:69], v[172:175], v[218:221], v[66:69]
	s_setprio 0
	s_add_i32 s60, s48, s41
	v_lshl_add_u64 v[192:193], s[36:37], 0, v[132:133]
	s_mov_b32 m0, s60
	ds_read_b128 v[176:179], v142 offset:16384
	ds_read_b128 v[180:183], v142 offset:17408
	ds_read_b128 v[184:187], v142 offset:18432
	ds_read_b128 v[188:191], v142 offset:19456
	ds_read_b128 v[198:201], v142 offset:20480
	ds_read_b128 v[210:213], v142 offset:21504
	ds_read_b128 v[214:217], v142 offset:22528
	ds_read_b128 v[218:221], v142 offset:23552
	global_load_lds_dwordx4 v[192:193], off
	s_add_i32 m0, s60, 0x2000
	s_add_u32 s60, s36, 0x20000
	v_lshl_add_u64 v[202:203], s[36:37], 0, v[134:135]
	s_addc_u32 s61, s37, 0
	s_add_i32 s62, s49, s41
	global_load_lds_dwordx4 v[202:203], off
	v_lshl_add_u64 v[206:207], s[60:61], 0, v[132:133]
	s_mov_b32 m0, s62
	v_lshl_add_u64 v[222:223], s[38:39], 0, v[136:137]
	global_load_lds_dwordx4 v[206:207], off
	v_lshl_add_u64 v[206:207], s[60:61], 0, v[134:135]
	s_add_i32 m0, s62, 0x2000
	s_nop 0
	global_load_lds_dwordx4 v[206:207], off
	v_lshl_add_u64 v[206:207], s[38:39], 0, v[130:131]
	s_mov_b32 m0, s27
	s_nop 0
	global_load_lds_dwordx4 v[206:207], off
	s_mov_b32 m0, s42
	s_nop 0
	global_load_lds_dwordx4 v[222:223], off
	s_waitcnt vmcnt(8)
	s_waitcnt lgkmcnt(0)
	s_barrier
	s_setprio 1
	s_waitcnt lgkmcnt(0)
	v_mfma_f32_16x16x32_bf16 v[62:65], v[144:147], v[176:179], 0
	v_mfma_f32_16x16x32_bf16 v[58:61], v[152:155], v[176:179], 0
	v_mfma_f32_16x16x32_bf16 v[54:57], v[144:147], v[184:187], 0
	v_mfma_f32_16x16x32_bf16 v[50:53], v[152:155], v[184:187], 0
	v_mfma_f32_16x16x32_bf16 v[38:41], v[144:147], v[198:201], 0
	v_mfma_f32_16x16x32_bf16 v[34:37], v[152:155], v[198:201], 0
	v_mfma_f32_16x16x32_bf16 v[22:25], v[144:147], v[214:217], 0
	v_mfma_f32_16x16x32_bf16 v[18:21], v[152:155], v[214:217], 0
	v_mfma_f32_16x16x32_bf16 v[62:65], v[148:151], v[180:183], v[62:65]
	v_mfma_f32_16x16x32_bf16 v[58:61], v[156:159], v[180:183], v[58:61]
	v_mfma_f32_16x16x32_bf16 v[54:57], v[148:151], v[188:191], v[54:57]
	v_mfma_f32_16x16x32_bf16 v[50:53], v[156:159], v[188:191], v[50:53]
	v_mfma_f32_16x16x32_bf16 v[38:41], v[148:151], v[210:213], v[38:41]
	v_mfma_f32_16x16x32_bf16 v[34:37], v[156:159], v[210:213], v[34:37]
	v_mfma_f32_16x16x32_bf16 v[22:25], v[148:151], v[218:221], v[22:25]
	v_mfma_f32_16x16x32_bf16 v[18:21], v[156:159], v[218:221], v[18:21]
	s_setprio 0
	s_setprio 1
	v_mfma_f32_16x16x32_bf16 v[46:49], v[160:163], v[176:179], 0
	v_mfma_f32_16x16x32_bf16 v[42:45], v[168:171], v[176:179], 0
	v_mfma_f32_16x16x32_bf16 v[30:33], v[160:163], v[184:187], 0
	v_mfma_f32_16x16x32_bf16 v[26:29], v[168:171], v[184:187], 0
	v_mfma_f32_16x16x32_bf16 v[14:17], v[160:163], v[198:201], 0
	v_mfma_f32_16x16x32_bf16 v[10:13], v[168:171], v[198:201], 0
	v_mfma_f32_16x16x32_bf16 v[6:9], v[160:163], v[214:217], 0
	v_mfma_f32_16x16x32_bf16 v[2:5], v[168:171], v[214:217], 0
	v_mfma_f32_16x16x32_bf16 v[46:49], v[164:167], v[180:183], v[46:49]
	v_mfma_f32_16x16x32_bf16 v[42:45], v[172:175], v[180:183], v[42:45]
	v_mfma_f32_16x16x32_bf16 v[30:33], v[164:167], v[188:191], v[30:33]
	v_mfma_f32_16x16x32_bf16 v[26:29], v[172:175], v[188:191], v[26:29]
	v_mfma_f32_16x16x32_bf16 v[14:17], v[164:167], v[210:213], v[14:17]
	v_mfma_f32_16x16x32_bf16 v[10:13], v[172:175], v[210:213], v[10:13]
	v_mfma_f32_16x16x32_bf16 v[6:9], v[164:167], v[218:221], v[6:9]
	s_barrier
	v_mfma_f32_16x16x32_bf16 v[2:5], v[172:175], v[218:221], v[2:5]
	s_setprio 0
	s_add_i32 s60, 0, 0x18000
	v_add_u32_e32 v143, s60, v139
	s_add_i32 s61, 0, 0x1c000
	ds_read_b128 v[144:147], v143
	ds_read_b128 v[148:151], v143 offset:1024
	ds_read_b128 v[152:155], v143 offset:2048
	ds_read_b128 v[156:159], v143 offset:3072
	v_add_u32_e32 v143, s61, v139
	ds_read_b128 v[160:163], v143
	ds_read_b128 v[164:167], v143 offset:1024
	ds_read_b128 v[168:171], v143 offset:2048
	ds_read_b128 v[172:175], v143 offset:3072
	s_add_u32 s38, s38, 0x20000
	s_addc_u32 s39, s39, 0
	s_mov_b32 m0, s43
	v_lshl_add_u64 v[224:225], s[38:39], 0, v[130:131]
	ds_read_b128 v[176:179], v142 offset:32768
	ds_read_b128 v[180:183], v142 offset:33792
	ds_read_b128 v[184:187], v142 offset:34816
	ds_read_b128 v[188:191], v142 offset:35840
	ds_read_b128 v[198:201], v142 offset:36864
	ds_read_b128 v[210:213], v142 offset:37888
	ds_read_b128 v[214:217], v142 offset:38912
	ds_read_b128 v[218:221], v142 offset:39936
	global_load_lds_dwordx4 v[224:225], off
	v_lshl_add_u64 v[224:225], s[38:39], 0, v[136:137]
	s_mov_b32 m0, s44
	s_nop 0
	global_load_lds_dwordx4 v[224:225], off
	s_waitcnt vmcnt(8)
	s_waitcnt lgkmcnt(0)
	s_barrier
	s_setprio 1
	s_waitcnt lgkmcnt(0)
	v_mfma_f32_16x16x32_bf16 v[126:129], v[144:147], v[176:179], v[126:129]
	v_mfma_f32_16x16x32_bf16 v[122:125], v[152:155], v[176:179], v[122:125]
	v_mfma_f32_16x16x32_bf16 v[118:121], v[144:147], v[184:187], v[118:121]
	v_mfma_f32_16x16x32_bf16 v[114:117], v[152:155], v[184:187], v[114:117]
	v_mfma_f32_16x16x32_bf16 v[102:105], v[144:147], v[198:201], v[102:105]
	v_mfma_f32_16x16x32_bf16 v[98:101], v[152:155], v[198:201], v[98:101]
	v_mfma_f32_16x16x32_bf16 v[86:89], v[144:147], v[214:217], v[86:89]
	v_mfma_f32_16x16x32_bf16 v[82:85], v[152:155], v[214:217], v[82:85]
	v_mfma_f32_16x16x32_bf16 v[126:129], v[148:151], v[180:183], v[126:129]
	v_mfma_f32_16x16x32_bf16 v[122:125], v[156:159], v[180:183], v[122:125]
	v_mfma_f32_16x16x32_bf16 v[118:121], v[148:151], v[188:191], v[118:121]
	v_mfma_f32_16x16x32_bf16 v[114:117], v[156:159], v[188:191], v[114:117]
	v_mfma_f32_16x16x32_bf16 v[102:105], v[148:151], v[210:213], v[102:105]
	v_mfma_f32_16x16x32_bf16 v[98:101], v[156:159], v[210:213], v[98:101]
	v_mfma_f32_16x16x32_bf16 v[86:89], v[148:151], v[218:221], v[86:89]
	v_mfma_f32_16x16x32_bf16 v[82:85], v[156:159], v[218:221], v[82:85]
	s_setprio 0
	s_setprio 1
	v_mfma_f32_16x16x32_bf16 v[110:113], v[160:163], v[176:179], v[110:113]
	v_mfma_f32_16x16x32_bf16 v[106:109], v[168:171], v[176:179], v[106:109]
	v_mfma_f32_16x16x32_bf16 v[94:97], v[160:163], v[184:187], v[94:97]
	v_mfma_f32_16x16x32_bf16 v[90:93], v[168:171], v[184:187], v[90:93]
	v_mfma_f32_16x16x32_bf16 v[78:81], v[160:163], v[198:201], v[78:81]
	v_mfma_f32_16x16x32_bf16 v[74:77], v[168:171], v[198:201], v[74:77]
	v_mfma_f32_16x16x32_bf16 v[70:73], v[160:163], v[214:217], v[70:73]
	v_mfma_f32_16x16x32_bf16 v[66:69], v[168:171], v[214:217], v[66:69]
	v_mfma_f32_16x16x32_bf16 v[110:113], v[164:167], v[180:183], v[110:113]
	v_mfma_f32_16x16x32_bf16 v[106:109], v[172:175], v[180:183], v[106:109]
	v_mfma_f32_16x16x32_bf16 v[94:97], v[164:167], v[188:191], v[94:97]
	v_mfma_f32_16x16x32_bf16 v[90:93], v[172:175], v[188:191], v[90:93]
	v_mfma_f32_16x16x32_bf16 v[78:81], v[164:167], v[210:213], v[78:81]
	v_mfma_f32_16x16x32_bf16 v[74:77], v[172:175], v[210:213], v[74:77]
	v_mfma_f32_16x16x32_bf16 v[70:73], v[164:167], v[218:221], v[70:73]
	s_barrier
	v_mfma_f32_16x16x32_bf16 v[66:69], v[172:175], v[218:221], v[66:69]
	s_setprio 0
	s_add_i32 s38, s60, s41
	v_lshl_add_u64 v[192:193], v[192:193], 0, s[6:7]
	s_mov_b32 m0, s38
	ds_read_b128 v[176:179], v142 offset:49152
	ds_read_b128 v[180:183], v142 offset:50176
	ds_read_b128 v[184:187], v142 offset:51200
	ds_read_b128 v[188:191], v142 offset:52224
	ds_read_b128 v[198:201], v142 offset:53248
	ds_read_b128 v[210:213], v142 offset:54272
	ds_read_b128 v[214:217], v142 offset:55296
	ds_read_b128 v[218:221], v142 offset:56320
	global_load_lds_dwordx4 v[192:193], off
	s_add_i32 m0, s38, 0x2000
	s_add_u32 s36, s36, 0x20080
	v_lshl_add_u64 v[192:193], v[202:203], 0, s[6:7]
	s_addc_u32 s37, s37, 0
	s_add_i32 s38, s61, s41
	global_load_lds_dwordx4 v[192:193], off
	v_lshl_add_u64 v[192:193], s[36:37], 0, v[132:133]
	s_mov_b32 m0, s38
	s_nop 0
	global_load_lds_dwordx4 v[192:193], off
	v_lshl_add_u64 v[192:193], s[36:37], 0, v[134:135]
	s_add_i32 m0, s38, 0x2000
	s_nop 0
	global_load_lds_dwordx4 v[192:193], off
	v_lshl_add_u64 v[192:193], v[206:207], 0, s[6:7]
	s_mov_b32 m0, s46
	s_nop 0
	global_load_lds_dwordx4 v[192:193], off
	v_lshl_add_u64 v[192:193], v[222:223], 0, s[6:7]
	s_mov_b32 m0, s47
	s_nop 0
	global_load_lds_dwordx4 v[192:193], off
	s_waitcnt vmcnt(8)
	s_waitcnt lgkmcnt(0)
	s_barrier
	s_setprio 1
	s_waitcnt lgkmcnt(0)
	v_mfma_f32_16x16x32_bf16 v[62:65], v[144:147], v[176:179], v[62:65]
	v_mfma_f32_16x16x32_bf16 v[58:61], v[152:155], v[176:179], v[58:61]
	v_mfma_f32_16x16x32_bf16 v[54:57], v[144:147], v[184:187], v[54:57]
	v_mfma_f32_16x16x32_bf16 v[50:53], v[152:155], v[184:187], v[50:53]
	v_mfma_f32_16x16x32_bf16 v[38:41], v[144:147], v[198:201], v[38:41]
	v_mfma_f32_16x16x32_bf16 v[34:37], v[152:155], v[198:201], v[34:37]
	v_mfma_f32_16x16x32_bf16 v[22:25], v[144:147], v[214:217], v[22:25]
	v_mfma_f32_16x16x32_bf16 v[18:21], v[152:155], v[214:217], v[18:21]
	v_mfma_f32_16x16x32_bf16 v[62:65], v[148:151], v[180:183], v[62:65]
	v_mfma_f32_16x16x32_bf16 v[58:61], v[156:159], v[180:183], v[58:61]
	v_mfma_f32_16x16x32_bf16 v[54:57], v[148:151], v[188:191], v[54:57]
	v_mfma_f32_16x16x32_bf16 v[50:53], v[156:159], v[188:191], v[50:53]
	v_mfma_f32_16x16x32_bf16 v[38:41], v[148:151], v[210:213], v[38:41]
	v_mfma_f32_16x16x32_bf16 v[34:37], v[156:159], v[210:213], v[34:37]
	v_mfma_f32_16x16x32_bf16 v[22:25], v[148:151], v[218:221], v[22:25]
	v_mfma_f32_16x16x32_bf16 v[18:21], v[156:159], v[218:221], v[18:21]
	s_setprio 0
	s_setprio 1
	v_mfma_f32_16x16x32_bf16 v[46:49], v[160:163], v[176:179], v[46:49]
	v_mfma_f32_16x16x32_bf16 v[42:45], v[168:171], v[176:179], v[42:45]
	v_mfma_f32_16x16x32_bf16 v[30:33], v[160:163], v[184:187], v[30:33]
	v_mfma_f32_16x16x32_bf16 v[26:29], v[168:171], v[184:187], v[26:29]
	v_mfma_f32_16x16x32_bf16 v[14:17], v[160:163], v[198:201], v[14:17]
	v_mfma_f32_16x16x32_bf16 v[10:13], v[168:171], v[198:201], v[10:13]
	v_mfma_f32_16x16x32_bf16 v[6:9], v[160:163], v[214:217], v[6:9]
	v_mfma_f32_16x16x32_bf16 v[2:5], v[168:171], v[214:217], v[2:5]
	v_mfma_f32_16x16x32_bf16 v[46:49], v[164:167], v[180:183], v[46:49]
	v_mfma_f32_16x16x32_bf16 v[42:45], v[172:175], v[180:183], v[42:45]
	v_mfma_f32_16x16x32_bf16 v[30:33], v[164:167], v[188:191], v[30:33]
	v_mfma_f32_16x16x32_bf16 v[26:29], v[172:175], v[188:191], v[26:29]
	v_mfma_f32_16x16x32_bf16 v[14:17], v[164:167], v[210:213], v[14:17]
	v_mfma_f32_16x16x32_bf16 v[10:13], v[172:175], v[210:213], v[10:13]
	v_mfma_f32_16x16x32_bf16 v[6:9], v[164:167], v[218:221], v[6:9]
	s_barrier
	v_mfma_f32_16x16x32_bf16 v[2:5], v[172:175], v[218:221], v[2:5]
	s_setprio 0
	s_add_i32 s59, s59, 2
	s_add_u32 s34, s34, 0x100
	s_addc_u32 s35, s35, 0
	s_add_u32 s57, s57, 0x100
	s_addc_u32 s58, s58, 0
	s_cmp_gt_u32 s59, 5
	s_cbranch_scc0 .LBB0_714
	s_branch .Lpeeldone_9
.LBB0_714:
	ds_read_b128 v[144:147], v140
	ds_read_b128 v[148:151], v140 offset:1024
	ds_read_b128 v[152:155], v140 offset:2048
	ds_read_b128 v[156:159], v140 offset:3072
	ds_read_b128 v[160:163], v141
	ds_read_b128 v[164:167], v141 offset:1024
	ds_read_b128 v[168:171], v141 offset:2048
	ds_read_b128 v[172:175], v141 offset:3072
	s_add_u32 s36, s34, 0xfffe0080
	s_addc_u32 s37, s35, -1
	s_cmp_eq_u32 s59, 4
	s_cselect_b32 s39, s21, s37
	s_cselect_b32 s38, s55, s36
	s_cselect_b32 s37, s25, s58
	s_cselect_b32 s36, s56, s57
	v_lshl_add_u64 v[192:193], s[34:35], 0, v[130:131]
	s_add_i32 m0, s27, 0xc000
	ds_read_b128 v[176:179], v142
	ds_read_b128 v[180:183], v142 offset:1024
	ds_read_b128 v[184:187], v142 offset:2048
	ds_read_b128 v[188:191], v142 offset:3072
	ds_read_b128 v[198:201], v142 offset:4096
	ds_read_b128 v[210:213], v142 offset:5120
	ds_read_b128 v[214:217], v142 offset:6144
	ds_read_b128 v[218:221], v142 offset:7168
	global_load_lds_dwordx4 v[192:193], off
	v_lshl_add_u64 v[192:193], s[34:35], 0, v[136:137]
	s_add_i32 m0, s27, 0xe000
	s_nop 0
	global_load_lds_dwordx4 v[192:193], off
	s_waitcnt vmcnt(8)
	s_waitcnt lgkmcnt(0)
	s_barrier
	s_setprio 1
	s_waitcnt lgkmcnt(0)
	v_mfma_f32_16x16x32_bf16 v[126:129], v[144:147], v[176:179], v[126:129]
	v_mfma_f32_16x16x32_bf16 v[122:125], v[152:155], v[176:179], v[122:125]
	v_mfma_f32_16x16x32_bf16 v[118:121], v[144:147], v[184:187], v[118:121]
	v_mfma_f32_16x16x32_bf16 v[114:117], v[152:155], v[184:187], v[114:117]
	v_mfma_f32_16x16x32_bf16 v[102:105], v[144:147], v[198:201], v[102:105]
	v_mfma_f32_16x16x32_bf16 v[98:101], v[152:155], v[198:201], v[98:101]
	v_mfma_f32_16x16x32_bf16 v[86:89], v[144:147], v[214:217], v[86:89]
	v_mfma_f32_16x16x32_bf16 v[82:85], v[152:155], v[214:217], v[82:85]
	v_mfma_f32_16x16x32_bf16 v[126:129], v[148:151], v[180:183], v[126:129]
	v_mfma_f32_16x16x32_bf16 v[122:125], v[156:159], v[180:183], v[122:125]
	v_mfma_f32_16x16x32_bf16 v[118:121], v[148:151], v[188:191], v[118:121]
	v_mfma_f32_16x16x32_bf16 v[114:117], v[156:159], v[188:191], v[114:117]
	v_mfma_f32_16x16x32_bf16 v[102:105], v[148:151], v[210:213], v[102:105]
	v_mfma_f32_16x16x32_bf16 v[98:101], v[156:159], v[210:213], v[98:101]
	v_mfma_f32_16x16x32_bf16 v[86:89], v[148:151], v[218:221], v[86:89]
	v_mfma_f32_16x16x32_bf16 v[82:85], v[156:159], v[218:221], v[82:85]
	s_setprio 0
	s_setprio 1
	v_mfma_f32_16x16x32_bf16 v[110:113], v[160:163], v[176:179], v[110:113]
	v_mfma_f32_16x16x32_bf16 v[106:109], v[168:171], v[176:179], v[106:109]
	v_mfma_f32_16x16x32_bf16 v[94:97], v[160:163], v[184:187], v[94:97]
	v_mfma_f32_16x16x32_bf16 v[90:93], v[168:171], v[184:187], v[90:93]
	v_mfma_f32_16x16x32_bf16 v[78:81], v[160:163], v[198:201], v[78:81]
	v_mfma_f32_16x16x32_bf16 v[74:77], v[168:171], v[198:201], v[74:77]
	v_mfma_f32_16x16x32_bf16 v[70:73], v[160:163], v[214:217], v[70:73]
	v_mfma_f32_16x16x32_bf16 v[66:69], v[168:171], v[214:217], v[66:69]
	v_mfma_f32_16x16x32_bf16 v[110:113], v[164:167], v[180:183], v[110:113]
	v_mfma_f32_16x16x32_bf16 v[106:109], v[172:175], v[180:183], v[106:109]
	v_mfma_f32_16x16x32_bf16 v[94:97], v[164:167], v[188:191], v[94:97]
	v_mfma_f32_16x16x32_bf16 v[90:93], v[172:175], v[188:191], v[90:93]
	v_mfma_f32_16x16x32_bf16 v[78:81], v[164:167], v[210:213], v[78:81]
	v_mfma_f32_16x16x32_bf16 v[74:77], v[172:175], v[210:213], v[74:77]
	v_mfma_f32_16x16x32_bf16 v[70:73], v[164:167], v[218:221], v[70:73]
	s_barrier
	v_mfma_f32_16x16x32_bf16 v[66:69], v[172:175], v[218:221], v[66:69]
	s_setprio 0
	s_add_i32 s60, s48, s41
	v_lshl_add_u64 v[192:193], s[36:37], 0, v[132:133]
	s_mov_b32 m0, s60
	ds_read_b128 v[176:179], v142 offset:16384
	ds_read_b128 v[180:183], v142 offset:17408
	ds_read_b128 v[184:187], v142 offset:18432
	ds_read_b128 v[188:191], v142 offset:19456
	ds_read_b128 v[198:201], v142 offset:20480
	ds_read_b128 v[210:213], v142 offset:21504
	ds_read_b128 v[214:217], v142 offset:22528
	ds_read_b128 v[218:221], v142 offset:23552
	global_load_lds_dwordx4 v[192:193], off
	s_add_i32 m0, s60, 0x2000
	s_add_u32 s60, s36, 0x20000
	v_lshl_add_u64 v[202:203], s[36:37], 0, v[134:135]
	s_addc_u32 s61, s37, 0
	s_add_i32 s62, s49, s41
	global_load_lds_dwordx4 v[202:203], off
	v_lshl_add_u64 v[206:207], s[60:61], 0, v[132:133]
	s_mov_b32 m0, s62
	v_lshl_add_u64 v[222:223], s[38:39], 0, v[136:137]
	global_load_lds_dwordx4 v[206:207], off
	v_lshl_add_u64 v[206:207], s[60:61], 0, v[134:135]
	s_add_i32 m0, s62, 0x2000
	s_nop 0
	global_load_lds_dwordx4 v[206:207], off
	v_lshl_add_u64 v[206:207], s[38:39], 0, v[130:131]
	s_mov_b32 m0, s27
	s_nop 0
	global_load_lds_dwordx4 v[206:207], off
	s_mov_b32 m0, s42
	s_nop 0
	global_load_lds_dwordx4 v[222:223], off
	s_waitcnt vmcnt(8)
	s_waitcnt lgkmcnt(0)
	s_barrier
	s_setprio 1
	s_waitcnt lgkmcnt(0)
	v_mfma_f32_16x16x32_bf16 v[62:65], v[144:147], v[176:179], v[62:65]
	v_mfma_f32_16x16x32_bf16 v[58:61], v[152:155], v[176:179], v[58:61]
	v_mfma_f32_16x16x32_bf16 v[54:57], v[144:147], v[184:187], v[54:57]
	v_mfma_f32_16x16x32_bf16 v[50:53], v[152:155], v[184:187], v[50:53]
	v_mfma_f32_16x16x32_bf16 v[38:41], v[144:147], v[198:201], v[38:41]
	v_mfma_f32_16x16x32_bf16 v[34:37], v[152:155], v[198:201], v[34:37]
	v_mfma_f32_16x16x32_bf16 v[22:25], v[144:147], v[214:217], v[22:25]
	v_mfma_f32_16x16x32_bf16 v[18:21], v[152:155], v[214:217], v[18:21]
	v_mfma_f32_16x16x32_bf16 v[62:65], v[148:151], v[180:183], v[62:65]
	v_mfma_f32_16x16x32_bf16 v[58:61], v[156:159], v[180:183], v[58:61]
	v_mfma_f32_16x16x32_bf16 v[54:57], v[148:151], v[188:191], v[54:57]
	v_mfma_f32_16x16x32_bf16 v[50:53], v[156:159], v[188:191], v[50:53]
	v_mfma_f32_16x16x32_bf16 v[38:41], v[148:151], v[210:213], v[38:41]
	v_mfma_f32_16x16x32_bf16 v[34:37], v[156:159], v[210:213], v[34:37]
	v_mfma_f32_16x16x32_bf16 v[22:25], v[148:151], v[218:221], v[22:25]
	v_mfma_f32_16x16x32_bf16 v[18:21], v[156:159], v[218:221], v[18:21]
	s_setprio 0
	s_setprio 1
	v_mfma_f32_16x16x32_bf16 v[46:49], v[160:163], v[176:179], v[46:49]
	v_mfma_f32_16x16x32_bf16 v[42:45], v[168:171], v[176:179], v[42:45]
	v_mfma_f32_16x16x32_bf16 v[30:33], v[160:163], v[184:187], v[30:33]
	v_mfma_f32_16x16x32_bf16 v[26:29], v[168:171], v[184:187], v[26:29]
	v_mfma_f32_16x16x32_bf16 v[14:17], v[160:163], v[198:201], v[14:17]
	v_mfma_f32_16x16x32_bf16 v[10:13], v[168:171], v[198:201], v[10:13]
	v_mfma_f32_16x16x32_bf16 v[6:9], v[160:163], v[214:217], v[6:9]
	v_mfma_f32_16x16x32_bf16 v[2:5], v[168:171], v[214:217], v[2:5]
	v_mfma_f32_16x16x32_bf16 v[46:49], v[164:167], v[180:183], v[46:49]
	v_mfma_f32_16x16x32_bf16 v[42:45], v[172:175], v[180:183], v[42:45]
	v_mfma_f32_16x16x32_bf16 v[30:33], v[164:167], v[188:191], v[30:33]
	v_mfma_f32_16x16x32_bf16 v[26:29], v[172:175], v[188:191], v[26:29]
	v_mfma_f32_16x16x32_bf16 v[14:17], v[164:167], v[210:213], v[14:17]
	v_mfma_f32_16x16x32_bf16 v[10:13], v[172:175], v[210:213], v[10:13]
	v_mfma_f32_16x16x32_bf16 v[6:9], v[164:167], v[218:221], v[6:9]
	s_barrier
	v_mfma_f32_16x16x32_bf16 v[2:5], v[172:175], v[218:221], v[2:5]
	s_setprio 0
	s_add_i32 s60, 0, 0x18000
	v_add_u32_e32 v143, s60, v139
	s_add_i32 s61, 0, 0x1c000
	ds_read_b128 v[144:147], v143
	ds_read_b128 v[148:151], v143 offset:1024
	ds_read_b128 v[152:155], v143 offset:2048
	ds_read_b128 v[156:159], v143 offset:3072
	v_add_u32_e32 v143, s61, v139
	ds_read_b128 v[160:163], v143
	ds_read_b128 v[164:167], v143 offset:1024
	ds_read_b128 v[168:171], v143 offset:2048
	ds_read_b128 v[172:175], v143 offset:3072
	s_add_u32 s38, s38, 0x20000
	s_addc_u32 s39, s39, 0
	s_mov_b32 m0, s43
	v_lshl_add_u64 v[224:225], s[38:39], 0, v[130:131]
	ds_read_b128 v[176:179], v142 offset:32768
	ds_read_b128 v[180:183], v142 offset:33792
	ds_read_b128 v[184:187], v142 offset:34816
	ds_read_b128 v[188:191], v142 offset:35840
	ds_read_b128 v[198:201], v142 offset:36864
	ds_read_b128 v[210:213], v142 offset:37888
	ds_read_b128 v[214:217], v142 offset:38912
	ds_read_b128 v[218:221], v142 offset:39936
	global_load_lds_dwordx4 v[224:225], off
	v_lshl_add_u64 v[224:225], s[38:39], 0, v[136:137]
	s_mov_b32 m0, s44
	s_nop 0
	global_load_lds_dwordx4 v[224:225], off
	s_waitcnt vmcnt(8)
	s_waitcnt lgkmcnt(0)
	s_barrier
	s_setprio 1
	s_waitcnt lgkmcnt(0)
	v_mfma_f32_16x16x32_bf16 v[126:129], v[144:147], v[176:179], v[126:129]
	v_mfma_f32_16x16x32_bf16 v[122:125], v[152:155], v[176:179], v[122:125]
	v_mfma_f32_16x16x32_bf16 v[118:121], v[144:147], v[184:187], v[118:121]
	v_mfma_f32_16x16x32_bf16 v[114:117], v[152:155], v[184:187], v[114:117]
	v_mfma_f32_16x16x32_bf16 v[102:105], v[144:147], v[198:201], v[102:105]
	v_mfma_f32_16x16x32_bf16 v[98:101], v[152:155], v[198:201], v[98:101]
	v_mfma_f32_16x16x32_bf16 v[86:89], v[144:147], v[214:217], v[86:89]
	v_mfma_f32_16x16x32_bf16 v[82:85], v[152:155], v[214:217], v[82:85]
	v_mfma_f32_16x16x32_bf16 v[126:129], v[148:151], v[180:183], v[126:129]
	v_mfma_f32_16x16x32_bf16 v[122:125], v[156:159], v[180:183], v[122:125]
	v_mfma_f32_16x16x32_bf16 v[118:121], v[148:151], v[188:191], v[118:121]
	v_mfma_f32_16x16x32_bf16 v[114:117], v[156:159], v[188:191], v[114:117]
	v_mfma_f32_16x16x32_bf16 v[102:105], v[148:151], v[210:213], v[102:105]
	v_mfma_f32_16x16x32_bf16 v[98:101], v[156:159], v[210:213], v[98:101]
	v_mfma_f32_16x16x32_bf16 v[86:89], v[148:151], v[218:221], v[86:89]
	v_mfma_f32_16x16x32_bf16 v[82:85], v[156:159], v[218:221], v[82:85]
	s_setprio 0
	s_setprio 1
	v_mfma_f32_16x16x32_bf16 v[110:113], v[160:163], v[176:179], v[110:113]
	v_mfma_f32_16x16x32_bf16 v[106:109], v[168:171], v[176:179], v[106:109]
	v_mfma_f32_16x16x32_bf16 v[94:97], v[160:163], v[184:187], v[94:97]
	v_mfma_f32_16x16x32_bf16 v[90:93], v[168:171], v[184:187], v[90:93]
	v_mfma_f32_16x16x32_bf16 v[78:81], v[160:163], v[198:201], v[78:81]
	v_mfma_f32_16x16x32_bf16 v[74:77], v[168:171], v[198:201], v[74:77]
	v_mfma_f32_16x16x32_bf16 v[70:73], v[160:163], v[214:217], v[70:73]
	v_mfma_f32_16x16x32_bf16 v[66:69], v[168:171], v[214:217], v[66:69]
	v_mfma_f32_16x16x32_bf16 v[110:113], v[164:167], v[180:183], v[110:113]
	v_mfma_f32_16x16x32_bf16 v[106:109], v[172:175], v[180:183], v[106:109]
	v_mfma_f32_16x16x32_bf16 v[94:97], v[164:167], v[188:191], v[94:97]
	v_mfma_f32_16x16x32_bf16 v[90:93], v[172:175], v[188:191], v[90:93]
	v_mfma_f32_16x16x32_bf16 v[78:81], v[164:167], v[210:213], v[78:81]
	v_mfma_f32_16x16x32_bf16 v[74:77], v[172:175], v[210:213], v[74:77]
	v_mfma_f32_16x16x32_bf16 v[70:73], v[164:167], v[218:221], v[70:73]
	s_barrier
	v_mfma_f32_16x16x32_bf16 v[66:69], v[172:175], v[218:221], v[66:69]
	s_setprio 0
	s_add_i32 s38, s60, s41
	v_lshl_add_u64 v[192:193], v[192:193], 0, s[6:7]
	s_mov_b32 m0, s38
	ds_read_b128 v[176:179], v142 offset:49152
	ds_read_b128 v[180:183], v142 offset:50176
	ds_read_b128 v[184:187], v142 offset:51200
	ds_read_b128 v[188:191], v142 offset:52224
	ds_read_b128 v[198:201], v142 offset:53248
	ds_read_b128 v[210:213], v142 offset:54272
	ds_read_b128 v[214:217], v142 offset:55296
	ds_read_b128 v[218:221], v142 offset:56320
	global_load_lds_dwordx4 v[192:193], off
	s_add_i32 m0, s38, 0x2000
	s_add_u32 s36, s36, 0x20080
	v_lshl_add_u64 v[192:193], v[202:203], 0, s[6:7]
	s_addc_u32 s37, s37, 0
	s_add_i32 s38, s61, s41
	global_load_lds_dwordx4 v[192:193], off
	v_lshl_add_u64 v[192:193], s[36:37], 0, v[132:133]
	s_mov_b32 m0, s38
	s_nop 0
	global_load_lds_dwordx4 v[192:193], off
	v_lshl_add_u64 v[192:193], s[36:37], 0, v[134:135]
	s_add_i32 m0, s38, 0x2000
	s_nop 0
	global_load_lds_dwordx4 v[192:193], off
	v_lshl_add_u64 v[192:193], v[206:207], 0, s[6:7]
	s_mov_b32 m0, s46
	s_nop 0
	global_load_lds_dwordx4 v[192:193], off
	v_lshl_add_u64 v[192:193], v[222:223], 0, s[6:7]
	s_mov_b32 m0, s47
	s_nop 0
	global_load_lds_dwordx4 v[192:193], off
	s_waitcnt vmcnt(8)
	s_waitcnt lgkmcnt(0)
	s_barrier
	s_setprio 1
	s_waitcnt lgkmcnt(0)
	v_mfma_f32_16x16x32_bf16 v[62:65], v[144:147], v[176:179], v[62:65]
	v_mfma_f32_16x16x32_bf16 v[58:61], v[152:155], v[176:179], v[58:61]
	v_mfma_f32_16x16x32_bf16 v[54:57], v[144:147], v[184:187], v[54:57]
	v_mfma_f32_16x16x32_bf16 v[50:53], v[152:155], v[184:187], v[50:53]
	v_mfma_f32_16x16x32_bf16 v[38:41], v[144:147], v[198:201], v[38:41]
	v_mfma_f32_16x16x32_bf16 v[34:37], v[152:155], v[198:201], v[34:37]
	v_mfma_f32_16x16x32_bf16 v[22:25], v[144:147], v[214:217], v[22:25]
	v_mfma_f32_16x16x32_bf16 v[18:21], v[152:155], v[214:217], v[18:21]
	v_mfma_f32_16x16x32_bf16 v[62:65], v[148:151], v[180:183], v[62:65]
	v_mfma_f32_16x16x32_bf16 v[58:61], v[156:159], v[180:183], v[58:61]
	v_mfma_f32_16x16x32_bf16 v[54:57], v[148:151], v[188:191], v[54:57]
	v_mfma_f32_16x16x32_bf16 v[50:53], v[156:159], v[188:191], v[50:53]
	v_mfma_f32_16x16x32_bf16 v[38:41], v[148:151], v[210:213], v[38:41]
	v_mfma_f32_16x16x32_bf16 v[34:37], v[156:159], v[210:213], v[34:37]
	v_mfma_f32_16x16x32_bf16 v[22:25], v[148:151], v[218:221], v[22:25]
	v_mfma_f32_16x16x32_bf16 v[18:21], v[156:159], v[218:221], v[18:21]
	s_setprio 0
	s_setprio 1
	v_mfma_f32_16x16x32_bf16 v[46:49], v[160:163], v[176:179], v[46:49]
	v_mfma_f32_16x16x32_bf16 v[42:45], v[168:171], v[176:179], v[42:45]
	v_mfma_f32_16x16x32_bf16 v[30:33], v[160:163], v[184:187], v[30:33]
	v_mfma_f32_16x16x32_bf16 v[26:29], v[168:171], v[184:187], v[26:29]
	v_mfma_f32_16x16x32_bf16 v[14:17], v[160:163], v[198:201], v[14:17]
	v_mfma_f32_16x16x32_bf16 v[10:13], v[168:171], v[198:201], v[10:13]
	v_mfma_f32_16x16x32_bf16 v[6:9], v[160:163], v[214:217], v[6:9]
	v_mfma_f32_16x16x32_bf16 v[2:5], v[168:171], v[214:217], v[2:5]
	v_mfma_f32_16x16x32_bf16 v[46:49], v[164:167], v[180:183], v[46:49]
	v_mfma_f32_16x16x32_bf16 v[42:45], v[172:175], v[180:183], v[42:45]
	v_mfma_f32_16x16x32_bf16 v[30:33], v[164:167], v[188:191], v[30:33]
	v_mfma_f32_16x16x32_bf16 v[26:29], v[172:175], v[188:191], v[26:29]
	v_mfma_f32_16x16x32_bf16 v[14:17], v[164:167], v[210:213], v[14:17]
	v_mfma_f32_16x16x32_bf16 v[10:13], v[172:175], v[210:213], v[10:13]
	v_mfma_f32_16x16x32_bf16 v[6:9], v[164:167], v[218:221], v[6:9]
	s_barrier
	v_mfma_f32_16x16x32_bf16 v[2:5], v[172:175], v[218:221], v[2:5]
	s_setprio 0
	s_add_i32 s59, s59, 2
	s_add_u32 s34, s34, 0x100
	s_addc_u32 s35, s35, 0
	s_add_u32 s57, s57, 0x100
	s_addc_u32 s58, s58, 0
	s_cmp_gt_u32 s59, 5
	s_cbranch_scc0 .LBB0_714

.Lpeel_8:
	ds_read_b128 v[130:133], v170
	ds_read_b128 v[134:137], v170 offset:1024
	ds_read_b128 v[138:141], v170 offset:2048
	ds_read_b128 v[142:145], v170 offset:3072
	ds_read_b128 v[160:163], v171
	ds_read_b128 v[164:167], v171 offset:1024
	ds_read_b128 v[174:177], v171 offset:2048
	ds_read_b128 v[178:181], v171 offset:3072
	s_add_i32 s31, s21, 2
	s_add_u32 s36, s34, 0xfff80080
	s_addc_u32 s37, s35, -1
	s_cmp_eq_u32 s30, s21
	s_cselect_b32 s39, s23, s37
	s_cselect_b32 s38, s22, s36
	s_cselect_b32 s37, s25, s19
	s_cselect_b32 s36, s24, s17
	v_lshl_add_u64 v[202:203], s[34:35], 0, v[156:157]
	s_add_i32 m0, s27, 0xc000
	ds_read_b128 v[182:185], v172
	ds_read_b128 v[186:189], v172 offset:1024
	ds_read_b128 v[190:193], v172 offset:2048
	ds_read_b128 v[198:201], v172 offset:3072
	ds_read_b128 v[210:213], v172 offset:4096
	ds_read_b128 v[214:217], v172 offset:5120
	global_load_lds_dwordx4 v[202:203], off
	v_lshl_add_u64 v[202:203], s[34:35], 0, v[158:159]
	s_add_i32 m0, s27, 0xe000
	s_nop 0
	global_load_lds_dwordx4 v[202:203], off
	s_waitcnt vmcnt(8)
	s_waitcnt lgkmcnt(0)
	s_barrier
	s_setprio 1
	s_waitcnt lgkmcnt(0)
	v_mfma_f32_16x16x32_bf16 v[126:129], v[130:133], v[182:185], 0
	v_mfma_f32_16x16x32_bf16 v[122:125], v[138:141], v[182:185], 0
	v_mfma_f32_16x16x32_bf16 v[118:121], v[130:133], v[190:193], 0
	v_mfma_f32_16x16x32_bf16 v[110:113], v[138:141], v[190:193], 0
	v_mfma_f32_16x16x32_bf16 v[94:97], v[130:133], v[210:213], 0
	v_mfma_f32_16x16x32_bf16 v[90:93], v[138:141], v[210:213], 0
	v_mfma_f32_16x16x32_bf16 v[78:81], v[130:133], v[218:221], 0
	v_mfma_f32_16x16x32_bf16 v[74:77], v[138:141], v[218:221], 0
	v_mfma_f32_16x16x32_bf16 v[126:129], v[134:137], v[186:189], v[126:129]
	v_mfma_f32_16x16x32_bf16 v[122:125], v[142:145], v[186:189], v[122:125]
	v_mfma_f32_16x16x32_bf16 v[118:121], v[134:137], v[198:201], v[118:121]
	v_mfma_f32_16x16x32_bf16 v[110:113], v[142:145], v[198:201], v[110:113]
	v_mfma_f32_16x16x32_bf16 v[94:97], v[134:137], v[214:217], v[94:97]
	v_mfma_f32_16x16x32_bf16 v[90:93], v[142:145], v[214:217], v[90:93]
	v_mfma_f32_16x16x32_bf16 v[78:81], v[134:137], v[222:225], v[78:81]
	v_mfma_f32_16x16x32_bf16 v[74:77], v[142:145], v[222:225], v[74:77]
	s_setprio 0
	s_setprio 1
	v_mfma_f32_16x16x32_bf16 v[114:117], v[160:163], v[182:185], 0
	v_mfma_f32_16x16x32_bf16 v[106:109], v[174:177], v[182:185], 0
	v_mfma_f32_16x16x32_bf16 v[102:105], v[160:163], v[190:193], 0
	v_mfma_f32_16x16x32_bf16 v[98:101], v[174:177], v[190:193], 0
	v_mfma_f32_16x16x32_bf16 v[86:89], v[160:163], v[210:213], 0
	v_mfma_f32_16x16x32_bf16 v[82:85], v[174:177], v[210:213], 0
	v_mfma_f32_16x16x32_bf16 v[70:73], v[160:163], v[218:221], 0
	v_mfma_f32_16x16x32_bf16 v[66:69], v[174:177], v[218:221], 0
	v_mfma_f32_16x16x32_bf16 v[114:117], v[164:167], v[186:189], v[114:117]
	v_mfma_f32_16x16x32_bf16 v[106:109], v[178:181], v[186:189], v[106:109]
	v_mfma_f32_16x16x32_bf16 v[102:105], v[164:167], v[198:201], v[102:105]
	v_mfma_f32_16x16x32_bf16 v[98:101], v[178:181], v[198:201], v[98:101]
	v_mfma_f32_16x16x32_bf16 v[86:89], v[164:167], v[214:217], v[86:89]
	v_mfma_f32_16x16x32_bf16 v[82:85], v[178:181], v[214:217], v[82:85]
	v_mfma_f32_16x16x32_bf16 v[70:73], v[164:167], v[222:225], v[70:73]
	s_barrier
	v_mfma_f32_16x16x32_bf16 v[66:69], v[178:181], v[222:225], v[66:69]
	s_setprio 0
	s_add_i32 s21, s63, s33
	v_lshl_add_u64 v[202:203], s[36:37], 0, v[148:149]
	s_mov_b32 m0, s21
	ds_read_b128 v[182:185], v172 offset:16384
	ds_read_b128 v[186:189], v172 offset:17408
	ds_read_b128 v[190:193], v172 offset:18432
	ds_read_b128 v[198:201], v172 offset:19456
	ds_read_b128 v[210:213], v172 offset:20480
	ds_read_b128 v[214:217], v172 offset:21504
	ds_read_b128 v[218:221], v172 offset:22528
	ds_read_b128 v[222:225], v172 offset:23552
	global_load_lds_dwordx4 v[202:203], off
	s_add_i32 m0, s21, 0x2000
	s_add_u32 s40, s36, 0x80000
	v_lshl_add_u64 v[206:207], s[36:37], 0, v[152:153]
	s_addc_u32 s41, s37, 0
	s_add_i32 s21, s64, s33
	global_load_lds_dwordx4 v[206:207], off
	v_lshl_add_u64 v[226:227], s[40:41], 0, v[148:149]
	s_mov_b32 m0, s21
	v_lshl_add_u64 v[228:229], s[38:39], 0, v[150:151]
	global_load_lds_dwordx4 v[226:227], off
	v_lshl_add_u64 v[226:227], s[40:41], 0, v[152:153]
	s_add_i32 m0, s21, 0x2000
	s_nop 0
	global_load_lds_dwordx4 v[226:227], off
	v_lshl_add_u64 v[226:227], s[38:39], 0, v[146:147]
	s_mov_b32 m0, s27
	s_nop 0
	global_load_lds_dwordx4 v[226:227], off
	s_mov_b32 m0, s29
	s_nop 0
	global_load_lds_dwordx4 v[228:229], off
	s_waitcnt vmcnt(8)
	s_waitcnt lgkmcnt(0)
	s_barrier
	s_setprio 1
	s_waitcnt lgkmcnt(0)
	v_mfma_f32_16x16x32_bf16 v[62:65], v[130:133], v[182:185], 0
	v_mfma_f32_16x16x32_bf16 v[58:61], v[138:141], v[182:185], 0
	v_mfma_f32_16x16x32_bf16 v[46:49], v[130:133], v[190:193], 0
	v_mfma_f32_16x16x32_bf16 v[42:45], v[138:141], v[190:193], 0
	v_mfma_f32_16x16x32_bf16 v[30:33], v[130:133], v[210:213], 0
	v_mfma_f32_16x16x32_bf16 v[26:29], v[138:141], v[210:213], 0
	v_mfma_f32_16x16x32_bf16 v[14:17], v[130:133], v[218:221], 0
	v_mfma_f32_16x16x32_bf16 v[10:13], v[138:141], v[218:221], 0
	v_mfma_f32_16x16x32_bf16 v[62:65], v[134:137], v[186:189], v[62:65]
	v_mfma_f32_16x16x32_bf16 v[58:61], v[142:145], v[186:189], v[58:61]
	v_mfma_f32_16x16x32_bf16 v[46:49], v[134:137], v[198:201], v[46:49]
	v_mfma_f32_16x16x32_bf16 v[42:45], v[142:145], v[198:201], v[42:45]
	v_mfma_f32_16x16x32_bf16 v[30:33], v[134:137], v[214:217], v[30:33]
	v_mfma_f32_16x16x32_bf16 v[26:29], v[142:145], v[214:217], v[26:29]
	v_mfma_f32_16x16x32_bf16 v[14:17], v[134:137], v[222:225], v[14:17]
	v_mfma_f32_16x16x32_bf16 v[10:13], v[142:145], v[222:225], v[10:13]
	s_setprio 0
	s_setprio 1
	v_mfma_f32_16x16x32_bf16 v[54:57], v[160:163], v[182:185], 0
	v_mfma_f32_16x16x32_bf16 v[50:53], v[174:177], v[182:185], 0
	v_mfma_f32_16x16x32_bf16 v[38:41], v[160:163], v[190:193], 0
	v_mfma_f32_16x16x32_bf16 v[34:37], v[174:177], v[190:193], 0
	v_mfma_f32_16x16x32_bf16 v[22:25], v[160:163], v[210:213], 0
	v_mfma_f32_16x16x32_bf16 v[18:21], v[174:177], v[210:213], 0
	v_mfma_f32_16x16x32_bf16 v[6:9], v[160:163], v[218:221], 0
	v_mfma_f32_16x16x32_bf16 v[2:5], v[174:177], v[218:221], 0
	v_mfma_f32_16x16x32_bf16 v[54:57], v[164:167], v[186:189], v[54:57]
	v_mfma_f32_16x16x32_bf16 v[50:53], v[178:181], v[186:189], v[50:53]
	v_mfma_f32_16x16x32_bf16 v[38:41], v[164:167], v[198:201], v[38:41]
	v_mfma_f32_16x16x32_bf16 v[34:37], v[178:181], v[198:201], v[34:37]
	v_mfma_f32_16x16x32_bf16 v[22:25], v[164:167], v[214:217], v[22:25]
	v_mfma_f32_16x16x32_bf16 v[18:21], v[178:181], v[214:217], v[18:21]
	v_mfma_f32_16x16x32_bf16 v[6:9], v[164:167], v[222:225], v[6:9]
	s_barrier
	v_mfma_f32_16x16x32_bf16 v[2:5], v[178:181], v[222:225], v[2:5]
	s_setprio 0
	s_add_i32 s21, 0, 0x18000
	s_add_i32 s40, 0, 0x1c000
	v_add_u32_e32 v142, s21, v168
	v_add_u32_e32 v173, s40, v168
	ds_read_b128 v[130:133], v142
	ds_read_b128 v[134:137], v142 offset:1024
	ds_read_b128 v[138:141], v142 offset:2048
	ds_read_b128 v[142:145], v142 offset:3072
	ds_read_b128 v[160:163], v173
	ds_read_b128 v[164:167], v173 offset:1024
	ds_read_b128 v[174:177], v173 offset:2048
	ds_read_b128 v[178:181], v173 offset:3072
	s_add_u32 s38, s38, 0x80000
	s_addc_u32 s39, s39, 0
	s_mov_b32 m0, s42
	v_lshl_add_u64 v[230:231], s[38:39], 0, v[146:147]
	ds_read_b128 v[182:185], v172 offset:32768
	ds_read_b128 v[186:189], v172 offset:33792
	ds_read_b128 v[190:193], v172 offset:34816
	ds_read_b128 v[198:201], v172 offset:35840
	ds_read_b128 v[210:213], v172 offset:36864
	ds_read_b128 v[214:217], v172 offset:37888
	ds_read_b128 v[218:221], v172 offset:38912
	ds_read_b128 v[222:225], v172 offset:39936
	global_load_lds_dwordx4 v[230:231], off
	v_lshl_add_u64 v[230:231], s[38:39], 0, v[150:151]
	s_mov_b32 m0, s43
	s_nop 0
	global_load_lds_dwordx4 v[230:231], off
	s_waitcnt vmcnt(8)
	s_waitcnt lgkmcnt(0)
	s_barrier
	s_setprio 1
	s_waitcnt lgkmcnt(0)
	v_mfma_f32_16x16x32_bf16 v[126:129], v[130:133], v[182:185], v[126:129]
	v_mfma_f32_16x16x32_bf16 v[122:125], v[138:141], v[182:185], v[122:125]
	v_mfma_f32_16x16x32_bf16 v[118:121], v[130:133], v[190:193], v[118:121]
	v_mfma_f32_16x16x32_bf16 v[110:113], v[138:141], v[190:193], v[110:113]
	v_mfma_f32_16x16x32_bf16 v[94:97], v[130:133], v[210:213], v[94:97]
	v_mfma_f32_16x16x32_bf16 v[90:93], v[138:141], v[210:213], v[90:93]
	v_mfma_f32_16x16x32_bf16 v[78:81], v[130:133], v[218:221], v[78:81]
	v_mfma_f32_16x16x32_bf16 v[74:77], v[138:141], v[218:221], v[74:77]
	v_mfma_f32_16x16x32_bf16 v[126:129], v[134:137], v[186:189], v[126:129]
	v_mfma_f32_16x16x32_bf16 v[122:125], v[142:145], v[186:189], v[122:125]
	v_mfma_f32_16x16x32_bf16 v[118:121], v[134:137], v[198:201], v[118:121]
	v_mfma_f32_16x16x32_bf16 v[110:113], v[142:145], v[198:201], v[110:113]
	v_mfma_f32_16x16x32_bf16 v[94:97], v[134:137], v[214:217], v[94:97]
	v_mfma_f32_16x16x32_bf16 v[90:93], v[142:145], v[214:217], v[90:93]
	v_mfma_f32_16x16x32_bf16 v[78:81], v[134:137], v[222:225], v[78:81]
	v_mfma_f32_16x16x32_bf16 v[74:77], v[142:145], v[222:225], v[74:77]
	s_setprio 0
	s_setprio 1
	v_mfma_f32_16x16x32_bf16 v[114:117], v[160:163], v[182:185], v[114:117]
	v_mfma_f32_16x16x32_bf16 v[106:109], v[174:177], v[182:185], v[106:109]
	v_mfma_f32_16x16x32_bf16 v[102:105], v[160:163], v[190:193], v[102:105]
	v_mfma_f32_16x16x32_bf16 v[98:101], v[174:177], v[190:193], v[98:101]
	v_mfma_f32_16x16x32_bf16 v[86:89], v[160:163], v[210:213], v[86:89]
	v_mfma_f32_16x16x32_bf16 v[82:85], v[174:177], v[210:213], v[82:85]
	v_mfma_f32_16x16x32_bf16 v[70:73], v[160:163], v[218:221], v[70:73]
	v_mfma_f32_16x16x32_bf16 v[66:69], v[174:177], v[218:221], v[66:69]
	v_mfma_f32_16x16x32_bf16 v[114:117], v[164:167], v[186:189], v[114:117]
	v_mfma_f32_16x16x32_bf16 v[106:109], v[178:181], v[186:189], v[106:109]
	v_mfma_f32_16x16x32_bf16 v[102:105], v[164:167], v[198:201], v[102:105]
	v_mfma_f32_16x16x32_bf16 v[98:101], v[178:181], v[198:201], v[98:101]
	v_mfma_f32_16x16x32_bf16 v[86:89], v[164:167], v[214:217], v[86:89]
	v_mfma_f32_16x16x32_bf16 v[82:85], v[178:181], v[214:217], v[82:85]
	v_mfma_f32_16x16x32_bf16 v[70:73], v[164:167], v[222:225], v[70:73]
	s_barrier
	v_mfma_f32_16x16x32_bf16 v[66:69], v[178:181], v[222:225], v[66:69]
	s_setprio 0
	s_add_i32 s21, s21, s33
	v_lshl_add_u64 v[202:203], v[202:203], 0, s[12:13]
	s_mov_b32 m0, s21
	ds_read_b128 v[182:185], v172 offset:49152
	ds_read_b128 v[186:189], v172 offset:50176
	ds_read_b128 v[190:193], v172 offset:51200
	ds_read_b128 v[198:201], v172 offset:52224
	ds_read_b128 v[210:213], v172 offset:53248
	ds_read_b128 v[214:217], v172 offset:54272
	ds_read_b128 v[218:221], v172 offset:55296
	ds_read_b128 v[222:225], v172 offset:56320
	global_load_lds_dwordx4 v[202:203], off
	s_add_i32 m0, s21, 0x2000
	s_add_u32 s36, s36, 0x80080
	v_lshl_add_u64 v[202:203], v[206:207], 0, s[12:13]
	s_addc_u32 s37, s37, 0
	s_add_i32 s21, s40, s33
	global_load_lds_dwordx4 v[202:203], off
	v_lshl_add_u64 v[202:203], s[36:37], 0, v[148:149]
	s_mov_b32 m0, s21
	s_nop 0
	global_load_lds_dwordx4 v[202:203], off
	v_lshl_add_u64 v[202:203], s[36:37], 0, v[152:153]
	s_add_i32 m0, s21, 0x2000
	s_nop 0
	global_load_lds_dwordx4 v[202:203], off
	v_lshl_add_u64 v[202:203], v[226:227], 0, s[12:13]
	s_mov_b32 m0, s53
	s_nop 0
	global_load_lds_dwordx4 v[202:203], off
	v_lshl_add_u64 v[202:203], v[228:229], 0, s[12:13]
	s_mov_b32 m0, s54
	s_nop 0
	global_load_lds_dwordx4 v[202:203], off
	s_waitcnt vmcnt(8)
	s_waitcnt lgkmcnt(0)
	s_barrier
	s_setprio 1
	s_waitcnt lgkmcnt(0)
	v_mfma_f32_16x16x32_bf16 v[62:65], v[130:133], v[182:185], v[62:65]
	v_mfma_f32_16x16x32_bf16 v[58:61], v[138:141], v[182:185], v[58:61]
	v_mfma_f32_16x16x32_bf16 v[46:49], v[130:133], v[190:193], v[46:49]
	v_mfma_f32_16x16x32_bf16 v[42:45], v[138:141], v[190:193], v[42:45]
	v_mfma_f32_16x16x32_bf16 v[30:33], v[130:133], v[210:213], v[30:33]
	v_mfma_f32_16x16x32_bf16 v[26:29], v[138:141], v[210:213], v[26:29]
	v_mfma_f32_16x16x32_bf16 v[14:17], v[130:133], v[218:221], v[14:17]
	v_mfma_f32_16x16x32_bf16 v[10:13], v[138:141], v[218:221], v[10:13]
	v_mfma_f32_16x16x32_bf16 v[62:65], v[134:137], v[186:189], v[62:65]
	v_mfma_f32_16x16x32_bf16 v[58:61], v[142:145], v[186:189], v[58:61]
	v_mfma_f32_16x16x32_bf16 v[46:49], v[134:137], v[198:201], v[46:49]
	v_mfma_f32_16x16x32_bf16 v[42:45], v[142:145], v[198:201], v[42:45]
	v_mfma_f32_16x16x32_bf16 v[30:33], v[134:137], v[214:217], v[30:33]
	v_mfma_f32_16x16x32_bf16 v[26:29], v[142:145], v[214:217], v[26:29]
	v_mfma_f32_16x16x32_bf16 v[14:17], v[134:137], v[222:225], v[14:17]
	v_mfma_f32_16x16x32_bf16 v[10:13], v[142:145], v[222:225], v[10:13]
	s_setprio 0
	s_setprio 1
	v_mfma_f32_16x16x32_bf16 v[54:57], v[160:163], v[182:185], v[54:57]
	v_mfma_f32_16x16x32_bf16 v[50:53], v[174:177], v[182:185], v[50:53]
	v_mfma_f32_16x16x32_bf16 v[38:41], v[160:163], v[190:193], v[38:41]
	v_mfma_f32_16x16x32_bf16 v[34:37], v[174:177], v[190:193], v[34:37]
	v_mfma_f32_16x16x32_bf16 v[22:25], v[160:163], v[210:213], v[22:25]
	v_mfma_f32_16x16x32_bf16 v[18:21], v[174:177], v[210:213], v[18:21]
	v_mfma_f32_16x16x32_bf16 v[6:9], v[160:163], v[218:221], v[6:9]
	v_mfma_f32_16x16x32_bf16 v[2:5], v[174:177], v[218:221], v[2:5]
	v_mfma_f32_16x16x32_bf16 v[54:57], v[164:167], v[186:189], v[54:57]
	v_mfma_f32_16x16x32_bf16 v[50:53], v[178:181], v[186:189], v[50:53]
	v_mfma_f32_16x16x32_bf16 v[38:41], v[164:167], v[198:201], v[38:41]
	v_mfma_f32_16x16x32_bf16 v[34:37], v[178:181], v[198:201], v[34:37]
	v_mfma_f32_16x16x32_bf16 v[22:25], v[164:167], v[214:217], v[22:25]
	v_mfma_f32_16x16x32_bf16 v[18:21], v[178:181], v[214:217], v[18:21]
	v_mfma_f32_16x16x32_bf16 v[6:9], v[164:167], v[222:225], v[6:9]
	s_barrier
	v_mfma_f32_16x16x32_bf16 v[2:5], v[178:181], v[222:225], v[2:5]
	s_setprio 0
	s_add_u32 s34, s34, 0x100
	s_addc_u32 s35, s35, 0
	s_add_u32 s17, s17, 0x100
	s_addc_u32 s19, s19, 0
	s_cmp_ge_i32 s31, s69
	s_mov_b32 s21, s31
	s_cbranch_scc0 .LBB0_1122
	s_branch .Lpeeldone_8
.LBB0_1122:
	ds_read_b128 v[130:133], v170
	ds_read_b128 v[134:137], v170 offset:1024
	ds_read_b128 v[138:141], v170 offset:2048
	ds_read_b128 v[142:145], v170 offset:3072
	ds_read_b128 v[160:163], v171
	ds_read_b128 v[164:167], v171 offset:1024
	ds_read_b128 v[174:177], v171 offset:2048
	ds_read_b128 v[178:181], v171 offset:3072
	s_add_i32 s31, s21, 2
	s_add_u32 s36, s34, 0xfff80080
	s_addc_u32 s37, s35, -1
	s_cmp_eq_u32 s30, s21
	s_cselect_b32 s39, s23, s37
	s_cselect_b32 s38, s22, s36
	s_cselect_b32 s37, s25, s19
	s_cselect_b32 s36, s24, s17
	v_lshl_add_u64 v[202:203], s[34:35], 0, v[156:157]
	s_add_i32 m0, s27, 0xc000
	ds_read_b128 v[182:185], v172
	ds_read_b128 v[186:189], v172 offset:1024
	ds_read_b128 v[190:193], v172 offset:2048
	ds_read_b128 v[198:201], v172 offset:3072
	ds_read_b128 v[210:213], v172 offset:4096
	ds_read_b128 v[214:217], v172 offset:5120
	ds_read_b128 v[218:221], v172 offset:6144
	ds_read_b128 v[222:225], v172 offset:7168
	global_load_lds_dwordx4 v[202:203], off
	v_lshl_add_u64 v[202:203], s[34:35], 0, v[158:159]
	s_add_i32 m0, s27, 0xe000
	s_nop 0
	global_load_lds_dwordx4 v[202:203], off
	s_waitcnt vmcnt(8)
	s_waitcnt lgkmcnt(0)
	s_barrier
	s_setprio 1
	s_waitcnt lgkmcnt(0)
	v_mfma_f32_16x16x32_bf16 v[126:129], v[130:133], v[182:185], v[126:129]
	v_mfma_f32_16x16x32_bf16 v[122:125], v[138:141], v[182:185], v[122:125]
	v_mfma_f32_16x16x32_bf16 v[118:121], v[130:133], v[190:193], v[118:121]
	v_mfma_f32_16x16x32_bf16 v[110:113], v[138:141], v[190:193], v[110:113]
	v_mfma_f32_16x16x32_bf16 v[94:97], v[130:133], v[210:213], v[94:97]
	v_mfma_f32_16x16x32_bf16 v[90:93], v[138:141], v[210:213], v[90:93]
	v_mfma_f32_16x16x32_bf16 v[78:81], v[130:133], v[218:221], v[78:81]
	v_mfma_f32_16x16x32_bf16 v[74:77], v[138:141], v[218:221], v[74:77]
	v_mfma_f32_16x16x32_bf16 v[126:129], v[134:137], v[186:189], v[126:129]
	v_mfma_f32_16x16x32_bf16 v[122:125], v[142:145], v[186:189], v[122:125]
	v_mfma_f32_16x16x32_bf16 v[118:121], v[134:137], v[198:201], v[118:121]
	v_mfma_f32_16x16x32_bf16 v[110:113], v[142:145], v[198:201], v[110:113]
	v_mfma_f32_16x16x32_bf16 v[94:97], v[134:137], v[214:217], v[94:97]
	v_mfma_f32_16x16x32_bf16 v[90:93], v[142:145], v[214:217], v[90:93]
	v_mfma_f32_16x16x32_bf16 v[78:81], v[134:137], v[222:225], v[78:81]
	v_mfma_f32_16x16x32_bf16 v[74:77], v[142:145], v[222:225], v[74:77]
	s_setprio 0
	s_setprio 1
	v_mfma_f32_16x16x32_bf16 v[114:117], v[160:163], v[182:185], v[114:117]
	v_mfma_f32_16x16x32_bf16 v[106:109], v[174:177], v[182:185], v[106:109]
	v_mfma_f32_16x16x32_bf16 v[102:105], v[160:163], v[190:193], v[102:105]
	v_mfma_f32_16x16x32_bf16 v[98:101], v[174:177], v[190:193], v[98:101]
	v_mfma_f32_16x16x32_bf16 v[86:89], v[160:163], v[210:213], v[86:89]
	v_mfma_f32_16x16x32_bf16 v[82:85], v[174:177], v[210:213], v[82:85]
	v_mfma_f32_16x16x32_bf16 v[70:73], v[160:163], v[218:221], v[70:73]
	v_mfma_f32_16x16x32_bf16 v[66:69], v[174:177], v[218:221], v[66:69]
	v_mfma_f32_16x16x32_bf16 v[114:117], v[164:167], v[186:189], v[114:117]
	v_mfma_f32_16x16x32_bf16 v[106:109], v[178:181], v[186:189], v[106:109]
	v_mfma_f32_16x16x32_bf16 v[102:105], v[164:167], v[198:201], v[102:105]
	v_mfma_f32_16x16x32_bf16 v[98:101], v[178:181], v[198:201], v[98:101]
	v_mfma_f32_16x16x32_bf16 v[86:89], v[164:167], v[214:217], v[86:89]
	v_mfma_f32_16x16x32_bf16 v[82:85], v[178:181], v[214:217], v[82:85]
	v_mfma_f32_16x16x32_bf16 v[70:73], v[164:167], v[222:225], v[70:73]
	s_barrier
	v_mfma_f32_16x16x32_bf16 v[66:69], v[178:181], v[222:225], v[66:69]
	s_setprio 0
	s_add_i32 s21, s63, s33
	v_lshl_add_u64 v[202:203], s[36:37], 0, v[148:149]
	s_mov_b32 m0, s21
	ds_read_b128 v[182:185], v172 offset:16384
	ds_read_b128 v[186:189], v172 offset:17408
	ds_read_b128 v[190:193], v172 offset:18432
	ds_read_b128 v[198:201], v172 offset:19456
	ds_read_b128 v[210:213], v172 offset:20480
	ds_read_b128 v[214:217], v172 offset:21504
	ds_read_b128 v[218:221], v172 offset:22528
	ds_read_b128 v[222:225], v172 offset:23552
	global_load_lds_dwordx4 v[202:203], off
	s_add_i32 m0, s21, 0x2000
	s_add_u32 s40, s36, 0x80000
	v_lshl_add_u64 v[206:207], s[36:37], 0, v[152:153]
	s_addc_u32 s41, s37, 0
	s_add_i32 s21, s64, s33
	global_load_lds_dwordx4 v[206:207], off
	v_lshl_add_u64 v[226:227], s[40:41], 0, v[148:149]
	s_mov_b32 m0, s21
	v_lshl_add_u64 v[228:229], s[38:39], 0, v[150:151]
	global_load_lds_dwordx4 v[226:227], off
	v_lshl_add_u64 v[226:227], s[40:41], 0, v[152:153]
	s_add_i32 m0, s21, 0x2000
	s_nop 0
	global_load_lds_dwordx4 v[226:227], off
	v_lshl_add_u64 v[226:227], s[38:39], 0, v[146:147]
	s_mov_b32 m0, s27
	s_nop 0
	global_load_lds_dwordx4 v[226:227], off
	s_mov_b32 m0, s29
	s_nop 0
	global_load_lds_dwordx4 v[228:229], off
	s_waitcnt vmcnt(8)
	s_waitcnt lgkmcnt(0)
	s_barrier
	s_setprio 1
	s_waitcnt lgkmcnt(0)
	v_mfma_f32_16x16x32_bf16 v[62:65], v[130:133], v[182:185], v[62:65]
	v_mfma_f32_16x16x32_bf16 v[58:61], v[138:141], v[182:185], v[58:61]
	v_mfma_f32_16x16x32_bf16 v[46:49], v[130:133], v[190:193], v[46:49]
	v_mfma_f32_16x16x32_bf16 v[42:45], v[138:141], v[190:193], v[42:45]
	v_mfma_f32_16x16x32_bf16 v[30:33], v[130:133], v[210:213], v[30:33]
	v_mfma_f32_16x16x32_bf16 v[26:29], v[138:141], v[210:213], v[26:29]
	v_mfma_f32_16x16x32_bf16 v[14:17], v[130:133], v[218:221], v[14:17]
	v_mfma_f32_16x16x32_bf16 v[10:13], v[138:141], v[218:221], v[10:13]
	v_mfma_f32_16x16x32_bf16 v[62:65], v[134:137], v[186:189], v[62:65]
	v_mfma_f32_16x16x32_bf16 v[58:61], v[142:145], v[186:189], v[58:61]
	v_mfma_f32_16x16x32_bf16 v[46:49], v[134:137], v[198:201], v[46:49]
	v_mfma_f32_16x16x32_bf16 v[42:45], v[142:145], v[198:201], v[42:45]
	v_mfma_f32_16x16x32_bf16 v[30:33], v[134:137], v[214:217], v[30:33]
	v_mfma_f32_16x16x32_bf16 v[26:29], v[142:145], v[214:217], v[26:29]
	v_mfma_f32_16x16x32_bf16 v[14:17], v[134:137], v[222:225], v[14:17]
	v_mfma_f32_16x16x32_bf16 v[10:13], v[142:145], v[222:225], v[10:13]
	s_setprio 0
	s_setprio 1
	v_mfma_f32_16x16x32_bf16 v[54:57], v[160:163], v[182:185], v[54:57]
	v_mfma_f32_16x16x32_bf16 v[50:53], v[174:177], v[182:185], v[50:53]
	v_mfma_f32_16x16x32_bf16 v[38:41], v[160:163], v[190:193], v[38:41]
	v_mfma_f32_16x16x32_bf16 v[34:37], v[174:177], v[190:193], v[34:37]
	v_mfma_f32_16x16x32_bf16 v[22:25], v[160:163], v[210:213], v[22:25]
	v_mfma_f32_16x16x32_bf16 v[18:21], v[174:177], v[210:213], v[18:21]
	v_mfma_f32_16x16x32_bf16 v[6:9], v[160:163], v[218:221], v[6:9]
	v_mfma_f32_16x16x32_bf16 v[2:5], v[174:177], v[218:221], v[2:5]
	v_mfma_f32_16x16x32_bf16 v[54:57], v[164:167], v[186:189], v[54:57]
	v_mfma_f32_16x16x32_bf16 v[50:53], v[178:181], v[186:189], v[50:53]
	v_mfma_f32_16x16x32_bf16 v[38:41], v[164:167], v[198:201], v[38:41]
	v_mfma_f32_16x16x32_bf16 v[34:37], v[178:181], v[198:201], v[34:37]
	v_mfma_f32_16x16x32_bf16 v[22:25], v[164:167], v[214:217], v[22:25]
	v_mfma_f32_16x16x32_bf16 v[18:21], v[178:181], v[214:217], v[18:21]
	v_mfma_f32_16x16x32_bf16 v[6:9], v[164:167], v[222:225], v[6:9]
	s_barrier
	v_mfma_f32_16x16x32_bf16 v[2:5], v[178:181], v[222:225], v[2:5]
	s_setprio 0
	s_add_i32 s21, 0, 0x18000
	s_add_i32 s40, 0, 0x1c000
	v_add_u32_e32 v142, s21, v168
	v_add_u32_e32 v173, s40, v168
	ds_read_b128 v[130:133], v142
	ds_read_b128 v[134:137], v142 offset:1024
	ds_read_b128 v[138:141], v142 offset:2048
	ds_read_b128 v[142:145], v142 offset:3072
	ds_read_b128 v[160:163], v173
	ds_read_b128 v[164:167], v173 offset:1024
	ds_read_b128 v[174:177], v173 offset:2048
	ds_read_b128 v[178:181], v173 offset:3072
	s_add_u32 s38, s38, 0x80000
	s_addc_u32 s39, s39, 0
	s_mov_b32 m0, s42
	v_lshl_add_u64 v[230:231], s[38:39], 0, v[146:147]
	ds_read_b128 v[182:185], v172 offset:32768
	ds_read_b128 v[186:189], v172 offset:33792
	ds_read_b128 v[190:193], v172 offset:34816
	ds_read_b128 v[198:201], v172 offset:35840
	ds_read_b128 v[210:213], v172 offset:36864
	ds_read_b128 v[214:217], v172 offset:37888
	ds_read_b128 v[218:221], v172 offset:38912
	ds_read_b128 v[222:225], v172 offset:39936
	global_load_lds_dwordx4 v[230:231], off
	v_lshl_add_u64 v[230:231], s[38:39], 0, v[150:151]
	s_mov_b32 m0, s43
	s_nop 0
	global_load_lds_dwordx4 v[230:231], off
	s_waitcnt vmcnt(8)
	s_waitcnt lgkmcnt(0)
	s_barrier
	s_setprio 1
	s_waitcnt lgkmcnt(0)
	v_mfma_f32_16x16x32_bf16 v[126:129], v[130:133], v[182:185], v[126:129]
	v_mfma_f32_16x16x32_bf16 v[122:125], v[138:141], v[182:185], v[122:125]
	v_mfma_f32_16x16x32_bf16 v[118:121], v[130:133], v[190:193], v[118:121]
	v_mfma_f32_16x16x32_bf16 v[110:113], v[138:141], v[190:193], v[110:113]
	v_mfma_f32_16x16x32_bf16 v[94:97], v[130:133], v[210:213], v[94:97]
	v_mfma_f32_16x16x32_bf16 v[90:93], v[138:141], v[210:213], v[90:93]
	v_mfma_f32_16x16x32_bf16 v[78:81], v[130:133], v[218:221], v[78:81]
	v_mfma_f32_16x16x32_bf16 v[74:77], v[138:141], v[218:221], v[74:77]
	v_mfma_f32_16x16x32_bf16 v[126:129], v[134:137], v[186:189], v[126:129]
	v_mfma_f32_16x16x32_bf16 v[122:125], v[142:145], v[186:189], v[122:125]
	v_mfma_f32_16x16x32_bf16 v[118:121], v[134:137], v[198:201], v[118:121]
	v_mfma_f32_16x16x32_bf16 v[110:113], v[142:145], v[198:201], v[110:113]
	v_mfma_f32_16x16x32_bf16 v[94:97], v[134:137], v[214:217], v[94:97]
	v_mfma_f32_16x16x32_bf16 v[90:93], v[142:145], v[214:217], v[90:93]
	v_mfma_f32_16x16x32_bf16 v[78:81], v[134:137], v[222:225], v[78:81]
	v_mfma_f32_16x16x32_bf16 v[74:77], v[142:145], v[222:225], v[74:77]
	s_setprio 0
	s_setprio 1
	v_mfma_f32_16x16x32_bf16 v[114:117], v[160:163], v[182:185], v[114:117]
	v_mfma_f32_16x16x32_bf16 v[106:109], v[174:177], v[182:185], v[106:109]
	v_mfma_f32_16x16x32_bf16 v[102:105], v[160:163], v[190:193], v[102:105]
	v_mfma_f32_16x16x32_bf16 v[98:101], v[174:177], v[190:193], v[98:101]
	v_mfma_f32_16x16x32_bf16 v[86:89], v[160:163], v[210:213], v[86:89]
	v_mfma_f32_16x16x32_bf16 v[82:85], v[174:177], v[210:213], v[82:85]
	v_mfma_f32_16x16x32_bf16 v[70:73], v[160:163], v[218:221], v[70:73]
	v_mfma_f32_16x16x32_bf16 v[66:69], v[174:177], v[218:221], v[66:69]
	v_mfma_f32_16x16x32_bf16 v[114:117], v[164:167], v[186:189], v[114:117]
	v_mfma_f32_16x16x32_bf16 v[106:109], v[178:181], v[186:189], v[106:109]
	v_mfma_f32_16x16x32_bf16 v[102:105], v[164:167], v[198:201], v[102:105]
	v_mfma_f32_16x16x32_bf16 v[98:101], v[178:181], v[198:201], v[98:101]
	v_mfma_f32_16x16x32_bf16 v[86:89], v[164:167], v[214:217], v[86:89]
	v_mfma_f32_16x16x32_bf16 v[82:85], v[178:181], v[214:217], v[82:85]
	v_mfma_f32_16x16x32_bf16 v[70:73], v[164:167], v[222:225], v[70:73]
	s_barrier
	v_mfma_f32_16x16x32_bf16 v[66:69], v[178:181], v[222:225], v[66:69]
	s_setprio 0
	s_add_i32 s21, s21, s33
	v_lshl_add_u64 v[202:203], v[202:203], 0, s[12:13]
	s_mov_b32 m0, s21
	ds_read_b128 v[182:185], v172 offset:49152
	ds_read_b128 v[186:189], v172 offset:50176
	ds_read_b128 v[190:193], v172 offset:51200
	ds_read_b128 v[198:201], v172 offset:52224
	ds_read_b128 v[210:213], v172 offset:53248
	ds_read_b128 v[214:217], v172 offset:54272
	ds_read_b128 v[218:221], v172 offset:55296
	ds_read_b128 v[222:225], v172 offset:56320
	global_load_lds_dwordx4 v[202:203], off
	s_add_i32 m0, s21, 0x2000
	s_add_u32 s36, s36, 0x80080
	v_lshl_add_u64 v[202:203], v[206:207], 0, s[12:13]
	s_addc_u32 s37, s37, 0
	s_add_i32 s21, s40, s33
	global_load_lds_dwordx4 v[202:203], off
	v_lshl_add_u64 v[202:203], s[36:37], 0, v[148:149]
	s_mov_b32 m0, s21
	s_nop 0
	global_load_lds_dwordx4 v[202:203], off
	v_lshl_add_u64 v[202:203], s[36:37], 0, v[152:153]
	s_add_i32 m0, s21, 0x2000
	s_nop 0
	global_load_lds_dwordx4 v[202:203], off
	v_lshl_add_u64 v[202:203], v[226:227], 0, s[12:13]
	s_mov_b32 m0, s53
	s_nop 0
	global_load_lds_dwordx4 v[202:203], off
	v_lshl_add_u64 v[202:203], v[228:229], 0, s[12:13]
	s_mov_b32 m0, s54
	s_nop 0
	global_load_lds_dwordx4 v[202:203], off
	s_waitcnt vmcnt(8)
	s_waitcnt lgkmcnt(0)
	s_barrier
	s_setprio 1
	s_waitcnt lgkmcnt(0)
	v_mfma_f32_16x16x32_bf16 v[62:65], v[130:133], v[182:185], v[62:65]
	v_mfma_f32_16x16x32_bf16 v[58:61], v[138:141], v[182:185], v[58:61]
	v_mfma_f32_16x16x32_bf16 v[46:49], v[130:133], v[190:193], v[46:49]
	v_mfma_f32_16x16x32_bf16 v[42:45], v[138:141], v[190:193], v[42:45]
	v_mfma_f32_16x16x32_bf16 v[30:33], v[130:133], v[210:213], v[30:33]
	v_mfma_f32_16x16x32_bf16 v[26:29], v[138:141], v[210:213], v[26:29]
	v_mfma_f32_16x16x32_bf16 v[14:17], v[130:133], v[218:221], v[14:17]
	v_mfma_f32_16x16x32_bf16 v[10:13], v[138:141], v[218:221], v[10:13]
	v_mfma_f32_16x16x32_bf16 v[62:65], v[134:137], v[186:189], v[62:65]
	v_mfma_f32_16x16x32_bf16 v[58:61], v[142:145], v[186:189], v[58:61]
	v_mfma_f32_16x16x32_bf16 v[46:49], v[134:137], v[198:201], v[46:49]
	v_mfma_f32_16x16x32_bf16 v[42:45], v[142:145], v[198:201], v[42:45]
	v_mfma_f32_16x16x32_bf16 v[30:33], v[134:137], v[214:217], v[30:33]
	v_mfma_f32_16x16x32_bf16 v[26:29], v[142:145], v[214:217], v[26:29]
	v_mfma_f32_16x16x32_bf16 v[14:17], v[134:137], v[222:225], v[14:17]
	v_mfma_f32_16x16x32_bf16 v[10:13], v[142:145], v[222:225], v[10:13]
	s_setprio 0
	s_setprio 1
	v_mfma_f32_16x16x32_bf16 v[54:57], v[160:163], v[182:185], v[54:57]
	v_mfma_f32_16x16x32_bf16 v[50:53], v[174:177], v[182:185], v[50:53]
	v_mfma_f32_16x16x32_bf16 v[38:41], v[160:163], v[190:193], v[38:41]
	v_mfma_f32_16x16x32_bf16 v[34:37], v[174:177], v[190:193], v[34:37]
	v_mfma_f32_16x16x32_bf16 v[22:25], v[160:163], v[210:213], v[22:25]
	v_mfma_f32_16x16x32_bf16 v[18:21], v[174:177], v[210:213], v[18:21]
	v_mfma_f32_16x16x32_bf16 v[6:9], v[160:163], v[218:221], v[6:9]
	v_mfma_f32_16x16x32_bf16 v[2:5], v[174:177], v[218:221], v[2:5]
	v_mfma_f32_16x16x32_bf16 v[54:57], v[164:167], v[186:189], v[54:57]
	v_mfma_f32_16x16x32_bf16 v[50:53], v[178:181], v[186:189], v[50:53]
	v_mfma_f32_16x16x32_bf16 v[38:41], v[164:167], v[198:201], v[38:41]
	v_mfma_f32_16x16x32_bf16 v[34:37], v[178:181], v[198:201], v[34:37]
	v_mfma_f32_16x16x32_bf16 v[22:25], v[164:167], v[214:217], v[22:25]
	v_mfma_f32_16x16x32_bf16 v[18:21], v[178:181], v[214:217], v[18:21]
	v_mfma_f32_16x16x32_bf16 v[6:9], v[164:167], v[222:225], v[6:9]
	s_barrier
	v_mfma_f32_16x16x32_bf16 v[2:5], v[178:181], v[222:225], v[2:5]
	s_setprio 0
	s_add_u32 s34, s34, 0x100
	s_addc_u32 s35, s35, 0
	s_add_u32 s17, s17, 0x100
	s_addc_u32 s19, s19, 0
	s_cmp_ge_i32 s31, s69
	s_mov_b32 s21, s31
	s_cbranch_scc0 .LBB0_1122

.Lpeel_7:
	ds_read_b128 v[152:155], v148
	ds_read_b128 v[156:159], v148 offset:1024
	s_add_i32 s29, s19, 2
	s_add_u32 s34, s30, 0xfff80080
	s_addc_u32 s35, s31, -1
	s_cmp_eq_u32 s28, s19
	s_cselect_b32 s37, s21, s35
	s_cselect_b32 s36, s20, s34
	s_cselect_b32 s35, s23, s17
	s_cselect_b32 s34, s22, s15
	v_lshl_add_u64 v[144:145], s[30:31], 0, v[140:141]
	s_add_i32 m0, s27, 0xc000
	global_load_lds_dwordx4 v[144:145], off
	v_lshl_add_u64 v[144:145], s[30:31], 0, v[142:143]
	s_add_i32 m0, s27, 0xe000
	s_nop 0
	global_load_lds_dwordx4 v[144:145], off
	s_waitcnt vmcnt(8)
	s_waitcnt lgkmcnt(0)
	s_barrier
	s_setprio 1
	s_waitcnt lgkmcnt(0)
	v_mfma_f32_16x16x32_bf16 v[126:129], v[152:155], v[184:187], 0
	v_mfma_f32_16x16x32_bf16 v[122:125], v[160:163], v[184:187], 0
	v_mfma_f32_16x16x32_bf16 v[110:113], v[152:155], v[198:201], 0
	v_mfma_f32_16x16x32_bf16 v[106:109], v[160:163], v[198:201], 0
	v_mfma_f32_16x16x32_bf16 v[94:97], v[152:155], v[214:217], 0
	v_mfma_f32_16x16x32_bf16 v[90:93], v[160:163], v[214:217], 0
	v_mfma_f32_16x16x32_bf16 v[78:81], v[152:155], v[222:225], 0
	v_mfma_f32_16x16x32_bf16 v[74:77], v[160:163], v[222:225], 0
	v_mfma_f32_16x16x32_bf16 v[126:129], v[156:159], v[188:191], v[126:129]
	v_mfma_f32_16x16x32_bf16 v[122:125], v[164:167], v[188:191], v[122:125]
	v_mfma_f32_16x16x32_bf16 v[110:113], v[156:159], v[210:213], v[110:113]
	v_mfma_f32_16x16x32_bf16 v[106:109], v[164:167], v[210:213], v[106:109]
	v_mfma_f32_16x16x32_bf16 v[94:97], v[156:159], v[218:221], v[94:97]
	v_mfma_f32_16x16x32_bf16 v[90:93], v[164:167], v[218:221], v[90:93]
	v_mfma_f32_16x16x32_bf16 v[78:81], v[156:159], v[226:229], v[78:81]
	v_mfma_f32_16x16x32_bf16 v[74:77], v[164:167], v[226:229], v[74:77]
	s_setprio 0
	s_setprio 1
	v_mfma_f32_16x16x32_bf16 v[118:121], v[168:171], v[184:187], 0
	v_mfma_f32_16x16x32_bf16 v[114:117], v[176:179], v[184:187], 0
	v_mfma_f32_16x16x32_bf16 v[102:105], v[168:171], v[198:201], 0
	v_mfma_f32_16x16x32_bf16 v[98:101], v[176:179], v[198:201], 0
	v_mfma_f32_16x16x32_bf16 v[86:89], v[168:171], v[214:217], 0
	v_mfma_f32_16x16x32_bf16 v[82:85], v[176:179], v[214:217], 0
	v_mfma_f32_16x16x32_bf16 v[70:73], v[168:171], v[222:225], 0
	v_mfma_f32_16x16x32_bf16 v[66:69], v[176:179], v[222:225], 0
	v_mfma_f32_16x16x32_bf16 v[118:121], v[172:175], v[188:191], v[118:121]
	v_mfma_f32_16x16x32_bf16 v[114:117], v[180:183], v[188:191], v[114:117]
	v_mfma_f32_16x16x32_bf16 v[102:105], v[172:175], v[210:213], v[102:105]
	v_mfma_f32_16x16x32_bf16 v[98:101], v[180:183], v[210:213], v[98:101]
	v_mfma_f32_16x16x32_bf16 v[86:89], v[172:175], v[218:221], v[86:89]
	v_mfma_f32_16x16x32_bf16 v[82:85], v[180:183], v[218:221], v[82:85]
	v_mfma_f32_16x16x32_bf16 v[70:73], v[172:175], v[226:229], v[70:73]
	s_barrier
	v_mfma_f32_16x16x32_bf16 v[66:69], v[180:183], v[226:229], v[66:69]
	s_setprio 0
	s_add_i32 s19, s60, s33
	v_lshl_add_u64 v[144:145], s[34:35], 0, v[132:133]
	s_mov_b32 m0, s19
	ds_read_b128 v[184:187], v150 offset:16384
	ds_read_b128 v[188:191], v150 offset:17408
	ds_read_b128 v[198:201], v150 offset:18432
	ds_read_b128 v[210:213], v150 offset:19456
	ds_read_b128 v[214:217], v150 offset:20480
	ds_read_b128 v[218:221], v150 offset:21504
	ds_read_b128 v[222:225], v150 offset:22528
	ds_read_b128 v[226:229], v150 offset:23552
	global_load_lds_dwordx4 v[144:145], off
	s_add_i32 m0, s19, 0x2000
	s_add_u32 s38, s34, 0x80000
	v_lshl_add_u64 v[192:193], s[34:35], 0, v[136:137]
	s_addc_u32 s39, s35, 0
	s_add_i32 s19, s61, s33
	global_load_lds_dwordx4 v[192:193], off
	v_lshl_add_u64 v[202:203], s[38:39], 0, v[132:133]
	s_mov_b32 m0, s19
	v_lshl_add_u64 v[206:207], s[36:37], 0, v[134:135]
	global_load_lds_dwordx4 v[202:203], off
	v_lshl_add_u64 v[202:203], s[38:39], 0, v[136:137]
	s_add_i32 m0, s19, 0x2000
	s_nop 0
	global_load_lds_dwordx4 v[202:203], off
	v_lshl_add_u64 v[202:203], s[36:37], 0, v[130:131]
	s_mov_b32 m0, s27
	s_nop 0
	global_load_lds_dwordx4 v[202:203], off
	s_mov_b32 m0, s41
	s_nop 0
	global_load_lds_dwordx4 v[206:207], off
	s_waitcnt vmcnt(8)
	s_waitcnt lgkmcnt(0)
	s_barrier
	s_setprio 1
	s_waitcnt lgkmcnt(0)
	v_mfma_f32_16x16x32_bf16 v[62:65], v[152:155], v[184:187], 0
	v_mfma_f32_16x16x32_bf16 v[58:61], v[160:163], v[184:187], 0
	v_mfma_f32_16x16x32_bf16 v[46:49], v[152:155], v[198:201], 0
	v_mfma_f32_16x16x32_bf16 v[42:45], v[160:163], v[198:201], 0
	v_mfma_f32_16x16x32_bf16 v[30:33], v[152:155], v[214:217], 0
	v_mfma_f32_16x16x32_bf16 v[26:29], v[160:163], v[214:217], 0
	v_mfma_f32_16x16x32_bf16 v[14:17], v[152:155], v[222:225], 0
	v_mfma_f32_16x16x32_bf16 v[10:13], v[160:163], v[222:225], 0
	v_mfma_f32_16x16x32_bf16 v[62:65], v[156:159], v[188:191], v[62:65]
	v_mfma_f32_16x16x32_bf16 v[58:61], v[164:167], v[188:191], v[58:61]
	v_mfma_f32_16x16x32_bf16 v[46:49], v[156:159], v[210:213], v[46:49]
	v_mfma_f32_16x16x32_bf16 v[42:45], v[164:167], v[210:213], v[42:45]
	v_mfma_f32_16x16x32_bf16 v[30:33], v[156:159], v[218:221], v[30:33]
	v_mfma_f32_16x16x32_bf16 v[26:29], v[164:167], v[218:221], v[26:29]
	v_mfma_f32_16x16x32_bf16 v[14:17], v[156:159], v[226:229], v[14:17]
	v_mfma_f32_16x16x32_bf16 v[10:13], v[164:167], v[226:229], v[10:13]
	s_setprio 0
	s_setprio 1
	v_mfma_f32_16x16x32_bf16 v[54:57], v[168:171], v[184:187], 0
	v_mfma_f32_16x16x32_bf16 v[50:53], v[176:179], v[184:187], 0
	v_mfma_f32_16x16x32_bf16 v[38:41], v[168:171], v[198:201], 0
	v_mfma_f32_16x16x32_bf16 v[34:37], v[176:179], v[198:201], 0
	v_mfma_f32_16x16x32_bf16 v[22:25], v[168:171], v[214:217], 0
	v_mfma_f32_16x16x32_bf16 v[18:21], v[176:179], v[214:217], 0
	v_mfma_f32_16x16x32_bf16 v[6:9], v[168:171], v[222:225], 0
	v_mfma_f32_16x16x32_bf16 v[2:5], v[176:179], v[222:225], 0
	v_mfma_f32_16x16x32_bf16 v[54:57], v[172:175], v[188:191], v[54:57]
	v_mfma_f32_16x16x32_bf16 v[50:53], v[180:183], v[188:191], v[50:53]
	v_mfma_f32_16x16x32_bf16 v[38:41], v[172:175], v[210:213], v[38:41]
	v_mfma_f32_16x16x32_bf16 v[34:37], v[180:183], v[210:213], v[34:37]
	v_mfma_f32_16x16x32_bf16 v[22:25], v[172:175], v[218:221], v[22:25]
	v_mfma_f32_16x16x32_bf16 v[18:21], v[180:183], v[218:221], v[18:21]
	v_mfma_f32_16x16x32_bf16 v[6:9], v[172:175], v[226:229], v[6:9]
	s_barrier
	v_mfma_f32_16x16x32_bf16 v[2:5], v[180:183], v[226:229], v[2:5]
	s_setprio 0
	s_add_i32 s19, 0, 0x18000
	v_add_u32_e32 v151, s19, v146
	s_add_i32 s38, 0, 0x1c000
	ds_read_b128 v[152:155], v151
	ds_read_b128 v[156:159], v151 offset:1024
	ds_read_b128 v[160:163], v151 offset:2048
	ds_read_b128 v[164:167], v151 offset:3072
	v_add_u32_e32 v151, s38, v146
	ds_read_b128 v[168:171], v151
	ds_read_b128 v[172:175], v151 offset:1024
	ds_read_b128 v[176:179], v151 offset:2048
	ds_read_b128 v[180:183], v151 offset:3072
	s_add_u32 s36, s36, 0x80000
	s_addc_u32 s37, s37, 0
	s_mov_b32 m0, s42
	v_lshl_add_u64 v[230:231], s[36:37], 0, v[130:131]
	ds_read_b128 v[184:187], v150 offset:32768
	ds_read_b128 v[188:191], v150 offset:33792
	ds_read_b128 v[198:201], v150 offset:34816
	ds_read_b128 v[210:213], v150 offset:35840
	ds_read_b128 v[214:217], v150 offset:36864
	ds_read_b128 v[218:221], v150 offset:37888
	ds_read_b128 v[222:225], v150 offset:38912
	ds_read_b128 v[226:229], v150 offset:39936
	global_load_lds_dwordx4 v[230:231], off
	v_lshl_add_u64 v[230:231], s[36:37], 0, v[134:135]
	s_mov_b32 m0, s43
	s_nop 0
	global_load_lds_dwordx4 v[230:231], off
	s_waitcnt vmcnt(8)
	s_waitcnt lgkmcnt(0)
	s_barrier
	s_setprio 1
	s_waitcnt lgkmcnt(0)
	v_mfma_f32_16x16x32_bf16 v[126:129], v[152:155], v[184:187], v[126:129]
	v_mfma_f32_16x16x32_bf16 v[122:125], v[160:163], v[184:187], v[122:125]
	v_mfma_f32_16x16x32_bf16 v[110:113], v[152:155], v[198:201], v[110:113]
	v_mfma_f32_16x16x32_bf16 v[106:109], v[160:163], v[198:201], v[106:109]
	v_mfma_f32_16x16x32_bf16 v[94:97], v[152:155], v[214:217], v[94:97]
	v_mfma_f32_16x16x32_bf16 v[90:93], v[160:163], v[214:217], v[90:93]
	v_mfma_f32_16x16x32_bf16 v[78:81], v[152:155], v[222:225], v[78:81]
	v_mfma_f32_16x16x32_bf16 v[74:77], v[160:163], v[222:225], v[74:77]
	v_mfma_f32_16x16x32_bf16 v[126:129], v[156:159], v[188:191], v[126:129]
	v_mfma_f32_16x16x32_bf16 v[122:125], v[164:167], v[188:191], v[122:125]
	v_mfma_f32_16x16x32_bf16 v[110:113], v[156:159], v[210:213], v[110:113]
	v_mfma_f32_16x16x32_bf16 v[106:109], v[164:167], v[210:213], v[106:109]
	v_mfma_f32_16x16x32_bf16 v[94:97], v[156:159], v[218:221], v[94:97]
	v_mfma_f32_16x16x32_bf16 v[90:93], v[164:167], v[218:221], v[90:93]
	v_mfma_f32_16x16x32_bf16 v[78:81], v[156:159], v[226:229], v[78:81]
	v_mfma_f32_16x16x32_bf16 v[74:77], v[164:167], v[226:229], v[74:77]
	s_setprio 0
	s_setprio 1
	v_mfma_f32_16x16x32_bf16 v[118:121], v[168:171], v[184:187], v[118:121]
	v_mfma_f32_16x16x32_bf16 v[114:117], v[176:179], v[184:187], v[114:117]
	v_mfma_f32_16x16x32_bf16 v[102:105], v[168:171], v[198:201], v[102:105]
	v_mfma_f32_16x16x32_bf16 v[98:101], v[176:179], v[198:201], v[98:101]
	v_mfma_f32_16x16x32_bf16 v[86:89], v[168:171], v[214:217], v[86:89]
	v_mfma_f32_16x16x32_bf16 v[82:85], v[176:179], v[214:217], v[82:85]
	v_mfma_f32_16x16x32_bf16 v[70:73], v[168:171], v[222:225], v[70:73]
	v_mfma_f32_16x16x32_bf16 v[66:69], v[176:179], v[222:225], v[66:69]
	v_mfma_f32_16x16x32_bf16 v[118:121], v[172:175], v[188:191], v[118:121]
	v_mfma_f32_16x16x32_bf16 v[114:117], v[180:183], v[188:191], v[114:117]
	v_mfma_f32_16x16x32_bf16 v[102:105], v[172:175], v[210:213], v[102:105]
	v_mfma_f32_16x16x32_bf16 v[98:101], v[180:183], v[210:213], v[98:101]
	v_mfma_f32_16x16x32_bf16 v[86:89], v[172:175], v[218:221], v[86:89]
	v_mfma_f32_16x16x32_bf16 v[82:85], v[180:183], v[218:221], v[82:85]
	v_mfma_f32_16x16x32_bf16 v[70:73], v[172:175], v[226:229], v[70:73]
	s_barrier
	v_mfma_f32_16x16x32_bf16 v[66:69], v[180:183], v[226:229], v[66:69]
	s_setprio 0
	s_add_i32 s19, s19, s33
	v_lshl_add_u64 v[144:145], v[144:145], 0, s[10:11]
	s_mov_b32 m0, s19
	ds_read_b128 v[184:187], v150 offset:49152
	ds_read_b128 v[188:191], v150 offset:50176
	ds_read_b128 v[198:201], v150 offset:51200
	ds_read_b128 v[210:213], v150 offset:52224
	ds_read_b128 v[214:217], v150 offset:53248
	ds_read_b128 v[218:221], v150 offset:54272
	ds_read_b128 v[222:225], v150 offset:55296
	ds_read_b128 v[226:229], v150 offset:56320
	global_load_lds_dwordx4 v[144:145], off
	s_add_i32 m0, s19, 0x2000
	s_add_u32 s34, s34, 0x80080
	v_lshl_add_u64 v[144:145], v[192:193], 0, s[10:11]
	s_addc_u32 s35, s35, 0
	s_add_i32 s19, s38, s33
	global_load_lds_dwordx4 v[144:145], off
	v_lshl_add_u64 v[144:145], s[34:35], 0, v[132:133]
	s_mov_b32 m0, s19
	s_nop 0
	global_load_lds_dwordx4 v[144:145], off
	v_lshl_add_u64 v[144:145], s[34:35], 0, v[136:137]
	s_add_i32 m0, s19, 0x2000
	s_nop 0
	global_load_lds_dwordx4 v[144:145], off
	v_lshl_add_u64 v[144:145], v[202:203], 0, s[10:11]
	s_mov_b32 m0, s51
	s_nop 0
	global_load_lds_dwordx4 v[144:145], off
	v_lshl_add_u64 v[144:145], v[206:207], 0, s[10:11]
	s_mov_b32 m0, s52
	s_nop 0
	global_load_lds_dwordx4 v[144:145], off
	s_waitcnt vmcnt(8)
	s_waitcnt lgkmcnt(0)
	s_barrier
	s_setprio 1
	s_waitcnt lgkmcnt(0)
	v_mfma_f32_16x16x32_bf16 v[62:65], v[152:155], v[184:187], v[62:65]
	v_mfma_f32_16x16x32_bf16 v[58:61], v[160:163], v[184:187], v[58:61]
	v_mfma_f32_16x16x32_bf16 v[46:49], v[152:155], v[198:201], v[46:49]
	v_mfma_f32_16x16x32_bf16 v[42:45], v[160:163], v[198:201], v[42:45]
	v_mfma_f32_16x16x32_bf16 v[30:33], v[152:155], v[214:217], v[30:33]
	v_mfma_f32_16x16x32_bf16 v[26:29], v[160:163], v[214:217], v[26:29]
	v_mfma_f32_16x16x32_bf16 v[14:17], v[152:155], v[222:225], v[14:17]
	v_mfma_f32_16x16x32_bf16 v[10:13], v[160:163], v[222:225], v[10:13]
	v_mfma_f32_16x16x32_bf16 v[62:65], v[156:159], v[188:191], v[62:65]
	v_mfma_f32_16x16x32_bf16 v[58:61], v[164:167], v[188:191], v[58:61]
	v_mfma_f32_16x16x32_bf16 v[46:49], v[156:159], v[210:213], v[46:49]
	v_mfma_f32_16x16x32_bf16 v[42:45], v[164:167], v[210:213], v[42:45]
	v_mfma_f32_16x16x32_bf16 v[30:33], v[156:159], v[218:221], v[30:33]
	v_mfma_f32_16x16x32_bf16 v[26:29], v[164:167], v[218:221], v[26:29]
	v_mfma_f32_16x16x32_bf16 v[14:17], v[156:159], v[226:229], v[14:17]
	v_mfma_f32_16x16x32_bf16 v[10:13], v[164:167], v[226:229], v[10:13]
	s_setprio 0
	s_setprio 1
	v_mfma_f32_16x16x32_bf16 v[54:57], v[168:171], v[184:187], v[54:57]
	v_mfma_f32_16x16x32_bf16 v[50:53], v[176:179], v[184:187], v[50:53]
	v_mfma_f32_16x16x32_bf16 v[38:41], v[168:171], v[198:201], v[38:41]
	v_mfma_f32_16x16x32_bf16 v[34:37], v[176:179], v[198:201], v[34:37]
	v_mfma_f32_16x16x32_bf16 v[22:25], v[168:171], v[214:217], v[22:25]
	v_mfma_f32_16x16x32_bf16 v[18:21], v[176:179], v[214:217], v[18:21]
	v_mfma_f32_16x16x32_bf16 v[6:9], v[168:171], v[222:225], v[6:9]
	v_mfma_f32_16x16x32_bf16 v[2:5], v[176:179], v[222:225], v[2:5]
	v_mfma_f32_16x16x32_bf16 v[54:57], v[172:175], v[188:191], v[54:57]
	v_mfma_f32_16x16x32_bf16 v[50:53], v[180:183], v[188:191], v[50:53]
	v_mfma_f32_16x16x32_bf16 v[38:41], v[172:175], v[210:213], v[38:41]
	v_mfma_f32_16x16x32_bf16 v[34:37], v[180:183], v[210:213], v[34:37]
	v_mfma_f32_16x16x32_bf16 v[22:25], v[172:175], v[218:221], v[22:25]
	v_mfma_f32_16x16x32_bf16 v[18:21], v[180:183], v[218:221], v[18:21]
	v_mfma_f32_16x16x32_bf16 v[6:9], v[172:175], v[226:229], v[6:9]
	s_barrier
	v_mfma_f32_16x16x32_bf16 v[2:5], v[180:183], v[226:229], v[2:5]
	s_setprio 0
	s_add_u32 s30, s30, 0x100
	s_addc_u32 s31, s31, 0
	s_add_u32 s15, s15, 0x100
	s_addc_u32 s17, s17, 0
	s_cmp_ge_i32 s29, s68
	s_mov_b32 s19, s29
	s_cbranch_scc0 .LBB0_1315
	s_branch .Lpeeldone_7
.LBB0_1315:
	ds_read_b128 v[152:155], v148
	ds_read_b128 v[156:159], v148 offset:1024
	ds_read_b128 v[160:163], v148 offset:2048
	ds_read_b128 v[164:167], v148 offset:3072
	ds_read_b128 v[168:171], v149
	ds_read_b128 v[172:175], v149 offset:1024
	ds_read_b128 v[176:179], v149 offset:2048
	ds_read_b128 v[180:183], v149 offset:3072
	s_add_i32 s29, s19, 2
	s_add_u32 s34, s30, 0xfff80080
	s_addc_u32 s35, s31, -1
	s_cmp_eq_u32 s28, s19
	s_cselect_b32 s37, s21, s35
	s_cselect_b32 s36, s20, s34
	s_cselect_b32 s35, s23, s17
	s_cselect_b32 s34, s22, s15
	v_lshl_add_u64 v[144:145], s[30:31], 0, v[140:141]
	s_add_i32 m0, s27, 0xc000
	ds_read_b128 v[184:187], v150
	ds_read_b128 v[188:191], v150 offset:1024
	ds_read_b128 v[198:201], v150 offset:2048
	ds_read_b128 v[210:213], v150 offset:3072
	ds_read_b128 v[214:217], v150 offset:4096
	ds_read_b128 v[218:221], v150 offset:5120
	ds_read_b128 v[222:225], v150 offset:6144
	ds_read_b128 v[226:229], v150 offset:7168
	global_load_lds_dwordx4 v[144:145], off
	v_lshl_add_u64 v[144:145], s[30:31], 0, v[142:143]
	s_add_i32 m0, s27, 0xe000
	s_nop 0
	global_load_lds_dwordx4 v[144:145], off
	s_waitcnt vmcnt(8)
	s_waitcnt lgkmcnt(0)
	s_barrier
	s_setprio 1
	s_waitcnt lgkmcnt(0)
	v_mfma_f32_16x16x32_bf16 v[126:129], v[152:155], v[184:187], v[126:129]
	v_mfma_f32_16x16x32_bf16 v[122:125], v[160:163], v[184:187], v[122:125]
	v_mfma_f32_16x16x32_bf16 v[110:113], v[152:155], v[198:201], v[110:113]
	v_mfma_f32_16x16x32_bf16 v[106:109], v[160:163], v[198:201], v[106:109]
	v_mfma_f32_16x16x32_bf16 v[94:97], v[152:155], v[214:217], v[94:97]
	v_mfma_f32_16x16x32_bf16 v[90:93], v[160:163], v[214:217], v[90:93]
	v_mfma_f32_16x16x32_bf16 v[78:81], v[152:155], v[222:225], v[78:81]
	v_mfma_f32_16x16x32_bf16 v[74:77], v[160:163], v[222:225], v[74:77]
	v_mfma_f32_16x16x32_bf16 v[126:129], v[156:159], v[188:191], v[126:129]
	v_mfma_f32_16x16x32_bf16 v[122:125], v[164:167], v[188:191], v[122:125]
	v_mfma_f32_16x16x32_bf16 v[110:113], v[156:159], v[210:213], v[110:113]
	v_mfma_f32_16x16x32_bf16 v[106:109], v[164:167], v[210:213], v[106:109]
	v_mfma_f32_16x16x32_bf16 v[94:97], v[156:159], v[218:221], v[94:97]
	v_mfma_f32_16x16x32_bf16 v[90:93], v[164:167], v[218:221], v[90:93]
	v_mfma_f32_16x16x32_bf16 v[78:81], v[156:159], v[226:229], v[78:81]
	v_mfma_f32_16x16x32_bf16 v[74:77], v[164:167], v[226:229], v[74:77]
	s_setprio 0
	s_setprio 1
	v_mfma_f32_16x16x32_bf16 v[118:121], v[168:171], v[184:187], v[118:121]
	v_mfma_f32_16x16x32_bf16 v[114:117], v[176:179], v[184:187], v[114:117]
	v_mfma_f32_16x16x32_bf16 v[102:105], v[168:171], v[198:201], v[102:105]
	v_mfma_f32_16x16x32_bf16 v[98:101], v[176:179], v[198:201], v[98:101]
	v_mfma_f32_16x16x32_bf16 v[86:89], v[168:171], v[214:217], v[86:89]
	v_mfma_f32_16x16x32_bf16 v[82:85], v[176:179], v[214:217], v[82:85]
	v_mfma_f32_16x16x32_bf16 v[70:73], v[168:171], v[222:225], v[70:73]
	v_mfma_f32_16x16x32_bf16 v[66:69], v[176:179], v[222:225], v[66:69]
	v_mfma_f32_16x16x32_bf16 v[118:121], v[172:175], v[188:191], v[118:121]
	v_mfma_f32_16x16x32_bf16 v[114:117], v[180:183], v[188:191], v[114:117]
	v_mfma_f32_16x16x32_bf16 v[102:105], v[172:175], v[210:213], v[102:105]
	v_mfma_f32_16x16x32_bf16 v[98:101], v[180:183], v[210:213], v[98:101]
	v_mfma_f32_16x16x32_bf16 v[86:89], v[172:175], v[218:221], v[86:89]
	v_mfma_f32_16x16x32_bf16 v[82:85], v[180:183], v[218:221], v[82:85]
	v_mfma_f32_16x16x32_bf16 v[70:73], v[172:175], v[226:229], v[70:73]
	s_barrier
	v_mfma_f32_16x16x32_bf16 v[66:69], v[180:183], v[226:229], v[66:69]
	s_setprio 0
	s_add_i32 s19, s60, s33
	v_lshl_add_u64 v[144:145], s[34:35], 0, v[132:133]
	s_mov_b32 m0, s19
	ds_read_b128 v[184:187], v150 offset:16384
	ds_read_b128 v[188:191], v150 offset:17408
	ds_read_b128 v[198:201], v150 offset:18432
	ds_read_b128 v[210:213], v150 offset:19456
	ds_read_b128 v[214:217], v150 offset:20480
	ds_read_b128 v[218:221], v150 offset:21504
	ds_read_b128 v[222:225], v150 offset:22528
	ds_read_b128 v[226:229], v150 offset:23552
	global_load_lds_dwordx4 v[144:145], off
	s_add_i32 m0, s19, 0x2000
	s_add_u32 s38, s34, 0x80000
	v_lshl_add_u64 v[192:193], s[34:35], 0, v[136:137]
	s_addc_u32 s39, s35, 0
	s_add_i32 s19, s61, s33
	global_load_lds_dwordx4 v[192:193], off
	v_lshl_add_u64 v[202:203], s[38:39], 0, v[132:133]
	s_mov_b32 m0, s19
	v_lshl_add_u64 v[206:207], s[36:37], 0, v[134:135]
	global_load_lds_dwordx4 v[202:203], off
	v_lshl_add_u64 v[202:203], s[38:39], 0, v[136:137]
	s_add_i32 m0, s19, 0x2000
	s_nop 0
	global_load_lds_dwordx4 v[202:203], off
	v_lshl_add_u64 v[202:203], s[36:37], 0, v[130:131]
	s_mov_b32 m0, s27
	s_nop 0
	global_load_lds_dwordx4 v[202:203], off
	s_mov_b32 m0, s41
	s_nop 0
	global_load_lds_dwordx4 v[206:207], off
	s_waitcnt vmcnt(8)
	s_waitcnt lgkmcnt(0)
	s_barrier
	s_setprio 1
	s_waitcnt lgkmcnt(0)
	v_mfma_f32_16x16x32_bf16 v[62:65], v[152:155], v[184:187], v[62:65]
	v_mfma_f32_16x16x32_bf16 v[58:61], v[160:163], v[184:187], v[58:61]
	v_mfma_f32_16x16x32_bf16 v[46:49], v[152:155], v[198:201], v[46:49]
	v_mfma_f32_16x16x32_bf16 v[42:45], v[160:163], v[198:201], v[42:45]
	v_mfma_f32_16x16x32_bf16 v[30:33], v[152:155], v[214:217], v[30:33]
	v_mfma_f32_16x16x32_bf16 v[26:29], v[160:163], v[214:217], v[26:29]
	v_mfma_f32_16x16x32_bf16 v[14:17], v[152:155], v[222:225], v[14:17]
	v_mfma_f32_16x16x32_bf16 v[10:13], v[160:163], v[222:225], v[10:13]
	v_mfma_f32_16x16x32_bf16 v[62:65], v[156:159], v[188:191], v[62:65]
	v_mfma_f32_16x16x32_bf16 v[58:61], v[164:167], v[188:191], v[58:61]
	v_mfma_f32_16x16x32_bf16 v[46:49], v[156:159], v[210:213], v[46:49]
	v_mfma_f32_16x16x32_bf16 v[42:45], v[164:167], v[210:213], v[42:45]
	v_mfma_f32_16x16x32_bf16 v[30:33], v[156:159], v[218:221], v[30:33]
	v_mfma_f32_16x16x32_bf16 v[26:29], v[164:167], v[218:221], v[26:29]
	v_mfma_f32_16x16x32_bf16 v[14:17], v[156:159], v[226:229], v[14:17]
	v_mfma_f32_16x16x32_bf16 v[10:13], v[164:167], v[226:229], v[10:13]
	s_setprio 0
	s_setprio 1
	v_mfma_f32_16x16x32_bf16 v[54:57], v[168:171], v[184:187], v[54:57]
	v_mfma_f32_16x16x32_bf16 v[50:53], v[176:179], v[184:187], v[50:53]
	v_mfma_f32_16x16x32_bf16 v[38:41], v[168:171], v[198:201], v[38:41]
	v_mfma_f32_16x16x32_bf16 v[34:37], v[176:179], v[198:201], v[34:37]
	v_mfma_f32_16x16x32_bf16 v[22:25], v[168:171], v[214:217], v[22:25]
	v_mfma_f32_16x16x32_bf16 v[18:21], v[176:179], v[214:217], v[18:21]
	v_mfma_f32_16x16x32_bf16 v[6:9], v[168:171], v[222:225], v[6:9]
	v_mfma_f32_16x16x32_bf16 v[2:5], v[176:179], v[222:225], v[2:5]
	v_mfma_f32_16x16x32_bf16 v[54:57], v[172:175], v[188:191], v[54:57]
	v_mfma_f32_16x16x32_bf16 v[50:53], v[180:183], v[188:191], v[50:53]
	v_mfma_f32_16x16x32_bf16 v[38:41], v[172:175], v[210:213], v[38:41]
	v_mfma_f32_16x16x32_bf16 v[34:37], v[180:183], v[210:213], v[34:37]
	v_mfma_f32_16x16x32_bf16 v[22:25], v[172:175], v[218:221], v[22:25]
	v_mfma_f32_16x16x32_bf16 v[18:21], v[180:183], v[218:221], v[18:21]
	v_mfma_f32_16x16x32_bf16 v[6:9], v[172:175], v[226:229], v[6:9]
	s_barrier
	v_mfma_f32_16x16x32_bf16 v[2:5], v[180:183], v[226:229], v[2:5]
	s_setprio 0
	s_add_i32 s19, 0, 0x18000
	v_add_u32_e32 v151, s19, v146
	s_add_i32 s38, 0, 0x1c000
	ds_read_b128 v[152:155], v151
	ds_read_b128 v[156:159], v151 offset:1024
	ds_read_b128 v[160:163], v151 offset:2048
	ds_read_b128 v[164:167], v151 offset:3072
	v_add_u32_e32 v151, s38, v146
	ds_read_b128 v[168:171], v151
	ds_read_b128 v[172:175], v151 offset:1024
	ds_read_b128 v[176:179], v151 offset:2048
	ds_read_b128 v[180:183], v151 offset:3072
	s_add_u32 s36, s36, 0x80000
	s_addc_u32 s37, s37, 0
	s_mov_b32 m0, s42
	v_lshl_add_u64 v[230:231], s[36:37], 0, v[130:131]
	ds_read_b128 v[184:187], v150 offset:32768
	ds_read_b128 v[188:191], v150 offset:33792
	ds_read_b128 v[198:201], v150 offset:34816
	ds_read_b128 v[210:213], v150 offset:35840
	ds_read_b128 v[214:217], v150 offset:36864
	ds_read_b128 v[218:221], v150 offset:37888
	ds_read_b128 v[222:225], v150 offset:38912
	ds_read_b128 v[226:229], v150 offset:39936
	global_load_lds_dwordx4 v[230:231], off
	v_lshl_add_u64 v[230:231], s[36:37], 0, v[134:135]
	s_mov_b32 m0, s43
	s_nop 0
	global_load_lds_dwordx4 v[230:231], off
	s_waitcnt vmcnt(8)
	s_waitcnt lgkmcnt(0)
	s_barrier
	s_setprio 1
	s_waitcnt lgkmcnt(0)
	v_mfma_f32_16x16x32_bf16 v[126:129], v[152:155], v[184:187], v[126:129]
	v_mfma_f32_16x16x32_bf16 v[122:125], v[160:163], v[184:187], v[122:125]
	v_mfma_f32_16x16x32_bf16 v[110:113], v[152:155], v[198:201], v[110:113]
	v_mfma_f32_16x16x32_bf16 v[106:109], v[160:163], v[198:201], v[106:109]
	v_mfma_f32_16x16x32_bf16 v[94:97], v[152:155], v[214:217], v[94:97]
	v_mfma_f32_16x16x32_bf16 v[90:93], v[160:163], v[214:217], v[90:93]
	v_mfma_f32_16x16x32_bf16 v[78:81], v[152:155], v[222:225], v[78:81]
	v_mfma_f32_16x16x32_bf16 v[74:77], v[160:163], v[222:225], v[74:77]
	v_mfma_f32_16x16x32_bf16 v[126:129], v[156:159], v[188:191], v[126:129]
	v_mfma_f32_16x16x32_bf16 v[122:125], v[164:167], v[188:191], v[122:125]
	v_mfma_f32_16x16x32_bf16 v[110:113], v[156:159], v[210:213], v[110:113]
	v_mfma_f32_16x16x32_bf16 v[106:109], v[164:167], v[210:213], v[106:109]
	v_mfma_f32_16x16x32_bf16 v[94:97], v[156:159], v[218:221], v[94:97]
	v_mfma_f32_16x16x32_bf16 v[90:93], v[164:167], v[218:221], v[90:93]
	v_mfma_f32_16x16x32_bf16 v[78:81], v[156:159], v[226:229], v[78:81]
	v_mfma_f32_16x16x32_bf16 v[74:77], v[164:167], v[226:229], v[74:77]
	s_setprio 0
	s_setprio 1
	v_mfma_f32_16x16x32_bf16 v[118:121], v[168:171], v[184:187], v[118:121]
	v_mfma_f32_16x16x32_bf16 v[114:117], v[176:179], v[184:187], v[114:117]
	v_mfma_f32_16x16x32_bf16 v[102:105], v[168:171], v[198:201], v[102:105]
	v_mfma_f32_16x16x32_bf16 v[98:101], v[176:179], v[198:201], v[98:101]
	v_mfma_f32_16x16x32_bf16 v[86:89], v[168:171], v[214:217], v[86:89]
	v_mfma_f32_16x16x32_bf16 v[82:85], v[176:179], v[214:217], v[82:85]
	v_mfma_f32_16x16x32_bf16 v[70:73], v[168:171], v[222:225], v[70:73]
	v_mfma_f32_16x16x32_bf16 v[66:69], v[176:179], v[222:225], v[66:69]
	v_mfma_f32_16x16x32_bf16 v[118:121], v[172:175], v[188:191], v[118:121]
	v_mfma_f32_16x16x32_bf16 v[114:117], v[180:183], v[188:191], v[114:117]
	v_mfma_f32_16x16x32_bf16 v[102:105], v[172:175], v[210:213], v[102:105]
	v_mfma_f32_16x16x32_bf16 v[98:101], v[180:183], v[210:213], v[98:101]
	v_mfma_f32_16x16x32_bf16 v[86:89], v[172:175], v[218:221], v[86:89]
	v_mfma_f32_16x16x32_bf16 v[82:85], v[180:183], v[218:221], v[82:85]
	v_mfma_f32_16x16x32_bf16 v[70:73], v[172:175], v[226:229], v[70:73]
	s_barrier
	v_mfma_f32_16x16x32_bf16 v[66:69], v[180:183], v[226:229], v[66:69]
	s_setprio 0
	s_add_i32 s19, s19, s33
	v_lshl_add_u64 v[144:145], v[144:145], 0, s[10:11]
	s_mov_b32 m0, s19
	ds_read_b128 v[184:187], v150 offset:49152
	ds_read_b128 v[188:191], v150 offset:50176
	ds_read_b128 v[198:201], v150 offset:51200
	ds_read_b128 v[210:213], v150 offset:52224
	ds_read_b128 v[214:217], v150 offset:53248
	ds_read_b128 v[218:221], v150 offset:54272
	ds_read_b128 v[222:225], v150 offset:55296
	ds_read_b128 v[226:229], v150 offset:56320
	global_load_lds_dwordx4 v[144:145], off
	s_add_i32 m0, s19, 0x2000
	s_add_u32 s34, s34, 0x80080
	v_lshl_add_u64 v[144:145], v[192:193], 0, s[10:11]
	s_addc_u32 s35, s35, 0
	s_add_i32 s19, s38, s33
	global_load_lds_dwordx4 v[144:145], off
	v_lshl_add_u64 v[144:145], s[34:35], 0, v[132:133]
	s_mov_b32 m0, s19
	s_nop 0
	global_load_lds_dwordx4 v[144:145], off
	v_lshl_add_u64 v[144:145], s[34:35], 0, v[136:137]
	s_add_i32 m0, s19, 0x2000
	s_nop 0
	global_load_lds_dwordx4 v[144:145], off
	v_lshl_add_u64 v[144:145], v[202:203], 0, s[10:11]
	s_mov_b32 m0, s51
	s_nop 0
	global_load_lds_dwordx4 v[144:145], off
	v_lshl_add_u64 v[144:145], v[206:207], 0, s[10:11]
	s_mov_b32 m0, s52
	s_nop 0
	global_load_lds_dwordx4 v[144:145], off
	s_waitcnt vmcnt(8)
	s_waitcnt lgkmcnt(0)
	s_barrier
	s_setprio 1
	s_waitcnt lgkmcnt(0)
	v_mfma_f32_16x16x32_bf16 v[62:65], v[152:155], v[184:187], v[62:65]
	v_mfma_f32_16x16x32_bf16 v[58:61], v[160:163], v[184:187], v[58:61]
	v_mfma_f32_16x16x32_bf16 v[46:49], v[152:155], v[198:201], v[46:49]
	v_mfma_f32_16x16x32_bf16 v[42:45], v[160:163], v[198:201], v[42:45]
	v_mfma_f32_16x16x32_bf16 v[30:33], v[152:155], v[214:217], v[30:33]
	v_mfma_f32_16x16x32_bf16 v[26:29], v[160:163], v[214:217], v[26:29]
	v_mfma_f32_16x16x32_bf16 v[14:17], v[152:155], v[222:225], v[14:17]
	v_mfma_f32_16x16x32_bf16 v[10:13], v[160:163], v[222:225], v[10:13]
	v_mfma_f32_16x16x32_bf16 v[62:65], v[156:159], v[188:191], v[62:65]
	v_mfma_f32_16x16x32_bf16 v[58:61], v[164:167], v[188:191], v[58:61]
	v_mfma_f32_16x16x32_bf16 v[46:49], v[156:159], v[210:213], v[46:49]
	v_mfma_f32_16x16x32_bf16 v[42:45], v[164:167], v[210:213], v[42:45]
	v_mfma_f32_16x16x32_bf16 v[30:33], v[156:159], v[218:221], v[30:33]
	v_mfma_f32_16x16x32_bf16 v[26:29], v[164:167], v[218:221], v[26:29]
	v_mfma_f32_16x16x32_bf16 v[14:17], v[156:159], v[226:229], v[14:17]
	v_mfma_f32_16x16x32_bf16 v[10:13], v[164:167], v[226:229], v[10:13]
	s_setprio 0
	s_setprio 1
	v_mfma_f32_16x16x32_bf16 v[54:57], v[168:171], v[184:187], v[54:57]
	v_mfma_f32_16x16x32_bf16 v[50:53], v[176:179], v[184:187], v[50:53]
	v_mfma_f32_16x16x32_bf16 v[38:41], v[168:171], v[198:201], v[38:41]
	v_mfma_f32_16x16x32_bf16 v[34:37], v[176:179], v[198:201], v[34:37]
	v_mfma_f32_16x16x32_bf16 v[22:25], v[168:171], v[214:217], v[22:25]
	v_mfma_f32_16x16x32_bf16 v[18:21], v[176:179], v[214:217], v[18:21]
	v_mfma_f32_16x16x32_bf16 v[6:9], v[168:171], v[222:225], v[6:9]
	v_mfma_f32_16x16x32_bf16 v[2:5], v[176:179], v[222:225], v[2:5]
	v_mfma_f32_16x16x32_bf16 v[54:57], v[172:175], v[188:191], v[54:57]
	v_mfma_f32_16x16x32_bf16 v[50:53], v[180:183], v[188:191], v[50:53]
	v_mfma_f32_16x16x32_bf16 v[38:41], v[172:175], v[210:213], v[38:41]
	v_mfma_f32_16x16x32_bf16 v[34:37], v[180:183], v[210:213], v[34:37]
	v_mfma_f32_16x16x32_bf16 v[22:25], v[172:175], v[218:221], v[22:25]
	v_mfma_f32_16x16x32_bf16 v[18:21], v[180:183], v[218:221], v[18:21]
	v_mfma_f32_16x16x32_bf16 v[6:9], v[172:175], v[226:229], v[6:9]
	s_barrier
	v_mfma_f32_16x16x32_bf16 v[2:5], v[180:183], v[226:229], v[2:5]
	s_setprio 0
	s_add_u32 s30, s30, 0x100
	s_addc_u32 s31, s31, 0
	s_add_u32 s15, s15, 0x100
	s_addc_u32 s17, s17, 0
	s_cmp_ge_i32 s29, s68
	s_mov_b32 s19, s29
	s_cbranch_scc0 .LBB0_1315

.Lpeel_6:
	ds_read_b128 v[144:147], v166
	ds_read_b128 v[148:151], v166 offset:1024
	ds_read_b128 v[152:155], v166 offset:2048
	ds_read_b128 v[156:159], v166 offset:3072
	ds_read_b128 v[160:163], v167
	ds_read_b128 v[170:173], v167 offset:1024
	ds_read_b128 v[174:177], v167 offset:2048
	ds_read_b128 v[178:181], v167 offset:3072
	s_add_i32 s30, s26, 2
	s_add_u32 s27, s24, 0xffea0080
	s_addc_u32 s28, s25, -1
	s_cmp_eq_u32 s22, s26
	s_cselect_b32 s26, s20, s17
	s_cselect_b32 s29, s19, s28
	s_cselect_b32 s28, s18, s27
	s_cselect_b32 s27, s21, s23
	v_lshl_add_u64 v[202:203], s[24:25], 0, v[140:141]
	s_add_i32 m0, s34, 0xc000
	ds_read_b128 v[182:185], v168
	ds_read_b128 v[186:189], v168 offset:1024
	ds_read_b128 v[190:193], v168 offset:2048
	ds_read_b128 v[198:201], v168 offset:3072
	ds_read_b128 v[210:213], v168 offset:4096
	ds_read_b128 v[214:217], v168 offset:5120
	ds_read_b128 v[218:221], v168 offset:6144
	ds_read_b128 v[222:225], v168 offset:7168
	global_load_lds_dwordx4 v[202:203], off
	v_lshl_add_u64 v[202:203], s[24:25], 0, v[142:143]
	s_add_i32 m0, s34, 0xe000
	s_nop 0
	global_load_lds_dwordx4 v[202:203], off
	s_waitcnt vmcnt(8)
	s_waitcnt lgkmcnt(0)
	s_barrier
	s_setprio 1
	s_waitcnt lgkmcnt(0)
	v_mfma_f32_16x16x32_bf16 v[126:129], v[144:147], v[182:185], 0
	v_mfma_f32_16x16x32_bf16 v[122:125], v[152:155], v[182:185], 0
	v_mfma_f32_16x16x32_bf16 v[114:117], v[144:147], v[190:193], 0
	v_mfma_f32_16x16x32_bf16 v[106:109], v[152:155], v[190:193], 0
	v_mfma_f32_16x16x32_bf16 v[94:97], v[144:147], v[210:213], 0
	v_mfma_f32_16x16x32_bf16 v[90:93], v[152:155], v[210:213], 0
	v_mfma_f32_16x16x32_bf16 v[78:81], v[144:147], v[218:221], 0
	v_mfma_f32_16x16x32_bf16 v[74:77], v[152:155], v[218:221], 0
	v_mfma_f32_16x16x32_bf16 v[126:129], v[148:151], v[186:189], v[126:129]
	v_mfma_f32_16x16x32_bf16 v[122:125], v[156:159], v[186:189], v[122:125]
	v_mfma_f32_16x16x32_bf16 v[114:117], v[148:151], v[198:201], v[114:117]
	v_mfma_f32_16x16x32_bf16 v[106:109], v[156:159], v[198:201], v[106:109]
	v_mfma_f32_16x16x32_bf16 v[94:97], v[148:151], v[214:217], v[94:97]
	v_mfma_f32_16x16x32_bf16 v[90:93], v[156:159], v[214:217], v[90:93]
	v_mfma_f32_16x16x32_bf16 v[78:81], v[148:151], v[222:225], v[78:81]
	v_mfma_f32_16x16x32_bf16 v[74:77], v[156:159], v[222:225], v[74:77]
	s_setprio 0
	s_setprio 1
	v_mfma_f32_16x16x32_bf16 v[118:121], v[160:163], v[182:185], 0
	v_mfma_f32_16x16x32_bf16 v[110:113], v[174:177], v[182:185], 0
	v_mfma_f32_16x16x32_bf16 v[102:105], v[160:163], v[190:193], 0
	v_mfma_f32_16x16x32_bf16 v[98:101], v[174:177], v[190:193], 0
	v_mfma_f32_16x16x32_bf16 v[86:89], v[160:163], v[210:213], 0
	v_mfma_f32_16x16x32_bf16 v[82:85], v[174:177], v[210:213], 0
	v_mfma_f32_16x16x32_bf16 v[70:73], v[160:163], v[218:221], 0
	v_mfma_f32_16x16x32_bf16 v[66:69], v[174:177], v[218:221], 0
	v_mfma_f32_16x16x32_bf16 v[118:121], v[170:173], v[186:189], v[118:121]
	v_mfma_f32_16x16x32_bf16 v[110:113], v[178:181], v[186:189], v[110:113]
	v_mfma_f32_16x16x32_bf16 v[102:105], v[170:173], v[198:201], v[102:105]
	v_mfma_f32_16x16x32_bf16 v[98:101], v[178:181], v[198:201], v[98:101]
	v_mfma_f32_16x16x32_bf16 v[86:89], v[170:173], v[214:217], v[86:89]
	v_mfma_f32_16x16x32_bf16 v[82:85], v[178:181], v[214:217], v[82:85]
	v_mfma_f32_16x16x32_bf16 v[70:73], v[170:173], v[222:225], v[70:73]
	s_barrier
	v_mfma_f32_16x16x32_bf16 v[66:69], v[178:181], v[222:225], v[66:69]
	s_setprio 0
	s_add_i32 s31, s57, s33
	v_lshl_add_u64 v[202:203], s[26:27], 0, v[132:133]
	s_mov_b32 m0, s31
	ds_read_b128 v[182:185], v168 offset:16384
	ds_read_b128 v[186:189], v168 offset:17408
	ds_read_b128 v[190:193], v168 offset:18432
	ds_read_b128 v[198:201], v168 offset:19456
	ds_read_b128 v[210:213], v168 offset:20480
	ds_read_b128 v[214:217], v168 offset:21504
	ds_read_b128 v[218:221], v168 offset:22528
	ds_read_b128 v[222:225], v168 offset:23552
	global_load_lds_dwordx4 v[202:203], off
	s_add_i32 m0, s31, 0x2000
	s_add_u32 s68, s26, 0x160000
	v_lshl_add_u64 v[206:207], s[26:27], 0, v[136:137]
	s_addc_u32 s69, s27, 0
	s_add_i32 s31, s58, s33
	global_load_lds_dwordx4 v[206:207], off
	v_lshl_add_u64 v[226:227], s[68:69], 0, v[132:133]
	s_mov_b32 m0, s31
	v_lshl_add_u64 v[228:229], s[28:29], 0, v[134:135]
	global_load_lds_dwordx4 v[226:227], off
	v_lshl_add_u64 v[226:227], s[68:69], 0, v[136:137]
	s_add_i32 m0, s31, 0x2000
	s_nop 0
	global_load_lds_dwordx4 v[226:227], off
	v_lshl_add_u64 v[226:227], s[28:29], 0, v[130:131]
	s_mov_b32 m0, s34
	s_nop 0
	global_load_lds_dwordx4 v[226:227], off
	s_mov_b32 m0, s35
	s_nop 0
	global_load_lds_dwordx4 v[228:229], off
	s_waitcnt vmcnt(8)
	s_waitcnt lgkmcnt(0)
	s_barrier
	s_setprio 1
	s_waitcnt lgkmcnt(0)
	v_mfma_f32_16x16x32_bf16 v[62:65], v[144:147], v[182:185], 0
	v_mfma_f32_16x16x32_bf16 v[58:61], v[152:155], v[182:185], 0
	v_mfma_f32_16x16x32_bf16 v[46:49], v[144:147], v[190:193], 0
	v_mfma_f32_16x16x32_bf16 v[42:45], v[152:155], v[190:193], 0
	v_mfma_f32_16x16x32_bf16 v[30:33], v[144:147], v[210:213], 0
	v_mfma_f32_16x16x32_bf16 v[26:29], v[152:155], v[210:213], 0
	v_mfma_f32_16x16x32_bf16 v[14:17], v[144:147], v[218:221], 0
	v_mfma_f32_16x16x32_bf16 v[10:13], v[152:155], v[218:221], 0
	v_mfma_f32_16x16x32_bf16 v[62:65], v[148:151], v[186:189], v[62:65]
	v_mfma_f32_16x16x32_bf16 v[58:61], v[156:159], v[186:189], v[58:61]
	v_mfma_f32_16x16x32_bf16 v[46:49], v[148:151], v[198:201], v[46:49]
	v_mfma_f32_16x16x32_bf16 v[42:45], v[156:159], v[198:201], v[42:45]
	v_mfma_f32_16x16x32_bf16 v[30:33], v[148:151], v[214:217], v[30:33]
	v_mfma_f32_16x16x32_bf16 v[26:29], v[156:159], v[214:217], v[26:29]
	v_mfma_f32_16x16x32_bf16 v[14:17], v[148:151], v[222:225], v[14:17]
	v_mfma_f32_16x16x32_bf16 v[10:13], v[156:159], v[222:225], v[10:13]
	s_setprio 0
	s_setprio 1
	v_mfma_f32_16x16x32_bf16 v[54:57], v[160:163], v[182:185], 0
	v_mfma_f32_16x16x32_bf16 v[50:53], v[174:177], v[182:185], 0
	v_mfma_f32_16x16x32_bf16 v[38:41], v[160:163], v[190:193], 0
	v_mfma_f32_16x16x32_bf16 v[34:37], v[174:177], v[190:193], 0
	v_mfma_f32_16x16x32_bf16 v[22:25], v[160:163], v[210:213], 0
	v_mfma_f32_16x16x32_bf16 v[18:21], v[174:177], v[210:213], 0
	v_mfma_f32_16x16x32_bf16 v[6:9], v[160:163], v[218:221], 0
	v_mfma_f32_16x16x32_bf16 v[2:5], v[174:177], v[218:221], 0
	v_mfma_f32_16x16x32_bf16 v[54:57], v[170:173], v[186:189], v[54:57]
	v_mfma_f32_16x16x32_bf16 v[50:53], v[178:181], v[186:189], v[50:53]
	v_mfma_f32_16x16x32_bf16 v[38:41], v[170:173], v[198:201], v[38:41]
	v_mfma_f32_16x16x32_bf16 v[34:37], v[178:181], v[198:201], v[34:37]
	v_mfma_f32_16x16x32_bf16 v[22:25], v[170:173], v[214:217], v[22:25]
	v_mfma_f32_16x16x32_bf16 v[18:21], v[178:181], v[214:217], v[18:21]
	v_mfma_f32_16x16x32_bf16 v[6:9], v[170:173], v[222:225], v[6:9]
	s_barrier
	v_mfma_f32_16x16x32_bf16 v[2:5], v[178:181], v[222:225], v[2:5]
	s_setprio 0
	s_add_i32 s31, 0, 0x18000
	s_add_i32 s68, 0, 0x1c000
	v_add_u32_e32 v156, s31, v164
	v_add_u32_e32 v169, s68, v164
	ds_read_b128 v[144:147], v156
	ds_read_b128 v[148:151], v156 offset:1024
	ds_read_b128 v[152:155], v156 offset:2048
	ds_read_b128 v[156:159], v156 offset:3072
	ds_read_b128 v[160:163], v169
	ds_read_b128 v[170:173], v169 offset:1024
	ds_read_b128 v[174:177], v169 offset:2048
	ds_read_b128 v[178:181], v169 offset:3072
	s_add_u32 s28, s28, 0x160000
	s_addc_u32 s29, s29, 0
	s_mov_b32 m0, s36
	v_lshl_add_u64 v[230:231], s[28:29], 0, v[130:131]
	ds_read_b128 v[182:185], v168 offset:32768
	ds_read_b128 v[186:189], v168 offset:33792
	ds_read_b128 v[190:193], v168 offset:34816
	ds_read_b128 v[198:201], v168 offset:35840
	ds_read_b128 v[210:213], v168 offset:36864
	ds_read_b128 v[214:217], v168 offset:37888
	ds_read_b128 v[218:221], v168 offset:38912
	ds_read_b128 v[222:225], v168 offset:39936
	global_load_lds_dwordx4 v[230:231], off
	v_lshl_add_u64 v[230:231], s[28:29], 0, v[134:135]
	s_mov_b32 m0, s37
	s_nop 0
	global_load_lds_dwordx4 v[230:231], off
	s_waitcnt vmcnt(8)
	s_waitcnt lgkmcnt(0)
	s_barrier
	s_setprio 1
	s_waitcnt lgkmcnt(0)
	v_mfma_f32_16x16x32_bf16 v[126:129], v[144:147], v[182:185], v[126:129]
	v_mfma_f32_16x16x32_bf16 v[122:125], v[152:155], v[182:185], v[122:125]
	v_mfma_f32_16x16x32_bf16 v[114:117], v[144:147], v[190:193], v[114:117]
	v_mfma_f32_16x16x32_bf16 v[106:109], v[152:155], v[190:193], v[106:109]
	v_mfma_f32_16x16x32_bf16 v[94:97], v[144:147], v[210:213], v[94:97]
	v_mfma_f32_16x16x32_bf16 v[90:93], v[152:155], v[210:213], v[90:93]
	v_mfma_f32_16x16x32_bf16 v[78:81], v[144:147], v[218:221], v[78:81]
	v_mfma_f32_16x16x32_bf16 v[74:77], v[152:155], v[218:221], v[74:77]
	v_mfma_f32_16x16x32_bf16 v[126:129], v[148:151], v[186:189], v[126:129]
	v_mfma_f32_16x16x32_bf16 v[122:125], v[156:159], v[186:189], v[122:125]
	v_mfma_f32_16x16x32_bf16 v[114:117], v[148:151], v[198:201], v[114:117]
	v_mfma_f32_16x16x32_bf16 v[106:109], v[156:159], v[198:201], v[106:109]
	v_mfma_f32_16x16x32_bf16 v[94:97], v[148:151], v[214:217], v[94:97]
	v_mfma_f32_16x16x32_bf16 v[90:93], v[156:159], v[214:217], v[90:93]
	v_mfma_f32_16x16x32_bf16 v[78:81], v[148:151], v[222:225], v[78:81]
	v_mfma_f32_16x16x32_bf16 v[74:77], v[156:159], v[222:225], v[74:77]
	s_setprio 0
	s_setprio 1
	v_mfma_f32_16x16x32_bf16 v[118:121], v[160:163], v[182:185], v[118:121]
	v_mfma_f32_16x16x32_bf16 v[110:113], v[174:177], v[182:185], v[110:113]
	v_mfma_f32_16x16x32_bf16 v[102:105], v[160:163], v[190:193], v[102:105]
	v_mfma_f32_16x16x32_bf16 v[98:101], v[174:177], v[190:193], v[98:101]
	v_mfma_f32_16x16x32_bf16 v[86:89], v[160:163], v[210:213], v[86:89]
	v_mfma_f32_16x16x32_bf16 v[82:85], v[174:177], v[210:213], v[82:85]
	v_mfma_f32_16x16x32_bf16 v[70:73], v[160:163], v[218:221], v[70:73]
	v_mfma_f32_16x16x32_bf16 v[66:69], v[174:177], v[218:221], v[66:69]
	v_mfma_f32_16x16x32_bf16 v[118:121], v[170:173], v[186:189], v[118:121]
	v_mfma_f32_16x16x32_bf16 v[110:113], v[178:181], v[186:189], v[110:113]
	v_mfma_f32_16x16x32_bf16 v[102:105], v[170:173], v[198:201], v[102:105]
	v_mfma_f32_16x16x32_bf16 v[98:101], v[178:181], v[198:201], v[98:101]
	v_mfma_f32_16x16x32_bf16 v[86:89], v[170:173], v[214:217], v[86:89]
	v_mfma_f32_16x16x32_bf16 v[82:85], v[178:181], v[214:217], v[82:85]
	v_mfma_f32_16x16x32_bf16 v[70:73], v[170:173], v[222:225], v[70:73]
	s_barrier
	v_mfma_f32_16x16x32_bf16 v[66:69], v[178:181], v[222:225], v[66:69]
	s_setprio 0
	s_add_i32 s28, s31, s33
	v_lshl_add_u64 v[202:203], v[202:203], 0, s[12:13]
	s_mov_b32 m0, s28
	ds_read_b128 v[182:185], v168 offset:49152
	ds_read_b128 v[186:189], v168 offset:50176
	ds_read_b128 v[190:193], v168 offset:51200
	ds_read_b128 v[198:201], v168 offset:52224
	ds_read_b128 v[210:213], v168 offset:53248
	ds_read_b128 v[214:217], v168 offset:54272
	ds_read_b128 v[218:221], v168 offset:55296
	ds_read_b128 v[222:225], v168 offset:56320
	global_load_lds_dwordx4 v[202:203], off
	s_add_i32 m0, s28, 0x2000
	s_add_u32 s26, s26, 0x160080
	v_lshl_add_u64 v[202:203], v[206:207], 0, s[12:13]
	s_addc_u32 s27, s27, 0
	s_add_i32 s28, s68, s33
	global_load_lds_dwordx4 v[202:203], off
	v_lshl_add_u64 v[202:203], s[26:27], 0, v[132:133]
	s_mov_b32 m0, s28
	s_nop 0
	global_load_lds_dwordx4 v[202:203], off
	v_lshl_add_u64 v[202:203], s[26:27], 0, v[136:137]
	s_add_i32 m0, s28, 0x2000
	s_nop 0
	global_load_lds_dwordx4 v[202:203], off
	v_lshl_add_u64 v[202:203], v[226:227], 0, s[12:13]
	s_mov_b32 m0, s47
	s_nop 0
	global_load_lds_dwordx4 v[202:203], off
	v_lshl_add_u64 v[202:203], v[228:229], 0, s[12:13]
	s_mov_b32 m0, s48
	s_nop 0
	global_load_lds_dwordx4 v[202:203], off
	s_waitcnt vmcnt(8)
	s_waitcnt lgkmcnt(0)
	s_barrier
	s_setprio 1
	s_waitcnt lgkmcnt(0)
	v_mfma_f32_16x16x32_bf16 v[62:65], v[144:147], v[182:185], v[62:65]
	v_mfma_f32_16x16x32_bf16 v[58:61], v[152:155], v[182:185], v[58:61]
	v_mfma_f32_16x16x32_bf16 v[46:49], v[144:147], v[190:193], v[46:49]
	v_mfma_f32_16x16x32_bf16 v[42:45], v[152:155], v[190:193], v[42:45]
	v_mfma_f32_16x16x32_bf16 v[30:33], v[144:147], v[210:213], v[30:33]
	v_mfma_f32_16x16x32_bf16 v[26:29], v[152:155], v[210:213], v[26:29]
	v_mfma_f32_16x16x32_bf16 v[14:17], v[144:147], v[218:221], v[14:17]
	v_mfma_f32_16x16x32_bf16 v[10:13], v[152:155], v[218:221], v[10:13]
	v_mfma_f32_16x16x32_bf16 v[62:65], v[148:151], v[186:189], v[62:65]
	v_mfma_f32_16x16x32_bf16 v[58:61], v[156:159], v[186:189], v[58:61]
	v_mfma_f32_16x16x32_bf16 v[46:49], v[148:151], v[198:201], v[46:49]
	v_mfma_f32_16x16x32_bf16 v[42:45], v[156:159], v[198:201], v[42:45]
	v_mfma_f32_16x16x32_bf16 v[30:33], v[148:151], v[214:217], v[30:33]
	v_mfma_f32_16x16x32_bf16 v[26:29], v[156:159], v[214:217], v[26:29]
	v_mfma_f32_16x16x32_bf16 v[14:17], v[148:151], v[222:225], v[14:17]
	v_mfma_f32_16x16x32_bf16 v[10:13], v[156:159], v[222:225], v[10:13]
	s_setprio 0
	s_setprio 1
	v_mfma_f32_16x16x32_bf16 v[54:57], v[160:163], v[182:185], v[54:57]
	v_mfma_f32_16x16x32_bf16 v[50:53], v[174:177], v[182:185], v[50:53]
	v_mfma_f32_16x16x32_bf16 v[38:41], v[160:163], v[190:193], v[38:41]
	v_mfma_f32_16x16x32_bf16 v[34:37], v[174:177], v[190:193], v[34:37]
	v_mfma_f32_16x16x32_bf16 v[22:25], v[160:163], v[210:213], v[22:25]
	v_mfma_f32_16x16x32_bf16 v[18:21], v[174:177], v[210:213], v[18:21]
	v_mfma_f32_16x16x32_bf16 v[6:9], v[160:163], v[218:221], v[6:9]
	v_mfma_f32_16x16x32_bf16 v[2:5], v[174:177], v[218:221], v[2:5]
	v_mfma_f32_16x16x32_bf16 v[54:57], v[170:173], v[186:189], v[54:57]
	v_mfma_f32_16x16x32_bf16 v[50:53], v[178:181], v[186:189], v[50:53]
	v_mfma_f32_16x16x32_bf16 v[38:41], v[170:173], v[198:201], v[38:41]
	v_mfma_f32_16x16x32_bf16 v[34:37], v[178:181], v[198:201], v[34:37]
	v_mfma_f32_16x16x32_bf16 v[22:25], v[170:173], v[214:217], v[22:25]
	v_mfma_f32_16x16x32_bf16 v[18:21], v[178:181], v[214:217], v[18:21]
	v_mfma_f32_16x16x32_bf16 v[6:9], v[170:173], v[222:225], v[6:9]
	s_barrier
	v_mfma_f32_16x16x32_bf16 v[2:5], v[178:181], v[222:225], v[2:5]
	s_setprio 0
	s_add_u32 s24, s24, 0x100
	s_addc_u32 s25, s25, 0
	s_add_u32 s17, s17, 0x100
	s_addc_u32 s23, s23, 0
	s_cmp_ge_i32 s30, s67
	s_mov_b32 s26, s30
	s_cbranch_scc0 .LBB0_1451
	s_branch .Lpeeldone_6
.LBB0_1451:
	ds_read_b128 v[144:147], v166
	ds_read_b128 v[148:151], v166 offset:1024
	ds_read_b128 v[152:155], v166 offset:2048
	ds_read_b128 v[156:159], v166 offset:3072
	ds_read_b128 v[160:163], v167
	ds_read_b128 v[170:173], v167 offset:1024
	ds_read_b128 v[174:177], v167 offset:2048
	ds_read_b128 v[178:181], v167 offset:3072
	s_add_i32 s30, s26, 2
	s_add_u32 s27, s24, 0xffea0080
	s_addc_u32 s28, s25, -1
	s_cmp_eq_u32 s22, s26
	s_cselect_b32 s26, s20, s17
	s_cselect_b32 s29, s19, s28
	s_cselect_b32 s28, s18, s27
	s_cselect_b32 s27, s21, s23
	v_lshl_add_u64 v[202:203], s[24:25], 0, v[140:141]
	s_add_i32 m0, s34, 0xc000
	ds_read_b128 v[182:185], v168
	ds_read_b128 v[186:189], v168 offset:1024
	ds_read_b128 v[190:193], v168 offset:2048
	ds_read_b128 v[198:201], v168 offset:3072
	ds_read_b128 v[210:213], v168 offset:4096
	ds_read_b128 v[214:217], v168 offset:5120
	ds_read_b128 v[218:221], v168 offset:6144
	ds_read_b128 v[222:225], v168 offset:7168
	global_load_lds_dwordx4 v[202:203], off
	v_lshl_add_u64 v[202:203], s[24:25], 0, v[142:143]
	s_add_i32 m0, s34, 0xe000
	s_nop 0
	global_load_lds_dwordx4 v[202:203], off
	s_waitcnt vmcnt(8)
	s_waitcnt lgkmcnt(0)
	s_barrier
	s_setprio 1
	s_waitcnt lgkmcnt(0)
	v_mfma_f32_16x16x32_bf16 v[126:129], v[144:147], v[182:185], v[126:129]
	v_mfma_f32_16x16x32_bf16 v[122:125], v[152:155], v[182:185], v[122:125]
	v_mfma_f32_16x16x32_bf16 v[114:117], v[144:147], v[190:193], v[114:117]
	v_mfma_f32_16x16x32_bf16 v[106:109], v[152:155], v[190:193], v[106:109]
	v_mfma_f32_16x16x32_bf16 v[94:97], v[144:147], v[210:213], v[94:97]
	v_mfma_f32_16x16x32_bf16 v[90:93], v[152:155], v[210:213], v[90:93]
	v_mfma_f32_16x16x32_bf16 v[78:81], v[144:147], v[218:221], v[78:81]
	v_mfma_f32_16x16x32_bf16 v[74:77], v[152:155], v[218:221], v[74:77]
	v_mfma_f32_16x16x32_bf16 v[126:129], v[148:151], v[186:189], v[126:129]
	v_mfma_f32_16x16x32_bf16 v[122:125], v[156:159], v[186:189], v[122:125]
	v_mfma_f32_16x16x32_bf16 v[114:117], v[148:151], v[198:201], v[114:117]
	v_mfma_f32_16x16x32_bf16 v[106:109], v[156:159], v[198:201], v[106:109]
	v_mfma_f32_16x16x32_bf16 v[94:97], v[148:151], v[214:217], v[94:97]
	v_mfma_f32_16x16x32_bf16 v[90:93], v[156:159], v[214:217], v[90:93]
	v_mfma_f32_16x16x32_bf16 v[78:81], v[148:151], v[222:225], v[78:81]
	v_mfma_f32_16x16x32_bf16 v[74:77], v[156:159], v[222:225], v[74:77]
	s_setprio 0
	s_setprio 1
	v_mfma_f32_16x16x32_bf16 v[118:121], v[160:163], v[182:185], v[118:121]
	v_mfma_f32_16x16x32_bf16 v[110:113], v[174:177], v[182:185], v[110:113]
	v_mfma_f32_16x16x32_bf16 v[102:105], v[160:163], v[190:193], v[102:105]
	v_mfma_f32_16x16x32_bf16 v[98:101], v[174:177], v[190:193], v[98:101]
	v_mfma_f32_16x16x32_bf16 v[86:89], v[160:163], v[210:213], v[86:89]
	v_mfma_f32_16x16x32_bf16 v[82:85], v[174:177], v[210:213], v[82:85]
	v_mfma_f32_16x16x32_bf16 v[70:73], v[160:163], v[218:221], v[70:73]
	v_mfma_f32_16x16x32_bf16 v[66:69], v[174:177], v[218:221], v[66:69]
	v_mfma_f32_16x16x32_bf16 v[118:121], v[170:173], v[186:189], v[118:121]
	v_mfma_f32_16x16x32_bf16 v[110:113], v[178:181], v[186:189], v[110:113]
	v_mfma_f32_16x16x32_bf16 v[102:105], v[170:173], v[198:201], v[102:105]
	v_mfma_f32_16x16x32_bf16 v[98:101], v[178:181], v[198:201], v[98:101]
	v_mfma_f32_16x16x32_bf16 v[86:89], v[170:173], v[214:217], v[86:89]
	v_mfma_f32_16x16x32_bf16 v[82:85], v[178:181], v[214:217], v[82:85]
	v_mfma_f32_16x16x32_bf16 v[70:73], v[170:173], v[222:225], v[70:73]
	s_barrier
	v_mfma_f32_16x16x32_bf16 v[66:69], v[178:181], v[222:225], v[66:69]
	s_setprio 0
	s_add_i32 s31, s57, s33
	v_lshl_add_u64 v[202:203], s[26:27], 0, v[132:133]
	s_mov_b32 m0, s31
	ds_read_b128 v[182:185], v168 offset:16384
	ds_read_b128 v[186:189], v168 offset:17408
	ds_read_b128 v[190:193], v168 offset:18432
	ds_read_b128 v[198:201], v168 offset:19456
	ds_read_b128 v[210:213], v168 offset:20480
	ds_read_b128 v[214:217], v168 offset:21504
	ds_read_b128 v[218:221], v168 offset:22528
	ds_read_b128 v[222:225], v168 offset:23552
	global_load_lds_dwordx4 v[202:203], off
	s_add_i32 m0, s31, 0x2000
	s_add_u32 s68, s26, 0x160000
	v_lshl_add_u64 v[206:207], s[26:27], 0, v[136:137]
	s_addc_u32 s69, s27, 0
	s_add_i32 s31, s58, s33
	global_load_lds_dwordx4 v[206:207], off
	v_lshl_add_u64 v[226:227], s[68:69], 0, v[132:133]
	s_mov_b32 m0, s31
	v_lshl_add_u64 v[228:229], s[28:29], 0, v[134:135]
	global_load_lds_dwordx4 v[226:227], off
	v_lshl_add_u64 v[226:227], s[68:69], 0, v[136:137]
	s_add_i32 m0, s31, 0x2000
	s_nop 0
	global_load_lds_dwordx4 v[226:227], off
	v_lshl_add_u64 v[226:227], s[28:29], 0, v[130:131]
	s_mov_b32 m0, s34
	s_nop 0
	global_load_lds_dwordx4 v[226:227], off
	s_mov_b32 m0, s35
	s_nop 0
	global_load_lds_dwordx4 v[228:229], off
	s_waitcnt vmcnt(8)
	s_waitcnt lgkmcnt(0)
	s_barrier
	s_setprio 1
	s_waitcnt lgkmcnt(0)
	v_mfma_f32_16x16x32_bf16 v[62:65], v[144:147], v[182:185], v[62:65]
	v_mfma_f32_16x16x32_bf16 v[58:61], v[152:155], v[182:185], v[58:61]
	v_mfma_f32_16x16x32_bf16 v[46:49], v[144:147], v[190:193], v[46:49]
	v_mfma_f32_16x16x32_bf16 v[42:45], v[152:155], v[190:193], v[42:45]
	v_mfma_f32_16x16x32_bf16 v[30:33], v[144:147], v[210:213], v[30:33]
	v_mfma_f32_16x16x32_bf16 v[26:29], v[152:155], v[210:213], v[26:29]
	v_mfma_f32_16x16x32_bf16 v[14:17], v[144:147], v[218:221], v[14:17]
	v_mfma_f32_16x16x32_bf16 v[10:13], v[152:155], v[218:221], v[10:13]
	v_mfma_f32_16x16x32_bf16 v[62:65], v[148:151], v[186:189], v[62:65]
	v_mfma_f32_16x16x32_bf16 v[58:61], v[156:159], v[186:189], v[58:61]
	v_mfma_f32_16x16x32_bf16 v[46:49], v[148:151], v[198:201], v[46:49]
	v_mfma_f32_16x16x32_bf16 v[42:45], v[156:159], v[198:201], v[42:45]
	v_mfma_f32_16x16x32_bf16 v[30:33], v[148:151], v[214:217], v[30:33]
	v_mfma_f32_16x16x32_bf16 v[26:29], v[156:159], v[214:217], v[26:29]
	v_mfma_f32_16x16x32_bf16 v[14:17], v[148:151], v[222:225], v[14:17]
	v_mfma_f32_16x16x32_bf16 v[10:13], v[156:159], v[222:225], v[10:13]
	s_setprio 0
	s_setprio 1
	v_mfma_f32_16x16x32_bf16 v[54:57], v[160:163], v[182:185], v[54:57]
	v_mfma_f32_16x16x32_bf16 v[50:53], v[174:177], v[182:185], v[50:53]
	v_mfma_f32_16x16x32_bf16 v[38:41], v[160:163], v[190:193], v[38:41]
	v_mfma_f32_16x16x32_bf16 v[34:37], v[174:177], v[190:193], v[34:37]
	v_mfma_f32_16x16x32_bf16 v[22:25], v[160:163], v[210:213], v[22:25]
	v_mfma_f32_16x16x32_bf16 v[18:21], v[174:177], v[210:213], v[18:21]
	v_mfma_f32_16x16x32_bf16 v[6:9], v[160:163], v[218:221], v[6:9]
	v_mfma_f32_16x16x32_bf16 v[2:5], v[174:177], v[218:221], v[2:5]
	v_mfma_f32_16x16x32_bf16 v[54:57], v[170:173], v[186:189], v[54:57]
	v_mfma_f32_16x16x32_bf16 v[50:53], v[178:181], v[186:189], v[50:53]
	v_mfma_f32_16x16x32_bf16 v[38:41], v[170:173], v[198:201], v[38:41]
	v_mfma_f32_16x16x32_bf16 v[34:37], v[178:181], v[198:201], v[34:37]
	v_mfma_f32_16x16x32_bf16 v[22:25], v[170:173], v[214:217], v[22:25]
	v_mfma_f32_16x16x32_bf16 v[18:21], v[178:181], v[214:217], v[18:21]
	v_mfma_f32_16x16x32_bf16 v[6:9], v[170:173], v[222:225], v[6:9]
	s_barrier
	v_mfma_f32_16x16x32_bf16 v[2:5], v[178:181], v[222:225], v[2:5]
	s_setprio 0
	s_add_i32 s31, 0, 0x18000
	s_add_i32 s68, 0, 0x1c000
	v_add_u32_e32 v156, s31, v164
	v_add_u32_e32 v169, s68, v164
	ds_read_b128 v[144:147], v156
	ds_read_b128 v[148:151], v156 offset:1024
	ds_read_b128 v[152:155], v156 offset:2048
	ds_read_b128 v[156:159], v156 offset:3072
	ds_read_b128 v[160:163], v169
	ds_read_b128 v[170:173], v169 offset:1024
	ds_read_b128 v[174:177], v169 offset:2048
	ds_read_b128 v[178:181], v169 offset:3072
	s_add_u32 s28, s28, 0x160000
	s_addc_u32 s29, s29, 0
	s_mov_b32 m0, s36
	v_lshl_add_u64 v[230:231], s[28:29], 0, v[130:131]
	ds_read_b128 v[182:185], v168 offset:32768
	ds_read_b128 v[186:189], v168 offset:33792
	ds_read_b128 v[190:193], v168 offset:34816
	ds_read_b128 v[198:201], v168 offset:35840
	ds_read_b128 v[210:213], v168 offset:36864
	ds_read_b128 v[214:217], v168 offset:37888
	ds_read_b128 v[218:221], v168 offset:38912
	ds_read_b128 v[222:225], v168 offset:39936
	global_load_lds_dwordx4 v[230:231], off
	v_lshl_add_u64 v[230:231], s[28:29], 0, v[134:135]
	s_mov_b32 m0, s37
	s_nop 0
	global_load_lds_dwordx4 v[230:231], off
	s_waitcnt vmcnt(8)
	s_waitcnt lgkmcnt(0)
	s_barrier
	s_setprio 1
	s_waitcnt lgkmcnt(0)
	v_mfma_f32_16x16x32_bf16 v[126:129], v[144:147], v[182:185], v[126:129]
	v_mfma_f32_16x16x32_bf16 v[122:125], v[152:155], v[182:185], v[122:125]
	v_mfma_f32_16x16x32_bf16 v[114:117], v[144:147], v[190:193], v[114:117]
	v_mfma_f32_16x16x32_bf16 v[106:109], v[152:155], v[190:193], v[106:109]
	v_mfma_f32_16x16x32_bf16 v[94:97], v[144:147], v[210:213], v[94:97]
	v_mfma_f32_16x16x32_bf16 v[90:93], v[152:155], v[210:213], v[90:93]
	v_mfma_f32_16x16x32_bf16 v[78:81], v[144:147], v[218:221], v[78:81]
	v_mfma_f32_16x16x32_bf16 v[74:77], v[152:155], v[218:221], v[74:77]
	v_mfma_f32_16x16x32_bf16 v[126:129], v[148:151], v[186:189], v[126:129]
	v_mfma_f32_16x16x32_bf16 v[122:125], v[156:159], v[186:189], v[122:125]
	v_mfma_f32_16x16x32_bf16 v[114:117], v[148:151], v[198:201], v[114:117]
	v_mfma_f32_16x16x32_bf16 v[106:109], v[156:159], v[198:201], v[106:109]
	v_mfma_f32_16x16x32_bf16 v[94:97], v[148:151], v[214:217], v[94:97]
	v_mfma_f32_16x16x32_bf16 v[90:93], v[156:159], v[214:217], v[90:93]
	v_mfma_f32_16x16x32_bf16 v[78:81], v[148:151], v[222:225], v[78:81]
	v_mfma_f32_16x16x32_bf16 v[74:77], v[156:159], v[222:225], v[74:77]
	s_setprio 0
	s_setprio 1
	v_mfma_f32_16x16x32_bf16 v[118:121], v[160:163], v[182:185], v[118:121]
	v_mfma_f32_16x16x32_bf16 v[110:113], v[174:177], v[182:185], v[110:113]
	v_mfma_f32_16x16x32_bf16 v[102:105], v[160:163], v[190:193], v[102:105]
	v_mfma_f32_16x16x32_bf16 v[98:101], v[174:177], v[190:193], v[98:101]
	v_mfma_f32_16x16x32_bf16 v[86:89], v[160:163], v[210:213], v[86:89]
	v_mfma_f32_16x16x32_bf16 v[82:85], v[174:177], v[210:213], v[82:85]
	v_mfma_f32_16x16x32_bf16 v[70:73], v[160:163], v[218:221], v[70:73]
	v_mfma_f32_16x16x32_bf16 v[66:69], v[174:177], v[218:221], v[66:69]
	v_mfma_f32_16x16x32_bf16 v[118:121], v[170:173], v[186:189], v[118:121]
	v_mfma_f32_16x16x32_bf16 v[110:113], v[178:181], v[186:189], v[110:113]
	v_mfma_f32_16x16x32_bf16 v[102:105], v[170:173], v[198:201], v[102:105]
	v_mfma_f32_16x16x32_bf16 v[98:101], v[178:181], v[198:201], v[98:101]
	v_mfma_f32_16x16x32_bf16 v[86:89], v[170:173], v[214:217], v[86:89]
	v_mfma_f32_16x16x32_bf16 v[82:85], v[178:181], v[214:217], v[82:85]
	v_mfma_f32_16x16x32_bf16 v[70:73], v[170:173], v[222:225], v[70:73]
	s_barrier
	v_mfma_f32_16x16x32_bf16 v[66:69], v[178:181], v[222:225], v[66:69]
	s_setprio 0
	s_add_i32 s28, s31, s33
	v_lshl_add_u64 v[202:203], v[202:203], 0, s[12:13]
	s_mov_b32 m0, s28
	ds_read_b128 v[182:185], v168 offset:49152
	ds_read_b128 v[186:189], v168 offset:50176
	ds_read_b128 v[190:193], v168 offset:51200
	ds_read_b128 v[198:201], v168 offset:52224
	ds_read_b128 v[210:213], v168 offset:53248
	ds_read_b128 v[214:217], v168 offset:54272
	ds_read_b128 v[218:221], v168 offset:55296
	ds_read_b128 v[222:225], v168 offset:56320
	global_load_lds_dwordx4 v[202:203], off
	s_add_i32 m0, s28, 0x2000
	s_add_u32 s26, s26, 0x160080
	v_lshl_add_u64 v[202:203], v[206:207], 0, s[12:13]
	s_addc_u32 s27, s27, 0
	s_add_i32 s28, s68, s33
	global_load_lds_dwordx4 v[202:203], off
	v_lshl_add_u64 v[202:203], s[26:27], 0, v[132:133]
	s_mov_b32 m0, s28
	s_nop 0
	global_load_lds_dwordx4 v[202:203], off
	v_lshl_add_u64 v[202:203], s[26:27], 0, v[136:137]
	s_add_i32 m0, s28, 0x2000
	s_nop 0
	global_load_lds_dwordx4 v[202:203], off
	v_lshl_add_u64 v[202:203], v[226:227], 0, s[12:13]
	s_mov_b32 m0, s47
	s_nop 0
	global_load_lds_dwordx4 v[202:203], off
	v_lshl_add_u64 v[202:203], v[228:229], 0, s[12:13]
	s_mov_b32 m0, s48
	s_nop 0
	global_load_lds_dwordx4 v[202:203], off
	s_waitcnt vmcnt(8)
	s_waitcnt lgkmcnt(0)
	s_barrier
	s_setprio 1
	s_waitcnt lgkmcnt(0)
	v_mfma_f32_16x16x32_bf16 v[62:65], v[144:147], v[182:185], v[62:65]
	v_mfma_f32_16x16x32_bf16 v[58:61], v[152:155], v[182:185], v[58:61]
	v_mfma_f32_16x16x32_bf16 v[46:49], v[144:147], v[190:193], v[46:49]
	v_mfma_f32_16x16x32_bf16 v[42:45], v[152:155], v[190:193], v[42:45]
	v_mfma_f32_16x16x32_bf16 v[30:33], v[144:147], v[210:213], v[30:33]
	v_mfma_f32_16x16x32_bf16 v[26:29], v[152:155], v[210:213], v[26:29]
	v_mfma_f32_16x16x32_bf16 v[14:17], v[144:147], v[218:221], v[14:17]
	v_mfma_f32_16x16x32_bf16 v[10:13], v[152:155], v[218:221], v[10:13]
	v_mfma_f32_16x16x32_bf16 v[62:65], v[148:151], v[186:189], v[62:65]
	v_mfma_f32_16x16x32_bf16 v[58:61], v[156:159], v[186:189], v[58:61]
	v_mfma_f32_16x16x32_bf16 v[46:49], v[148:151], v[198:201], v[46:49]
	v_mfma_f32_16x16x32_bf16 v[42:45], v[156:159], v[198:201], v[42:45]
	v_mfma_f32_16x16x32_bf16 v[30:33], v[148:151], v[214:217], v[30:33]
	v_mfma_f32_16x16x32_bf16 v[26:29], v[156:159], v[214:217], v[26:29]
	v_mfma_f32_16x16x32_bf16 v[14:17], v[148:151], v[222:225], v[14:17]
	v_mfma_f32_16x16x32_bf16 v[10:13], v[156:159], v[222:225], v[10:13]
	s_setprio 0
	s_setprio 1
	v_mfma_f32_16x16x32_bf16 v[54:57], v[160:163], v[182:185], v[54:57]
	v_mfma_f32_16x16x32_bf16 v[50:53], v[174:177], v[182:185], v[50:53]
	v_mfma_f32_16x16x32_bf16 v[38:41], v[160:163], v[190:193], v[38:41]
	v_mfma_f32_16x16x32_bf16 v[34:37], v[174:177], v[190:193], v[34:37]
	v_mfma_f32_16x16x32_bf16 v[22:25], v[160:163], v[210:213], v[22:25]
	v_mfma_f32_16x16x32_bf16 v[18:21], v[174:177], v[210:213], v[18:21]
	v_mfma_f32_16x16x32_bf16 v[6:9], v[160:163], v[218:221], v[6:9]
	v_mfma_f32_16x16x32_bf16 v[2:5], v[174:177], v[218:221], v[2:5]
	v_mfma_f32_16x16x32_bf16 v[54:57], v[170:173], v[186:189], v[54:57]
	v_mfma_f32_16x16x32_bf16 v[50:53], v[178:181], v[186:189], v[50:53]
	v_mfma_f32_16x16x32_bf16 v[38:41], v[170:173], v[198:201], v[38:41]
	v_mfma_f32_16x16x32_bf16 v[34:37], v[178:181], v[198:201], v[34:37]
	v_mfma_f32_16x16x32_bf16 v[22:25], v[170:173], v[214:217], v[22:25]
	v_mfma_f32_16x16x32_bf16 v[18:21], v[178:181], v[214:217], v[18:21]
	v_mfma_f32_16x16x32_bf16 v[6:9], v[170:173], v[222:225], v[6:9]
	s_barrier
	v_mfma_f32_16x16x32_bf16 v[2:5], v[178:181], v[222:225], v[2:5]
	s_setprio 0
	s_add_u32 s24, s24, 0x100
	s_addc_u32 s25, s25, 0
	s_add_u32 s17, s17, 0x100
	s_addc_u32 s23, s23, 0
	s_cmp_ge_i32 s30, s67
	s_mov_b32 s26, s30
	s_cbranch_scc0 .LBB0_1451

.Lpeel_3:
	s_add_i32 s29, s23, 2
	s_add_u32 s34, s30, 0xfff80080
	s_addc_u32 s35, s31, -1
	s_cmp_eq_u32 s28, s23
	s_cselect_b32 s37, s25, s35
	s_cselect_b32 s36, s24, s34
	s_cselect_b32 s35, s27, s21
	s_cselect_b32 s34, s26, s19
	v_lshl_add_u64 v[202:203], s[30:31], 0, v[140:141]
	s_add_i32 m0, s15, 0xc000
	global_load_lds_dwordx4 v[202:203], off
	v_lshl_add_u64 v[202:203], s[30:31], 0, v[142:143]
	s_add_i32 m0, s15, 0xe000
	s_nop 0
	global_load_lds_dwordx4 v[202:203], off
	s_waitcnt vmcnt(8)
	s_waitcnt lgkmcnt(0)
	s_barrier
	s_setprio 1
	s_waitcnt lgkmcnt(0)
	v_mfma_f32_16x16x32_bf16 v[126:129], v[150:153], v[182:185], 0
	v_mfma_f32_16x16x32_bf16 v[122:125], v[158:161], v[182:185], 0
	v_mfma_f32_16x16x32_bf16 v[118:121], v[150:153], v[190:193], 0
	v_mfma_f32_16x16x32_bf16 v[114:117], v[158:161], v[190:193], 0
	v_mfma_f32_16x16x32_bf16 v[110:113], v[150:153], v[210:213], 0
	v_mfma_f32_16x16x32_bf16 v[106:109], v[158:161], v[210:213], 0
	v_mfma_f32_16x16x32_bf16 v[102:105], v[150:153], v[218:221], 0
	v_mfma_f32_16x16x32_bf16 v[98:101], v[158:161], v[218:221], 0
	v_mfma_f32_16x16x32_bf16 v[126:129], v[154:157], v[186:189], v[126:129]
	v_mfma_f32_16x16x32_bf16 v[122:125], v[162:165], v[186:189], v[122:125]
	v_mfma_f32_16x16x32_bf16 v[118:121], v[154:157], v[198:201], v[118:121]
	v_mfma_f32_16x16x32_bf16 v[114:117], v[162:165], v[198:201], v[114:117]
	v_mfma_f32_16x16x32_bf16 v[110:113], v[154:157], v[214:217], v[110:113]
	v_mfma_f32_16x16x32_bf16 v[106:109], v[162:165], v[214:217], v[106:109]
	v_mfma_f32_16x16x32_bf16 v[102:105], v[154:157], v[222:225], v[102:105]
	v_mfma_f32_16x16x32_bf16 v[98:101], v[162:165], v[222:225], v[98:101]
	s_setprio 0
	s_setprio 1
	v_mfma_f32_16x16x32_bf16 v[94:97], v[166:169], v[182:185], 0
	v_mfma_f32_16x16x32_bf16 v[90:93], v[174:177], v[182:185], 0
	v_mfma_f32_16x16x32_bf16 v[86:89], v[166:169], v[190:193], 0
	v_mfma_f32_16x16x32_bf16 v[82:85], v[174:177], v[190:193], 0
	v_mfma_f32_16x16x32_bf16 v[78:81], v[166:169], v[210:213], 0
	v_mfma_f32_16x16x32_bf16 v[74:77], v[174:177], v[210:213], 0
	v_mfma_f32_16x16x32_bf16 v[70:73], v[166:169], v[218:221], 0
	v_mfma_f32_16x16x32_bf16 v[66:69], v[174:177], v[218:221], 0
	v_mfma_f32_16x16x32_bf16 v[94:97], v[170:173], v[186:189], v[94:97]
	v_mfma_f32_16x16x32_bf16 v[90:93], v[178:181], v[186:189], v[90:93]
	v_mfma_f32_16x16x32_bf16 v[86:89], v[170:173], v[198:201], v[86:89]
	v_mfma_f32_16x16x32_bf16 v[82:85], v[178:181], v[198:201], v[82:85]
	v_mfma_f32_16x16x32_bf16 v[78:81], v[170:173], v[214:217], v[78:81]
	v_mfma_f32_16x16x32_bf16 v[74:77], v[178:181], v[214:217], v[74:77]
	v_mfma_f32_16x16x32_bf16 v[70:73], v[170:173], v[222:225], v[70:73]
	s_barrier
	v_mfma_f32_16x16x32_bf16 v[66:69], v[178:181], v[222:225], v[66:69]
	s_setprio 0
	s_add_i32 s23, s60, s33
	v_lshl_add_u64 v[202:203], s[34:35], 0, v[132:133]
	s_mov_b32 m0, s23
	ds_read_b128 v[182:185], v148 offset:16384
	ds_read_b128 v[186:189], v148 offset:17408
	ds_read_b128 v[190:193], v148 offset:18432
	ds_read_b128 v[198:201], v148 offset:19456
	ds_read_b128 v[210:213], v148 offset:20480
	ds_read_b128 v[214:217], v148 offset:21504
	ds_read_b128 v[218:221], v148 offset:22528
	ds_read_b128 v[222:225], v148 offset:23552
	global_load_lds_dwordx4 v[202:203], off
	s_add_i32 m0, s23, 0x2000
	s_add_u32 s38, s34, 0x80000
	v_lshl_add_u64 v[206:207], s[34:35], 0, v[136:137]
	s_addc_u32 s39, s35, 0
	s_add_i32 s23, s61, s33
	global_load_lds_dwordx4 v[206:207], off
	v_lshl_add_u64 v[226:227], s[38:39], 0, v[132:133]
	s_mov_b32 m0, s23
	v_lshl_add_u64 v[228:229], s[36:37], 0, v[134:135]
	global_load_lds_dwordx4 v[226:227], off
	v_lshl_add_u64 v[226:227], s[38:39], 0, v[136:137]
	s_add_i32 m0, s23, 0x2000
	s_nop 0
	global_load_lds_dwordx4 v[226:227], off
	v_lshl_add_u64 v[226:227], s[36:37], 0, v[130:131]
	s_mov_b32 m0, s15
	s_nop 0
	global_load_lds_dwordx4 v[226:227], off
	s_mov_b32 m0, s41
	s_nop 0
	global_load_lds_dwordx4 v[228:229], off
	s_waitcnt vmcnt(8)
	s_waitcnt lgkmcnt(0)
	s_barrier
	s_setprio 1
	s_waitcnt lgkmcnt(0)
	v_mfma_f32_16x16x32_bf16 v[62:65], v[150:153], v[182:185], 0
	v_mfma_f32_16x16x32_bf16 v[58:61], v[158:161], v[182:185], 0
	v_mfma_f32_16x16x32_bf16 v[54:57], v[150:153], v[190:193], 0
	v_mfma_f32_16x16x32_bf16 v[50:53], v[158:161], v[190:193], 0
	v_mfma_f32_16x16x32_bf16 v[46:49], v[150:153], v[210:213], 0
	v_mfma_f32_16x16x32_bf16 v[42:45], v[158:161], v[210:213], 0
	v_mfma_f32_16x16x32_bf16 v[38:41], v[150:153], v[218:221], 0
	v_mfma_f32_16x16x32_bf16 v[34:37], v[158:161], v[218:221], 0
	v_mfma_f32_16x16x32_bf16 v[62:65], v[154:157], v[186:189], v[62:65]
	v_mfma_f32_16x16x32_bf16 v[58:61], v[162:165], v[186:189], v[58:61]
	v_mfma_f32_16x16x32_bf16 v[54:57], v[154:157], v[198:201], v[54:57]
	v_mfma_f32_16x16x32_bf16 v[50:53], v[162:165], v[198:201], v[50:53]
	v_mfma_f32_16x16x32_bf16 v[46:49], v[154:157], v[214:217], v[46:49]
	v_mfma_f32_16x16x32_bf16 v[42:45], v[162:165], v[214:217], v[42:45]
	v_mfma_f32_16x16x32_bf16 v[38:41], v[154:157], v[222:225], v[38:41]
	v_mfma_f32_16x16x32_bf16 v[34:37], v[162:165], v[222:225], v[34:37]
	s_setprio 0
	s_setprio 1
	v_mfma_f32_16x16x32_bf16 v[30:33], v[166:169], v[182:185], 0
	v_mfma_f32_16x16x32_bf16 v[26:29], v[174:177], v[182:185], 0
	v_mfma_f32_16x16x32_bf16 v[22:25], v[166:169], v[190:193], 0
	v_mfma_f32_16x16x32_bf16 v[18:21], v[174:177], v[190:193], 0
	v_mfma_f32_16x16x32_bf16 v[14:17], v[166:169], v[210:213], 0
	v_mfma_f32_16x16x32_bf16 v[10:13], v[174:177], v[210:213], 0
	v_mfma_f32_16x16x32_bf16 v[6:9], v[166:169], v[218:221], 0
	v_mfma_f32_16x16x32_bf16 v[2:5], v[174:177], v[218:221], 0
	v_mfma_f32_16x16x32_bf16 v[30:33], v[170:173], v[186:189], v[30:33]
	v_mfma_f32_16x16x32_bf16 v[26:29], v[178:181], v[186:189], v[26:29]
	v_mfma_f32_16x16x32_bf16 v[22:25], v[170:173], v[198:201], v[22:25]
	v_mfma_f32_16x16x32_bf16 v[18:21], v[178:181], v[198:201], v[18:21]
	v_mfma_f32_16x16x32_bf16 v[14:17], v[170:173], v[214:217], v[14:17]
	v_mfma_f32_16x16x32_bf16 v[10:13], v[178:181], v[214:217], v[10:13]
	v_mfma_f32_16x16x32_bf16 v[6:9], v[170:173], v[222:225], v[6:9]
	s_barrier
	v_mfma_f32_16x16x32_bf16 v[2:5], v[178:181], v[222:225], v[2:5]
	s_setprio 0
	s_add_i32 s23, 0, 0x18000
	v_add_u32_e32 v149, s23, v144
	s_add_i32 s38, 0, 0x1c000
	ds_read_b128 v[150:153], v149
	ds_read_b128 v[154:157], v149 offset:1024
	ds_read_b128 v[158:161], v149 offset:2048
	ds_read_b128 v[162:165], v149 offset:3072
	v_add_u32_e32 v149, s38, v144
	ds_read_b128 v[166:169], v149
	ds_read_b128 v[170:173], v149 offset:1024
	ds_read_b128 v[174:177], v149 offset:2048
	ds_read_b128 v[178:181], v149 offset:3072
	s_add_u32 s36, s36, 0x80000
	s_addc_u32 s37, s37, 0
	s_mov_b32 m0, s42
	v_lshl_add_u64 v[230:231], s[36:37], 0, v[130:131]
	ds_read_b128 v[182:185], v148 offset:32768
	ds_read_b128 v[186:189], v148 offset:33792
	ds_read_b128 v[190:193], v148 offset:34816
	ds_read_b128 v[198:201], v148 offset:35840
	ds_read_b128 v[210:213], v148 offset:36864
	ds_read_b128 v[214:217], v148 offset:37888
	ds_read_b128 v[218:221], v148 offset:38912
	ds_read_b128 v[222:225], v148 offset:39936
	global_load_lds_dwordx4 v[230:231], off
	v_lshl_add_u64 v[230:231], s[36:37], 0, v[134:135]
	s_mov_b32 m0, s43
	s_nop 0
	global_load_lds_dwordx4 v[230:231], off
	s_waitcnt vmcnt(8)
	s_waitcnt lgkmcnt(0)
	s_barrier
	s_setprio 1
	s_waitcnt lgkmcnt(0)
	v_mfma_f32_16x16x32_bf16 v[126:129], v[150:153], v[182:185], v[126:129]
	v_mfma_f32_16x16x32_bf16 v[122:125], v[158:161], v[182:185], v[122:125]
	v_mfma_f32_16x16x32_bf16 v[118:121], v[150:153], v[190:193], v[118:121]
	v_mfma_f32_16x16x32_bf16 v[114:117], v[158:161], v[190:193], v[114:117]
	v_mfma_f32_16x16x32_bf16 v[110:113], v[150:153], v[210:213], v[110:113]
	v_mfma_f32_16x16x32_bf16 v[106:109], v[158:161], v[210:213], v[106:109]
	v_mfma_f32_16x16x32_bf16 v[102:105], v[150:153], v[218:221], v[102:105]
	v_mfma_f32_16x16x32_bf16 v[98:101], v[158:161], v[218:221], v[98:101]
	v_mfma_f32_16x16x32_bf16 v[126:129], v[154:157], v[186:189], v[126:129]
	v_mfma_f32_16x16x32_bf16 v[122:125], v[162:165], v[186:189], v[122:125]
	v_mfma_f32_16x16x32_bf16 v[118:121], v[154:157], v[198:201], v[118:121]
	v_mfma_f32_16x16x32_bf16 v[114:117], v[162:165], v[198:201], v[114:117]
	v_mfma_f32_16x16x32_bf16 v[110:113], v[154:157], v[214:217], v[110:113]
	v_mfma_f32_16x16x32_bf16 v[106:109], v[162:165], v[214:217], v[106:109]
	v_mfma_f32_16x16x32_bf16 v[102:105], v[154:157], v[222:225], v[102:105]
	v_mfma_f32_16x16x32_bf16 v[98:101], v[162:165], v[222:225], v[98:101]
	s_setprio 0
	s_setprio 1
	v_mfma_f32_16x16x32_bf16 v[94:97], v[166:169], v[182:185], v[94:97]
	v_mfma_f32_16x16x32_bf16 v[90:93], v[174:177], v[182:185], v[90:93]
	v_mfma_f32_16x16x32_bf16 v[86:89], v[166:169], v[190:193], v[86:89]
	v_mfma_f32_16x16x32_bf16 v[82:85], v[174:177], v[190:193], v[82:85]
	v_mfma_f32_16x16x32_bf16 v[78:81], v[166:169], v[210:213], v[78:81]
	v_mfma_f32_16x16x32_bf16 v[74:77], v[174:177], v[210:213], v[74:77]
	v_mfma_f32_16x16x32_bf16 v[70:73], v[166:169], v[218:221], v[70:73]
	v_mfma_f32_16x16x32_bf16 v[66:69], v[174:177], v[218:221], v[66:69]
	v_mfma_f32_16x16x32_bf16 v[94:97], v[170:173], v[186:189], v[94:97]
	v_mfma_f32_16x16x32_bf16 v[90:93], v[178:181], v[186:189], v[90:93]
	v_mfma_f32_16x16x32_bf16 v[86:89], v[170:173], v[198:201], v[86:89]
	v_mfma_f32_16x16x32_bf16 v[82:85], v[178:181], v[198:201], v[82:85]
	v_mfma_f32_16x16x32_bf16 v[78:81], v[170:173], v[214:217], v[78:81]
	v_mfma_f32_16x16x32_bf16 v[74:77], v[178:181], v[214:217], v[74:77]
	v_mfma_f32_16x16x32_bf16 v[70:73], v[170:173], v[222:225], v[70:73]
	s_barrier
	v_mfma_f32_16x16x32_bf16 v[66:69], v[178:181], v[222:225], v[66:69]
	s_setprio 0
	s_add_i32 s23, s23, s33
	v_lshl_add_u64 v[202:203], v[202:203], 0, s[10:11]
	s_mov_b32 m0, s23
	ds_read_b128 v[182:185], v148 offset:49152
	ds_read_b128 v[186:189], v148 offset:50176
	ds_read_b128 v[190:193], v148 offset:51200
	ds_read_b128 v[198:201], v148 offset:52224
	ds_read_b128 v[210:213], v148 offset:53248
	ds_read_b128 v[214:217], v148 offset:54272
	ds_read_b128 v[218:221], v148 offset:55296
	ds_read_b128 v[222:225], v148 offset:56320
	global_load_lds_dwordx4 v[202:203], off
	s_add_i32 m0, s23, 0x2000
	s_add_u32 s34, s34, 0x80080
	v_lshl_add_u64 v[202:203], v[206:207], 0, s[10:11]
	s_addc_u32 s35, s35, 0
	s_add_i32 s23, s38, s33
	global_load_lds_dwordx4 v[202:203], off
	v_lshl_add_u64 v[202:203], s[34:35], 0, v[132:133]
	s_mov_b32 m0, s23
	s_nop 0
	global_load_lds_dwordx4 v[202:203], off
	v_lshl_add_u64 v[202:203], s[34:35], 0, v[136:137]
	s_add_i32 m0, s23, 0x2000
	s_nop 0
	global_load_lds_dwordx4 v[202:203], off
	v_lshl_add_u64 v[202:203], v[226:227], 0, s[10:11]
	s_mov_b32 m0, s51
	s_nop 0
	global_load_lds_dwordx4 v[202:203], off
	v_lshl_add_u64 v[202:203], v[228:229], 0, s[10:11]
	s_mov_b32 m0, s52
	s_nop 0
	global_load_lds_dwordx4 v[202:203], off
	s_waitcnt vmcnt(8)
	s_waitcnt lgkmcnt(0)
	s_barrier
	s_setprio 1
	s_waitcnt lgkmcnt(0)
	v_mfma_f32_16x16x32_bf16 v[62:65], v[150:153], v[182:185], v[62:65]
	v_mfma_f32_16x16x32_bf16 v[58:61], v[158:161], v[182:185], v[58:61]
	v_mfma_f32_16x16x32_bf16 v[54:57], v[150:153], v[190:193], v[54:57]
	v_mfma_f32_16x16x32_bf16 v[50:53], v[158:161], v[190:193], v[50:53]
	v_mfma_f32_16x16x32_bf16 v[46:49], v[150:153], v[210:213], v[46:49]
	v_mfma_f32_16x16x32_bf16 v[42:45], v[158:161], v[210:213], v[42:45]
	v_mfma_f32_16x16x32_bf16 v[38:41], v[150:153], v[218:221], v[38:41]
	v_mfma_f32_16x16x32_bf16 v[34:37], v[158:161], v[218:221], v[34:37]
	v_mfma_f32_16x16x32_bf16 v[62:65], v[154:157], v[186:189], v[62:65]
	v_mfma_f32_16x16x32_bf16 v[58:61], v[162:165], v[186:189], v[58:61]
	v_mfma_f32_16x16x32_bf16 v[54:57], v[154:157], v[198:201], v[54:57]
	v_mfma_f32_16x16x32_bf16 v[50:53], v[162:165], v[198:201], v[50:53]
	v_mfma_f32_16x16x32_bf16 v[46:49], v[154:157], v[214:217], v[46:49]
	v_mfma_f32_16x16x32_bf16 v[42:45], v[162:165], v[214:217], v[42:45]
	v_mfma_f32_16x16x32_bf16 v[38:41], v[154:157], v[222:225], v[38:41]
	v_mfma_f32_16x16x32_bf16 v[34:37], v[162:165], v[222:225], v[34:37]
	s_setprio 0
	s_setprio 1
	v_mfma_f32_16x16x32_bf16 v[30:33], v[166:169], v[182:185], v[30:33]
	v_mfma_f32_16x16x32_bf16 v[26:29], v[174:177], v[182:185], v[26:29]
	v_mfma_f32_16x16x32_bf16 v[22:25], v[166:169], v[190:193], v[22:25]
	v_mfma_f32_16x16x32_bf16 v[18:21], v[174:177], v[190:193], v[18:21]
	v_mfma_f32_16x16x32_bf16 v[14:17], v[166:169], v[210:213], v[14:17]
	v_mfma_f32_16x16x32_bf16 v[10:13], v[174:177], v[210:213], v[10:13]
	v_mfma_f32_16x16x32_bf16 v[6:9], v[166:169], v[218:221], v[6:9]
	v_mfma_f32_16x16x32_bf16 v[2:5], v[174:177], v[218:221], v[2:5]
	v_mfma_f32_16x16x32_bf16 v[30:33], v[170:173], v[186:189], v[30:33]
	v_mfma_f32_16x16x32_bf16 v[26:29], v[178:181], v[186:189], v[26:29]
	v_mfma_f32_16x16x32_bf16 v[22:25], v[170:173], v[198:201], v[22:25]
	v_mfma_f32_16x16x32_bf16 v[18:21], v[178:181], v[198:201], v[18:21]
	v_mfma_f32_16x16x32_bf16 v[14:17], v[170:173], v[214:217], v[14:17]
	v_mfma_f32_16x16x32_bf16 v[10:13], v[178:181], v[214:217], v[10:13]
	v_mfma_f32_16x16x32_bf16 v[6:9], v[170:173], v[222:225], v[6:9]
	s_barrier
	v_mfma_f32_16x16x32_bf16 v[2:5], v[178:181], v[222:225], v[2:5]
	s_setprio 0
	s_add_u32 s30, s30, 0x100
	s_addc_u32 s31, s31, 0
	s_add_u32 s19, s19, 0x100
	s_addc_u32 s21, s21, 0
	s_cmp_ge_i32 s29, s68
	s_mov_b32 s23, s29
	s_cbranch_scc0 .LBB0_1973
	s_branch .Lpeeldone_3
.LBB0_1973:
	ds_read_b128 v[150:153], v146
	ds_read_b128 v[154:157], v146 offset:1024
	ds_read_b128 v[158:161], v146 offset:2048
	ds_read_b128 v[162:165], v146 offset:3072
	ds_read_b128 v[166:169], v147
	ds_read_b128 v[170:173], v147 offset:1024
	ds_read_b128 v[174:177], v147 offset:2048
	ds_read_b128 v[178:181], v147 offset:3072
	s_add_i32 s29, s23, 2
	s_add_u32 s34, s30, 0xfff80080
	s_addc_u32 s35, s31, -1
	s_cmp_eq_u32 s28, s23
	s_cselect_b32 s37, s25, s35
	s_cselect_b32 s36, s24, s34
	s_cselect_b32 s35, s27, s21
	s_cselect_b32 s34, s26, s19
	v_lshl_add_u64 v[202:203], s[30:31], 0, v[140:141]
	s_add_i32 m0, s15, 0xc000
	ds_read_b128 v[182:185], v148
	ds_read_b128 v[186:189], v148 offset:1024
	ds_read_b128 v[190:193], v148 offset:2048
	ds_read_b128 v[198:201], v148 offset:3072
	ds_read_b128 v[210:213], v148 offset:4096
	ds_read_b128 v[214:217], v148 offset:5120
	ds_read_b128 v[218:221], v148 offset:6144
	ds_read_b128 v[222:225], v148 offset:7168
	global_load_lds_dwordx4 v[202:203], off
	v_lshl_add_u64 v[202:203], s[30:31], 0, v[142:143]
	s_add_i32 m0, s15, 0xe000
	s_nop 0
	global_load_lds_dwordx4 v[202:203], off
	s_waitcnt vmcnt(8)
	s_waitcnt lgkmcnt(0)
	s_barrier
	s_setprio 1
	s_waitcnt lgkmcnt(0)
	v_mfma_f32_16x16x32_bf16 v[126:129], v[150:153], v[182:185], v[126:129]
	v_mfma_f32_16x16x32_bf16 v[122:125], v[158:161], v[182:185], v[122:125]
	v_mfma_f32_16x16x32_bf16 v[118:121], v[150:153], v[190:193], v[118:121]
	v_mfma_f32_16x16x32_bf16 v[114:117], v[158:161], v[190:193], v[114:117]
	v_mfma_f32_16x16x32_bf16 v[110:113], v[150:153], v[210:213], v[110:113]
	v_mfma_f32_16x16x32_bf16 v[106:109], v[158:161], v[210:213], v[106:109]
	v_mfma_f32_16x16x32_bf16 v[102:105], v[150:153], v[218:221], v[102:105]
	v_mfma_f32_16x16x32_bf16 v[98:101], v[158:161], v[218:221], v[98:101]
	v_mfma_f32_16x16x32_bf16 v[126:129], v[154:157], v[186:189], v[126:129]
	v_mfma_f32_16x16x32_bf16 v[122:125], v[162:165], v[186:189], v[122:125]
	v_mfma_f32_16x16x32_bf16 v[118:121], v[154:157], v[198:201], v[118:121]
	v_mfma_f32_16x16x32_bf16 v[114:117], v[162:165], v[198:201], v[114:117]
	v_mfma_f32_16x16x32_bf16 v[110:113], v[154:157], v[214:217], v[110:113]
	v_mfma_f32_16x16x32_bf16 v[106:109], v[162:165], v[214:217], v[106:109]
	v_mfma_f32_16x16x32_bf16 v[102:105], v[154:157], v[222:225], v[102:105]
	v_mfma_f32_16x16x32_bf16 v[98:101], v[162:165], v[222:225], v[98:101]
	s_setprio 0
	s_setprio 1
	v_mfma_f32_16x16x32_bf16 v[94:97], v[166:169], v[182:185], v[94:97]
	v_mfma_f32_16x16x32_bf16 v[90:93], v[174:177], v[182:185], v[90:93]
	v_mfma_f32_16x16x32_bf16 v[86:89], v[166:169], v[190:193], v[86:89]
	v_mfma_f32_16x16x32_bf16 v[82:85], v[174:177], v[190:193], v[82:85]
	v_mfma_f32_16x16x32_bf16 v[78:81], v[166:169], v[210:213], v[78:81]
	v_mfma_f32_16x16x32_bf16 v[74:77], v[174:177], v[210:213], v[74:77]
	v_mfma_f32_16x16x32_bf16 v[70:73], v[166:169], v[218:221], v[70:73]
	v_mfma_f32_16x16x32_bf16 v[66:69], v[174:177], v[218:221], v[66:69]
	v_mfma_f32_16x16x32_bf16 v[94:97], v[170:173], v[186:189], v[94:97]
	v_mfma_f32_16x16x32_bf16 v[90:93], v[178:181], v[186:189], v[90:93]
	v_mfma_f32_16x16x32_bf16 v[86:89], v[170:173], v[198:201], v[86:89]
	v_mfma_f32_16x16x32_bf16 v[82:85], v[178:181], v[198:201], v[82:85]
	v_mfma_f32_16x16x32_bf16 v[78:81], v[170:173], v[214:217], v[78:81]
	v_mfma_f32_16x16x32_bf16 v[74:77], v[178:181], v[214:217], v[74:77]
	v_mfma_f32_16x16x32_bf16 v[70:73], v[170:173], v[222:225], v[70:73]
	s_barrier
	v_mfma_f32_16x16x32_bf16 v[66:69], v[178:181], v[222:225], v[66:69]
	s_setprio 0
	s_add_i32 s23, s60, s33
	v_lshl_add_u64 v[202:203], s[34:35], 0, v[132:133]
	s_mov_b32 m0, s23
	ds_read_b128 v[182:185], v148 offset:16384
	ds_read_b128 v[186:189], v148 offset:17408
	ds_read_b128 v[190:193], v148 offset:18432
	ds_read_b128 v[198:201], v148 offset:19456
	ds_read_b128 v[210:213], v148 offset:20480
	ds_read_b128 v[214:217], v148 offset:21504
	ds_read_b128 v[218:221], v148 offset:22528
	ds_read_b128 v[222:225], v148 offset:23552
	global_load_lds_dwordx4 v[202:203], off
	s_add_i32 m0, s23, 0x2000
	s_add_u32 s38, s34, 0x80000
	v_lshl_add_u64 v[206:207], s[34:35], 0, v[136:137]
	s_addc_u32 s39, s35, 0
	s_add_i32 s23, s61, s33
	global_load_lds_dwordx4 v[206:207], off
	v_lshl_add_u64 v[226:227], s[38:39], 0, v[132:133]
	s_mov_b32 m0, s23
	v_lshl_add_u64 v[228:229], s[36:37], 0, v[134:135]
	global_load_lds_dwordx4 v[226:227], off
	v_lshl_add_u64 v[226:227], s[38:39], 0, v[136:137]
	s_add_i32 m0, s23, 0x2000
	s_nop 0
	global_load_lds_dwordx4 v[226:227], off
	v_lshl_add_u64 v[226:227], s[36:37], 0, v[130:131]
	s_mov_b32 m0, s15
	s_nop 0
	global_load_lds_dwordx4 v[226:227], off
	s_mov_b32 m0, s41
	s_nop 0
	global_load_lds_dwordx4 v[228:229], off
	s_waitcnt vmcnt(8)
	s_waitcnt lgkmcnt(0)
	s_barrier
	s_setprio 1
	s_waitcnt lgkmcnt(0)
	v_mfma_f32_16x16x32_bf16 v[62:65], v[150:153], v[182:185], v[62:65]
	v_mfma_f32_16x16x32_bf16 v[58:61], v[158:161], v[182:185], v[58:61]
	v_mfma_f32_16x16x32_bf16 v[54:57], v[150:153], v[190:193], v[54:57]
	v_mfma_f32_16x16x32_bf16 v[50:53], v[158:161], v[190:193], v[50:53]
	v_mfma_f32_16x16x32_bf16 v[46:49], v[150:153], v[210:213], v[46:49]
	v_mfma_f32_16x16x32_bf16 v[42:45], v[158:161], v[210:213], v[42:45]
	v_mfma_f32_16x16x32_bf16 v[38:41], v[150:153], v[218:221], v[38:41]
	v_mfma_f32_16x16x32_bf16 v[34:37], v[158:161], v[218:221], v[34:37]
	v_mfma_f32_16x16x32_bf16 v[62:65], v[154:157], v[186:189], v[62:65]
	v_mfma_f32_16x16x32_bf16 v[58:61], v[162:165], v[186:189], v[58:61]
	v_mfma_f32_16x16x32_bf16 v[54:57], v[154:157], v[198:201], v[54:57]
	v_mfma_f32_16x16x32_bf16 v[50:53], v[162:165], v[198:201], v[50:53]
	v_mfma_f32_16x16x32_bf16 v[46:49], v[154:157], v[214:217], v[46:49]
	v_mfma_f32_16x16x32_bf16 v[42:45], v[162:165], v[214:217], v[42:45]
	v_mfma_f32_16x16x32_bf16 v[38:41], v[154:157], v[222:225], v[38:41]
	v_mfma_f32_16x16x32_bf16 v[34:37], v[162:165], v[222:225], v[34:37]
	s_setprio 0
	s_setprio 1
	v_mfma_f32_16x16x32_bf16 v[30:33], v[166:169], v[182:185], v[30:33]
	v_mfma_f32_16x16x32_bf16 v[26:29], v[174:177], v[182:185], v[26:29]
	v_mfma_f32_16x16x32_bf16 v[22:25], v[166:169], v[190:193], v[22:25]
	v_mfma_f32_16x16x32_bf16 v[18:21], v[174:177], v[190:193], v[18:21]
	v_mfma_f32_16x16x32_bf16 v[14:17], v[166:169], v[210:213], v[14:17]
	v_mfma_f32_16x16x32_bf16 v[10:13], v[174:177], v[210:213], v[10:13]
	v_mfma_f32_16x16x32_bf16 v[6:9], v[166:169], v[218:221], v[6:9]
	v_mfma_f32_16x16x32_bf16 v[2:5], v[174:177], v[218:221], v[2:5]
	v_mfma_f32_16x16x32_bf16 v[30:33], v[170:173], v[186:189], v[30:33]
	v_mfma_f32_16x16x32_bf16 v[26:29], v[178:181], v[186:189], v[26:29]
	v_mfma_f32_16x16x32_bf16 v[22:25], v[170:173], v[198:201], v[22:25]
	v_mfma_f32_16x16x32_bf16 v[18:21], v[178:181], v[198:201], v[18:21]
	v_mfma_f32_16x16x32_bf16 v[14:17], v[170:173], v[214:217], v[14:17]
	v_mfma_f32_16x16x32_bf16 v[10:13], v[178:181], v[214:217], v[10:13]
	v_mfma_f32_16x16x32_bf16 v[6:9], v[170:173], v[222:225], v[6:9]
	s_barrier
	v_mfma_f32_16x16x32_bf16 v[2:5], v[178:181], v[222:225], v[2:5]
	s_setprio 0
	s_add_i32 s23, 0, 0x18000
	v_add_u32_e32 v149, s23, v144
	s_add_i32 s38, 0, 0x1c000
	ds_read_b128 v[150:153], v149
	ds_read_b128 v[154:157], v149 offset:1024
	ds_read_b128 v[158:161], v149 offset:2048
	ds_read_b128 v[162:165], v149 offset:3072
	v_add_u32_e32 v149, s38, v144
	ds_read_b128 v[166:169], v149
	ds_read_b128 v[170:173], v149 offset:1024
	ds_read_b128 v[174:177], v149 offset:2048
	ds_read_b128 v[178:181], v149 offset:3072
	s_add_u32 s36, s36, 0x80000
	s_addc_u32 s37, s37, 0
	s_mov_b32 m0, s42
	v_lshl_add_u64 v[230:231], s[36:37], 0, v[130:131]
	ds_read_b128 v[182:185], v148 offset:32768
	ds_read_b128 v[186:189], v148 offset:33792
	ds_read_b128 v[190:193], v148 offset:34816
	ds_read_b128 v[198:201], v148 offset:35840
	ds_read_b128 v[210:213], v148 offset:36864
	ds_read_b128 v[214:217], v148 offset:37888
	ds_read_b128 v[218:221], v148 offset:38912
	ds_read_b128 v[222:225], v148 offset:39936
	global_load_lds_dwordx4 v[230:231], off
	v_lshl_add_u64 v[230:231], s[36:37], 0, v[134:135]
	s_mov_b32 m0, s43
	s_nop 0
	global_load_lds_dwordx4 v[230:231], off
	s_waitcnt vmcnt(8)
	s_waitcnt lgkmcnt(0)
	s_barrier
	s_setprio 1
	s_waitcnt lgkmcnt(0)
	v_mfma_f32_16x16x32_bf16 v[126:129], v[150:153], v[182:185], v[126:129]
	v_mfma_f32_16x16x32_bf16 v[122:125], v[158:161], v[182:185], v[122:125]
	v_mfma_f32_16x16x32_bf16 v[118:121], v[150:153], v[190:193], v[118:121]
	v_mfma_f32_16x16x32_bf16 v[114:117], v[158:161], v[190:193], v[114:117]
	v_mfma_f32_16x16x32_bf16 v[110:113], v[150:153], v[210:213], v[110:113]
	v_mfma_f32_16x16x32_bf16 v[106:109], v[158:161], v[210:213], v[106:109]
	v_mfma_f32_16x16x32_bf16 v[102:105], v[150:153], v[218:221], v[102:105]
	v_mfma_f32_16x16x32_bf16 v[98:101], v[158:161], v[218:221], v[98:101]
	v_mfma_f32_16x16x32_bf16 v[126:129], v[154:157], v[186:189], v[126:129]
	v_mfma_f32_16x16x32_bf16 v[122:125], v[162:165], v[186:189], v[122:125]
	v_mfma_f32_16x16x32_bf16 v[118:121], v[154:157], v[198:201], v[118:121]
	v_mfma_f32_16x16x32_bf16 v[114:117], v[162:165], v[198:201], v[114:117]
	v_mfma_f32_16x16x32_bf16 v[110:113], v[154:157], v[214:217], v[110:113]
	v_mfma_f32_16x16x32_bf16 v[106:109], v[162:165], v[214:217], v[106:109]
	v_mfma_f32_16x16x32_bf16 v[102:105], v[154:157], v[222:225], v[102:105]
	v_mfma_f32_16x16x32_bf16 v[98:101], v[162:165], v[222:225], v[98:101]
	s_setprio 0
	s_setprio 1
	v_mfma_f32_16x16x32_bf16 v[94:97], v[166:169], v[182:185], v[94:97]
	v_mfma_f32_16x16x32_bf16 v[90:93], v[174:177], v[182:185], v[90:93]
	v_mfma_f32_16x16x32_bf16 v[86:89], v[166:169], v[190:193], v[86:89]
	v_mfma_f32_16x16x32_bf16 v[82:85], v[174:177], v[190:193], v[82:85]
	v_mfma_f32_16x16x32_bf16 v[78:81], v[166:169], v[210:213], v[78:81]
	v_mfma_f32_16x16x32_bf16 v[74:77], v[174:177], v[210:213], v[74:77]
	v_mfma_f32_16x16x32_bf16 v[70:73], v[166:169], v[218:221], v[70:73]
	v_mfma_f32_16x16x32_bf16 v[66:69], v[174:177], v[218:221], v[66:69]
	v_mfma_f32_16x16x32_bf16 v[94:97], v[170:173], v[186:189], v[94:97]
	v_mfma_f32_16x16x32_bf16 v[90:93], v[178:181], v[186:189], v[90:93]
	v_mfma_f32_16x16x32_bf16 v[86:89], v[170:173], v[198:201], v[86:89]
	v_mfma_f32_16x16x32_bf16 v[82:85], v[178:181], v[198:201], v[82:85]
	v_mfma_f32_16x16x32_bf16 v[78:81], v[170:173], v[214:217], v[78:81]
	v_mfma_f32_16x16x32_bf16 v[74:77], v[178:181], v[214:217], v[74:77]
	v_mfma_f32_16x16x32_bf16 v[70:73], v[170:173], v[222:225], v[70:73]
	s_barrier
	v_mfma_f32_16x16x32_bf16 v[66:69], v[178:181], v[222:225], v[66:69]
	s_setprio 0
	s_add_i32 s23, s23, s33
	v_lshl_add_u64 v[202:203], v[202:203], 0, s[10:11]
	s_mov_b32 m0, s23
	ds_read_b128 v[182:185], v148 offset:49152
	ds_read_b128 v[186:189], v148 offset:50176
	ds_read_b128 v[190:193], v148 offset:51200
	ds_read_b128 v[198:201], v148 offset:52224
	ds_read_b128 v[210:213], v148 offset:53248
	ds_read_b128 v[214:217], v148 offset:54272
	ds_read_b128 v[218:221], v148 offset:55296
	ds_read_b128 v[222:225], v148 offset:56320
	global_load_lds_dwordx4 v[202:203], off
	s_add_i32 m0, s23, 0x2000
	s_add_u32 s34, s34, 0x80080
	v_lshl_add_u64 v[202:203], v[206:207], 0, s[10:11]
	s_addc_u32 s35, s35, 0
	s_add_i32 s23, s38, s33
	global_load_lds_dwordx4 v[202:203], off
	v_lshl_add_u64 v[202:203], s[34:35], 0, v[132:133]
	s_mov_b32 m0, s23
	s_nop 0
	global_load_lds_dwordx4 v[202:203], off
	v_lshl_add_u64 v[202:203], s[34:35], 0, v[136:137]
	s_add_i32 m0, s23, 0x2000
	s_nop 0
	global_load_lds_dwordx4 v[202:203], off
	v_lshl_add_u64 v[202:203], v[226:227], 0, s[10:11]
	s_mov_b32 m0, s51
	s_nop 0
	global_load_lds_dwordx4 v[202:203], off
	v_lshl_add_u64 v[202:203], v[228:229], 0, s[10:11]
	s_mov_b32 m0, s52
	s_nop 0
	global_load_lds_dwordx4 v[202:203], off
	s_waitcnt vmcnt(8)
	s_waitcnt lgkmcnt(0)
	s_barrier
	s_setprio 1
	s_waitcnt lgkmcnt(0)
	v_mfma_f32_16x16x32_bf16 v[62:65], v[150:153], v[182:185], v[62:65]
	v_mfma_f32_16x16x32_bf16 v[58:61], v[158:161], v[182:185], v[58:61]
	v_mfma_f32_16x16x32_bf16 v[54:57], v[150:153], v[190:193], v[54:57]
	v_mfma_f32_16x16x32_bf16 v[50:53], v[158:161], v[190:193], v[50:53]
	v_mfma_f32_16x16x32_bf16 v[46:49], v[150:153], v[210:213], v[46:49]
	v_mfma_f32_16x16x32_bf16 v[42:45], v[158:161], v[210:213], v[42:45]
	v_mfma_f32_16x16x32_bf16 v[38:41], v[150:153], v[218:221], v[38:41]
	v_mfma_f32_16x16x32_bf16 v[34:37], v[158:161], v[218:221], v[34:37]
	v_mfma_f32_16x16x32_bf16 v[62:65], v[154:157], v[186:189], v[62:65]
	v_mfma_f32_16x16x32_bf16 v[58:61], v[162:165], v[186:189], v[58:61]
	v_mfma_f32_16x16x32_bf16 v[54:57], v[154:157], v[198:201], v[54:57]
	v_mfma_f32_16x16x32_bf16 v[50:53], v[162:165], v[198:201], v[50:53]
	v_mfma_f32_16x16x32_bf16 v[46:49], v[154:157], v[214:217], v[46:49]
	v_mfma_f32_16x16x32_bf16 v[42:45], v[162:165], v[214:217], v[42:45]
	v_mfma_f32_16x16x32_bf16 v[38:41], v[154:157], v[222:225], v[38:41]
	v_mfma_f32_16x16x32_bf16 v[34:37], v[162:165], v[222:225], v[34:37]
	s_setprio 0
	s_setprio 1
	v_mfma_f32_16x16x32_bf16 v[30:33], v[166:169], v[182:185], v[30:33]
	v_mfma_f32_16x16x32_bf16 v[26:29], v[174:177], v[182:185], v[26:29]
	v_mfma_f32_16x16x32_bf16 v[22:25], v[166:169], v[190:193], v[22:25]
	v_mfma_f32_16x16x32_bf16 v[18:21], v[174:177], v[190:193], v[18:21]
	v_mfma_f32_16x16x32_bf16 v[14:17], v[166:169], v[210:213], v[14:17]
	v_mfma_f32_16x16x32_bf16 v[10:13], v[174:177], v[210:213], v[10:13]
	v_mfma_f32_16x16x32_bf16 v[6:9], v[166:169], v[218:221], v[6:9]
	v_mfma_f32_16x16x32_bf16 v[2:5], v[174:177], v[218:221], v[2:5]
	v_mfma_f32_16x16x32_bf16 v[30:33], v[170:173], v[186:189], v[30:33]
	v_mfma_f32_16x16x32_bf16 v[26:29], v[178:181], v[186:189], v[26:29]
	v_mfma_f32_16x16x32_bf16 v[22:25], v[170:173], v[198:201], v[22:25]
	v_mfma_f32_16x16x32_bf16 v[18:21], v[178:181], v[198:201], v[18:21]
	v_mfma_f32_16x16x32_bf16 v[14:17], v[170:173], v[214:217], v[14:17]
	v_mfma_f32_16x16x32_bf16 v[10:13], v[178:181], v[214:217], v[10:13]
	v_mfma_f32_16x16x32_bf16 v[6:9], v[170:173], v[222:225], v[6:9]
	s_barrier
	v_mfma_f32_16x16x32_bf16 v[2:5], v[178:181], v[222:225], v[2:5]
	s_setprio 0
	s_add_u32 s30, s30, 0x100
	s_addc_u32 s31, s31, 0
	s_add_u32 s19, s19, 0x100
	s_addc_u32 s21, s21, 0
	s_cmp_ge_i32 s29, s68
	s_mov_b32 s23, s29
	s_cbranch_scc0 .LBB0_1973

.Lpeel_1:
	ds_read_b128 v[152:155], v148
	ds_read_b128 v[156:159], v148 offset:1024
	s_add_i32 s29, s19, 2
	s_add_u32 s34, s30, 0xfff80080
	s_addc_u32 s35, s31, -1
	s_cmp_eq_u32 s28, s19
	s_cselect_b32 s37, s21, s35
	s_cselect_b32 s36, s20, s34
	s_cselect_b32 s35, s23, s17
	s_cselect_b32 s34, s22, s15
	v_lshl_add_u64 v[144:145], s[30:31], 0, v[140:141]
	s_add_i32 m0, s27, 0xc000
	global_load_lds_dwordx4 v[144:145], off
	v_lshl_add_u64 v[144:145], s[30:31], 0, v[142:143]
	s_add_i32 m0, s27, 0xe000
	s_nop 0
	global_load_lds_dwordx4 v[144:145], off
	s_waitcnt vmcnt(8)
	s_waitcnt lgkmcnt(0)
	s_barrier
	s_setprio 1
	s_waitcnt lgkmcnt(0)
	v_mfma_f32_16x16x32_bf16 v[126:129], v[152:155], v[184:187], 0
	v_mfma_f32_16x16x32_bf16 v[122:125], v[160:163], v[184:187], 0
	v_mfma_f32_16x16x32_bf16 v[110:113], v[152:155], v[192:195], 0
	v_mfma_f32_16x16x32_bf16 v[106:109], v[160:163], v[192:195], 0
	v_mfma_f32_16x16x32_bf16 v[94:97], v[152:155], v[210:213], 0
	v_mfma_f32_16x16x32_bf16 v[90:93], v[160:163], v[210:213], 0
	v_mfma_f32_16x16x32_bf16 v[78:81], v[152:155], v[218:221], 0
	v_mfma_f32_16x16x32_bf16 v[74:77], v[160:163], v[218:221], 0
	v_mfma_f32_16x16x32_bf16 v[126:129], v[156:159], v[188:191], v[126:129]
	v_mfma_f32_16x16x32_bf16 v[122:125], v[164:167], v[188:191], v[122:125]
	v_mfma_f32_16x16x32_bf16 v[110:113], v[156:159], v[198:201], v[110:113]
	v_mfma_f32_16x16x32_bf16 v[106:109], v[164:167], v[198:201], v[106:109]
	v_mfma_f32_16x16x32_bf16 v[94:97], v[156:159], v[214:217], v[94:97]
	v_mfma_f32_16x16x32_bf16 v[90:93], v[164:167], v[214:217], v[90:93]
	v_mfma_f32_16x16x32_bf16 v[78:81], v[156:159], v[222:225], v[78:81]
	v_mfma_f32_16x16x32_bf16 v[74:77], v[164:167], v[222:225], v[74:77]
	s_setprio 0
	s_setprio 1
	v_mfma_f32_16x16x32_bf16 v[118:121], v[168:171], v[184:187], 0
	v_mfma_f32_16x16x32_bf16 v[114:117], v[176:179], v[184:187], 0
	v_mfma_f32_16x16x32_bf16 v[102:105], v[168:171], v[192:195], 0
	v_mfma_f32_16x16x32_bf16 v[98:101], v[176:179], v[192:195], 0
	v_mfma_f32_16x16x32_bf16 v[86:89], v[168:171], v[210:213], 0
	v_mfma_f32_16x16x32_bf16 v[82:85], v[176:179], v[210:213], 0
	v_mfma_f32_16x16x32_bf16 v[70:73], v[168:171], v[218:221], 0
	v_mfma_f32_16x16x32_bf16 v[66:69], v[176:179], v[218:221], 0
	v_mfma_f32_16x16x32_bf16 v[118:121], v[172:175], v[188:191], v[118:121]
	v_mfma_f32_16x16x32_bf16 v[114:117], v[180:183], v[188:191], v[114:117]
	v_mfma_f32_16x16x32_bf16 v[102:105], v[172:175], v[198:201], v[102:105]
	v_mfma_f32_16x16x32_bf16 v[98:101], v[180:183], v[198:201], v[98:101]
	v_mfma_f32_16x16x32_bf16 v[86:89], v[172:175], v[214:217], v[86:89]
	v_mfma_f32_16x16x32_bf16 v[82:85], v[180:183], v[214:217], v[82:85]
	v_mfma_f32_16x16x32_bf16 v[70:73], v[172:175], v[222:225], v[70:73]
	s_barrier
	v_mfma_f32_16x16x32_bf16 v[66:69], v[180:183], v[222:225], v[66:69]
	s_setprio 0
	s_add_i32 s19, s60, s33
	v_lshl_add_u64 v[144:145], s[34:35], 0, v[132:133]
	s_mov_b32 m0, s19
	ds_read_b128 v[184:187], v150 offset:16384
	ds_read_b128 v[188:191], v150 offset:17408
	ds_read_b128 v[192:195], v150 offset:18432
	ds_read_b128 v[198:201], v150 offset:19456
	ds_read_b128 v[210:213], v150 offset:20480
	ds_read_b128 v[214:217], v150 offset:21504
	ds_read_b128 v[218:221], v150 offset:22528
	ds_read_b128 v[222:225], v150 offset:23552
	global_load_lds_dwordx4 v[144:145], off
	s_add_i32 m0, s19, 0x2000
	s_add_u32 s38, s34, 0x80000
	v_lshl_add_u64 v[202:203], s[34:35], 0, v[136:137]
	s_addc_u32 s39, s35, 0
	s_add_i32 s19, s61, s33
	global_load_lds_dwordx4 v[202:203], off
	v_lshl_add_u64 v[206:207], s[38:39], 0, v[132:133]
	s_mov_b32 m0, s19
	v_lshl_add_u64 v[226:227], s[36:37], 0, v[134:135]
	global_load_lds_dwordx4 v[206:207], off
	v_lshl_add_u64 v[206:207], s[38:39], 0, v[136:137]
	s_add_i32 m0, s19, 0x2000
	s_nop 0
	global_load_lds_dwordx4 v[206:207], off
	v_lshl_add_u64 v[206:207], s[36:37], 0, v[130:131]
	s_mov_b32 m0, s27
	s_nop 0
	global_load_lds_dwordx4 v[206:207], off
	s_mov_b32 m0, s41
	s_nop 0
	global_load_lds_dwordx4 v[226:227], off
	s_waitcnt vmcnt(8)
	s_waitcnt lgkmcnt(0)
	s_barrier
	s_setprio 1
	s_waitcnt lgkmcnt(0)
	v_mfma_f32_16x16x32_bf16 v[62:65], v[152:155], v[184:187], 0
	v_mfma_f32_16x16x32_bf16 v[58:61], v[160:163], v[184:187], 0
	v_mfma_f32_16x16x32_bf16 v[46:49], v[152:155], v[192:195], 0
	v_mfma_f32_16x16x32_bf16 v[42:45], v[160:163], v[192:195], 0
	v_mfma_f32_16x16x32_bf16 v[30:33], v[152:155], v[210:213], 0
	v_mfma_f32_16x16x32_bf16 v[26:29], v[160:163], v[210:213], 0
	v_mfma_f32_16x16x32_bf16 v[14:17], v[152:155], v[218:221], 0
	v_mfma_f32_16x16x32_bf16 v[10:13], v[160:163], v[218:221], 0
	v_mfma_f32_16x16x32_bf16 v[62:65], v[156:159], v[188:191], v[62:65]
	v_mfma_f32_16x16x32_bf16 v[58:61], v[164:167], v[188:191], v[58:61]
	v_mfma_f32_16x16x32_bf16 v[46:49], v[156:159], v[198:201], v[46:49]
	v_mfma_f32_16x16x32_bf16 v[42:45], v[164:167], v[198:201], v[42:45]
	v_mfma_f32_16x16x32_bf16 v[30:33], v[156:159], v[214:217], v[30:33]
	v_mfma_f32_16x16x32_bf16 v[26:29], v[164:167], v[214:217], v[26:29]
	v_mfma_f32_16x16x32_bf16 v[14:17], v[156:159], v[222:225], v[14:17]
	v_mfma_f32_16x16x32_bf16 v[10:13], v[164:167], v[222:225], v[10:13]
	s_setprio 0
	s_setprio 1
	v_mfma_f32_16x16x32_bf16 v[54:57], v[168:171], v[184:187], 0
	v_mfma_f32_16x16x32_bf16 v[50:53], v[176:179], v[184:187], 0
	v_mfma_f32_16x16x32_bf16 v[38:41], v[168:171], v[192:195], 0
	v_mfma_f32_16x16x32_bf16 v[34:37], v[176:179], v[192:195], 0
	v_mfma_f32_16x16x32_bf16 v[22:25], v[168:171], v[210:213], 0
	v_mfma_f32_16x16x32_bf16 v[18:21], v[176:179], v[210:213], 0
	v_mfma_f32_16x16x32_bf16 v[6:9], v[168:171], v[218:221], 0
	v_mfma_f32_16x16x32_bf16 v[2:5], v[176:179], v[218:221], 0
	v_mfma_f32_16x16x32_bf16 v[54:57], v[172:175], v[188:191], v[54:57]
	v_mfma_f32_16x16x32_bf16 v[50:53], v[180:183], v[188:191], v[50:53]
	v_mfma_f32_16x16x32_bf16 v[38:41], v[172:175], v[198:201], v[38:41]
	v_mfma_f32_16x16x32_bf16 v[34:37], v[180:183], v[198:201], v[34:37]
	v_mfma_f32_16x16x32_bf16 v[22:25], v[172:175], v[214:217], v[22:25]
	v_mfma_f32_16x16x32_bf16 v[18:21], v[180:183], v[214:217], v[18:21]
	v_mfma_f32_16x16x32_bf16 v[6:9], v[172:175], v[222:225], v[6:9]
	s_barrier
	v_mfma_f32_16x16x32_bf16 v[2:5], v[180:183], v[222:225], v[2:5]
	s_setprio 0
	s_add_i32 s19, 0, 0x18000
	v_add_u32_e32 v151, s19, v146
	s_add_i32 s38, 0, 0x1c000
	ds_read_b128 v[152:155], v151
	ds_read_b128 v[156:159], v151 offset:1024
	ds_read_b128 v[160:163], v151 offset:2048
	ds_read_b128 v[164:167], v151 offset:3072
	v_add_u32_e32 v151, s38, v146
	ds_read_b128 v[168:171], v151
	ds_read_b128 v[172:175], v151 offset:1024
	ds_read_b128 v[176:179], v151 offset:2048
	ds_read_b128 v[180:183], v151 offset:3072
	s_add_u32 s36, s36, 0x80000
	s_addc_u32 s37, s37, 0
	s_mov_b32 m0, s42
	v_lshl_add_u64 v[228:229], s[36:37], 0, v[130:131]
	ds_read_b128 v[184:187], v150 offset:32768
	ds_read_b128 v[188:191], v150 offset:33792
	ds_read_b128 v[192:195], v150 offset:34816
	ds_read_b128 v[198:201], v150 offset:35840
	ds_read_b128 v[210:213], v150 offset:36864
	ds_read_b128 v[214:217], v150 offset:37888
	ds_read_b128 v[218:221], v150 offset:38912
	ds_read_b128 v[222:225], v150 offset:39936
	global_load_lds_dwordx4 v[228:229], off
	v_lshl_add_u64 v[228:229], s[36:37], 0, v[134:135]
	s_mov_b32 m0, s43
	s_nop 0
	global_load_lds_dwordx4 v[228:229], off
	s_waitcnt vmcnt(8)
	s_waitcnt lgkmcnt(0)
	s_barrier
	s_setprio 1
	s_waitcnt lgkmcnt(0)
	v_mfma_f32_16x16x32_bf16 v[126:129], v[152:155], v[184:187], v[126:129]
	v_mfma_f32_16x16x32_bf16 v[122:125], v[160:163], v[184:187], v[122:125]
	v_mfma_f32_16x16x32_bf16 v[110:113], v[152:155], v[192:195], v[110:113]
	v_mfma_f32_16x16x32_bf16 v[106:109], v[160:163], v[192:195], v[106:109]
	v_mfma_f32_16x16x32_bf16 v[94:97], v[152:155], v[210:213], v[94:97]
	v_mfma_f32_16x16x32_bf16 v[90:93], v[160:163], v[210:213], v[90:93]
	v_mfma_f32_16x16x32_bf16 v[78:81], v[152:155], v[218:221], v[78:81]
	v_mfma_f32_16x16x32_bf16 v[74:77], v[160:163], v[218:221], v[74:77]
	v_mfma_f32_16x16x32_bf16 v[126:129], v[156:159], v[188:191], v[126:129]
	v_mfma_f32_16x16x32_bf16 v[122:125], v[164:167], v[188:191], v[122:125]
	v_mfma_f32_16x16x32_bf16 v[110:113], v[156:159], v[198:201], v[110:113]
	v_mfma_f32_16x16x32_bf16 v[106:109], v[164:167], v[198:201], v[106:109]
	v_mfma_f32_16x16x32_bf16 v[94:97], v[156:159], v[214:217], v[94:97]
	v_mfma_f32_16x16x32_bf16 v[90:93], v[164:167], v[214:217], v[90:93]
	v_mfma_f32_16x16x32_bf16 v[78:81], v[156:159], v[222:225], v[78:81]
	v_mfma_f32_16x16x32_bf16 v[74:77], v[164:167], v[222:225], v[74:77]
	s_setprio 0
	s_setprio 1
	v_mfma_f32_16x16x32_bf16 v[118:121], v[168:171], v[184:187], v[118:121]
	v_mfma_f32_16x16x32_bf16 v[114:117], v[176:179], v[184:187], v[114:117]
	v_mfma_f32_16x16x32_bf16 v[102:105], v[168:171], v[192:195], v[102:105]
	v_mfma_f32_16x16x32_bf16 v[98:101], v[176:179], v[192:195], v[98:101]
	v_mfma_f32_16x16x32_bf16 v[86:89], v[168:171], v[210:213], v[86:89]
	v_mfma_f32_16x16x32_bf16 v[82:85], v[176:179], v[210:213], v[82:85]
	v_mfma_f32_16x16x32_bf16 v[70:73], v[168:171], v[218:221], v[70:73]
	v_mfma_f32_16x16x32_bf16 v[66:69], v[176:179], v[218:221], v[66:69]
	v_mfma_f32_16x16x32_bf16 v[118:121], v[172:175], v[188:191], v[118:121]
	v_mfma_f32_16x16x32_bf16 v[114:117], v[180:183], v[188:191], v[114:117]
	v_mfma_f32_16x16x32_bf16 v[102:105], v[172:175], v[198:201], v[102:105]
	v_mfma_f32_16x16x32_bf16 v[98:101], v[180:183], v[198:201], v[98:101]
	v_mfma_f32_16x16x32_bf16 v[86:89], v[172:175], v[214:217], v[86:89]
	v_mfma_f32_16x16x32_bf16 v[82:85], v[180:183], v[214:217], v[82:85]
	v_mfma_f32_16x16x32_bf16 v[70:73], v[172:175], v[222:225], v[70:73]
	s_barrier
	v_mfma_f32_16x16x32_bf16 v[66:69], v[180:183], v[222:225], v[66:69]
	s_setprio 0
	s_add_i32 s19, s19, s33
	v_lshl_add_u64 v[144:145], v[144:145], 0, s[10:11]
	s_mov_b32 m0, s19
	ds_read_b128 v[184:187], v150 offset:49152
	ds_read_b128 v[188:191], v150 offset:50176
	ds_read_b128 v[192:195], v150 offset:51200
	ds_read_b128 v[198:201], v150 offset:52224
	ds_read_b128 v[210:213], v150 offset:53248
	ds_read_b128 v[214:217], v150 offset:54272
	ds_read_b128 v[218:221], v150 offset:55296
	ds_read_b128 v[222:225], v150 offset:56320
	global_load_lds_dwordx4 v[144:145], off
	s_add_i32 m0, s19, 0x2000
	s_add_u32 s34, s34, 0x80080
	v_lshl_add_u64 v[144:145], v[202:203], 0, s[10:11]
	s_addc_u32 s35, s35, 0
	s_add_i32 s19, s38, s33
	global_load_lds_dwordx4 v[144:145], off
	v_lshl_add_u64 v[144:145], s[34:35], 0, v[132:133]
	s_mov_b32 m0, s19
	s_nop 0
	global_load_lds_dwordx4 v[144:145], off
	v_lshl_add_u64 v[144:145], s[34:35], 0, v[136:137]
	s_add_i32 m0, s19, 0x2000
	s_nop 0
	global_load_lds_dwordx4 v[144:145], off
	v_lshl_add_u64 v[144:145], v[206:207], 0, s[10:11]
	s_mov_b32 m0, s51
	s_nop 0
	global_load_lds_dwordx4 v[144:145], off
	v_lshl_add_u64 v[144:145], v[226:227], 0, s[10:11]
	s_mov_b32 m0, s52
	s_nop 0
	global_load_lds_dwordx4 v[144:145], off
	s_waitcnt vmcnt(8)
	s_waitcnt lgkmcnt(0)
	s_barrier
	s_setprio 1
	s_waitcnt lgkmcnt(0)
	v_mfma_f32_16x16x32_bf16 v[62:65], v[152:155], v[184:187], v[62:65]
	v_mfma_f32_16x16x32_bf16 v[58:61], v[160:163], v[184:187], v[58:61]
	v_mfma_f32_16x16x32_bf16 v[46:49], v[152:155], v[192:195], v[46:49]
	v_mfma_f32_16x16x32_bf16 v[42:45], v[160:163], v[192:195], v[42:45]
	v_mfma_f32_16x16x32_bf16 v[30:33], v[152:155], v[210:213], v[30:33]
	v_mfma_f32_16x16x32_bf16 v[26:29], v[160:163], v[210:213], v[26:29]
	v_mfma_f32_16x16x32_bf16 v[14:17], v[152:155], v[218:221], v[14:17]
	v_mfma_f32_16x16x32_bf16 v[10:13], v[160:163], v[218:221], v[10:13]
	v_mfma_f32_16x16x32_bf16 v[62:65], v[156:159], v[188:191], v[62:65]
	v_mfma_f32_16x16x32_bf16 v[58:61], v[164:167], v[188:191], v[58:61]
	v_mfma_f32_16x16x32_bf16 v[46:49], v[156:159], v[198:201], v[46:49]
	v_mfma_f32_16x16x32_bf16 v[42:45], v[164:167], v[198:201], v[42:45]
	v_mfma_f32_16x16x32_bf16 v[30:33], v[156:159], v[214:217], v[30:33]
	v_mfma_f32_16x16x32_bf16 v[26:29], v[164:167], v[214:217], v[26:29]
	v_mfma_f32_16x16x32_bf16 v[14:17], v[156:159], v[222:225], v[14:17]
	v_mfma_f32_16x16x32_bf16 v[10:13], v[164:167], v[222:225], v[10:13]
	s_setprio 0
	s_setprio 1
	v_mfma_f32_16x16x32_bf16 v[54:57], v[168:171], v[184:187], v[54:57]
	v_mfma_f32_16x16x32_bf16 v[50:53], v[176:179], v[184:187], v[50:53]
	v_mfma_f32_16x16x32_bf16 v[38:41], v[168:171], v[192:195], v[38:41]
	v_mfma_f32_16x16x32_bf16 v[34:37], v[176:179], v[192:195], v[34:37]
	v_mfma_f32_16x16x32_bf16 v[22:25], v[168:171], v[210:213], v[22:25]
	v_mfma_f32_16x16x32_bf16 v[18:21], v[176:179], v[210:213], v[18:21]
	v_mfma_f32_16x16x32_bf16 v[6:9], v[168:171], v[218:221], v[6:9]
	v_mfma_f32_16x16x32_bf16 v[2:5], v[176:179], v[218:221], v[2:5]
	v_mfma_f32_16x16x32_bf16 v[54:57], v[172:175], v[188:191], v[54:57]
	v_mfma_f32_16x16x32_bf16 v[50:53], v[180:183], v[188:191], v[50:53]
	v_mfma_f32_16x16x32_bf16 v[38:41], v[172:175], v[198:201], v[38:41]
	v_mfma_f32_16x16x32_bf16 v[34:37], v[180:183], v[198:201], v[34:37]
	v_mfma_f32_16x16x32_bf16 v[22:25], v[172:175], v[214:217], v[22:25]
	v_mfma_f32_16x16x32_bf16 v[18:21], v[180:183], v[214:217], v[18:21]
	v_mfma_f32_16x16x32_bf16 v[6:9], v[172:175], v[222:225], v[6:9]
	s_barrier
	v_mfma_f32_16x16x32_bf16 v[2:5], v[180:183], v[222:225], v[2:5]
	s_setprio 0
	s_add_u32 s30, s30, 0x100
	s_addc_u32 s31, s31, 0
	s_add_u32 s15, s15, 0x100
	s_addc_u32 s17, s17, 0
	s_cmp_ge_i32 s29, s68
	s_mov_b32 s19, s29
	s_cbranch_scc0 .LBB0_2547
	s_branch .Lpeeldone_1
.LBB0_2547:
	ds_read_b128 v[152:155], v148
	ds_read_b128 v[156:159], v148 offset:1024
	ds_read_b128 v[160:163], v148 offset:2048
	ds_read_b128 v[164:167], v148 offset:3072
	ds_read_b128 v[168:171], v149
	ds_read_b128 v[172:175], v149 offset:1024
	ds_read_b128 v[176:179], v149 offset:2048
	ds_read_b128 v[180:183], v149 offset:3072
	s_add_i32 s29, s19, 2
	s_add_u32 s34, s30, 0xfff80080
	s_addc_u32 s35, s31, -1
	s_cmp_eq_u32 s28, s19
	s_cselect_b32 s37, s21, s35
	s_cselect_b32 s36, s20, s34
	s_cselect_b32 s35, s23, s17
	s_cselect_b32 s34, s22, s15
	v_lshl_add_u64 v[144:145], s[30:31], 0, v[140:141]
	s_add_i32 m0, s27, 0xc000
	ds_read_b128 v[184:187], v150
	ds_read_b128 v[188:191], v150 offset:1024
	ds_read_b128 v[192:195], v150 offset:2048
	ds_read_b128 v[198:201], v150 offset:3072
	ds_read_b128 v[210:213], v150 offset:4096
	ds_read_b128 v[214:217], v150 offset:5120
	ds_read_b128 v[218:221], v150 offset:6144
	ds_read_b128 v[222:225], v150 offset:7168
	global_load_lds_dwordx4 v[144:145], off
	v_lshl_add_u64 v[144:145], s[30:31], 0, v[142:143]
	s_add_i32 m0, s27, 0xe000
	s_nop 0
	global_load_lds_dwordx4 v[144:145], off
	s_waitcnt vmcnt(8)
	s_waitcnt lgkmcnt(0)
	s_barrier
	s_setprio 1
	s_waitcnt lgkmcnt(0)
	v_mfma_f32_16x16x32_bf16 v[126:129], v[152:155], v[184:187], v[126:129]
	v_mfma_f32_16x16x32_bf16 v[122:125], v[160:163], v[184:187], v[122:125]
	v_mfma_f32_16x16x32_bf16 v[110:113], v[152:155], v[192:195], v[110:113]
	v_mfma_f32_16x16x32_bf16 v[106:109], v[160:163], v[192:195], v[106:109]
	v_mfma_f32_16x16x32_bf16 v[94:97], v[152:155], v[210:213], v[94:97]
	v_mfma_f32_16x16x32_bf16 v[90:93], v[160:163], v[210:213], v[90:93]
	v_mfma_f32_16x16x32_bf16 v[78:81], v[152:155], v[218:221], v[78:81]
	v_mfma_f32_16x16x32_bf16 v[74:77], v[160:163], v[218:221], v[74:77]
	v_mfma_f32_16x16x32_bf16 v[126:129], v[156:159], v[188:191], v[126:129]
	v_mfma_f32_16x16x32_bf16 v[122:125], v[164:167], v[188:191], v[122:125]
	v_mfma_f32_16x16x32_bf16 v[110:113], v[156:159], v[198:201], v[110:113]
	v_mfma_f32_16x16x32_bf16 v[106:109], v[164:167], v[198:201], v[106:109]
	v_mfma_f32_16x16x32_bf16 v[94:97], v[156:159], v[214:217], v[94:97]
	v_mfma_f32_16x16x32_bf16 v[90:93], v[164:167], v[214:217], v[90:93]
	v_mfma_f32_16x16x32_bf16 v[78:81], v[156:159], v[222:225], v[78:81]
	v_mfma_f32_16x16x32_bf16 v[74:77], v[164:167], v[222:225], v[74:77]
	s_setprio 0
	s_setprio 1
	v_mfma_f32_16x16x32_bf16 v[118:121], v[168:171], v[184:187], v[118:121]
	v_mfma_f32_16x16x32_bf16 v[114:117], v[176:179], v[184:187], v[114:117]
	v_mfma_f32_16x16x32_bf16 v[102:105], v[168:171], v[192:195], v[102:105]
	v_mfma_f32_16x16x32_bf16 v[98:101], v[176:179], v[192:195], v[98:101]
	v_mfma_f32_16x16x32_bf16 v[86:89], v[168:171], v[210:213], v[86:89]
	v_mfma_f32_16x16x32_bf16 v[82:85], v[176:179], v[210:213], v[82:85]
	v_mfma_f32_16x16x32_bf16 v[70:73], v[168:171], v[218:221], v[70:73]
	v_mfma_f32_16x16x32_bf16 v[66:69], v[176:179], v[218:221], v[66:69]
	v_mfma_f32_16x16x32_bf16 v[118:121], v[172:175], v[188:191], v[118:121]
	v_mfma_f32_16x16x32_bf16 v[114:117], v[180:183], v[188:191], v[114:117]
	v_mfma_f32_16x16x32_bf16 v[102:105], v[172:175], v[198:201], v[102:105]
	v_mfma_f32_16x16x32_bf16 v[98:101], v[180:183], v[198:201], v[98:101]
	v_mfma_f32_16x16x32_bf16 v[86:89], v[172:175], v[214:217], v[86:89]
	v_mfma_f32_16x16x32_bf16 v[82:85], v[180:183], v[214:217], v[82:85]
	v_mfma_f32_16x16x32_bf16 v[70:73], v[172:175], v[222:225], v[70:73]
	s_barrier
	v_mfma_f32_16x16x32_bf16 v[66:69], v[180:183], v[222:225], v[66:69]
	s_setprio 0
	s_add_i32 s19, s60, s33
	v_lshl_add_u64 v[144:145], s[34:35], 0, v[132:133]
	s_mov_b32 m0, s19
	ds_read_b128 v[184:187], v150 offset:16384
	ds_read_b128 v[188:191], v150 offset:17408
	ds_read_b128 v[192:195], v150 offset:18432
	ds_read_b128 v[198:201], v150 offset:19456
	ds_read_b128 v[210:213], v150 offset:20480
	ds_read_b128 v[214:217], v150 offset:21504
	ds_read_b128 v[218:221], v150 offset:22528
	ds_read_b128 v[222:225], v150 offset:23552
	global_load_lds_dwordx4 v[144:145], off
	s_add_i32 m0, s19, 0x2000
	s_add_u32 s38, s34, 0x80000
	v_lshl_add_u64 v[202:203], s[34:35], 0, v[136:137]
	s_addc_u32 s39, s35, 0
	s_add_i32 s19, s61, s33
	global_load_lds_dwordx4 v[202:203], off
	v_lshl_add_u64 v[206:207], s[38:39], 0, v[132:133]
	s_mov_b32 m0, s19
	v_lshl_add_u64 v[226:227], s[36:37], 0, v[134:135]
	global_load_lds_dwordx4 v[206:207], off
	v_lshl_add_u64 v[206:207], s[38:39], 0, v[136:137]
	s_add_i32 m0, s19, 0x2000
	s_nop 0
	global_load_lds_dwordx4 v[206:207], off
	v_lshl_add_u64 v[206:207], s[36:37], 0, v[130:131]
	s_mov_b32 m0, s27
	s_nop 0
	global_load_lds_dwordx4 v[206:207], off
	s_mov_b32 m0, s41
	s_nop 0
	global_load_lds_dwordx4 v[226:227], off
	s_waitcnt vmcnt(8)
	s_waitcnt lgkmcnt(0)
	s_barrier
	s_setprio 1
	s_waitcnt lgkmcnt(0)
	v_mfma_f32_16x16x32_bf16 v[62:65], v[152:155], v[184:187], v[62:65]
	v_mfma_f32_16x16x32_bf16 v[58:61], v[160:163], v[184:187], v[58:61]
	v_mfma_f32_16x16x32_bf16 v[46:49], v[152:155], v[192:195], v[46:49]
	v_mfma_f32_16x16x32_bf16 v[42:45], v[160:163], v[192:195], v[42:45]
	v_mfma_f32_16x16x32_bf16 v[30:33], v[152:155], v[210:213], v[30:33]
	v_mfma_f32_16x16x32_bf16 v[26:29], v[160:163], v[210:213], v[26:29]
	v_mfma_f32_16x16x32_bf16 v[14:17], v[152:155], v[218:221], v[14:17]
	v_mfma_f32_16x16x32_bf16 v[10:13], v[160:163], v[218:221], v[10:13]
	v_mfma_f32_16x16x32_bf16 v[62:65], v[156:159], v[188:191], v[62:65]
	v_mfma_f32_16x16x32_bf16 v[58:61], v[164:167], v[188:191], v[58:61]
	v_mfma_f32_16x16x32_bf16 v[46:49], v[156:159], v[198:201], v[46:49]
	v_mfma_f32_16x16x32_bf16 v[42:45], v[164:167], v[198:201], v[42:45]
	v_mfma_f32_16x16x32_bf16 v[30:33], v[156:159], v[214:217], v[30:33]
	v_mfma_f32_16x16x32_bf16 v[26:29], v[164:167], v[214:217], v[26:29]
	v_mfma_f32_16x16x32_bf16 v[14:17], v[156:159], v[222:225], v[14:17]
	v_mfma_f32_16x16x32_bf16 v[10:13], v[164:167], v[222:225], v[10:13]
	s_setprio 0
	s_setprio 1
	v_mfma_f32_16x16x32_bf16 v[54:57], v[168:171], v[184:187], v[54:57]
	v_mfma_f32_16x16x32_bf16 v[50:53], v[176:179], v[184:187], v[50:53]
	v_mfma_f32_16x16x32_bf16 v[38:41], v[168:171], v[192:195], v[38:41]
	v_mfma_f32_16x16x32_bf16 v[34:37], v[176:179], v[192:195], v[34:37]
	v_mfma_f32_16x16x32_bf16 v[22:25], v[168:171], v[210:213], v[22:25]
	v_mfma_f32_16x16x32_bf16 v[18:21], v[176:179], v[210:213], v[18:21]
	v_mfma_f32_16x16x32_bf16 v[6:9], v[168:171], v[218:221], v[6:9]
	v_mfma_f32_16x16x32_bf16 v[2:5], v[176:179], v[218:221], v[2:5]
	v_mfma_f32_16x16x32_bf16 v[54:57], v[172:175], v[188:191], v[54:57]
	v_mfma_f32_16x16x32_bf16 v[50:53], v[180:183], v[188:191], v[50:53]
	v_mfma_f32_16x16x32_bf16 v[38:41], v[172:175], v[198:201], v[38:41]
	v_mfma_f32_16x16x32_bf16 v[34:37], v[180:183], v[198:201], v[34:37]
	v_mfma_f32_16x16x32_bf16 v[22:25], v[172:175], v[214:217], v[22:25]
	v_mfma_f32_16x16x32_bf16 v[18:21], v[180:183], v[214:217], v[18:21]
	v_mfma_f32_16x16x32_bf16 v[6:9], v[172:175], v[222:225], v[6:9]
	s_barrier
	v_mfma_f32_16x16x32_bf16 v[2:5], v[180:183], v[222:225], v[2:5]
	s_setprio 0
	s_add_i32 s19, 0, 0x18000
	v_add_u32_e32 v151, s19, v146
	s_add_i32 s38, 0, 0x1c000
	ds_read_b128 v[152:155], v151
	ds_read_b128 v[156:159], v151 offset:1024
	ds_read_b128 v[160:163], v151 offset:2048
	ds_read_b128 v[164:167], v151 offset:3072
	v_add_u32_e32 v151, s38, v146
	ds_read_b128 v[168:171], v151
	ds_read_b128 v[172:175], v151 offset:1024
	ds_read_b128 v[176:179], v151 offset:2048
	ds_read_b128 v[180:183], v151 offset:3072
	s_add_u32 s36, s36, 0x80000
	s_addc_u32 s37, s37, 0
	s_mov_b32 m0, s42
	v_lshl_add_u64 v[228:229], s[36:37], 0, v[130:131]
	ds_read_b128 v[184:187], v150 offset:32768
	ds_read_b128 v[188:191], v150 offset:33792
	ds_read_b128 v[192:195], v150 offset:34816
	ds_read_b128 v[198:201], v150 offset:35840
	ds_read_b128 v[210:213], v150 offset:36864
	ds_read_b128 v[214:217], v150 offset:37888
	ds_read_b128 v[218:221], v150 offset:38912
	ds_read_b128 v[222:225], v150 offset:39936
	global_load_lds_dwordx4 v[228:229], off
	v_lshl_add_u64 v[228:229], s[36:37], 0, v[134:135]
	s_mov_b32 m0, s43
	s_nop 0
	global_load_lds_dwordx4 v[228:229], off
	s_waitcnt vmcnt(8)
	s_waitcnt lgkmcnt(0)
	s_barrier
	s_setprio 1
	s_waitcnt lgkmcnt(0)
	v_mfma_f32_16x16x32_bf16 v[126:129], v[152:155], v[184:187], v[126:129]
	v_mfma_f32_16x16x32_bf16 v[122:125], v[160:163], v[184:187], v[122:125]
	v_mfma_f32_16x16x32_bf16 v[110:113], v[152:155], v[192:195], v[110:113]
	v_mfma_f32_16x16x32_bf16 v[106:109], v[160:163], v[192:195], v[106:109]
	v_mfma_f32_16x16x32_bf16 v[94:97], v[152:155], v[210:213], v[94:97]
	v_mfma_f32_16x16x32_bf16 v[90:93], v[160:163], v[210:213], v[90:93]
	v_mfma_f32_16x16x32_bf16 v[78:81], v[152:155], v[218:221], v[78:81]
	v_mfma_f32_16x16x32_bf16 v[74:77], v[160:163], v[218:221], v[74:77]
	v_mfma_f32_16x16x32_bf16 v[126:129], v[156:159], v[188:191], v[126:129]
	v_mfma_f32_16x16x32_bf16 v[122:125], v[164:167], v[188:191], v[122:125]
	v_mfma_f32_16x16x32_bf16 v[110:113], v[156:159], v[198:201], v[110:113]
	v_mfma_f32_16x16x32_bf16 v[106:109], v[164:167], v[198:201], v[106:109]
	v_mfma_f32_16x16x32_bf16 v[94:97], v[156:159], v[214:217], v[94:97]
	v_mfma_f32_16x16x32_bf16 v[90:93], v[164:167], v[214:217], v[90:93]
	v_mfma_f32_16x16x32_bf16 v[78:81], v[156:159], v[222:225], v[78:81]
	v_mfma_f32_16x16x32_bf16 v[74:77], v[164:167], v[222:225], v[74:77]
	s_setprio 0
	s_setprio 1
	v_mfma_f32_16x16x32_bf16 v[118:121], v[168:171], v[184:187], v[118:121]
	v_mfma_f32_16x16x32_bf16 v[114:117], v[176:179], v[184:187], v[114:117]
	v_mfma_f32_16x16x32_bf16 v[102:105], v[168:171], v[192:195], v[102:105]
	v_mfma_f32_16x16x32_bf16 v[98:101], v[176:179], v[192:195], v[98:101]
	v_mfma_f32_16x16x32_bf16 v[86:89], v[168:171], v[210:213], v[86:89]
	v_mfma_f32_16x16x32_bf16 v[82:85], v[176:179], v[210:213], v[82:85]
	v_mfma_f32_16x16x32_bf16 v[70:73], v[168:171], v[218:221], v[70:73]
	v_mfma_f32_16x16x32_bf16 v[66:69], v[176:179], v[218:221], v[66:69]
	v_mfma_f32_16x16x32_bf16 v[118:121], v[172:175], v[188:191], v[118:121]
	v_mfma_f32_16x16x32_bf16 v[114:117], v[180:183], v[188:191], v[114:117]
	v_mfma_f32_16x16x32_bf16 v[102:105], v[172:175], v[198:201], v[102:105]
	v_mfma_f32_16x16x32_bf16 v[98:101], v[180:183], v[198:201], v[98:101]
	v_mfma_f32_16x16x32_bf16 v[86:89], v[172:175], v[214:217], v[86:89]
	v_mfma_f32_16x16x32_bf16 v[82:85], v[180:183], v[214:217], v[82:85]
	v_mfma_f32_16x16x32_bf16 v[70:73], v[172:175], v[222:225], v[70:73]
	s_barrier
	v_mfma_f32_16x16x32_bf16 v[66:69], v[180:183], v[222:225], v[66:69]
	s_setprio 0
	s_add_i32 s19, s19, s33
	v_lshl_add_u64 v[144:145], v[144:145], 0, s[10:11]
	s_mov_b32 m0, s19
	ds_read_b128 v[184:187], v150 offset:49152
	ds_read_b128 v[188:191], v150 offset:50176
	ds_read_b128 v[192:195], v150 offset:51200
	ds_read_b128 v[198:201], v150 offset:52224
	ds_read_b128 v[210:213], v150 offset:53248
	ds_read_b128 v[214:217], v150 offset:54272
	ds_read_b128 v[218:221], v150 offset:55296
	ds_read_b128 v[222:225], v150 offset:56320
	global_load_lds_dwordx4 v[144:145], off
	s_add_i32 m0, s19, 0x2000
	s_add_u32 s34, s34, 0x80080
	v_lshl_add_u64 v[144:145], v[202:203], 0, s[10:11]
	s_addc_u32 s35, s35, 0
	s_add_i32 s19, s38, s33
	global_load_lds_dwordx4 v[144:145], off
	v_lshl_add_u64 v[144:145], s[34:35], 0, v[132:133]
	s_mov_b32 m0, s19
	s_nop 0
	global_load_lds_dwordx4 v[144:145], off
	v_lshl_add_u64 v[144:145], s[34:35], 0, v[136:137]
	s_add_i32 m0, s19, 0x2000
	s_nop 0
	global_load_lds_dwordx4 v[144:145], off
	v_lshl_add_u64 v[144:145], v[206:207], 0, s[10:11]
	s_mov_b32 m0, s51
	s_nop 0
	global_load_lds_dwordx4 v[144:145], off
	v_lshl_add_u64 v[144:145], v[226:227], 0, s[10:11]
	s_mov_b32 m0, s52
	s_nop 0
	global_load_lds_dwordx4 v[144:145], off
	s_waitcnt vmcnt(8)
	s_waitcnt lgkmcnt(0)
	s_barrier
	s_setprio 1
	s_waitcnt lgkmcnt(0)
	v_mfma_f32_16x16x32_bf16 v[62:65], v[152:155], v[184:187], v[62:65]
	v_mfma_f32_16x16x32_bf16 v[58:61], v[160:163], v[184:187], v[58:61]
	v_mfma_f32_16x16x32_bf16 v[46:49], v[152:155], v[192:195], v[46:49]
	v_mfma_f32_16x16x32_bf16 v[42:45], v[160:163], v[192:195], v[42:45]
	v_mfma_f32_16x16x32_bf16 v[30:33], v[152:155], v[210:213], v[30:33]
	v_mfma_f32_16x16x32_bf16 v[26:29], v[160:163], v[210:213], v[26:29]
	v_mfma_f32_16x16x32_bf16 v[14:17], v[152:155], v[218:221], v[14:17]
	v_mfma_f32_16x16x32_bf16 v[10:13], v[160:163], v[218:221], v[10:13]
	v_mfma_f32_16x16x32_bf16 v[62:65], v[156:159], v[188:191], v[62:65]
	v_mfma_f32_16x16x32_bf16 v[58:61], v[164:167], v[188:191], v[58:61]
	v_mfma_f32_16x16x32_bf16 v[46:49], v[156:159], v[198:201], v[46:49]
	v_mfma_f32_16x16x32_bf16 v[42:45], v[164:167], v[198:201], v[42:45]
	v_mfma_f32_16x16x32_bf16 v[30:33], v[156:159], v[214:217], v[30:33]
	v_mfma_f32_16x16x32_bf16 v[26:29], v[164:167], v[214:217], v[26:29]
	v_mfma_f32_16x16x32_bf16 v[14:17], v[156:159], v[222:225], v[14:17]
	v_mfma_f32_16x16x32_bf16 v[10:13], v[164:167], v[222:225], v[10:13]
	s_setprio 0
	s_setprio 1
	v_mfma_f32_16x16x32_bf16 v[54:57], v[168:171], v[184:187], v[54:57]
	v_mfma_f32_16x16x32_bf16 v[50:53], v[176:179], v[184:187], v[50:53]
	v_mfma_f32_16x16x32_bf16 v[38:41], v[168:171], v[192:195], v[38:41]
	v_mfma_f32_16x16x32_bf16 v[34:37], v[176:179], v[192:195], v[34:37]
	v_mfma_f32_16x16x32_bf16 v[22:25], v[168:171], v[210:213], v[22:25]
	v_mfma_f32_16x16x32_bf16 v[18:21], v[176:179], v[210:213], v[18:21]
	v_mfma_f32_16x16x32_bf16 v[6:9], v[168:171], v[218:221], v[6:9]
	v_mfma_f32_16x16x32_bf16 v[2:5], v[176:179], v[218:221], v[2:5]
	v_mfma_f32_16x16x32_bf16 v[54:57], v[172:175], v[188:191], v[54:57]
	v_mfma_f32_16x16x32_bf16 v[50:53], v[180:183], v[188:191], v[50:53]
	v_mfma_f32_16x16x32_bf16 v[38:41], v[172:175], v[198:201], v[38:41]
	v_mfma_f32_16x16x32_bf16 v[34:37], v[180:183], v[198:201], v[34:37]
	v_mfma_f32_16x16x32_bf16 v[22:25], v[172:175], v[214:217], v[22:25]
	v_mfma_f32_16x16x32_bf16 v[18:21], v[180:183], v[214:217], v[18:21]
	v_mfma_f32_16x16x32_bf16 v[6:9], v[172:175], v[222:225], v[6:9]
	s_barrier
	v_mfma_f32_16x16x32_bf16 v[2:5], v[180:183], v[222:225], v[2:5]
	s_setprio 0
	s_add_u32 s30, s30, 0x100
	s_addc_u32 s31, s31, 0
	s_add_u32 s15, s15, 0x100
	s_addc_u32 s17, s17, 0
	s_cmp_ge_i32 s29, s68
	s_mov_b32 s19, s29
	s_cbranch_scc0 .LBB0_2547

.Lpeel_0:
	ds_read_b128 v[144:147], v170
	ds_read_b128 v[148:151], v170 offset:1024
	ds_read_b128 v[152:155], v170 offset:2048
	ds_read_b128 v[156:159], v170 offset:3072
	ds_read_b128 v[160:163], v171
	ds_read_b128 v[164:167], v171 offset:1024
	ds_read_b128 v[174:177], v171 offset:2048
	ds_read_b128 v[178:181], v171 offset:3072
	s_add_i32 s30, s26, 2
	s_add_u32 s27, s24, 0xffea0080
	s_addc_u32 s28, s25, -1
	s_cmp_eq_u32 s22, s26
	s_cselect_b32 s26, s20, s17
	s_cselect_b32 s29, s19, s28
	s_cselect_b32 s28, s18, s27
	s_cselect_b32 s27, s21, s23
	v_lshl_add_u64 v[214:215], s[24:25], 0, v[140:141]
	s_add_i32 m0, s34, 0xc000
	ds_read_b128 v[182:185], v172
	ds_read_b128 v[186:189], v172 offset:1024
	ds_read_b128 v[190:193], v172 offset:2048
	ds_read_b128 v[194:197], v172 offset:3072
	ds_read_b128 v[198:201], v172 offset:4096
	ds_read_b128 v[202:205], v172 offset:5120
	ds_read_b128 v[206:209], v172 offset:6144
	ds_read_b128 v[210:213], v172 offset:7168
	global_load_lds_dwordx4 v[214:215], off
	v_lshl_add_u64 v[214:215], s[24:25], 0, v[142:143]
	s_add_i32 m0, s34, 0xe000
	s_nop 0
	global_load_lds_dwordx4 v[214:215], off
	s_waitcnt vmcnt(8)
	s_waitcnt lgkmcnt(0)
	s_barrier
	s_setprio 1
	s_waitcnt lgkmcnt(0)
	v_mfma_f32_16x16x32_bf16 v[126:129], v[144:147], v[182:185], 0
	v_mfma_f32_16x16x32_bf16 v[122:125], v[152:155], v[182:185], 0
	v_mfma_f32_16x16x32_bf16 v[118:121], v[144:147], v[190:193], 0
	v_mfma_f32_16x16x32_bf16 v[110:113], v[152:155], v[190:193], 0
	v_mfma_f32_16x16x32_bf16 v[94:97], v[144:147], v[198:201], 0
	v_mfma_f32_16x16x32_bf16 v[90:93], v[152:155], v[198:201], 0
	v_mfma_f32_16x16x32_bf16 v[82:85], v[144:147], v[206:209], 0
	v_mfma_f32_16x16x32_bf16 v[74:77], v[152:155], v[206:209], 0
	v_mfma_f32_16x16x32_bf16 v[126:129], v[148:151], v[186:189], v[126:129]
	v_mfma_f32_16x16x32_bf16 v[122:125], v[156:159], v[186:189], v[122:125]
	v_mfma_f32_16x16x32_bf16 v[118:121], v[148:151], v[194:197], v[118:121]
	v_mfma_f32_16x16x32_bf16 v[110:113], v[156:159], v[194:197], v[110:113]
	v_mfma_f32_16x16x32_bf16 v[94:97], v[148:151], v[202:205], v[94:97]
	v_mfma_f32_16x16x32_bf16 v[90:93], v[156:159], v[202:205], v[90:93]
	v_mfma_f32_16x16x32_bf16 v[82:85], v[148:151], v[210:213], v[82:85]
	v_mfma_f32_16x16x32_bf16 v[74:77], v[156:159], v[210:213], v[74:77]
	s_setprio 0
	s_setprio 1
	v_mfma_f32_16x16x32_bf16 v[114:117], v[160:163], v[182:185], 0
	v_mfma_f32_16x16x32_bf16 v[106:109], v[174:177], v[182:185], 0
	v_mfma_f32_16x16x32_bf16 v[102:105], v[160:163], v[190:193], 0
	v_mfma_f32_16x16x32_bf16 v[98:101], v[174:177], v[190:193], 0
	v_mfma_f32_16x16x32_bf16 v[86:89], v[160:163], v[198:201], 0
	v_mfma_f32_16x16x32_bf16 v[78:81], v[174:177], v[198:201], 0
	v_mfma_f32_16x16x32_bf16 v[70:73], v[160:163], v[206:209], 0
	v_mfma_f32_16x16x32_bf16 v[66:69], v[174:177], v[206:209], 0
	v_mfma_f32_16x16x32_bf16 v[114:117], v[164:167], v[186:189], v[114:117]
	v_mfma_f32_16x16x32_bf16 v[106:109], v[178:181], v[186:189], v[106:109]
	v_mfma_f32_16x16x32_bf16 v[102:105], v[164:167], v[194:197], v[102:105]
	v_mfma_f32_16x16x32_bf16 v[98:101], v[178:181], v[194:197], v[98:101]
	v_mfma_f32_16x16x32_bf16 v[86:89], v[164:167], v[202:205], v[86:89]
	v_mfma_f32_16x16x32_bf16 v[78:81], v[178:181], v[202:205], v[78:81]
	v_mfma_f32_16x16x32_bf16 v[70:73], v[164:167], v[210:213], v[70:73]
	s_barrier
	v_mfma_f32_16x16x32_bf16 v[66:69], v[178:181], v[210:213], v[66:69]
	s_setprio 0
	s_add_i32 s31, s57, s33
	v_lshl_add_u64 v[214:215], s[26:27], 0, v[132:133]
	s_mov_b32 m0, s31
	ds_read_b128 v[182:185], v172 offset:16384
	ds_read_b128 v[186:189], v172 offset:17408
	ds_read_b128 v[190:193], v172 offset:18432
	ds_read_b128 v[194:197], v172 offset:19456
	ds_read_b128 v[198:201], v172 offset:20480
	ds_read_b128 v[202:205], v172 offset:21504
	ds_read_b128 v[206:209], v172 offset:22528
	ds_read_b128 v[210:213], v172 offset:23552
	global_load_lds_dwordx4 v[214:215], off
	s_add_i32 m0, s31, 0x2000
	s_add_u32 s68, s26, 0x160000
	v_lshl_add_u64 v[216:217], s[26:27], 0, v[136:137]
	s_addc_u32 s69, s27, 0
	s_add_i32 s31, s58, s33
	global_load_lds_dwordx4 v[216:217], off
	v_lshl_add_u64 v[218:219], s[68:69], 0, v[132:133]
	s_mov_b32 m0, s31
	v_lshl_add_u64 v[220:221], s[28:29], 0, v[134:135]
	global_load_lds_dwordx4 v[218:219], off
	v_lshl_add_u64 v[218:219], s[68:69], 0, v[136:137]
	s_add_i32 m0, s31, 0x2000
	s_nop 0
	global_load_lds_dwordx4 v[218:219], off
	v_lshl_add_u64 v[218:219], s[28:29], 0, v[130:131]
	s_mov_b32 m0, s34
	s_nop 0
	global_load_lds_dwordx4 v[218:219], off
	s_mov_b32 m0, s35
	s_nop 0
	global_load_lds_dwordx4 v[220:221], off
	s_waitcnt vmcnt(8)
	s_waitcnt lgkmcnt(0)
	s_barrier
	s_setprio 1
	s_waitcnt lgkmcnt(0)
	v_mfma_f32_16x16x32_bf16 v[62:65], v[144:147], v[182:185], 0
	v_mfma_f32_16x16x32_bf16 v[58:61], v[152:155], v[182:185], 0
	v_mfma_f32_16x16x32_bf16 v[50:53], v[144:147], v[190:193], 0
	v_mfma_f32_16x16x32_bf16 v[42:45], v[152:155], v[190:193], 0
	v_mfma_f32_16x16x32_bf16 v[30:33], v[144:147], v[198:201], 0
	v_mfma_f32_16x16x32_bf16 v[26:29], v[152:155], v[198:201], 0
	v_mfma_f32_16x16x32_bf16 v[18:21], v[144:147], v[206:209], 0
	v_mfma_f32_16x16x32_bf16 v[10:13], v[152:155], v[206:209], 0
	v_mfma_f32_16x16x32_bf16 v[62:65], v[148:151], v[186:189], v[62:65]
	v_mfma_f32_16x16x32_bf16 v[58:61], v[156:159], v[186:189], v[58:61]
	v_mfma_f32_16x16x32_bf16 v[50:53], v[148:151], v[194:197], v[50:53]
	v_mfma_f32_16x16x32_bf16 v[42:45], v[156:159], v[194:197], v[42:45]
	v_mfma_f32_16x16x32_bf16 v[30:33], v[148:151], v[202:205], v[30:33]
	v_mfma_f32_16x16x32_bf16 v[26:29], v[156:159], v[202:205], v[26:29]
	v_mfma_f32_16x16x32_bf16 v[18:21], v[148:151], v[210:213], v[18:21]
	v_mfma_f32_16x16x32_bf16 v[10:13], v[156:159], v[210:213], v[10:13]
	s_setprio 0
	s_setprio 1
	v_mfma_f32_16x16x32_bf16 v[54:57], v[160:163], v[182:185], 0
	v_mfma_f32_16x16x32_bf16 v[46:49], v[174:177], v[182:185], 0
	v_mfma_f32_16x16x32_bf16 v[38:41], v[160:163], v[190:193], 0
	v_mfma_f32_16x16x32_bf16 v[34:37], v[174:177], v[190:193], 0
	v_mfma_f32_16x16x32_bf16 v[22:25], v[160:163], v[198:201], 0
	v_mfma_f32_16x16x32_bf16 v[14:17], v[174:177], v[198:201], 0
	v_mfma_f32_16x16x32_bf16 v[6:9], v[160:163], v[206:209], 0
	v_mfma_f32_16x16x32_bf16 v[2:5], v[174:177], v[206:209], 0
	v_mfma_f32_16x16x32_bf16 v[54:57], v[164:167], v[186:189], v[54:57]
	v_mfma_f32_16x16x32_bf16 v[46:49], v[178:181], v[186:189], v[46:49]
	v_mfma_f32_16x16x32_bf16 v[38:41], v[164:167], v[194:197], v[38:41]
	v_mfma_f32_16x16x32_bf16 v[34:37], v[178:181], v[194:197], v[34:37]
	v_mfma_f32_16x16x32_bf16 v[22:25], v[164:167], v[202:205], v[22:25]
	v_mfma_f32_16x16x32_bf16 v[14:17], v[178:181], v[202:205], v[14:17]
	v_mfma_f32_16x16x32_bf16 v[6:9], v[164:167], v[210:213], v[6:9]
	s_barrier
	v_mfma_f32_16x16x32_bf16 v[2:5], v[178:181], v[210:213], v[2:5]
	s_setprio 0
	s_add_i32 s31, 0, 0x18000
	s_add_i32 s68, 0, 0x1c000
	v_add_u32_e32 v156, s31, v168
	v_add_u32_e32 v173, s68, v168
	ds_read_b128 v[144:147], v156
	ds_read_b128 v[148:151], v156 offset:1024
	ds_read_b128 v[152:155], v156 offset:2048
	ds_read_b128 v[156:159], v156 offset:3072
	ds_read_b128 v[160:163], v173
	ds_read_b128 v[164:167], v173 offset:1024
	ds_read_b128 v[174:177], v173 offset:2048
	ds_read_b128 v[178:181], v173 offset:3072
	s_add_u32 s28, s28, 0x160000
	s_addc_u32 s29, s29, 0
	s_mov_b32 m0, s36
	v_lshl_add_u64 v[222:223], s[28:29], 0, v[130:131]
	ds_read_b128 v[182:185], v172 offset:32768
	ds_read_b128 v[186:189], v172 offset:33792
	ds_read_b128 v[190:193], v172 offset:34816
	ds_read_b128 v[194:197], v172 offset:35840
	ds_read_b128 v[198:201], v172 offset:36864
	ds_read_b128 v[202:205], v172 offset:37888
	ds_read_b128 v[206:209], v172 offset:38912
	ds_read_b128 v[210:213], v172 offset:39936
	global_load_lds_dwordx4 v[222:223], off
	v_lshl_add_u64 v[222:223], s[28:29], 0, v[134:135]
	s_mov_b32 m0, s37
	s_nop 0
	global_load_lds_dwordx4 v[222:223], off
	s_waitcnt vmcnt(8)
	s_waitcnt lgkmcnt(0)
	s_barrier
	s_setprio 1
	s_waitcnt lgkmcnt(0)
	v_mfma_f32_16x16x32_bf16 v[126:129], v[144:147], v[182:185], v[126:129]
	v_mfma_f32_16x16x32_bf16 v[122:125], v[152:155], v[182:185], v[122:125]
	v_mfma_f32_16x16x32_bf16 v[118:121], v[144:147], v[190:193], v[118:121]
	v_mfma_f32_16x16x32_bf16 v[110:113], v[152:155], v[190:193], v[110:113]
	v_mfma_f32_16x16x32_bf16 v[94:97], v[144:147], v[198:201], v[94:97]
	v_mfma_f32_16x16x32_bf16 v[90:93], v[152:155], v[198:201], v[90:93]
	v_mfma_f32_16x16x32_bf16 v[82:85], v[144:147], v[206:209], v[82:85]
	v_mfma_f32_16x16x32_bf16 v[74:77], v[152:155], v[206:209], v[74:77]
	v_mfma_f32_16x16x32_bf16 v[126:129], v[148:151], v[186:189], v[126:129]
	v_mfma_f32_16x16x32_bf16 v[122:125], v[156:159], v[186:189], v[122:125]
	v_mfma_f32_16x16x32_bf16 v[118:121], v[148:151], v[194:197], v[118:121]
	v_mfma_f32_16x16x32_bf16 v[110:113], v[156:159], v[194:197], v[110:113]
	v_mfma_f32_16x16x32_bf16 v[94:97], v[148:151], v[202:205], v[94:97]
	v_mfma_f32_16x16x32_bf16 v[90:93], v[156:159], v[202:205], v[90:93]
	v_mfma_f32_16x16x32_bf16 v[82:85], v[148:151], v[210:213], v[82:85]
	v_mfma_f32_16x16x32_bf16 v[74:77], v[156:159], v[210:213], v[74:77]
	s_setprio 0
	s_setprio 1
	v_mfma_f32_16x16x32_bf16 v[114:117], v[160:163], v[182:185], v[114:117]
	v_mfma_f32_16x16x32_bf16 v[106:109], v[174:177], v[182:185], v[106:109]
	v_mfma_f32_16x16x32_bf16 v[102:105], v[160:163], v[190:193], v[102:105]
	v_mfma_f32_16x16x32_bf16 v[98:101], v[174:177], v[190:193], v[98:101]
	v_mfma_f32_16x16x32_bf16 v[86:89], v[160:163], v[198:201], v[86:89]
	v_mfma_f32_16x16x32_bf16 v[78:81], v[174:177], v[198:201], v[78:81]
	v_mfma_f32_16x16x32_bf16 v[70:73], v[160:163], v[206:209], v[70:73]
	v_mfma_f32_16x16x32_bf16 v[66:69], v[174:177], v[206:209], v[66:69]
	v_mfma_f32_16x16x32_bf16 v[114:117], v[164:167], v[186:189], v[114:117]
	v_mfma_f32_16x16x32_bf16 v[106:109], v[178:181], v[186:189], v[106:109]
	v_mfma_f32_16x16x32_bf16 v[102:105], v[164:167], v[194:197], v[102:105]
	v_mfma_f32_16x16x32_bf16 v[98:101], v[178:181], v[194:197], v[98:101]
	v_mfma_f32_16x16x32_bf16 v[86:89], v[164:167], v[202:205], v[86:89]
	v_mfma_f32_16x16x32_bf16 v[78:81], v[178:181], v[202:205], v[78:81]
	v_mfma_f32_16x16x32_bf16 v[70:73], v[164:167], v[210:213], v[70:73]
	s_barrier
	v_mfma_f32_16x16x32_bf16 v[66:69], v[178:181], v[210:213], v[66:69]
	s_setprio 0
	s_add_i32 s28, s31, s33
	v_lshl_add_u64 v[214:215], v[214:215], 0, s[12:13]
	s_mov_b32 m0, s28
	ds_read_b128 v[182:185], v172 offset:49152
	ds_read_b128 v[186:189], v172 offset:50176
	ds_read_b128 v[190:193], v172 offset:51200
	ds_read_b128 v[194:197], v172 offset:52224
	ds_read_b128 v[198:201], v172 offset:53248
	ds_read_b128 v[202:205], v172 offset:54272
	ds_read_b128 v[206:209], v172 offset:55296
	ds_read_b128 v[210:213], v172 offset:56320
	global_load_lds_dwordx4 v[214:215], off
	s_add_i32 m0, s28, 0x2000
	s_add_u32 s26, s26, 0x160080
	v_lshl_add_u64 v[214:215], v[216:217], 0, s[12:13]
	s_addc_u32 s27, s27, 0
	s_add_i32 s28, s68, s33
	global_load_lds_dwordx4 v[214:215], off
	v_lshl_add_u64 v[214:215], s[26:27], 0, v[132:133]
	s_mov_b32 m0, s28
	s_nop 0
	global_load_lds_dwordx4 v[214:215], off
	v_lshl_add_u64 v[214:215], s[26:27], 0, v[136:137]
	s_add_i32 m0, s28, 0x2000
	s_nop 0
	global_load_lds_dwordx4 v[214:215], off
	v_lshl_add_u64 v[214:215], v[218:219], 0, s[12:13]
	s_mov_b32 m0, s47
	s_nop 0
	global_load_lds_dwordx4 v[214:215], off
	v_lshl_add_u64 v[214:215], v[220:221], 0, s[12:13]
	s_mov_b32 m0, s48
	s_nop 0
	global_load_lds_dwordx4 v[214:215], off
	s_waitcnt vmcnt(8)
	s_waitcnt lgkmcnt(0)
	s_barrier
	s_setprio 1
	s_waitcnt lgkmcnt(0)
	v_mfma_f32_16x16x32_bf16 v[62:65], v[144:147], v[182:185], v[62:65]
	v_mfma_f32_16x16x32_bf16 v[58:61], v[152:155], v[182:185], v[58:61]
	v_mfma_f32_16x16x32_bf16 v[50:53], v[144:147], v[190:193], v[50:53]
	v_mfma_f32_16x16x32_bf16 v[42:45], v[152:155], v[190:193], v[42:45]
	v_mfma_f32_16x16x32_bf16 v[30:33], v[144:147], v[198:201], v[30:33]
	v_mfma_f32_16x16x32_bf16 v[26:29], v[152:155], v[198:201], v[26:29]
	v_mfma_f32_16x16x32_bf16 v[18:21], v[144:147], v[206:209], v[18:21]
	v_mfma_f32_16x16x32_bf16 v[10:13], v[152:155], v[206:209], v[10:13]
	v_mfma_f32_16x16x32_bf16 v[62:65], v[148:151], v[186:189], v[62:65]
	v_mfma_f32_16x16x32_bf16 v[58:61], v[156:159], v[186:189], v[58:61]
	v_mfma_f32_16x16x32_bf16 v[50:53], v[148:151], v[194:197], v[50:53]
	v_mfma_f32_16x16x32_bf16 v[42:45], v[156:159], v[194:197], v[42:45]
	v_mfma_f32_16x16x32_bf16 v[30:33], v[148:151], v[202:205], v[30:33]
	v_mfma_f32_16x16x32_bf16 v[26:29], v[156:159], v[202:205], v[26:29]
	v_mfma_f32_16x16x32_bf16 v[18:21], v[148:151], v[210:213], v[18:21]
	v_mfma_f32_16x16x32_bf16 v[10:13], v[156:159], v[210:213], v[10:13]
	s_setprio 0
	s_setprio 1
	v_mfma_f32_16x16x32_bf16 v[54:57], v[160:163], v[182:185], v[54:57]
	v_mfma_f32_16x16x32_bf16 v[46:49], v[174:177], v[182:185], v[46:49]
	v_mfma_f32_16x16x32_bf16 v[38:41], v[160:163], v[190:193], v[38:41]
	v_mfma_f32_16x16x32_bf16 v[34:37], v[174:177], v[190:193], v[34:37]
	v_mfma_f32_16x16x32_bf16 v[22:25], v[160:163], v[198:201], v[22:25]
	v_mfma_f32_16x16x32_bf16 v[14:17], v[174:177], v[198:201], v[14:17]
	v_mfma_f32_16x16x32_bf16 v[6:9], v[160:163], v[206:209], v[6:9]
	v_mfma_f32_16x16x32_bf16 v[2:5], v[174:177], v[206:209], v[2:5]
	v_mfma_f32_16x16x32_bf16 v[54:57], v[164:167], v[186:189], v[54:57]
	v_mfma_f32_16x16x32_bf16 v[46:49], v[178:181], v[186:189], v[46:49]
	v_mfma_f32_16x16x32_bf16 v[38:41], v[164:167], v[194:197], v[38:41]
	v_mfma_f32_16x16x32_bf16 v[34:37], v[178:181], v[194:197], v[34:37]
	v_mfma_f32_16x16x32_bf16 v[22:25], v[164:167], v[202:205], v[22:25]
	v_mfma_f32_16x16x32_bf16 v[14:17], v[178:181], v[202:205], v[14:17]
	v_mfma_f32_16x16x32_bf16 v[6:9], v[164:167], v[210:213], v[6:9]
	s_barrier
	v_mfma_f32_16x16x32_bf16 v[2:5], v[178:181], v[210:213], v[2:5]
	s_setprio 0
	s_add_u32 s24, s24, 0x100
	s_addc_u32 s25, s25, 0
	s_add_u32 s17, s17, 0x100
	s_addc_u32 s23, s23, 0
	s_cmp_ge_i32 s30, s67
	s_mov_b32 s26, s30
	s_cbranch_scc0 .LBB0_2683
	s_branch .Lpeeldone_0
.LBB0_2683:
	ds_read_b128 v[144:147], v170
	ds_read_b128 v[148:151], v170 offset:1024
	ds_read_b128 v[152:155], v170 offset:2048
	ds_read_b128 v[156:159], v170 offset:3072
	ds_read_b128 v[160:163], v171
	ds_read_b128 v[164:167], v171 offset:1024
	ds_read_b128 v[174:177], v171 offset:2048
	ds_read_b128 v[178:181], v171 offset:3072
	s_add_i32 s30, s26, 2
	s_add_u32 s27, s24, 0xffea0080
	s_addc_u32 s28, s25, -1
	s_cmp_eq_u32 s22, s26
	s_cselect_b32 s26, s20, s17
	s_cselect_b32 s29, s19, s28
	s_cselect_b32 s28, s18, s27
	s_cselect_b32 s27, s21, s23
	v_lshl_add_u64 v[214:215], s[24:25], 0, v[140:141]
	s_add_i32 m0, s34, 0xc000
	ds_read_b128 v[182:185], v172
	ds_read_b128 v[186:189], v172 offset:1024
	ds_read_b128 v[190:193], v172 offset:2048
	ds_read_b128 v[194:197], v172 offset:3072
	ds_read_b128 v[198:201], v172 offset:4096
	ds_read_b128 v[202:205], v172 offset:5120
	ds_read_b128 v[206:209], v172 offset:6144
	ds_read_b128 v[210:213], v172 offset:7168
	global_load_lds_dwordx4 v[214:215], off
	v_lshl_add_u64 v[214:215], s[24:25], 0, v[142:143]
	s_add_i32 m0, s34, 0xe000
	s_nop 0
	global_load_lds_dwordx4 v[214:215], off
	s_waitcnt vmcnt(8)
	s_waitcnt lgkmcnt(0)
	s_barrier
	s_setprio 1
	s_waitcnt lgkmcnt(0)
	v_mfma_f32_16x16x32_bf16 v[126:129], v[144:147], v[182:185], v[126:129]
	v_mfma_f32_16x16x32_bf16 v[122:125], v[152:155], v[182:185], v[122:125]
	v_mfma_f32_16x16x32_bf16 v[118:121], v[144:147], v[190:193], v[118:121]
	v_mfma_f32_16x16x32_bf16 v[110:113], v[152:155], v[190:193], v[110:113]
	v_mfma_f32_16x16x32_bf16 v[94:97], v[144:147], v[198:201], v[94:97]
	v_mfma_f32_16x16x32_bf16 v[90:93], v[152:155], v[198:201], v[90:93]
	v_mfma_f32_16x16x32_bf16 v[82:85], v[144:147], v[206:209], v[82:85]
	v_mfma_f32_16x16x32_bf16 v[74:77], v[152:155], v[206:209], v[74:77]
	v_mfma_f32_16x16x32_bf16 v[126:129], v[148:151], v[186:189], v[126:129]
	v_mfma_f32_16x16x32_bf16 v[122:125], v[156:159], v[186:189], v[122:125]
	v_mfma_f32_16x16x32_bf16 v[118:121], v[148:151], v[194:197], v[118:121]
	v_mfma_f32_16x16x32_bf16 v[110:113], v[156:159], v[194:197], v[110:113]
	v_mfma_f32_16x16x32_bf16 v[94:97], v[148:151], v[202:205], v[94:97]
	v_mfma_f32_16x16x32_bf16 v[90:93], v[156:159], v[202:205], v[90:93]
	v_mfma_f32_16x16x32_bf16 v[82:85], v[148:151], v[210:213], v[82:85]
	v_mfma_f32_16x16x32_bf16 v[74:77], v[156:159], v[210:213], v[74:77]
	s_setprio 0
	s_setprio 1
	v_mfma_f32_16x16x32_bf16 v[114:117], v[160:163], v[182:185], v[114:117]
	v_mfma_f32_16x16x32_bf16 v[106:109], v[174:177], v[182:185], v[106:109]
	v_mfma_f32_16x16x32_bf16 v[102:105], v[160:163], v[190:193], v[102:105]
	v_mfma_f32_16x16x32_bf16 v[98:101], v[174:177], v[190:193], v[98:101]
	v_mfma_f32_16x16x32_bf16 v[86:89], v[160:163], v[198:201], v[86:89]
	v_mfma_f32_16x16x32_bf16 v[78:81], v[174:177], v[198:201], v[78:81]
	v_mfma_f32_16x16x32_bf16 v[70:73], v[160:163], v[206:209], v[70:73]
	v_mfma_f32_16x16x32_bf16 v[66:69], v[174:177], v[206:209], v[66:69]
	v_mfma_f32_16x16x32_bf16 v[114:117], v[164:167], v[186:189], v[114:117]
	v_mfma_f32_16x16x32_bf16 v[106:109], v[178:181], v[186:189], v[106:109]
	v_mfma_f32_16x16x32_bf16 v[102:105], v[164:167], v[194:197], v[102:105]
	v_mfma_f32_16x16x32_bf16 v[98:101], v[178:181], v[194:197], v[98:101]
	v_mfma_f32_16x16x32_bf16 v[86:89], v[164:167], v[202:205], v[86:89]
	v_mfma_f32_16x16x32_bf16 v[78:81], v[178:181], v[202:205], v[78:81]
	v_mfma_f32_16x16x32_bf16 v[70:73], v[164:167], v[210:213], v[70:73]
	s_barrier
	v_mfma_f32_16x16x32_bf16 v[66:69], v[178:181], v[210:213], v[66:69]
	s_setprio 0
	s_add_i32 s31, s57, s33
	v_lshl_add_u64 v[214:215], s[26:27], 0, v[132:133]
	s_mov_b32 m0, s31
	ds_read_b128 v[182:185], v172 offset:16384
	ds_read_b128 v[186:189], v172 offset:17408
	ds_read_b128 v[190:193], v172 offset:18432
	ds_read_b128 v[194:197], v172 offset:19456
	ds_read_b128 v[198:201], v172 offset:20480
	ds_read_b128 v[202:205], v172 offset:21504
	ds_read_b128 v[206:209], v172 offset:22528
	ds_read_b128 v[210:213], v172 offset:23552
	global_load_lds_dwordx4 v[214:215], off
	s_add_i32 m0, s31, 0x2000
	s_add_u32 s68, s26, 0x160000
	v_lshl_add_u64 v[216:217], s[26:27], 0, v[136:137]
	s_addc_u32 s69, s27, 0
	s_add_i32 s31, s58, s33
	global_load_lds_dwordx4 v[216:217], off
	v_lshl_add_u64 v[218:219], s[68:69], 0, v[132:133]
	s_mov_b32 m0, s31
	v_lshl_add_u64 v[220:221], s[28:29], 0, v[134:135]
	global_load_lds_dwordx4 v[218:219], off
	v_lshl_add_u64 v[218:219], s[68:69], 0, v[136:137]
	s_add_i32 m0, s31, 0x2000
	s_nop 0
	global_load_lds_dwordx4 v[218:219], off
	v_lshl_add_u64 v[218:219], s[28:29], 0, v[130:131]
	s_mov_b32 m0, s34
	s_nop 0
	global_load_lds_dwordx4 v[218:219], off
	s_mov_b32 m0, s35
	s_nop 0
	global_load_lds_dwordx4 v[220:221], off
	s_waitcnt vmcnt(8)
	s_waitcnt lgkmcnt(0)
	s_barrier
	s_setprio 1
	s_waitcnt lgkmcnt(0)
	v_mfma_f32_16x16x32_bf16 v[62:65], v[144:147], v[182:185], v[62:65]
	v_mfma_f32_16x16x32_bf16 v[58:61], v[152:155], v[182:185], v[58:61]
	v_mfma_f32_16x16x32_bf16 v[50:53], v[144:147], v[190:193], v[50:53]
	v_mfma_f32_16x16x32_bf16 v[42:45], v[152:155], v[190:193], v[42:45]
	v_mfma_f32_16x16x32_bf16 v[30:33], v[144:147], v[198:201], v[30:33]
	v_mfma_f32_16x16x32_bf16 v[26:29], v[152:155], v[198:201], v[26:29]
	v_mfma_f32_16x16x32_bf16 v[18:21], v[144:147], v[206:209], v[18:21]
	v_mfma_f32_16x16x32_bf16 v[10:13], v[152:155], v[206:209], v[10:13]
	v_mfma_f32_16x16x32_bf16 v[62:65], v[148:151], v[186:189], v[62:65]
	v_mfma_f32_16x16x32_bf16 v[58:61], v[156:159], v[186:189], v[58:61]
	v_mfma_f32_16x16x32_bf16 v[50:53], v[148:151], v[194:197], v[50:53]
	v_mfma_f32_16x16x32_bf16 v[42:45], v[156:159], v[194:197], v[42:45]
	v_mfma_f32_16x16x32_bf16 v[30:33], v[148:151], v[202:205], v[30:33]
	v_mfma_f32_16x16x32_bf16 v[26:29], v[156:159], v[202:205], v[26:29]
	v_mfma_f32_16x16x32_bf16 v[18:21], v[148:151], v[210:213], v[18:21]
	v_mfma_f32_16x16x32_bf16 v[10:13], v[156:159], v[210:213], v[10:13]
	s_setprio 0
	s_setprio 1
	v_mfma_f32_16x16x32_bf16 v[54:57], v[160:163], v[182:185], v[54:57]
	v_mfma_f32_16x16x32_bf16 v[46:49], v[174:177], v[182:185], v[46:49]
	v_mfma_f32_16x16x32_bf16 v[38:41], v[160:163], v[190:193], v[38:41]
	v_mfma_f32_16x16x32_bf16 v[34:37], v[174:177], v[190:193], v[34:37]
	v_mfma_f32_16x16x32_bf16 v[22:25], v[160:163], v[198:201], v[22:25]
	v_mfma_f32_16x16x32_bf16 v[14:17], v[174:177], v[198:201], v[14:17]
	v_mfma_f32_16x16x32_bf16 v[6:9], v[160:163], v[206:209], v[6:9]
	v_mfma_f32_16x16x32_bf16 v[2:5], v[174:177], v[206:209], v[2:5]
	v_mfma_f32_16x16x32_bf16 v[54:57], v[164:167], v[186:189], v[54:57]
	v_mfma_f32_16x16x32_bf16 v[46:49], v[178:181], v[186:189], v[46:49]
	v_mfma_f32_16x16x32_bf16 v[38:41], v[164:167], v[194:197], v[38:41]
	v_mfma_f32_16x16x32_bf16 v[34:37], v[178:181], v[194:197], v[34:37]
	v_mfma_f32_16x16x32_bf16 v[22:25], v[164:167], v[202:205], v[22:25]
	v_mfma_f32_16x16x32_bf16 v[14:17], v[178:181], v[202:205], v[14:17]
	v_mfma_f32_16x16x32_bf16 v[6:9], v[164:167], v[210:213], v[6:9]
	s_barrier
	v_mfma_f32_16x16x32_bf16 v[2:5], v[178:181], v[210:213], v[2:5]
	s_setprio 0
	s_add_i32 s31, 0, 0x18000
	s_add_i32 s68, 0, 0x1c000
	v_add_u32_e32 v156, s31, v168
	v_add_u32_e32 v173, s68, v168
	ds_read_b128 v[144:147], v156
	ds_read_b128 v[148:151], v156 offset:1024
	ds_read_b128 v[152:155], v156 offset:2048
	ds_read_b128 v[156:159], v156 offset:3072
	ds_read_b128 v[160:163], v173
	ds_read_b128 v[164:167], v173 offset:1024
	ds_read_b128 v[174:177], v173 offset:2048
	ds_read_b128 v[178:181], v173 offset:3072
	s_add_u32 s28, s28, 0x160000
	s_addc_u32 s29, s29, 0
	s_mov_b32 m0, s36
	v_lshl_add_u64 v[222:223], s[28:29], 0, v[130:131]
	ds_read_b128 v[182:185], v172 offset:32768
	ds_read_b128 v[186:189], v172 offset:33792
	ds_read_b128 v[190:193], v172 offset:34816
	ds_read_b128 v[194:197], v172 offset:35840
	ds_read_b128 v[198:201], v172 offset:36864
	ds_read_b128 v[202:205], v172 offset:37888
	ds_read_b128 v[206:209], v172 offset:38912
	ds_read_b128 v[210:213], v172 offset:39936
	global_load_lds_dwordx4 v[222:223], off
	v_lshl_add_u64 v[222:223], s[28:29], 0, v[134:135]
	s_mov_b32 m0, s37
	s_nop 0
	global_load_lds_dwordx4 v[222:223], off
	s_waitcnt vmcnt(8)
	s_waitcnt lgkmcnt(0)
	s_barrier
	s_setprio 1
	s_waitcnt lgkmcnt(0)
	v_mfma_f32_16x16x32_bf16 v[126:129], v[144:147], v[182:185], v[126:129]
	v_mfma_f32_16x16x32_bf16 v[122:125], v[152:155], v[182:185], v[122:125]
	v_mfma_f32_16x16x32_bf16 v[118:121], v[144:147], v[190:193], v[118:121]
	v_mfma_f32_16x16x32_bf16 v[110:113], v[152:155], v[190:193], v[110:113]
	v_mfma_f32_16x16x32_bf16 v[94:97], v[144:147], v[198:201], v[94:97]
	v_mfma_f32_16x16x32_bf16 v[90:93], v[152:155], v[198:201], v[90:93]
	v_mfma_f32_16x16x32_bf16 v[82:85], v[144:147], v[206:209], v[82:85]
	v_mfma_f32_16x16x32_bf16 v[74:77], v[152:155], v[206:209], v[74:77]
	v_mfma_f32_16x16x32_bf16 v[126:129], v[148:151], v[186:189], v[126:129]
	v_mfma_f32_16x16x32_bf16 v[122:125], v[156:159], v[186:189], v[122:125]
	v_mfma_f32_16x16x32_bf16 v[118:121], v[148:151], v[194:197], v[118:121]
	v_mfma_f32_16x16x32_bf16 v[110:113], v[156:159], v[194:197], v[110:113]
	v_mfma_f32_16x16x32_bf16 v[94:97], v[148:151], v[202:205], v[94:97]
	v_mfma_f32_16x16x32_bf16 v[90:93], v[156:159], v[202:205], v[90:93]
	v_mfma_f32_16x16x32_bf16 v[82:85], v[148:151], v[210:213], v[82:85]
	v_mfma_f32_16x16x32_bf16 v[74:77], v[156:159], v[210:213], v[74:77]
	s_setprio 0
	s_setprio 1
	v_mfma_f32_16x16x32_bf16 v[114:117], v[160:163], v[182:185], v[114:117]
	v_mfma_f32_16x16x32_bf16 v[106:109], v[174:177], v[182:185], v[106:109]
	v_mfma_f32_16x16x32_bf16 v[102:105], v[160:163], v[190:193], v[102:105]
	v_mfma_f32_16x16x32_bf16 v[98:101], v[174:177], v[190:193], v[98:101]
	v_mfma_f32_16x16x32_bf16 v[86:89], v[160:163], v[198:201], v[86:89]
	v_mfma_f32_16x16x32_bf16 v[78:81], v[174:177], v[198:201], v[78:81]
	v_mfma_f32_16x16x32_bf16 v[70:73], v[160:163], v[206:209], v[70:73]
	v_mfma_f32_16x16x32_bf16 v[66:69], v[174:177], v[206:209], v[66:69]
	v_mfma_f32_16x16x32_bf16 v[114:117], v[164:167], v[186:189], v[114:117]
	v_mfma_f32_16x16x32_bf16 v[106:109], v[178:181], v[186:189], v[106:109]
	v_mfma_f32_16x16x32_bf16 v[102:105], v[164:167], v[194:197], v[102:105]
	v_mfma_f32_16x16x32_bf16 v[98:101], v[178:181], v[194:197], v[98:101]
	v_mfma_f32_16x16x32_bf16 v[86:89], v[164:167], v[202:205], v[86:89]
	v_mfma_f32_16x16x32_bf16 v[78:81], v[178:181], v[202:205], v[78:81]
	v_mfma_f32_16x16x32_bf16 v[70:73], v[164:167], v[210:213], v[70:73]
	s_barrier
	v_mfma_f32_16x16x32_bf16 v[66:69], v[178:181], v[210:213], v[66:69]
	s_setprio 0
	s_add_i32 s28, s31, s33
	v_lshl_add_u64 v[214:215], v[214:215], 0, s[12:13]
	s_mov_b32 m0, s28
	ds_read_b128 v[182:185], v172 offset:49152
	ds_read_b128 v[186:189], v172 offset:50176
	ds_read_b128 v[190:193], v172 offset:51200
	ds_read_b128 v[194:197], v172 offset:52224
	ds_read_b128 v[198:201], v172 offset:53248
	ds_read_b128 v[202:205], v172 offset:54272
	ds_read_b128 v[206:209], v172 offset:55296
	ds_read_b128 v[210:213], v172 offset:56320
	global_load_lds_dwordx4 v[214:215], off
	s_add_i32 m0, s28, 0x2000
	s_add_u32 s26, s26, 0x160080
	v_lshl_add_u64 v[214:215], v[216:217], 0, s[12:13]
	s_addc_u32 s27, s27, 0
	s_add_i32 s28, s68, s33
	global_load_lds_dwordx4 v[214:215], off
	v_lshl_add_u64 v[214:215], s[26:27], 0, v[132:133]
	s_mov_b32 m0, s28
	s_nop 0
	global_load_lds_dwordx4 v[214:215], off
	v_lshl_add_u64 v[214:215], s[26:27], 0, v[136:137]
	s_add_i32 m0, s28, 0x2000
	s_nop 0
	global_load_lds_dwordx4 v[214:215], off
	v_lshl_add_u64 v[214:215], v[218:219], 0, s[12:13]
	s_mov_b32 m0, s47
	s_nop 0
	global_load_lds_dwordx4 v[214:215], off
	v_lshl_add_u64 v[214:215], v[220:221], 0, s[12:13]
	s_mov_b32 m0, s48
	s_nop 0
	global_load_lds_dwordx4 v[214:215], off
	s_waitcnt vmcnt(8)
	s_waitcnt lgkmcnt(0)
	s_barrier
	s_setprio 1
	s_waitcnt lgkmcnt(0)
	v_mfma_f32_16x16x32_bf16 v[62:65], v[144:147], v[182:185], v[62:65]
	v_mfma_f32_16x16x32_bf16 v[58:61], v[152:155], v[182:185], v[58:61]
	v_mfma_f32_16x16x32_bf16 v[50:53], v[144:147], v[190:193], v[50:53]
	v_mfma_f32_16x16x32_bf16 v[42:45], v[152:155], v[190:193], v[42:45]
	v_mfma_f32_16x16x32_bf16 v[30:33], v[144:147], v[198:201], v[30:33]
	v_mfma_f32_16x16x32_bf16 v[26:29], v[152:155], v[198:201], v[26:29]
	v_mfma_f32_16x16x32_bf16 v[18:21], v[144:147], v[206:209], v[18:21]
	v_mfma_f32_16x16x32_bf16 v[10:13], v[152:155], v[206:209], v[10:13]
	v_mfma_f32_16x16x32_bf16 v[62:65], v[148:151], v[186:189], v[62:65]
	v_mfma_f32_16x16x32_bf16 v[58:61], v[156:159], v[186:189], v[58:61]
	v_mfma_f32_16x16x32_bf16 v[50:53], v[148:151], v[194:197], v[50:53]
	v_mfma_f32_16x16x32_bf16 v[42:45], v[156:159], v[194:197], v[42:45]
	v_mfma_f32_16x16x32_bf16 v[30:33], v[148:151], v[202:205], v[30:33]
	v_mfma_f32_16x16x32_bf16 v[26:29], v[156:159], v[202:205], v[26:29]
	v_mfma_f32_16x16x32_bf16 v[18:21], v[148:151], v[210:213], v[18:21]
	v_mfma_f32_16x16x32_bf16 v[10:13], v[156:159], v[210:213], v[10:13]
	s_setprio 0
	s_setprio 1
	v_mfma_f32_16x16x32_bf16 v[54:57], v[160:163], v[182:185], v[54:57]
	v_mfma_f32_16x16x32_bf16 v[46:49], v[174:177], v[182:185], v[46:49]
	v_mfma_f32_16x16x32_bf16 v[38:41], v[160:163], v[190:193], v[38:41]
	v_mfma_f32_16x16x32_bf16 v[34:37], v[174:177], v[190:193], v[34:37]
	v_mfma_f32_16x16x32_bf16 v[22:25], v[160:163], v[198:201], v[22:25]
	v_mfma_f32_16x16x32_bf16 v[14:17], v[174:177], v[198:201], v[14:17]
	v_mfma_f32_16x16x32_bf16 v[6:9], v[160:163], v[206:209], v[6:9]
	v_mfma_f32_16x16x32_bf16 v[2:5], v[174:177], v[206:209], v[2:5]
	v_mfma_f32_16x16x32_bf16 v[54:57], v[164:167], v[186:189], v[54:57]
	v_mfma_f32_16x16x32_bf16 v[46:49], v[178:181], v[186:189], v[46:49]
	v_mfma_f32_16x16x32_bf16 v[38:41], v[164:167], v[194:197], v[38:41]
	v_mfma_f32_16x16x32_bf16 v[34:37], v[178:181], v[194:197], v[34:37]
	v_mfma_f32_16x16x32_bf16 v[22:25], v[164:167], v[202:205], v[22:25]
	v_mfma_f32_16x16x32_bf16 v[14:17], v[178:181], v[202:205], v[14:17]
	v_mfma_f32_16x16x32_bf16 v[6:9], v[164:167], v[210:213], v[6:9]
	s_barrier
	v_mfma_f32_16x16x32_bf16 v[2:5], v[178:181], v[210:213], v[2:5]
	s_setprio 0
	s_add_u32 s24, s24, 0x100
	s_addc_u32 s25, s25, 0
	s_add_u32 s17, s17, 0x100
	s_addc_u32 s23, s23, 0
	s_cmp_ge_i32 s30, s67
	s_mov_b32 s26, s30
	s_cbranch_scc0 .LBB0_2683
